# speedup vs baseline: 1.0441x; 1.0155x over previous
; DEV bf16_t f2bf(float f) { return (bf16_t)(cvtpk(f, 0.f) & 0xffffu); }
;   DEV void operator()(f32x16 (&acc)[2][2], int mb, int nb, int r32, int hh) const {
; #pragma unroll
;     for (int mi = 0; mi < 2; ++mi)
; #pragma unroll
;       for (int ni = 0; ni < 2; ++ni)
; #pragma unroll
;         for (int r = 0; r < 16; ++r) {
;           int row = mb + mi * 32 + 8 * (r >> 2) + 4 * hh + (r & 3);
;           C[(size_t)row * ldc + nb + ni * 32 + r32] = f2bf(acc[mi][ni][r]);
;         }
;   }
.LBB0_67:
	s_or_b32 s2, s53, s31
	s_ashr_i32 s3, s2, 31
	s_add_i32 s52, s52, s30
	s_lshl_b64 s[2:3], s[2:3], 1
	v_lshl_or_b32 v152, v133, 2, s52
	s_add_u32 s2, s27, s2
	s_addc_u32 s3, s28, s3
	v_lshlrev_b32_e32 v154, 1, v130
	v_mov_b32_e32 v155, v0
	v_ashrrev_i32_e32 v153, 31, v152
	v_lshl_add_u64 v[154:155], s[2:3], 0, v[154:155]
	v_lshlrev_b64 v[156:157], 12, v[152:153]
	v_cvt_pk_bf16_f32 v1, v114, s0
	v_lshl_add_u64 v[156:157], v[154:155], 0, v[156:157]
	v_or_b32_e32 v114, 1, v152
	global_store_short v[156:157], v1, off
	v_cvt_pk_bf16_f32 v1, v115, s0
	v_ashrrev_i32_e32 v115, 31, v114
	v_or_b32_e32 v158, 2, v152
	v_lshlrev_b64 v[114:115], 12, v[114:115]
	v_ashrrev_i32_e32 v159, 31, v158
	v_lshl_add_u64 v[114:115], v[154:155], 0, v[114:115]
	v_lshlrev_b64 v[158:159], 12, v[158:159]
	global_store_short v[114:115], v1, off
	v_cvt_pk_bf16_f32 v1, v116, s0
	v_lshl_add_u64 v[158:159], v[154:155], 0, v[158:159]
	v_or_b32_e32 v116, 3, v152
	global_store_short v[158:159], v1, off
	v_cvt_pk_bf16_f32 v1, v117, s0
	v_ashrrev_i32_e32 v117, 31, v116
	v_or_b32_e32 v160, 8, v152
	v_lshlrev_b64 v[116:117], 12, v[116:117]
	v_ashrrev_i32_e32 v161, 31, v160
	v_lshl_add_u64 v[116:117], v[154:155], 0, v[116:117]
	v_lshlrev_b64 v[160:161], 12, v[160:161]
	global_store_short v[116:117], v1, off
	v_cvt_pk_bf16_f32 v1, v118, s0
	v_lshl_add_u64 v[160:161], v[154:155], 0, v[160:161]
	v_or_b32_e32 v118, 9, v152
	global_store_short v[160:161], v1, off
	v_cvt_pk_bf16_f32 v1, v119, s0
	v_ashrrev_i32_e32 v119, 31, v118
	v_or_b32_e32 v162, 10, v152
	v_lshlrev_b64 v[118:119], 12, v[118:119]
	v_ashrrev_i32_e32 v163, 31, v162
	v_lshl_add_u64 v[118:119], v[154:155], 0, v[118:119]
	v_lshlrev_b64 v[162:163], 12, v[162:163]
	global_store_short v[118:119], v1, off
	v_cvt_pk_bf16_f32 v1, v120, s0
	v_lshl_add_u64 v[162:163], v[154:155], 0, v[162:163]
	v_or_b32_e32 v120, 11, v152
	global_store_short v[162:163], v1, off
	v_cvt_pk_bf16_f32 v1, v121, s0
	v_ashrrev_i32_e32 v121, 31, v120
	v_or_b32_e32 v164, 16, v152
	v_lshlrev_b64 v[120:121], 12, v[120:121]
	v_ashrrev_i32_e32 v165, 31, v164
	v_lshl_add_u64 v[120:121], v[154:155], 0, v[120:121]
	v_lshlrev_b64 v[164:165], 12, v[164:165]
	global_store_short v[120:121], v1, off
	v_cvt_pk_bf16_f32 v1, v122, s0
	v_lshl_add_u64 v[164:165], v[154:155], 0, v[164:165]
	v_or_b32_e32 v122, 17, v152
	global_store_short v[164:165], v1, off
	v_cvt_pk_bf16_f32 v1, v123, s0
	v_ashrrev_i32_e32 v123, 31, v122
	v_or_b32_e32 v166, 18, v152
	v_lshlrev_b64 v[122:123], 12, v[122:123]
	v_ashrrev_i32_e32 v167, 31, v166
	v_lshl_add_u64 v[122:123], v[154:155], 0, v[122:123]
	v_lshlrev_b64 v[166:167], 12, v[166:167]
	global_store_short v[122:123], v1, off
	v_cvt_pk_bf16_f32 v1, v124, s0
	v_lshl_add_u64 v[166:167], v[154:155], 0, v[166:167]
	v_or_b32_e32 v124, 19, v152
	global_store_short v[166:167], v1, off
	v_cvt_pk_bf16_f32 v1, v125, s0
	v_ashrrev_i32_e32 v125, 31, v124
	v_or_b32_e32 v168, 24, v152
	v_lshlrev_b64 v[124:125], 12, v[124:125]
	v_ashrrev_i32_e32 v169, 31, v168
	v_lshl_add_u64 v[124:125], v[154:155], 0, v[124:125]
	v_lshlrev_b64 v[168:169], 12, v[168:169]
	global_store_short v[124:125], v1, off
	v_cvt_pk_bf16_f32 v1, v126, s0
	v_lshl_add_u64 v[168:169], v[154:155], 0, v[168:169]
	v_or_b32_e32 v126, 25, v152
	global_store_short v[168:169], v1, off
	v_cvt_pk_bf16_f32 v1, v127, s0
	v_ashrrev_i32_e32 v127, 31, v126
	v_or_b32_e32 v170, 26, v152
	v_lshlrev_b64 v[126:127], 12, v[126:127]
	v_ashrrev_i32_e32 v171, 31, v170
	v_lshl_add_u64 v[126:127], v[154:155], 0, v[126:127]
	v_lshlrev_b64 v[170:171], 12, v[170:171]
	global_store_short v[126:127], v1, off
	v_cvt_pk_bf16_f32 v1, v128, s0
	v_lshl_add_u64 v[170:171], v[154:155], 0, v[170:171]
	v_or_b32_e32 v128, 27, v152
	global_store_short v[170:171], v1, off
	v_cvt_pk_bf16_f32 v1, v129, s0
	v_ashrrev_i32_e32 v129, 31, v128
	v_lshlrev_b64 v[128:129], 12, v[128:129]
	v_lshl_add_u64 v[128:129], v[154:155], 0, v[128:129]
	global_store_short v[128:129], v1, off
	v_cvt_pk_bf16_f32 v1, v98, s0
	global_store_short v[156:157], v1, off offset:64
	v_cvt_pk_bf16_f32 v1, v99, s0
	global_store_short v[114:115], v1, off offset:64
	v_cvt_pk_bf16_f32 v1, v100, s0
	global_store_short v[158:159], v1, off offset:64
	v_cvt_pk_bf16_f32 v1, v101, s0
	global_store_short v[116:117], v1, off offset:64
	v_cvt_pk_bf16_f32 v1, v102, s0
	global_store_short v[160:161], v1, off offset:64
	v_cvt_pk_bf16_f32 v1, v103, s0
	global_store_short v[118:119], v1, off offset:64
	v_cvt_pk_bf16_f32 v1, v104, s0
	global_store_short v[162:163], v1, off offset:64
	v_cvt_pk_bf16_f32 v1, v105, s0
	global_store_short v[120:121], v1, off offset:64
	v_cvt_pk_bf16_f32 v1, v106, s0
	global_store_short v[164:165], v1, off offset:64
	v_cvt_pk_bf16_f32 v1, v107, s0
	global_store_short v[122:123], v1, off offset:64
	v_cvt_pk_bf16_f32 v1, v108, s0
	global_store_short v[166:167], v1, off offset:64
	v_cvt_pk_bf16_f32 v1, v109, s0
	global_store_short v[124:125], v1, off offset:64
	v_cvt_pk_bf16_f32 v1, v110, s0
	global_store_short v[168:169], v1, off offset:64
	v_cvt_pk_bf16_f32 v1, v111, s0
	v_or_b32_e32 v98, 32, v152
	global_store_short v[126:127], v1, off offset:64
	v_cvt_pk_bf16_f32 v1, v112, s0
	v_ashrrev_i32_e32 v99, 31, v98
	global_store_short v[170:171], v1, off offset:64
	v_cvt_pk_bf16_f32 v1, v113, s0
	v_lshlrev_b64 v[98:99], 12, v[98:99]
	global_store_short v[128:129], v1, off offset:64
	v_cvt_pk_bf16_f32 v1, v82, s0
	v_lshl_add_u64 v[98:99], v[154:155], 0, v[98:99]
	v_or_b32_e32 v82, 33, v152
	global_store_short v[98:99], v1, off
	v_cvt_pk_bf16_f32 v1, v83, s0
	v_ashrrev_i32_e32 v83, 31, v82
	v_or_b32_e32 v100, 34, v152
	v_lshlrev_b64 v[82:83], 12, v[82:83]
; DEV bf16_t f2bf(float f) { return (bf16_t)(cvtpk(f, 0.f) & 0xffffu); }
;   DEV void operator()(f32x16 (&acc)[2][2], int mb, int nb, int r32, int hh) const {
; #pragma unroll
;     for (int mi = 0; mi < 2; ++mi)
; #pragma unroll
;       for (int ni = 0; ni < 2; ++ni)
; #pragma unroll
;         for (int r = 0; r < 16; ++r) {
;           int row = mb + mi * 32 + 8 * (r >> 2) + 4 * hh + (r & 3);
;           C[(size_t)row * ldc + nb + ni * 32 + r32] = f2bf(acc[mi][ni][r]);
;         }
;   }
	v_ashrrev_i32_e32 v101, 31, v100
	v_lshl_add_u64 v[82:83], v[154:155], 0, v[82:83]
	v_lshlrev_b64 v[100:101], 12, v[100:101]
	global_store_short v[82:83], v1, off
	v_cvt_pk_bf16_f32 v1, v84, s0
	v_lshl_add_u64 v[100:101], v[154:155], 0, v[100:101]
	v_or_b32_e32 v84, 35, v152
	global_store_short v[100:101], v1, off
	v_cvt_pk_bf16_f32 v1, v85, s0
	v_ashrrev_i32_e32 v85, 31, v84
	v_or_b32_e32 v102, 40, v152
	v_lshlrev_b64 v[84:85], 12, v[84:85]
	v_ashrrev_i32_e32 v103, 31, v102
	v_lshl_add_u64 v[84:85], v[154:155], 0, v[84:85]
	v_lshlrev_b64 v[102:103], 12, v[102:103]
	global_store_short v[84:85], v1, off
	v_cvt_pk_bf16_f32 v1, v86, s0
	v_lshl_add_u64 v[102:103], v[154:155], 0, v[102:103]
	v_or_b32_e32 v86, 41, v152
	global_store_short v[102:103], v1, off
	v_cvt_pk_bf16_f32 v1, v87, s0
	v_ashrrev_i32_e32 v87, 31, v86
	v_or_b32_e32 v104, 42, v152
	v_lshlrev_b64 v[86:87], 12, v[86:87]
	v_ashrrev_i32_e32 v105, 31, v104
	v_lshl_add_u64 v[86:87], v[154:155], 0, v[86:87]
	v_lshlrev_b64 v[104:105], 12, v[104:105]
	global_store_short v[86:87], v1, off
	v_cvt_pk_bf16_f32 v1, v88, s0
	v_lshl_add_u64 v[104:105], v[154:155], 0, v[104:105]
	v_or_b32_e32 v88, 43, v152
	global_store_short v[104:105], v1, off
	v_cvt_pk_bf16_f32 v1, v89, s0
	v_ashrrev_i32_e32 v89, 31, v88
	v_or_b32_e32 v106, 48, v152
	v_lshlrev_b64 v[88:89], 12, v[88:89]
	v_ashrrev_i32_e32 v107, 31, v106
	v_lshl_add_u64 v[88:89], v[154:155], 0, v[88:89]
	v_lshlrev_b64 v[106:107], 12, v[106:107]
	global_store_short v[88:89], v1, off
	v_cvt_pk_bf16_f32 v1, v90, s0
	v_lshl_add_u64 v[106:107], v[154:155], 0, v[106:107]
	v_or_b32_e32 v90, 49, v152
	global_store_short v[106:107], v1, off
	v_cvt_pk_bf16_f32 v1, v91, s0
	v_ashrrev_i32_e32 v91, 31, v90
	v_or_b32_e32 v108, 50, v152
	v_lshlrev_b64 v[90:91], 12, v[90:91]
	v_ashrrev_i32_e32 v109, 31, v108
	v_lshl_add_u64 v[90:91], v[154:155], 0, v[90:91]
	v_lshlrev_b64 v[108:109], 12, v[108:109]
	global_store_short v[90:91], v1, off
	v_cvt_pk_bf16_f32 v1, v92, s0
	v_lshl_add_u64 v[108:109], v[154:155], 0, v[108:109]
	v_or_b32_e32 v92, 51, v152
	global_store_short v[108:109], v1, off
	v_cvt_pk_bf16_f32 v1, v93, s0
	v_ashrrev_i32_e32 v93, 31, v92
	v_or_b32_e32 v110, 56, v152
	v_lshlrev_b64 v[92:93], 12, v[92:93]
	v_ashrrev_i32_e32 v111, 31, v110
	v_lshl_add_u64 v[92:93], v[154:155], 0, v[92:93]
	v_lshlrev_b64 v[110:111], 12, v[110:111]
	global_store_short v[92:93], v1, off
	v_cvt_pk_bf16_f32 v1, v94, s0
	v_lshl_add_u64 v[110:111], v[154:155], 0, v[110:111]
	v_or_b32_e32 v94, 57, v152
	global_store_short v[110:111], v1, off
	v_cvt_pk_bf16_f32 v1, v95, s0
	v_ashrrev_i32_e32 v95, 31, v94
	v_or_b32_e32 v112, 58, v152
	v_lshlrev_b64 v[94:95], 12, v[94:95]
	v_ashrrev_i32_e32 v113, 31, v112
	v_lshl_add_u64 v[94:95], v[154:155], 0, v[94:95]
	v_lshlrev_b64 v[112:113], 12, v[112:113]
	global_store_short v[94:95], v1, off
	v_cvt_pk_bf16_f32 v1, v96, s0
	v_lshl_add_u64 v[112:113], v[154:155], 0, v[112:113]
	v_or_b32_e32 v96, 59, v152
	global_store_short v[112:113], v1, off
	v_cvt_pk_bf16_f32 v1, v97, s0
	v_ashrrev_i32_e32 v97, 31, v96
	v_lshlrev_b64 v[96:97], 12, v[96:97]
	v_lshl_add_u64 v[96:97], v[154:155], 0, v[96:97]
	global_store_short v[96:97], v1, off
	v_cvt_pk_bf16_f32 v1, v66, s0
	global_store_short v[98:99], v1, off offset:64
	v_cvt_pk_bf16_f32 v1, v67, s0
	global_store_short v[82:83], v1, off offset:64
	v_cvt_pk_bf16_f32 v1, v68, s0
	global_store_short v[100:101], v1, off offset:64
	v_cvt_pk_bf16_f32 v1, v69, s0
	global_store_short v[84:85], v1, off offset:64
	v_cvt_pk_bf16_f32 v1, v70, s0
	global_store_short v[102:103], v1, off offset:64
	v_cvt_pk_bf16_f32 v1, v71, s0
	global_store_short v[86:87], v1, off offset:64
	v_cvt_pk_bf16_f32 v1, v72, s0
	global_store_short v[104:105], v1, off offset:64
	v_cvt_pk_bf16_f32 v1, v73, s0
	global_store_short v[88:89], v1, off offset:64
	v_cvt_pk_bf16_f32 v1, v74, s0
	global_store_short v[106:107], v1, off offset:64
	v_cvt_pk_bf16_f32 v1, v75, s0
	global_store_short v[90:91], v1, off offset:64
	v_cvt_pk_bf16_f32 v1, v76, s0
	global_store_short v[108:109], v1, off offset:64
	v_cvt_pk_bf16_f32 v1, v77, s0
	global_store_short v[92:93], v1, off offset:64
	v_cvt_pk_bf16_f32 v1, v78, s0
	global_store_short v[110:111], v1, off offset:64
	v_cvt_pk_bf16_f32 v1, v79, s0
	v_or_b32_e32 v66, 64, v152
	global_store_short v[94:95], v1, off offset:64
	v_cvt_pk_bf16_f32 v1, v80, s0
	v_ashrrev_i32_e32 v67, 31, v66
	global_store_short v[112:113], v1, off offset:64
	v_cvt_pk_bf16_f32 v1, v81, s0
	v_lshlrev_b64 v[66:67], 12, v[66:67]
	global_store_short v[96:97], v1, off offset:64
	v_cvt_pk_bf16_f32 v1, v50, s0
	v_lshl_add_u64 v[66:67], v[154:155], 0, v[66:67]
	v_or_b32_e32 v50, 0x41, v152
	global_store_short v[66:67], v1, off
	v_cvt_pk_bf16_f32 v1, v51, s0
	v_ashrrev_i32_e32 v51, 31, v50
	v_or_b32_e32 v68, 0x42, v152
	v_lshlrev_b64 v[50:51], 12, v[50:51]
	v_ashrrev_i32_e32 v69, 31, v68
	v_lshl_add_u64 v[50:51], v[154:155], 0, v[50:51]
	v_lshlrev_b64 v[68:69], 12, v[68:69]
	global_store_short v[50:51], v1, off
	v_cvt_pk_bf16_f32 v1, v52, s0
	v_lshl_add_u64 v[68:69], v[154:155], 0, v[68:69]
	v_or_b32_e32 v52, 0x43, v152
	global_store_short v[68:69], v1, off
	v_cvt_pk_bf16_f32 v1, v53, s0
	v_ashrrev_i32_e32 v53, 31, v52
	v_or_b32_e32 v70, 0x48, v152
	v_lshlrev_b64 v[52:53], 12, v[52:53]
	v_ashrrev_i32_e32 v71, 31, v70
	v_lshl_add_u64 v[52:53], v[154:155], 0, v[52:53]
	v_lshlrev_b64 v[70:71], 12, v[70:71]
	global_store_short v[52:53], v1, off
	v_cvt_pk_bf16_f32 v1, v54, s0
	v_lshl_add_u64 v[70:71], v[154:155], 0, v[70:71]
	v_or_b32_e32 v54, 0x49, v152
	global_store_short v[70:71], v1, off
	v_cvt_pk_bf16_f32 v1, v55, s0
	v_ashrrev_i32_e32 v55, 31, v54
; DEV bf16_t f2bf(float f) { return (bf16_t)(cvtpk(f, 0.f) & 0xffffu); }
;   DEV void operator()(f32x16 (&acc)[2][2], int mb, int nb, int r32, int hh) const {
; #pragma unroll
;     for (int mi = 0; mi < 2; ++mi)
; #pragma unroll
;       for (int ni = 0; ni < 2; ++ni)
; #pragma unroll
;         for (int r = 0; r < 16; ++r) {
;           int row = mb + mi * 32 + 8 * (r >> 2) + 4 * hh + (r & 3);
;           C[(size_t)row * ldc + nb + ni * 32 + r32] = f2bf(acc[mi][ni][r]);
;         }
;   }
	v_or_b32_e32 v72, 0x4a, v152
	v_lshlrev_b64 v[54:55], 12, v[54:55]
	v_ashrrev_i32_e32 v73, 31, v72
	v_lshl_add_u64 v[54:55], v[154:155], 0, v[54:55]
	v_lshlrev_b64 v[72:73], 12, v[72:73]
	global_store_short v[54:55], v1, off
	v_cvt_pk_bf16_f32 v1, v56, s0
	v_lshl_add_u64 v[72:73], v[154:155], 0, v[72:73]
	v_or_b32_e32 v56, 0x4b, v152
	global_store_short v[72:73], v1, off
	v_cvt_pk_bf16_f32 v1, v57, s0
	v_ashrrev_i32_e32 v57, 31, v56
	v_or_b32_e32 v74, 0x50, v152
	v_lshlrev_b64 v[56:57], 12, v[56:57]
	v_ashrrev_i32_e32 v75, 31, v74
	v_lshl_add_u64 v[56:57], v[154:155], 0, v[56:57]
	v_lshlrev_b64 v[74:75], 12, v[74:75]
	global_store_short v[56:57], v1, off
	v_cvt_pk_bf16_f32 v1, v58, s0
	v_lshl_add_u64 v[74:75], v[154:155], 0, v[74:75]
	v_or_b32_e32 v58, 0x51, v152
	global_store_short v[74:75], v1, off
	v_cvt_pk_bf16_f32 v1, v59, s0
	v_ashrrev_i32_e32 v59, 31, v58
	v_or_b32_e32 v76, 0x52, v152
	v_lshlrev_b64 v[58:59], 12, v[58:59]
	v_ashrrev_i32_e32 v77, 31, v76
	v_lshl_add_u64 v[58:59], v[154:155], 0, v[58:59]
	v_lshlrev_b64 v[76:77], 12, v[76:77]
	global_store_short v[58:59], v1, off
	v_cvt_pk_bf16_f32 v1, v60, s0
	v_lshl_add_u64 v[76:77], v[154:155], 0, v[76:77]
	v_or_b32_e32 v60, 0x53, v152
	global_store_short v[76:77], v1, off
	v_cvt_pk_bf16_f32 v1, v61, s0
	v_ashrrev_i32_e32 v61, 31, v60
	v_or_b32_e32 v78, 0x58, v152
	v_lshlrev_b64 v[60:61], 12, v[60:61]
	v_ashrrev_i32_e32 v79, 31, v78
	v_lshl_add_u64 v[60:61], v[154:155], 0, v[60:61]
	v_lshlrev_b64 v[78:79], 12, v[78:79]
	global_store_short v[60:61], v1, off
	v_cvt_pk_bf16_f32 v1, v62, s0
	v_lshl_add_u64 v[78:79], v[154:155], 0, v[78:79]
	v_or_b32_e32 v62, 0x59, v152
	global_store_short v[78:79], v1, off
	v_cvt_pk_bf16_f32 v1, v63, s0
	v_ashrrev_i32_e32 v63, 31, v62
	v_or_b32_e32 v80, 0x5a, v152
	v_lshlrev_b64 v[62:63], 12, v[62:63]
	v_ashrrev_i32_e32 v81, 31, v80
	v_lshl_add_u64 v[62:63], v[154:155], 0, v[62:63]
	v_lshlrev_b64 v[80:81], 12, v[80:81]
	global_store_short v[62:63], v1, off
	v_cvt_pk_bf16_f32 v1, v64, s0
	v_lshl_add_u64 v[80:81], v[154:155], 0, v[80:81]
	v_or_b32_e32 v64, 0x5b, v152
	global_store_short v[80:81], v1, off
	v_cvt_pk_bf16_f32 v1, v65, s0
	v_ashrrev_i32_e32 v65, 31, v64
	v_lshlrev_b64 v[64:65], 12, v[64:65]
	v_lshl_add_u64 v[64:65], v[154:155], 0, v[64:65]
	global_store_short v[64:65], v1, off
	v_cvt_pk_bf16_f32 v1, v34, s0
	global_store_short v[66:67], v1, off offset:64
	v_cvt_pk_bf16_f32 v1, v35, s0
	global_store_short v[50:51], v1, off offset:64
	v_cvt_pk_bf16_f32 v1, v36, s0
	global_store_short v[68:69], v1, off offset:64
	v_cvt_pk_bf16_f32 v1, v37, s0
	global_store_short v[52:53], v1, off offset:64
	v_cvt_pk_bf16_f32 v1, v38, s0
	global_store_short v[70:71], v1, off offset:64
	v_cvt_pk_bf16_f32 v1, v39, s0
	global_store_short v[54:55], v1, off offset:64
	v_cvt_pk_bf16_f32 v1, v40, s0
	global_store_short v[72:73], v1, off offset:64
	v_cvt_pk_bf16_f32 v1, v41, s0
	global_store_short v[56:57], v1, off offset:64
	v_cvt_pk_bf16_f32 v1, v42, s0
	global_store_short v[74:75], v1, off offset:64
	v_cvt_pk_bf16_f32 v1, v43, s0
	global_store_short v[58:59], v1, off offset:64
	v_cvt_pk_bf16_f32 v1, v44, s0
	global_store_short v[76:77], v1, off offset:64
	v_cvt_pk_bf16_f32 v1, v45, s0
	global_store_short v[60:61], v1, off offset:64
	v_cvt_pk_bf16_f32 v1, v46, s0
	global_store_short v[78:79], v1, off offset:64
	v_cvt_pk_bf16_f32 v1, v47, s0
	v_or_b32_e32 v34, 0x60, v152
	global_store_short v[62:63], v1, off offset:64
	v_cvt_pk_bf16_f32 v1, v48, s0
	v_ashrrev_i32_e32 v35, 31, v34
	global_store_short v[80:81], v1, off offset:64
	v_cvt_pk_bf16_f32 v1, v49, s0
	v_lshlrev_b64 v[34:35], 12, v[34:35]
	global_store_short v[64:65], v1, off offset:64
	v_cvt_pk_bf16_f32 v1, v18, s0
	v_lshl_add_u64 v[34:35], v[154:155], 0, v[34:35]
	v_or_b32_e32 v18, 0x61, v152
	global_store_short v[34:35], v1, off
	v_cvt_pk_bf16_f32 v1, v19, s0
	v_ashrrev_i32_e32 v19, 31, v18
	v_or_b32_e32 v36, 0x62, v152
	v_lshlrev_b64 v[18:19], 12, v[18:19]
	v_ashrrev_i32_e32 v37, 31, v36
	v_lshl_add_u64 v[18:19], v[154:155], 0, v[18:19]
	v_lshlrev_b64 v[36:37], 12, v[36:37]
	global_store_short v[18:19], v1, off
	v_cvt_pk_bf16_f32 v1, v20, s0
	v_lshl_add_u64 v[36:37], v[154:155], 0, v[36:37]
; DEV bf16_t f2bf(float f) { return (bf16_t)(cvtpk(f, 0.f) & 0xffffu); }
;   DEV void operator()(f32x16 (&acc)[2][2], int mb, int nb, int r32, int hh) const {
; #pragma unroll
;     for (int mi = 0; mi < 2; ++mi)
; #pragma unroll
;       for (int ni = 0; ni < 2; ++ni)
; #pragma unroll
;         for (int r = 0; r < 16; ++r) {
;           int row = mb + mi * 32 + 8 * (r >> 2) + 4 * hh + (r & 3);
;           C[(size_t)row * ldc + nb + ni * 32 + r32] = f2bf(acc[mi][ni][r]);
;         }
;   }
	v_or_b32_e32 v20, 0x63, v152
	global_store_short v[36:37], v1, off
	v_cvt_pk_bf16_f32 v1, v21, s0
	v_ashrrev_i32_e32 v21, 31, v20
	v_or_b32_e32 v38, 0x68, v152
	v_lshlrev_b64 v[20:21], 12, v[20:21]
	v_ashrrev_i32_e32 v39, 31, v38
	v_lshl_add_u64 v[20:21], v[154:155], 0, v[20:21]
	v_lshlrev_b64 v[38:39], 12, v[38:39]
	global_store_short v[20:21], v1, off
	v_cvt_pk_bf16_f32 v1, v22, s0
	v_lshl_add_u64 v[38:39], v[154:155], 0, v[38:39]
	v_or_b32_e32 v22, 0x69, v152
	global_store_short v[38:39], v1, off
	v_cvt_pk_bf16_f32 v1, v23, s0
	v_ashrrev_i32_e32 v23, 31, v22
	v_or_b32_e32 v40, 0x6a, v152
	v_lshlrev_b64 v[22:23], 12, v[22:23]
	v_ashrrev_i32_e32 v41, 31, v40
	v_lshl_add_u64 v[22:23], v[154:155], 0, v[22:23]
	v_lshlrev_b64 v[40:41], 12, v[40:41]
	global_store_short v[22:23], v1, off
	v_cvt_pk_bf16_f32 v1, v24, s0
	v_lshl_add_u64 v[40:41], v[154:155], 0, v[40:41]
	v_or_b32_e32 v24, 0x6b, v152
	global_store_short v[40:41], v1, off
	v_cvt_pk_bf16_f32 v1, v25, s0
	v_ashrrev_i32_e32 v25, 31, v24
	v_or_b32_e32 v42, 0x70, v152
	v_lshlrev_b64 v[24:25], 12, v[24:25]
	v_ashrrev_i32_e32 v43, 31, v42
	v_lshl_add_u64 v[24:25], v[154:155], 0, v[24:25]
	v_lshlrev_b64 v[42:43], 12, v[42:43]
	global_store_short v[24:25], v1, off
	v_cvt_pk_bf16_f32 v1, v26, s0
	v_lshl_add_u64 v[42:43], v[154:155], 0, v[42:43]
	v_or_b32_e32 v26, 0x71, v152
	global_store_short v[42:43], v1, off
	v_cvt_pk_bf16_f32 v1, v27, s0
	v_ashrrev_i32_e32 v27, 31, v26
	v_or_b32_e32 v44, 0x72, v152
	v_lshlrev_b64 v[26:27], 12, v[26:27]
	v_ashrrev_i32_e32 v45, 31, v44
	v_lshl_add_u64 v[26:27], v[154:155], 0, v[26:27]
	v_lshlrev_b64 v[44:45], 12, v[44:45]
	global_store_short v[26:27], v1, off
	v_cvt_pk_bf16_f32 v1, v28, s0
	v_lshl_add_u64 v[44:45], v[154:155], 0, v[44:45]
	v_or_b32_e32 v28, 0x73, v152
	global_store_short v[44:45], v1, off
	v_cvt_pk_bf16_f32 v1, v29, s0
	v_ashrrev_i32_e32 v29, 31, v28
	v_or_b32_e32 v46, 0x78, v152
	v_lshlrev_b64 v[28:29], 12, v[28:29]
	v_ashrrev_i32_e32 v47, 31, v46
	v_lshl_add_u64 v[28:29], v[154:155], 0, v[28:29]
	v_lshlrev_b64 v[46:47], 12, v[46:47]
	global_store_short v[28:29], v1, off
	v_cvt_pk_bf16_f32 v1, v30, s0
	v_lshl_add_u64 v[46:47], v[154:155], 0, v[46:47]
	v_or_b32_e32 v30, 0x79, v152
	global_store_short v[46:47], v1, off
	v_cvt_pk_bf16_f32 v1, v31, s0
	v_ashrrev_i32_e32 v31, 31, v30
	v_or_b32_e32 v48, 0x7a, v152
	v_lshlrev_b64 v[30:31], 12, v[30:31]
	v_ashrrev_i32_e32 v49, 31, v48
	v_lshl_add_u64 v[30:31], v[154:155], 0, v[30:31]
	v_lshlrev_b64 v[48:49], 12, v[48:49]
	global_store_short v[30:31], v1, off
	v_cvt_pk_bf16_f32 v1, v32, s0
	v_lshl_add_u64 v[48:49], v[154:155], 0, v[48:49]
	v_or_b32_e32 v32, 0x7b, v152
	global_store_short v[48:49], v1, off
	v_cvt_pk_bf16_f32 v1, v33, s0
	v_ashrrev_i32_e32 v33, 31, v32
	v_lshlrev_b64 v[32:33], 12, v[32:33]
	v_lshl_add_u64 v[32:33], v[154:155], 0, v[32:33]
	global_store_short v[32:33], v1, off
	v_cvt_pk_bf16_f32 v1, v2, s0
	global_store_short v[34:35], v1, off offset:64
	v_cvt_pk_bf16_f32 v1, v3, s0
	global_store_short v[18:19], v1, off offset:64
	v_cvt_pk_bf16_f32 v1, v4, s0
	global_store_short v[36:37], v1, off offset:64
	v_cvt_pk_bf16_f32 v1, v5, s0
	global_store_short v[20:21], v1, off offset:64
	v_cvt_pk_bf16_f32 v1, v6, s0
	global_store_short v[38:39], v1, off offset:64
	v_cvt_pk_bf16_f32 v1, v7, s0
	global_store_short v[22:23], v1, off offset:64
	v_cvt_pk_bf16_f32 v1, v8, s0
	global_store_short v[40:41], v1, off offset:64
	v_cvt_pk_bf16_f32 v1, v9, s0
	global_store_short v[24:25], v1, off offset:64
	v_cvt_pk_bf16_f32 v1, v10, s0
	global_store_short v[42:43], v1, off offset:64
	v_cvt_pk_bf16_f32 v1, v11, s0
	global_store_short v[26:27], v1, off offset:64
	v_cvt_pk_bf16_f32 v1, v12, s0
	global_store_short v[44:45], v1, off offset:64
	v_cvt_pk_bf16_f32 v1, v13, s0
	global_store_short v[28:29], v1, off offset:64
	v_cvt_pk_bf16_f32 v1, v14, s0
	global_store_short v[46:47], v1, off offset:64
	v_cvt_pk_bf16_f32 v1, v15, s0
	global_store_short v[30:31], v1, off offset:64
	v_cvt_pk_bf16_f32 v1, v16, s0
	global_store_short v[48:49], v1, off offset:64
	v_cvt_pk_bf16_f32 v1, v17, s0
	s_mov_b64 s[2:3], -1
	s_and_b64 vcc, exec, s[0:1]
	global_store_short v[32:33], v1, off offset:64
	s_cbranch_vccnz .LBB0_82

; DEV float bf2f(unsigned h) { return __uint_as_float(h << 16); }
; DEV void phase_act(const Params& p, int l) {
;     ...
; #pragma unroll 4
;     for (int t = t0; t < t0 + 16; ++t) {
;       uint4 a = *(const uint4*)(U + (size_t)t * NUP + c), b2 = *(const uint4*)(U + (size_t)t * NUP + DFF + c);
;       const unsigned* pa = (const unsigned*)&a; const unsigned* pb = (const unsigned*)&b2;
;       float g[8], u[8], o[8];
; #pragma unroll
;       for (int i = 0; i < 4; ++i) { g[2 * i] = bf2f(pa[i] & 0xffff); g[2 * i + 1] = bf2f(pa[i] >> 16); u[2 * i] = bf2f(pb[i] & 0xffff); u[2 * i + 1] = bf2f(pb[i] >> 16); }
; #pragma unroll
;       for (int i = 0; i < 8; ++i) {
;         float cg_ = bg[i] + wg[0][i] * gm2[i] + wg[1][i] * gm1[i] + wg[2][i] * g[i];
;         float cu_ = bu[i] + wu[0][i] * um2[i] + wu[1][i] * um1[i] + wu[2][i] * u[i];
;         o[i] = gelu_tanh(cg_) * cu_;
;         gm2[i] = gm1[i]; gm1[i] = g[i]; um2[i] = um1[i]; um1[i] = u[i];
;       }
;       uint4 ov; ov.x = cvtpk(o[0], o[1]); ov.y = cvtpk(o[2], o[3]); ov.z = cvtpk(o[4], o[5]); ov.w = cvtpk(o[6], o[7]);
;       *(uint4*)(ACT + (size_t)t * DFF + c) = ov;
;     }
.LBB0_89:
	s_nop 0
	v_lshl_add_u64 v[104:105], v[74:75], 0, v[70:71]
	s_mov_b32 s98, 0x27bcd000
	v_add_co_u32_e32 v186, vcc, s98, v104
	s_mov_b32 s98, 0x27bd0000
	s_nop 0
	v_addc_co_u32_e32 v187, vcc, 0, v105, vcc
	global_load_dwordx4 v[162:165], v[186:187], off offset:2048
	v_add_co_u32_e32 v188, vcc, s98, v104
	s_mov_b32 s98, 0x27bd3000
	s_nop 0
	v_addc_co_u32_e32 v189, vcc, 0, v105, vcc
	global_load_dwordx4 v[166:169], v[188:189], off offset:1024
	v_add_co_u32_e32 v186, vcc, s98, v104
	s_mov_b32 s98, 0x27bd5000
	s_nop 0
	v_addc_co_u32_e32 v187, vcc, 0, v105, vcc
	global_load_dwordx4 v[170:173], v[186:187], off
	v_add_co_u32_e32 v188, vcc, s98, v104
	s_mov_b32 s98, 0x27bd8000
	s_nop 0
	v_addc_co_u32_e32 v189, vcc, 0, v105, vcc
	global_load_dwordx4 v[174:177], v[188:189], off offset:3072
	v_add_co_u32_e32 v186, vcc, s98, v104
	s_mov_b32 s98, 0x27bdb000
	s_nop 0
	v_addc_co_u32_e32 v187, vcc, 0, v105, vcc
	global_load_dwordx4 v[178:181], v[186:187], off offset:2048
	v_add_co_u32_e32 v188, vcc, s98, v104
	s_nop 0
	s_nop 0
	v_addc_co_u32_e32 v189, vcc, 0, v105, vcc
	global_load_dwordx4 v[182:185], v[188:189], off offset:1024
	v_add_co_u32_e32 v106, vcc, s65, v104
	s_mov_b32 s7, 0x27bca000
	s_nop 0
	v_addc_co_u32_e32 v107, vcc, 0, v105, vcc
	global_load_dwordx4 v[106:109], v[106:107], off
	v_add_co_u32_e32 v110, vcc, s7, v104
	s_nop 1
	v_addc_co_u32_e32 v111, vcc, 0, v105, vcc
	global_load_dwordx4 v[122:125], v[110:111], off offset:3072
	s_waitcnt vmcnt(0)
	v_pk_fma_f32 v[66:67], v[6:7], v[66:67], v[54:55]
	v_pk_fma_f32 v[66:67], v[22:23], v[88:89], v[66:67]
	v_pk_fma_f32 v[98:99], v[8:9], v[98:99], v[56:57]
	v_pk_fma_f32 v[102:103], v[14:15], v[102:103], v[62:63]
	v_pk_fma_f32 v[98:99], v[24:25], v[84:85], v[98:99]
	v_pk_fma_f32 v[102:103], v[30:31], v[90:91], v[102:103]
	v_pk_fma_f32 v[96:97], v[2:3], v[96:97], v[50:51]
	v_pk_fma_f32 v[100:101], v[16:17], v[100:101], v[64:65]
	v_pk_fma_f32 v[96:97], v[18:19], v[82:83], v[96:97]
	v_pk_fma_f32 v[100:101], v[32:33], v[86:87], v[100:101]
	v_pk_fma_f32 v[94:95], v[4:5], v[94:95], v[52:53]
	v_pk_fma_f32 v[68:69], v[10:11], v[68:69], v[58:59]
	v_pk_fma_f32 v[94:95], v[20:21], v[78:79], v[94:95]
	v_pk_fma_f32 v[68:69], v[26:27], v[80:81], v[68:69]
	v_pk_fma_f32 v[92:93], v[12:13], v[92:93], v[60:61]
	s_mov_b32 s7, 0x21bc8000
	v_pk_fma_f32 v[92:93], v[28:29], v[76:77], v[92:93]
	v_pk_fma_f32 v[86:87], v[16:17], v[86:87], v[64:65]
	v_pk_fma_f32 v[78:79], v[4:5], v[78:79], v[52:53]
	v_pk_fma_f32 v[80:81], v[10:11], v[80:81], v[58:59]
	v_pk_fma_f32 v[76:77], v[12:13], v[76:77], v[60:61]
	s_mov_b64 s[26:27], 0xb000
	s_add_i32 s6, s6, -4
	s_cmp_eq_u32 s6, 0
	s_waitcnt lgkmcnt(0)
	v_lshlrev_b32_e32 v120, 16, v106
	v_and_b32_e32 v121, 0xffff0000, v106
	v_pk_fma_f32 v[66:67], v[38:39], v[120:121], v[66:67]
	v_lshlrev_b32_e32 v116, 16, v107
	v_mul_f32_e32 v1, 0x3d372713, v66
	v_mul_f32_e32 v1, v66, v1
	v_fma_f32 v1, v66, v1, v66
	v_mul_f32_e32 v1, 0xc0135761, v1
	v_exp_f32_e32 v1, v1
	s_waitcnt vmcnt(0)
	v_lshlrev_b32_e32 v118, 16, v122
	v_and_b32_e32 v119, 0xffff0000, v122
	v_and_b32_e32 v117, 0xffff0000, v107
	v_add_f32_e32 v1, 1.0, v1
	v_rcp_f32_e32 v122, v1
	v_mul_f32_e32 v1, 0x3d372713, v67
	v_mul_f32_e32 v1, v67, v1
	v_fma_f32 v1, v67, v1, v67
	v_mul_f32_e32 v1, 0xc0135761, v1
	v_exp_f32_e32 v1, v1
	v_pk_fma_f32 v[98:99], v[40:41], v[116:117], v[98:99]
	v_lshlrev_b32_e32 v114, 16, v123
	v_and_b32_e32 v115, 0xffff0000, v123
	v_add_f32_e32 v1, 1.0, v1
	v_rcp_f32_e32 v123, v1
	v_mul_f32_e32 v1, 0x3d372713, v98
	v_mul_f32_e32 v1, v98, v1
	v_fma_f32 v1, v98, v1, v98
	v_mul_f32_e32 v1, 0xc0135761, v1
	v_exp_f32_e32 v1, v1
	v_pk_fma_f32 v[102:103], v[46:47], v[118:119], v[102:103]
	v_pk_mul_f32 v[66:67], v[66:67], v[122:123]
	v_lshlrev_b32_e32 v112, 16, v108
	v_add_f32_e32 v1, 1.0, v1
	v_pk_mul_f32 v[66:67], v[102:103], v[66:67]
	v_rcp_f32_e32 v102, v1
	v_mul_f32_e32 v1, 0x3d372713, v99
	v_mul_f32_e32 v1, v99, v1
	v_fma_f32 v1, v99, v1, v99
	v_mul_f32_e32 v1, 0xc0135761, v1
	v_exp_f32_e32 v1, v1
	v_and_b32_e32 v113, 0xffff0000, v108
	v_pk_fma_f32 v[96:97], v[34:35], v[112:113], v[96:97]
	v_pk_fma_f32 v[100:101], v[48:49], v[114:115], v[100:101]
	v_add_f32_e32 v1, 1.0, v1
	v_rcp_f32_e32 v103, v1
	v_mul_f32_e32 v1, 0x3d372713, v96
	v_mul_f32_e32 v1, v96, v1
	v_fma_f32 v1, v96, v1, v96
	v_mul_f32_e32 v1, 0xc0135761, v1
	v_exp_f32_e32 v1, v1
	v_pk_mul_f32 v[98:99], v[98:99], v[102:103]
	v_cvt_pk_bf16_f32 v66, v66, v67
	v_pk_mul_f32 v[98:99], v[100:101], v[98:99]
	v_add_f32_e32 v1, 1.0, v1
	v_cvt_pk_bf16_f32 v67, v98, v99
	v_rcp_f32_e32 v98, v1
	v_mul_f32_e32 v1, 0x3d372713, v97
	v_mul_f32_e32 v1, v97, v1
	v_fma_f32 v1, v97, v1, v97
	v_mul_f32_e32 v1, 0xc0135761, v1
	v_exp_f32_e32 v1, v1
	v_lshlrev_b32_e32 v108, 16, v109
	v_and_b32_e32 v109, 0xffff0000, v109
	v_pk_fma_f32 v[94:95], v[36:37], v[108:109], v[94:95]
	v_add_f32_e32 v1, 1.0, v1
	v_rcp_f32_e32 v99, v1
	v_mul_f32_e32 v1, 0x3d372713, v94
	v_mul_f32_e32 v1, v94, v1
	v_fma_f32 v1, v94, v1, v94
	v_mul_f32_e32 v1, 0xc0135761, v1
	v_exp_f32_e32 v1, v1
	v_lshlrev_b32_e32 v110, 16, v124
	v_and_b32_e32 v111, 0xffff0000, v124
	v_pk_fma_f32 v[68:69], v[42:43], v[110:111], v[68:69]
	v_pk_mul_f32 v[96:97], v[96:97], v[98:99]
	v_add_f32_e32 v1, 1.0, v1
	v_pk_mul_f32 v[68:69], v[68:69], v[96:97]
	v_rcp_f32_e32 v96, v1
	v_mul_f32_e32 v1, 0x3d372713, v95
	v_mul_f32_e32 v1, v95, v1
	v_fma_f32 v1, v95, v1, v95
	v_mul_f32_e32 v1, 0xc0135761, v1
	v_exp_f32_e32 v1, v1
	v_lshlrev_b32_e32 v106, 16, v125
	v_and_b32_e32 v107, 0xffff0000, v125
	v_pk_fma_f32 v[92:93], v[44:45], v[106:107], v[92:93]
	v_add_f32_e32 v1, 1.0, v1
	v_rcp_f32_e32 v97, v1
	v_lshl_add_u64 v[122:123], v[72:73], 0, v[70:71]
; DEV float bf2f(unsigned h) { return __uint_as_float(h << 16); }
; DEV void phase_act(const Params& p, int l) {
;     ...
; #pragma unroll 4
;     for (int t = t0; t < t0 + 16; ++t) {
;       uint4 a = *(const uint4*)(U + (size_t)t * NUP + c), b2 = *(const uint4*)(U + (size_t)t * NUP + DFF + c);
;       const unsigned* pa = (const unsigned*)&a; const unsigned* pb = (const unsigned*)&b2;
;       float g[8], u[8], o[8];
; #pragma unroll
;       for (int i = 0; i < 4; ++i) { g[2 * i] = bf2f(pa[i] & 0xffff); g[2 * i + 1] = bf2f(pa[i] >> 16); u[2 * i] = bf2f(pb[i] & 0xffff); u[2 * i + 1] = bf2f(pb[i] >> 16); }
; #pragma unroll
;       for (int i = 0; i < 8; ++i) {
;         float cg_ = bg[i] + wg[0][i] * gm2[i] + wg[1][i] * gm1[i] + wg[2][i] * g[i];
;         float cu_ = bu[i] + wu[0][i] * um2[i] + wu[1][i] * um1[i] + wu[2][i] * u[i];
;         o[i] = gelu_tanh(cg_) * cu_;
;         gm2[i] = gm1[i]; gm1[i] = g[i]; um2[i] = um1[i]; um1[i] = u[i];
;       }
;       uint4 ov; ov.x = cvtpk(o[0], o[1]); ov.y = cvtpk(o[2], o[3]); ov.z = cvtpk(o[4], o[5]); ov.w = cvtpk(o[6], o[7]);
;       *(uint4*)(ACT + (size_t)t * DFF + c) = ov;
;     }
	v_cvt_pk_bf16_f32 v68, v68, v69
	v_pk_fma_f32 v[86:87], v[32:33], v[114:115], v[86:87]
	v_pk_mul_f32 v[94:95], v[94:95], v[96:97]
	v_pk_fma_f32 v[78:79], v[20:21], v[108:109], v[78:79]
	v_pk_mul_f32 v[92:93], v[92:93], v[94:95]
	v_pk_fma_f32 v[80:81], v[26:27], v[110:111], v[80:81]
	v_cvt_pk_bf16_f32 v69, v92, v93
	v_add_co_u32_e32 v92, vcc, s7, v122
	s_mov_b32 s7, 0x27bcd000
	s_nop 0
	v_addc_co_u32_e32 v93, vcc, 0, v123, vcc
	global_store_dwordx4 v[92:93], v[66:69], off
	v_pk_fma_f32 v[76:77], v[28:29], v[106:107], v[76:77]
	v_lshl_add_u64 v[72:73], v[72:73], 0, s[26:27]
	v_add_co_u32_e32 v66, vcc, s7, v104
	s_mov_b32 s7, 0x27bd0000
	s_nop 0
	v_addc_co_u32_e32 v67, vcc, 0, v105, vcc
	v_mov_b32_e32 v66, v162
	v_mov_b32_e32 v67, v163
	v_mov_b32_e32 v68, v164
	v_mov_b32_e32 v69, v165
	v_add_co_u32_e32 v92, vcc, s7, v104
	s_mov_b32 s7, 0x21bca000
	s_nop 0
	v_addc_co_u32_e32 v93, vcc, 0, v105, vcc
	v_mov_b32_e32 v92, v166
	v_mov_b32_e32 v93, v167
	v_mov_b32_e32 v94, v168
	v_mov_b32_e32 v95, v169
	s_mov_b64 s[26:27], 0x16000
	v_lshl_add_u64 v[74:75], v[74:75], 0, s[26:27]
	s_nop 0
	v_lshlrev_b32_e32 v160, 16, v66
	v_and_b32_e32 v161, 0xffff0000, v66
	v_lshlrev_b32_e32 v156, 16, v67
	v_and_b32_e32 v157, 0xffff0000, v67
	v_pk_fma_f32 v[66:67], v[6:7], v[88:89], v[54:55]
	v_lshlrev_b32_e32 v152, 16, v68
	v_pk_fma_f32 v[66:67], v[22:23], v[120:121], v[66:67]
	v_and_b32_e32 v153, 0xffff0000, v68
	v_pk_fma_f32 v[66:67], v[38:39], v[160:161], v[66:67]
	v_lshlrev_b32_e32 v126, 16, v69
	v_mul_f32_e32 v1, 0x3d372713, v66
	v_mul_f32_e32 v1, v66, v1
	v_fma_f32 v1, v66, v1, v66
	v_mul_f32_e32 v1, 0xc0135761, v1
	v_exp_f32_e32 v1, v1
	v_and_b32_e32 v127, 0xffff0000, v69
	v_pk_fma_f32 v[88:89], v[14:15], v[90:91], v[62:63]
	v_lshlrev_b32_e32 v158, 16, v92
	v_add_f32_e32 v1, 1.0, v1
	v_rcp_f32_e32 v68, v1
	v_mul_f32_e32 v1, 0x3d372713, v67
	v_mul_f32_e32 v1, v67, v1
	v_fma_f32 v1, v67, v1, v67
	v_mul_f32_e32 v1, 0xc0135761, v1
	v_exp_f32_e32 v1, v1
	v_and_b32_e32 v159, 0xffff0000, v92
	v_lshlrev_b32_e32 v154, 16, v93
	v_and_b32_e32 v155, 0xffff0000, v93
	v_add_f32_e32 v1, 1.0, v1
	v_rcp_f32_e32 v69, v1
	v_pk_fma_f32 v[88:89], v[30:31], v[118:119], v[88:89]
	v_pk_fma_f32 v[86:87], v[48:49], v[154:155], v[86:87]
	v_pk_fma_f32 v[88:89], v[46:47], v[158:159], v[88:89]
	v_pk_mul_f32 v[66:67], v[66:67], v[68:69]
	v_pk_fma_f32 v[68:69], v[8:9], v[84:85], v[56:57]
	v_pk_mul_f32 v[66:67], v[88:89], v[66:67]
	v_pk_fma_f32 v[68:69], v[24:25], v[116:117], v[68:69]
	v_cvt_pk_bf16_f32 v66, v66, v67
	v_pk_fma_f32 v[68:69], v[40:41], v[156:157], v[68:69]
	v_pk_fma_f32 v[78:79], v[36:37], v[126:127], v[78:79]
	v_mul_f32_e32 v1, 0x3d372713, v68
	v_mul_f32_e32 v1, v68, v1
	v_fma_f32 v1, v68, v1, v68
	v_mul_f32_e32 v1, 0xc0135761, v1
	v_exp_f32_e32 v1, v1
	v_lshlrev_b32_e32 v128, 16, v94
	v_and_b32_e32 v129, 0xffff0000, v94
	v_pk_fma_f32 v[80:81], v[42:43], v[128:129], v[80:81]
	v_add_f32_e32 v1, 1.0, v1
	v_rcp_f32_e32 v84, v1
	v_mul_f32_e32 v1, 0x3d372713, v69
	v_mul_f32_e32 v1, v69, v1
	v_fma_f32 v1, v69, v1, v69
	v_mul_f32_e32 v1, 0xc0135761, v1
	v_exp_f32_e32 v1, v1
	v_lshlrev_b32_e32 v124, 16, v95
	v_and_b32_e32 v125, 0xffff0000, v95
	v_pk_fma_f32 v[76:77], v[44:45], v[124:125], v[76:77]
	v_add_f32_e32 v1, 1.0, v1
	v_rcp_f32_e32 v85, v1
	s_nop 0
	v_pk_mul_f32 v[68:69], v[68:69], v[84:85]
	s_nop 0
	v_pk_mul_f32 v[68:69], v[86:87], v[68:69]
	v_pk_fma_f32 v[84:85], v[12:13], v[106:107], v[60:61]
	v_cvt_pk_bf16_f32 v67, v68, v69
	v_pk_fma_f32 v[68:69], v[2:3], v[82:83], v[50:51]
	v_pk_fma_f32 v[84:85], v[28:29], v[124:125], v[84:85]
	v_pk_fma_f32 v[68:69], v[18:19], v[112:113], v[68:69]
	s_nop 0
	v_pk_fma_f32 v[68:69], v[34:35], v[152:153], v[68:69]
	s_nop 0
	v_mul_f32_e32 v1, 0x3d372713, v68
	v_mul_f32_e32 v1, v68, v1
	v_fma_f32 v1, v68, v1, v68
	v_mul_f32_e32 v1, 0xc0135761, v1
	v_exp_f32_e32 v1, v1
	s_nop 0
	v_add_f32_e32 v1, 1.0, v1
	v_rcp_f32_e32 v82, v1
	v_mul_f32_e32 v1, 0x3d372713, v69
	v_mul_f32_e32 v1, v69, v1
	v_fma_f32 v1, v69, v1, v69
	v_mul_f32_e32 v1, 0xc0135761, v1
	v_exp_f32_e32 v1, v1
	s_nop 0
	v_add_f32_e32 v1, 1.0, v1
	v_rcp_f32_e32 v83, v1
	v_mul_f32_e32 v1, 0x3d372713, v78
	v_mul_f32_e32 v1, v78, v1
	v_fma_f32 v1, v78, v1, v78
	v_mul_f32_e32 v1, 0xc0135761, v1
	v_exp_f32_e32 v1, v1
	v_pk_mul_f32 v[68:69], v[68:69], v[82:83]
	v_add_f32_e32 v1, 1.0, v1
	v_pk_mul_f32 v[68:69], v[80:81], v[68:69]
	v_rcp_f32_e32 v80, v1
	v_mul_f32_e32 v1, 0x3d372713, v79
	v_mul_f32_e32 v1, v79, v1
	v_fma_f32 v1, v79, v1, v79
	v_mul_f32_e32 v1, 0xc0135761, v1
	v_exp_f32_e32 v1, v1
	v_cvt_pk_bf16_f32 v68, v68, v69
	v_add_f32_e32 v1, 1.0, v1
	v_rcp_f32_e32 v81, v1
	s_nop 0
	v_pk_mul_f32 v[78:79], v[78:79], v[80:81]
	s_nop 0
	v_pk_mul_f32 v[76:77], v[76:77], v[78:79]
	s_nop 0
	v_cvt_pk_bf16_f32 v69, v76, v77
	v_add_co_u32_e32 v76, vcc, s7, v122
	s_mov_b32 s7, 0x27bd3000
	s_nop 0
	v_addc_co_u32_e32 v77, vcc, 0, v123, vcc
	global_store_dwordx4 v[76:77], v[66:69], off offset:3072
	s_nop 1
	v_add_co_u32_e32 v66, vcc, s7, v104
	s_mov_b32 s7, 0x27bd5000
	s_nop 0
	v_addc_co_u32_e32 v67, vcc, 0, v105, vcc
	v_mov_b32_e32 v76, v170
	v_mov_b32_e32 v77, v171
	v_mov_b32_e32 v78, v172
	v_mov_b32_e32 v79, v173
	v_add_co_u32_e32 v66, vcc, s7, v104
	s_mov_b32 s7, 0x21bcd000
	s_nop 0
	v_addc_co_u32_e32 v67, vcc, 0, v105, vcc
	v_mov_b32_e32 v80, v174
	v_mov_b32_e32 v81, v175
	v_mov_b32_e32 v82, v176
	v_mov_b32_e32 v83, v177
	s_nop 0
	v_lshlrev_b32_e32 v66, 16, v76
	v_and_b32_e32 v67, 0xffff0000, v76
	v_lshlrev_b32_e32 v98, 16, v77
	v_and_b32_e32 v99, 0xffff0000, v77
	v_pk_fma_f32 v[76:77], v[6:7], v[120:121], v[54:55]
	v_lshlrev_b32_e32 v96, 16, v78
	v_pk_fma_f32 v[76:77], v[22:23], v[160:161], v[76:77]
; DEV float bf2f(unsigned h) { return __uint_as_float(h << 16); }
; DEV void phase_act(const Params& p, int l) {
;     ...
;     for (int t = t0; t < t0 + 16; ++t) {
;       uint4 a = *(const uint4*)(U + (size_t)t * NUP + c), b2 = *(const uint4*)(U + (size_t)t * NUP + DFF + c);
;       const unsigned* pa = (const unsigned*)&a; const unsigned* pb = (const unsigned*)&b2;
;       float g[8], u[8], o[8];
; #pragma unroll
;       for (int i = 0; i < 4; ++i) { g[2 * i] = bf2f(pa[i] & 0xffff); g[2 * i + 1] = bf2f(pa[i] >> 16); u[2 * i] = bf2f(pb[i] & 0xffff); u[2 * i + 1] = bf2f(pb[i] >> 16); }
; #pragma unroll
;       for (int i = 0; i < 8; ++i) {
;         float cg_ = bg[i] + wg[0][i] * gm2[i] + wg[1][i] * gm1[i] + wg[2][i] * g[i];
;         float cu_ = bu[i] + wu[0][i] * um2[i] + wu[1][i] * um1[i] + wu[2][i] * u[i];
;         o[i] = gelu_tanh(cg_) * cu_;
;         gm2[i] = gm1[i]; gm1[i] = g[i]; um2[i] = um1[i]; um1[i] = u[i];
;       }
;       uint4 ov; ov.x = cvtpk(o[0], o[1]); ov.y = cvtpk(o[2], o[3]); ov.z = cvtpk(o[4], o[5]); ov.w = cvtpk(o[6], o[7]);
;       *(uint4*)(ACT + (size_t)t * DFF + c) = ov;
	v_and_b32_e32 v97, 0xffff0000, v78
	v_pk_fma_f32 v[76:77], v[38:39], v[66:67], v[76:77]
	v_lshlrev_b32_e32 v94, 16, v79
	v_mul_f32_e32 v1, 0x3d372713, v76
	v_mul_f32_e32 v1, v76, v1
	v_fma_f32 v1, v76, v1, v76
	v_mul_f32_e32 v1, 0xc0135761, v1
	v_exp_f32_e32 v1, v1
	v_and_b32_e32 v95, 0xffff0000, v79
	v_lshlrev_b32_e32 v102, 16, v80
	v_and_b32_e32 v103, 0xffff0000, v80
	v_add_f32_e32 v1, 1.0, v1
	v_rcp_f32_e32 v78, v1
	v_mul_f32_e32 v1, 0x3d372713, v77
	v_mul_f32_e32 v1, v77, v1
	v_fma_f32 v1, v77, v1, v77
	v_mul_f32_e32 v1, 0xc0135761, v1
	v_exp_f32_e32 v1, v1
	v_lshlrev_b32_e32 v100, 16, v81
	v_and_b32_e32 v101, 0xffff0000, v81
	v_pk_fma_f32 v[80:81], v[14:15], v[118:119], v[62:63]
	v_add_f32_e32 v1, 1.0, v1
	v_rcp_f32_e32 v79, v1
	v_pk_fma_f32 v[80:81], v[30:31], v[158:159], v[80:81]
	v_lshlrev_b32_e32 v68, 16, v82
	v_pk_fma_f32 v[80:81], v[46:47], v[102:103], v[80:81]
	v_pk_mul_f32 v[76:77], v[76:77], v[78:79]
	v_pk_fma_f32 v[78:79], v[8:9], v[116:117], v[56:57]
	v_pk_mul_f32 v[76:77], v[80:81], v[76:77]
	v_pk_fma_f32 v[78:79], v[24:25], v[156:157], v[78:79]
	v_and_b32_e32 v69, 0xffff0000, v82
	v_pk_fma_f32 v[78:79], v[40:41], v[98:99], v[78:79]
	v_lshlrev_b32_e32 v92, 16, v83
	v_mul_f32_e32 v1, 0x3d372713, v78
	v_mul_f32_e32 v1, v78, v1
	v_fma_f32 v1, v78, v1, v78
	v_mul_f32_e32 v1, 0xc0135761, v1
	v_exp_f32_e32 v1, v1
	v_and_b32_e32 v93, 0xffff0000, v83
	v_pk_fma_f32 v[82:83], v[16:17], v[114:115], v[64:65]
	v_cvt_pk_bf16_f32 v76, v76, v77
	v_add_f32_e32 v1, 1.0, v1
	v_rcp_f32_e32 v80, v1
	v_mul_f32_e32 v1, 0x3d372713, v79
	v_mul_f32_e32 v1, v79, v1
	v_fma_f32 v1, v79, v1, v79
	v_mul_f32_e32 v1, 0xc0135761, v1
	v_exp_f32_e32 v1, v1
	v_pk_fma_f32 v[82:83], v[32:33], v[154:155], v[82:83]
	v_pk_fma_f32 v[84:85], v[44:45], v[92:93], v[84:85]
	v_pk_fma_f32 v[82:83], v[48:49], v[100:101], v[82:83]
	v_add_f32_e32 v1, 1.0, v1
	v_rcp_f32_e32 v81, v1
	s_nop 0
	v_pk_mul_f32 v[78:79], v[78:79], v[80:81]
	s_nop 0
	v_pk_mul_f32 v[78:79], v[82:83], v[78:79]
	v_pk_fma_f32 v[82:83], v[10:11], v[110:111], v[58:59]
	v_cvt_pk_bf16_f32 v77, v78, v79
	v_pk_fma_f32 v[78:79], v[2:3], v[112:113], v[50:51]
	v_pk_fma_f32 v[82:83], v[26:27], v[128:129], v[82:83]
	v_pk_fma_f32 v[78:79], v[18:19], v[152:153], v[78:79]
	v_pk_fma_f32 v[82:83], v[42:43], v[68:69], v[82:83]
	v_pk_fma_f32 v[78:79], v[34:35], v[96:97], v[78:79]
	v_pk_fma_f32 v[110:111], v[16:17], v[154:155], v[64:65]
	v_mul_f32_e32 v1, 0x3d372713, v78
	v_mul_f32_e32 v1, v78, v1
	v_fma_f32 v1, v78, v1, v78
	v_mul_f32_e32 v1, 0xc0135761, v1
	v_exp_f32_e32 v1, v1
	v_pk_fma_f32 v[110:111], v[32:33], v[100:101], v[110:111]
	v_pk_fma_f32 v[112:113], v[12:13], v[124:125], v[60:61]
	v_add_f32_e32 v1, 1.0, v1
	v_rcp_f32_e32 v80, v1
	v_mul_f32_e32 v1, 0x3d372713, v79
	v_mul_f32_e32 v1, v79, v1
	v_fma_f32 v1, v79, v1, v79
	v_mul_f32_e32 v1, 0xc0135761, v1
	v_exp_f32_e32 v1, v1
	v_pk_fma_f32 v[112:113], v[28:29], v[92:93], v[112:113]
	v_add_f32_e32 v1, 1.0, v1
	v_rcp_f32_e32 v81, v1
	s_nop 0
	v_pk_mul_f32 v[78:79], v[78:79], v[80:81]
	v_pk_fma_f32 v[80:81], v[4:5], v[108:109], v[52:53]
	v_pk_mul_f32 v[78:79], v[82:83], v[78:79]
	v_pk_fma_f32 v[80:81], v[20:21], v[126:127], v[80:81]
	v_cvt_pk_bf16_f32 v78, v78, v79
	v_pk_fma_f32 v[80:81], v[36:37], v[94:95], v[80:81]
	v_pk_fma_f32 v[108:109], v[14:15], v[158:159], v[62:63]
	v_mul_f32_e32 v1, 0x3d372713, v80
	v_mul_f32_e32 v1, v80, v1
	v_fma_f32 v1, v80, v1, v80
	v_mul_f32_e32 v1, 0xc0135761, v1
	v_exp_f32_e32 v1, v1
	v_pk_fma_f32 v[108:109], v[30:31], v[102:103], v[108:109]
	v_add_f32_e32 v1, 1.0, v1
	v_rcp_f32_e32 v82, v1
	v_mul_f32_e32 v1, 0x3d372713, v81
	v_mul_f32_e32 v1, v81, v1
	v_fma_f32 v1, v81, v1, v81
	v_mul_f32_e32 v1, 0xc0135761, v1
	v_exp_f32_e32 v1, v1
	s_nop 0
	v_add_f32_e32 v1, 1.0, v1
	v_rcp_f32_e32 v83, v1
	s_nop 0
	v_pk_mul_f32 v[80:81], v[80:81], v[82:83]
	s_nop 0
	v_pk_mul_f32 v[80:81], v[84:85], v[80:81]
	s_nop 0
	v_cvt_pk_bf16_f32 v79, v80, v81
	v_add_co_u32_e32 v80, vcc, s7, v122
	s_mov_b32 s7, 0x27bd8000
	s_nop 0
	v_addc_co_u32_e32 v81, vcc, 0, v123, vcc
	global_store_dwordx4 v[80:81], v[76:79], off offset:2048
	s_nop 1
	v_add_co_u32_e32 v76, vcc, s7, v104
	s_mov_b32 s7, 0x27bdb000
	s_nop 0
	v_addc_co_u32_e32 v77, vcc, 0, v105, vcc
	v_add_co_u32_e32 v80, vcc, s7, v104
	v_mov_b32_e32 v76, v178
	v_mov_b32_e32 v77, v179
	v_mov_b32_e32 v78, v180
	v_mov_b32_e32 v79, v181
	s_nop 0
	v_addc_co_u32_e32 v81, vcc, 0, v105, vcc
; DEV void phase_act(const Params& p, int l) {
;     ...
;   for (int wi = blockIdx.x * 4 + wv; wi < 512 * 11; wi += gridDim.x * 4) {
;     int tch = wi / 11, cgp = wi % 11;
;     int c = (cgp * 64 + lane) * 8;
;     int t0 = tch * 16;
;     float wg[3][8], wu[3][8], bg[8], bu[8];
; #pragma unroll
;     for (int tap = 0; tap < 3; ++tap) {
;       float4 a = *(const float4*)(cw + tap * NUP + c), a2 = *(const float4*)(cw + tap * NUP + c + 4);
;       float4 u = *(const float4*)(cw + tap * NUP + DFF + c), u2 = *(const float4*)(cw + tap * NUP + DFF + c + 4);
;       wg[tap][0] = a.x; wg[tap][1] = a.y; wg[tap][2] = a.z; wg[tap][3] = a.w; wg[tap][4] = a2.x; wg[tap][5] = a2.y; wg[tap][6] = a2.z; wg[tap][7] = a2.w;
;       wu[tap][0] = u.x; wu[tap][1] = u.y; wu[tap][2] = u.z; wu[tap][3] = u.w; wu[tap][4] = u2.x; wu[tap][5] = u2.y; wu[tap][6] = u2.z; wu[tap][7] = u2.w;
;     }
;     { float4 a = *(const float4*)(cb + c), a2 = *(const float4*)(cb + c + 4), u = *(const float4*)(cb + DFF + c), u2 = *(const float4*)(cb + DFF + c + 4);
;       bg[0] = a.x; bg[1] = a.y; bg[2] = a.z; bg[3] = a.w; bg[4] = a2.x; bg[5] = a2.y; bg[6] = a2.z; bg[7] = a2.w;
;       bu[0] = u.x; bu[1] = u.y; bu[2] = u.z; bu[3] = u.w; bu[4] = u2.x; bu[5] = u2.y; bu[6] = u2.z; bu[7] = u2.w; }
;     float gm2[8], gm1[8], um2[8], um1[8];
;     const bool first = (t0 & 4095) == 0;
; #pragma unroll
;     for (int i = 0; i < 8; ++i) { gm2[i] = gm1[i] = um2[i] = um1[i] = 0.f; }
;     if (!first) {
;       uint4 a = *(const uint4*)(U + (size_t)(t0 - 2) * NUP + c), b2 = *(const uint4*)(U + (size_t)(t0 - 2) * NUP + DFF + c);
;       uint4 a1 = *(const uint4*)(U + (size_t)(t0 - 1) * NUP + c), b1 = *(const uint4*)(U + (size_t)(t0 - 1) * NUP + DFF + c);
;       const unsigned* pa = (const unsigned*)&a; const unsigned* pb = (const unsigned*)&b2; const unsigned* pa1 = (const unsigned*)&a1; const unsigned* pb1 = (const unsigned*)&b1;
; #pragma unroll
;       for (int i = 0; i < 4; ++i) {
;         gm2[2 * i] = bf2f(pa[i] & 0xffff); gm2[2 * i + 1] = bf2f(pa[i] >> 16); um2[2 * i] = bf2f(pb[i] & 0xffff); um2[2 * i + 1] = bf2f(pb[i] >> 16);
;         gm1[2 * i] = bf2f(pa1[i] & 0xffff); gm1[2 * i + 1] = bf2f(pa1[i] >> 16); um1[2 * i] = bf2f(pb1[i] & 0xffff); um1[2 * i + 1] = bf2f(pb1[i] >> 16);
;       }
;     }
; #pragma unroll 4
;     for (int t = t0; t < t0 + 16; ++t) {
	v_mov_b32_e32 v104, v182
	v_mov_b32_e32 v105, v183
	v_mov_b32_e32 v106, v184
	v_mov_b32_e32 v107, v185
	s_nop 0
	v_lshlrev_b32_e32 v88, 16, v76
	v_and_b32_e32 v89, 0xffff0000, v76
	v_lshlrev_b32_e32 v84, 16, v77
	v_lshlrev_b32_e32 v90, 16, v104
	v_and_b32_e32 v91, 0xffff0000, v104
	v_lshlrev_b32_e32 v86, 16, v105
	v_and_b32_e32 v87, 0xffff0000, v105
	v_pk_fma_f32 v[104:105], v[6:7], v[160:161], v[54:55]
	v_lshlrev_b32_e32 v80, 16, v106
	v_pk_fma_f32 v[104:105], v[22:23], v[66:67], v[104:105]
	v_and_b32_e32 v81, 0xffff0000, v106
	v_pk_fma_f32 v[104:105], v[38:39], v[88:89], v[104:105]
	v_and_b32_e32 v85, 0xffff0000, v77
	v_mul_f32_e32 v1, 0x3d372713, v104
	v_mul_f32_e32 v1, v104, v1
	v_fma_f32 v1, v104, v1, v104
	v_mul_f32_e32 v1, 0xc0135761, v1
	v_exp_f32_e32 v1, v1
	v_lshlrev_b32_e32 v76, 16, v107
	v_and_b32_e32 v77, 0xffff0000, v107
	v_pk_fma_f32 v[108:109], v[46:47], v[90:91], v[108:109]
	v_add_f32_e32 v1, 1.0, v1
	v_rcp_f32_e32 v106, v1
	v_mul_f32_e32 v1, 0x3d372713, v105
	v_mul_f32_e32 v1, v105, v1
	v_fma_f32 v1, v105, v1, v105
	v_mul_f32_e32 v1, 0xc0135761, v1
	v_exp_f32_e32 v1, v1
	v_pk_fma_f32 v[110:111], v[48:49], v[86:87], v[110:111]
	v_lshlrev_b32_e32 v82, 16, v78
	v_and_b32_e32 v83, 0xffff0000, v78
	v_add_f32_e32 v1, 1.0, v1
	v_rcp_f32_e32 v107, v1
	v_lshlrev_b32_e32 v78, 16, v79
	v_and_b32_e32 v79, 0xffff0000, v79
	v_pk_fma_f32 v[112:113], v[44:45], v[76:77], v[112:113]
	v_pk_mul_f32 v[104:105], v[104:105], v[106:107]
	v_pk_fma_f32 v[106:107], v[8:9], v[156:157], v[56:57]
	v_pk_mul_f32 v[104:105], v[108:109], v[104:105]
	v_pk_fma_f32 v[106:107], v[24:25], v[98:99], v[106:107]
	v_cvt_pk_bf16_f32 v104, v104, v105
	v_pk_fma_f32 v[106:107], v[40:41], v[84:85], v[106:107]
	s_nop 0
	v_mul_f32_e32 v1, 0x3d372713, v106
	v_mul_f32_e32 v1, v106, v1
	v_fma_f32 v1, v106, v1, v106
	v_mul_f32_e32 v1, 0xc0135761, v1
	v_exp_f32_e32 v1, v1
	s_nop 0
	v_add_f32_e32 v1, 1.0, v1
	v_rcp_f32_e32 v108, v1
	v_mul_f32_e32 v1, 0x3d372713, v107
	v_mul_f32_e32 v1, v107, v1
	v_fma_f32 v1, v107, v1, v107
	v_mul_f32_e32 v1, 0xc0135761, v1
	v_exp_f32_e32 v1, v1
	s_nop 0
	v_add_f32_e32 v1, 1.0, v1
	v_rcp_f32_e32 v109, v1
	s_nop 0
	v_pk_mul_f32 v[106:107], v[106:107], v[108:109]
	s_nop 0
	v_pk_mul_f32 v[106:107], v[110:111], v[106:107]
	v_pk_fma_f32 v[110:111], v[10:11], v[128:129], v[58:59]
	v_cvt_pk_bf16_f32 v105, v106, v107
	v_pk_fma_f32 v[106:107], v[2:3], v[152:153], v[50:51]
	v_pk_fma_f32 v[110:111], v[26:27], v[68:69], v[110:111]
	v_pk_fma_f32 v[106:107], v[18:19], v[96:97], v[106:107]
	v_pk_fma_f32 v[110:111], v[42:43], v[80:81], v[110:111]
	v_pk_fma_f32 v[106:107], v[34:35], v[82:83], v[106:107]
	s_nop 0
	v_mul_f32_e32 v1, 0x3d372713, v106
	v_mul_f32_e32 v1, v106, v1
	v_fma_f32 v1, v106, v1, v106
	v_mul_f32_e32 v1, 0xc0135761, v1
	v_exp_f32_e32 v1, v1
	s_nop 0
	v_add_f32_e32 v1, 1.0, v1
	v_rcp_f32_e32 v108, v1
	v_mul_f32_e32 v1, 0x3d372713, v107
	v_mul_f32_e32 v1, v107, v1
	v_fma_f32 v1, v107, v1, v107
	v_mul_f32_e32 v1, 0xc0135761, v1
	v_exp_f32_e32 v1, v1
	s_nop 0
	v_add_f32_e32 v1, 1.0, v1
	v_rcp_f32_e32 v109, v1
	s_nop 0
	v_pk_mul_f32 v[106:107], v[106:107], v[108:109]
	v_pk_fma_f32 v[108:109], v[4:5], v[126:127], v[52:53]
	v_pk_mul_f32 v[106:107], v[110:111], v[106:107]
	v_pk_fma_f32 v[108:109], v[20:21], v[94:95], v[108:109]
	v_cvt_pk_bf16_f32 v106, v106, v107
	v_pk_fma_f32 v[108:109], v[36:37], v[78:79], v[108:109]
	s_nop 0
	v_mul_f32_e32 v1, 0x3d372713, v108
	v_mul_f32_e32 v1, v108, v1
	v_fma_f32 v1, v108, v1, v108
	v_mul_f32_e32 v1, 0xc0135761, v1
	v_exp_f32_e32 v1, v1
	s_nop 0
	v_add_f32_e32 v1, 1.0, v1
	v_rcp_f32_e32 v110, v1
	v_mul_f32_e32 v1, 0x3d372713, v109
	v_mul_f32_e32 v1, v109, v1
	v_fma_f32 v1, v109, v1, v109
	v_mul_f32_e32 v1, 0xc0135761, v1
	v_exp_f32_e32 v1, v1
	s_nop 0
	v_add_f32_e32 v1, 1.0, v1
	v_rcp_f32_e32 v111, v1
	s_nop 0
	v_pk_mul_f32 v[108:109], v[108:109], v[110:111]
	s_nop 0
	v_pk_mul_f32 v[108:109], v[112:113], v[108:109]
	s_nop 0
	v_cvt_pk_bf16_f32 v107, v108, v109
	v_add_co_u32_e32 v108, vcc, 0x21bd0000, v122
	s_nop 1
	v_addc_co_u32_e32 v109, vcc, 0, v123, vcc
	global_store_dwordx4 v[108:109], v[104:107], off offset:1024
	s_cbranch_scc0 .LBB0_89
	v_readlane_b32 s6, v240, 48
	s_nop 1
	v_add_u32_e32 v130, s6, v130
	s_movk_i32 s6, 0x15ff
	v_cmp_lt_i32_e32 vcc, s6, v130
	s_or_b64 s[76:77], vcc, s[76:77]
	s_andn2_b64 exec, exec, s[76:77]
	s_cbranch_execnz .LBB0_86

; DEV f32x16 mfma(bf16x8 a, bf16x8 b, f32x16 c) { return __builtin_amdgcn_mfma_f32_32x32x16_bf16(a, b, c, 0, 0, 0); }
;     ...
;   for (int kt = 0; kt < nk; ++kt) {
;     if (kt + 1 < nk) { if (MI == 4) asm volatile("s_waitcnt vmcnt(6)" ::: "memory"); else asm volatile("s_waitcnt vmcnt(4)" ::: "memory"); } else asm volatile("s_waitcnt vmcnt(0)" ::: "memory");
;     __builtin_amdgcn_s_barrier();
;     if (kt + 2 < nk) { int s2 = stg + 2; if (s2 >= 3) s2 -= 3; g2_issue<MI>(ag + (size_t)(kt + 2) * 32, bg + (size_t)(kt + 2) * 32, lda, ldb, voffa, voffb, lds + s2 * G2_STAGE, w); }
;     const unsigned so = (unsigned)(stg * G2_STAGE);
;     __builtin_amdgcn_s_setprio(1);
; #pragma unroll
;     for (int ks = 0; ks < 2; ++ks) {
;       const unsigned aa = (ks ? la1 : la0) + so, bb = (ks ? lb1 : lb0) + so;
;       bf16x8 fb0, fb1, fa0, fa1, fa2, fa3;
;       asm volatile("ds_read_b128 %0, %1" : "=v"(fb0) : "v"(bb));
;       asm volatile("ds_read_b128 %0, %1 offset:2048" : "=v"(fb1) : "v"(bb));
;       asm volatile("ds_read_b128 %0, %1" : "=v"(fa0) : "v"(aa));
;       asm volatile("ds_read_b128 %0, %1 offset:2048" : "=v"(fa1) : "v"(aa));
;       if constexpr (MI == 4) {
;         asm volatile("ds_read_b128 %0, %1 offset:4096" : "=v"(fa2) : "v"(aa));
;         asm volatile("ds_read_b128 %0, %1 offset:6144" : "=v"(fa3) : "v"(aa));
;         __builtin_amdgcn_sched_barrier(0);
;         asm volatile("s_waitcnt lgkmcnt(3)" : "+v"(fb0), "+v"(fb1), "+v"(fa0));
;         acc[0][0][0] = mfma(fa0, fb0, acc[0][0][0]); acc[0][0][1] = mfma(fa0, fb1, acc[0][0][1]); __builtin_amdgcn_sched_barrier(0);
;         asm volatile("s_waitcnt lgkmcnt(2)" : "+v"(fa1));
;         acc[0][1][0] = mfma(fa1, fb0, acc[0][1][0]); acc[0][1][1] = mfma(fa1, fb1, acc[0][1][1]); __builtin_amdgcn_sched_barrier(0);
;         asm volatile("s_waitcnt lgkmcnt(1)" : "+v"(fa2));
;         acc[MI / 2 - 1][0][0] = mfma(fa2, fb0, acc[MI / 2 - 1][0][0]); acc[MI / 2 - 1][0][1] = mfma(fa2, fb1, acc[MI / 2 - 1][0][1]); __builtin_amdgcn_sched_barrier(0);
;         asm volatile("s_waitcnt lgkmcnt(0)" : "+v"(fa3));
;         acc[MI / 2 - 1][1][0] = mfma(fa3, fb0, acc[MI / 2 - 1][1][0]); acc[MI / 2 - 1][1][1] = mfma(fa3, fb1, acc[MI / 2 - 1][1][1]); __builtin_amdgcn_sched_barrier(0);
;       } else {
;         __builtin_amdgcn_sched_barrier(0);
;         asm volatile("s_waitcnt lgkmcnt(1)" : "+v"(fb0), "+v"(fb1), "+v"(fa0));
.LBB0_103:
	s_cmp_gt_i32 s21, 0
	s_cselect_b32 s22, -1, 2
	s_add_i32 s22, s22, s21
	s_mul_i32 s31, s22, 0x6000
	s_add_u32 s22, s19, s10
	s_addc_u32 s23, s20, s11
	s_add_i32 s52, s13, s31
	s_waitcnt vmcnt(6)
	s_barrier
	s_mov_b32 m0, s52
	s_nop 0
	global_load_lds_dwordx4 v143, s[22:23]
	s_add_u32 s52, s4, s10
	s_addc_u32 s53, s5, s11
	s_add_u32 s22, s52, 0x10080
	s_addc_u32 s23, s53, 0
	s_add_i32 s54, s14, s31
	s_mov_b32 m0, s54
	s_nop 0
	global_load_lds_dwordx4 v143, s[22:23]
	s_add_u32 s22, s52, 0x20080
	s_addc_u32 s23, s53, 0
	s_add_i32 s54, s15, s31
	s_mov_b32 m0, s54
	s_nop 0
	global_load_lds_dwordx4 v143, s[22:23]
	s_add_u32 s22, s52, 0x30080
	s_addc_u32 s23, s53, 0
	s_add_i32 s52, s16, s31
	s_addk_i32 s31, 0x4000
	s_mov_b32 m0, s52
	s_nop 0
	global_load_lds_dwordx4 v143, s[22:23]
	s_add_u32 s52, s8, s10
	s_addc_u32 s53, s9, s11
	s_add_u32 s22, s52, 0x80
	s_addc_u32 s23, s53, 0
	s_add_i32 s54, s31, s17
	s_mov_b32 m0, s54
	s_nop 0
	global_load_lds_dwordx4 v143, s[22:23]
	s_add_u32 s22, s52, 0x10080
	s_addc_u32 s23, s53, 0
	s_add_i32 s31, s31, s18
	s_mov_b32 m0, s31
	s_nop 0
	global_load_lds_dwordx4 v143, s[22:23]
	s_mul_i32 s22, s21, 0x6000
	s_setprio 1
	v_add_u32_e32 v149, s22, v133
	v_add_u32_e32 v176, s22, v138
	v_add_u32_e32 v172, v149, v145
	v_add_u32_e32 v156, v176, v145
	ds_read_b128 v[152:155], v156
	ds_read_b128 v[156:159], v156 offset:2048
	ds_read_b128 v[160:163], v172
	ds_read_b128 v[164:167], v172 offset:2048
	ds_read_b128 v[168:171], v172 offset:4096
	ds_read_b128 v[172:175], v172 offset:6144
	s_nop 0
	s_waitcnt lgkmcnt(3)
	s_nop 0
	v_mfma_f32_32x32x16_bf16 v[114:129], v[160:163], v[152:155], v[114:129]
	v_mfma_f32_32x32x16_bf16 v[98:113], v[160:163], v[156:159], v[98:113]
	s_waitcnt lgkmcnt(2)
	s_nop 0
	v_mfma_f32_32x32x16_bf16 v[82:97], v[164:167], v[152:155], v[82:97]
	v_mfma_f32_32x32x16_bf16 v[66:81], v[164:167], v[156:159], v[66:81]
	s_waitcnt lgkmcnt(1)
	s_nop 0
	v_mfma_f32_32x32x16_bf16 v[50:65], v[168:171], v[152:155], v[50:65]
	v_mfma_f32_32x32x16_bf16 v[34:49], v[168:171], v[156:159], v[34:49]
	s_waitcnt lgkmcnt(0)
	s_nop 0
	v_mfma_f32_32x32x16_bf16 v[18:33], v[172:175], v[152:155], v[18:33]
	v_mfma_f32_32x32x16_bf16 v[2:17], v[172:175], v[156:159], v[2:17]
	v_add_u32_e32 v156, v176, v141
	v_add_u32_e32 v149, v149, v141
	ds_read_b128 v[152:155], v156
	ds_read_b128 v[156:159], v156 offset:2048
	ds_read_b128 v[160:163], v149
	ds_read_b128 v[164:167], v149 offset:2048
	ds_read_b128 v[168:171], v149 offset:4096
	ds_read_b128 v[172:175], v149 offset:6144
	s_nop 0
	s_waitcnt lgkmcnt(3)
	s_nop 0
	v_mfma_f32_32x32x16_bf16 v[114:129], v[160:163], v[152:155], v[114:129]
	v_mfma_f32_32x32x16_bf16 v[98:113], v[160:163], v[156:159], v[98:113]
	s_waitcnt lgkmcnt(2)
	s_nop 0
	v_mfma_f32_32x32x16_bf16 v[82:97], v[164:167], v[152:155], v[82:97]
	v_mfma_f32_32x32x16_bf16 v[66:81], v[164:167], v[156:159], v[66:81]
	s_waitcnt lgkmcnt(1)
	s_nop 0
	v_mfma_f32_32x32x16_bf16 v[50:65], v[168:171], v[152:155], v[50:65]
	v_mfma_f32_32x32x16_bf16 v[34:49], v[168:171], v[156:159], v[34:49]
	s_waitcnt lgkmcnt(0)
	s_nop 0
	v_mfma_f32_32x32x16_bf16 v[18:33], v[172:175], v[152:155], v[18:33]
	v_mfma_f32_32x32x16_bf16 v[2:17], v[172:175], v[156:159], v[2:17]
	s_setprio 0
	s_add_i32 s22, s21, 1
	s_cmp_lg_u32 s21, 2
	s_cselect_b32 s21, s22, 0
	s_add_u32 s10, s10, 64
	s_addc_u32 s11, s11, 0
	s_cmpk_eq_i32 s10, 0xf80
	s_cbranch_scc0 .LBB0_103
	s_waitcnt vmcnt(6)
	s_barrier
	s_setprio 1
	v_or_b32_e32 v147, 0x10000, v147
	v_add_u32_e32 v143, 0xc000, v133
	v_add_u32_e32 v156, v147, v145
	v_add_u32_e32 v149, v143, v145
	ds_read_b128 v[152:155], v156
	ds_read_b128 v[156:159], v156 offset:2048
	ds_read_b128 v[160:163], v149
	ds_read_b128 v[164:167], v149 offset:2048
	ds_read_b128 v[168:171], v149 offset:4096
	ds_read_b128 v[172:175], v149 offset:6144
	s_nop 0
	s_waitcnt lgkmcnt(3)
	s_nop 0
	v_mfma_f32_32x32x16_bf16 v[114:129], v[160:163], v[152:155], v[114:129]
	v_mfma_f32_32x32x16_bf16 v[98:113], v[160:163], v[156:159], v[98:113]
	s_waitcnt lgkmcnt(2)
	s_nop 0
	v_mfma_f32_32x32x16_bf16 v[82:97], v[164:167], v[152:155], v[82:97]
	v_mfma_f32_32x32x16_bf16 v[66:81], v[164:167], v[156:159], v[66:81]
	s_waitcnt lgkmcnt(1)
	s_nop 0
	v_mfma_f32_32x32x16_bf16 v[50:65], v[168:171], v[152:155], v[50:65]
	v_mfma_f32_32x32x16_bf16 v[34:49], v[168:171], v[156:159], v[34:49]
	s_waitcnt lgkmcnt(0)
	s_nop 0
	v_mfma_f32_32x32x16_bf16 v[18:33], v[172:175], v[152:155], v[18:33]
	v_mfma_f32_32x32x16_bf16 v[2:17], v[172:175], v[156:159], v[2:17]
	v_add_u32_e32 v143, v143, v141
	v_add_u32_e32 v147, v147, v141
	ds_read_b128 v[152:155], v147
	ds_read_b128 v[156:159], v147 offset:2048
	ds_read_b128 v[160:163], v143
	ds_read_b128 v[164:167], v143 offset:2048
	ds_read_b128 v[168:171], v143 offset:4096
	ds_read_b128 v[172:175], v143 offset:6144
	s_nop 0
	s_waitcnt lgkmcnt(3)
	s_nop 0
	v_mfma_f32_32x32x16_bf16 v[114:129], v[160:163], v[152:155], v[114:129]
	v_mfma_f32_32x32x16_bf16 v[98:113], v[160:163], v[156:159], v[98:113]
	s_waitcnt lgkmcnt(2)
	s_nop 0
	v_mfma_f32_32x32x16_bf16 v[82:97], v[164:167], v[152:155], v[82:97]
	v_mfma_f32_32x32x16_bf16 v[66:81], v[164:167], v[156:159], v[66:81]
	s_waitcnt lgkmcnt(1)
	s_nop 0
	v_mfma_f32_32x32x16_bf16 v[50:65], v[168:171], v[152:155], v[50:65]
	v_mfma_f32_32x32x16_bf16 v[34:49], v[168:171], v[156:159], v[34:49]
	s_waitcnt lgkmcnt(0)
	s_nop 0
	v_mfma_f32_32x32x16_bf16 v[18:33], v[172:175], v[152:155], v[18:33]
	v_mfma_f32_32x32x16_bf16 v[2:17], v[172:175], v[156:159], v[2:17]
	s_setprio 0
	s_waitcnt vmcnt(0)
	s_barrier
; DEV f32x16 mfma(bf16x8 a, bf16x8 b, f32x16 c) { return __builtin_amdgcn_mfma_f32_32x32x16_bf16(a, b, c, 0, 0, 0); }
;     ...
;   for (int kt = 0; kt < nk; ++kt) {
;     if (kt + 1 < nk) { if (MI == 4) asm volatile("s_waitcnt vmcnt(6)" ::: "memory"); else asm volatile("s_waitcnt vmcnt(4)" ::: "memory"); } else asm volatile("s_waitcnt vmcnt(0)" ::: "memory");
;     __builtin_amdgcn_s_barrier();
;     if (kt + 2 < nk) { int s2 = stg + 2; if (s2 >= 3) s2 -= 3; g2_issue<MI>(ag + (size_t)(kt + 2) * 32, bg + (size_t)(kt + 2) * 32, lda, ldb, voffa, voffb, lds + s2 * G2_STAGE, w); }
;     const unsigned so = (unsigned)(stg * G2_STAGE);
;     __builtin_amdgcn_s_setprio(1);
; #pragma unroll
;     for (int ks = 0; ks < 2; ++ks) {
;       const unsigned aa = (ks ? la1 : la0) + so, bb = (ks ? lb1 : lb0) + so;
;       bf16x8 fb0, fb1, fa0, fa1, fa2, fa3;
;       asm volatile("ds_read_b128 %0, %1" : "=v"(fb0) : "v"(bb));
;       asm volatile("ds_read_b128 %0, %1 offset:2048" : "=v"(fb1) : "v"(bb));
;       asm volatile("ds_read_b128 %0, %1" : "=v"(fa0) : "v"(aa));
;       asm volatile("ds_read_b128 %0, %1 offset:2048" : "=v"(fa1) : "v"(aa));
;       if constexpr (MI == 4) {
;         asm volatile("ds_read_b128 %0, %1 offset:4096" : "=v"(fa2) : "v"(aa));
;         asm volatile("ds_read_b128 %0, %1 offset:6144" : "=v"(fa3) : "v"(aa));
;         __builtin_amdgcn_sched_barrier(0);
;         asm volatile("s_waitcnt lgkmcnt(3)" : "+v"(fb0), "+v"(fb1), "+v"(fa0));
;         acc[0][0][0] = mfma(fa0, fb0, acc[0][0][0]); acc[0][0][1] = mfma(fa0, fb1, acc[0][0][1]); __builtin_amdgcn_sched_barrier(0);
;         asm volatile("s_waitcnt lgkmcnt(2)" : "+v"(fa1));
;         acc[0][1][0] = mfma(fa1, fb0, acc[0][1][0]); acc[0][1][1] = mfma(fa1, fb1, acc[0][1][1]); __builtin_amdgcn_sched_barrier(0);
;         asm volatile("s_waitcnt lgkmcnt(1)" : "+v"(fa2));
;         acc[MI / 2 - 1][0][0] = mfma(fa2, fb0, acc[MI / 2 - 1][0][0]); acc[MI / 2 - 1][0][1] = mfma(fa2, fb1, acc[MI / 2 - 1][0][1]); __builtin_amdgcn_sched_barrier(0);
;         asm volatile("s_waitcnt lgkmcnt(0)" : "+v"(fa3));
;         acc[MI / 2 - 1][1][0] = mfma(fa3, fb0, acc[MI / 2 - 1][1][0]); acc[MI / 2 - 1][1][1] = mfma(fa3, fb1, acc[MI / 2 - 1][1][1]); __builtin_amdgcn_sched_barrier(0);
;       } else {
;         __builtin_amdgcn_sched_barrier(0);
;         asm volatile("s_waitcnt lgkmcnt(1)" : "+v"(fb0), "+v"(fb1), "+v"(fa0));
	s_setprio 1
	v_add_u32_e32 v143, v133, v145
	v_add_u32_e32 v145, v138, v145
	ds_read_b128 v[152:155], v145
	ds_read_b128 v[156:159], v145 offset:2048
	ds_read_b128 v[160:163], v143
	ds_read_b128 v[164:167], v143 offset:2048
	ds_read_b128 v[168:171], v143 offset:4096
	ds_read_b128 v[172:175], v143 offset:6144
	s_nop 0
	s_waitcnt lgkmcnt(3)
	s_nop 0
	v_mfma_f32_32x32x16_bf16 v[114:129], v[160:163], v[152:155], v[114:129]
	v_mfma_f32_32x32x16_bf16 v[98:113], v[160:163], v[156:159], v[98:113]
	s_waitcnt lgkmcnt(2)
	s_nop 0
	v_mfma_f32_32x32x16_bf16 v[82:97], v[164:167], v[152:155], v[82:97]
	v_mfma_f32_32x32x16_bf16 v[66:81], v[164:167], v[156:159], v[66:81]
	s_waitcnt lgkmcnt(1)
	s_nop 0
	v_mfma_f32_32x32x16_bf16 v[50:65], v[168:171], v[152:155], v[50:65]
	v_mfma_f32_32x32x16_bf16 v[34:49], v[168:171], v[156:159], v[34:49]
	s_waitcnt lgkmcnt(0)
	s_nop 0
	v_mfma_f32_32x32x16_bf16 v[18:33], v[172:175], v[152:155], v[18:33]
	v_mfma_f32_32x32x16_bf16 v[2:17], v[172:175], v[156:159], v[2:17]
	v_add_u32_e32 v133, v133, v141
	v_add_u32_e32 v138, v138, v141
	ds_read_b128 v[152:155], v138
	ds_read_b128 v[156:159], v138 offset:2048
	ds_read_b128 v[160:163], v133
	ds_read_b128 v[164:167], v133 offset:2048
	ds_read_b128 v[168:171], v133 offset:4096
	ds_read_b128 v[172:175], v133 offset:6144
	s_nop 0
	s_waitcnt lgkmcnt(3)
	s_nop 0
	v_mfma_f32_32x32x16_bf16 v[114:129], v[160:163], v[152:155], v[114:129]
	v_mfma_f32_32x32x16_bf16 v[98:113], v[160:163], v[156:159], v[98:113]
	s_waitcnt lgkmcnt(2)
	s_nop 0
	v_mfma_f32_32x32x16_bf16 v[82:97], v[164:167], v[152:155], v[82:97]
	v_mfma_f32_32x32x16_bf16 v[66:81], v[164:167], v[156:159], v[66:81]
	s_waitcnt lgkmcnt(1)
	s_nop 0
	v_mfma_f32_32x32x16_bf16 v[50:65], v[168:171], v[152:155], v[50:65]
	v_mfma_f32_32x32x16_bf16 v[34:49], v[168:171], v[156:159], v[34:49]
	s_waitcnt lgkmcnt(0)
	s_nop 0
	v_mfma_f32_32x32x16_bf16 v[18:33], v[172:175], v[152:155], v[18:33]
	v_mfma_f32_32x32x16_bf16 v[2:17], v[172:175], v[156:159], v[2:17]
	s_setprio 0
	s_add_i32 s1, s1, s0
	s_or_b32 s0, s3, s2
	v_lshl_or_b32 v130, v130, 2, s1
	s_ashr_i32 s1, s0, 31
	s_lshl_b64 s[0:1], s[0:1], 1
	s_add_u32 s0, s24, s0
	s_addc_u32 s1, s25, s1
	v_lshlrev_b32_e32 v152, 1, v1
	v_mov_b32_e32 v153, v0
	v_lshl_add_u64 v[152:153], s[0:1], 0, v[152:153]
	v_cvt_pk_bf16_f32 v1, v114, s0
	v_mad_i64_i32 v[154:155], s[0:1], v130, s67, v[152:153]
	s_waitcnt lgkmcnt(0)
	s_barrier
	global_store_short v[154:155], v1, off
	v_or_b32_e32 v1, 1, v130
	v_cvt_pk_bf16_f32 v133, v115, s0
	v_mad_i64_i32 v[114:115], s[0:1], v1, s67, v[152:153]
	v_or_b32_e32 v1, 2, v130
	s_nop 0
	v_cvt_pk_bf16_f32 v116, v116, s0
	v_mad_i64_i32 v[156:157], s[0:1], v1, s67, v[152:153]
	v_or_b32_e32 v1, 3, v130
	global_store_short v[114:115], v133, off
	global_store_short v[156:157], v116, off
	v_cvt_pk_bf16_f32 v133, v117, s0
	v_mad_i64_i32 v[116:117], s[0:1], v1, s67, v[152:153]
	v_or_b32_e32 v1, 8, v130
	s_nop 0
	v_cvt_pk_bf16_f32 v118, v118, s0
	v_mad_i64_i32 v[158:159], s[0:1], v1, s67, v[152:153]
	v_or_b32_e32 v1, 9, v130
	global_store_short v[116:117], v133, off
	global_store_short v[158:159], v118, off
	v_cvt_pk_bf16_f32 v133, v119, s0
	v_mad_i64_i32 v[118:119], s[0:1], v1, s67, v[152:153]
	v_or_b32_e32 v1, 10, v130
	s_nop 0
	v_cvt_pk_bf16_f32 v120, v120, s0
	v_mad_i64_i32 v[160:161], s[0:1], v1, s67, v[152:153]
	v_or_b32_e32 v1, 11, v130
	global_store_short v[118:119], v133, off
	global_store_short v[160:161], v120, off
	v_cvt_pk_bf16_f32 v133, v121, s0
	v_mad_i64_i32 v[120:121], s[0:1], v1, s67, v[152:153]
	v_or_b32_e32 v1, 16, v130
	s_nop 0
	v_cvt_pk_bf16_f32 v122, v122, s0
	v_mad_i64_i32 v[162:163], s[0:1], v1, s67, v[152:153]
	v_or_b32_e32 v1, 17, v130
	global_store_short v[120:121], v133, off
	global_store_short v[162:163], v122, off
	v_cvt_pk_bf16_f32 v133, v123, s0
	v_mad_i64_i32 v[122:123], s[0:1], v1, s67, v[152:153]
	v_or_b32_e32 v1, 18, v130
	s_nop 0
	v_cvt_pk_bf16_f32 v124, v124, s0
	v_mad_i64_i32 v[164:165], s[0:1], v1, s67, v[152:153]
	v_or_b32_e32 v1, 19, v130
	global_store_short v[122:123], v133, off
	global_store_short v[164:165], v124, off
	v_cvt_pk_bf16_f32 v133, v125, s0
	v_mad_i64_i32 v[124:125], s[0:1], v1, s67, v[152:153]
	v_or_b32_e32 v1, 24, v130
	s_nop 0
	v_cvt_pk_bf16_f32 v126, v126, s0
	v_mad_i64_i32 v[166:167], s[0:1], v1, s67, v[152:153]
	v_or_b32_e32 v1, 25, v130
	global_store_short v[124:125], v133, off
	global_store_short v[166:167], v126, off
	v_cvt_pk_bf16_f32 v133, v127, s0
	v_mad_i64_i32 v[126:127], s[0:1], v1, s67, v[152:153]
	v_or_b32_e32 v1, 26, v130
	s_nop 0
	v_cvt_pk_bf16_f32 v128, v128, s0
	v_mad_i64_i32 v[168:169], s[0:1], v1, s67, v[152:153]
	v_or_b32_e32 v1, 27, v130
	global_store_short v[126:127], v133, off
	global_store_short v[168:169], v128, off
	v_cvt_pk_bf16_f32 v133, v129, s0
	v_mad_i64_i32 v[128:129], s[0:1], v1, s67, v[152:153]
	global_store_short v[128:129], v133, off
	s_nop 0
	v_cvt_pk_bf16_f32 v1, v98, s0
	global_store_short v[154:155], v1, off offset:64
	v_cvt_pk_bf16_f32 v1, v99, s0
	global_store_short v[114:115], v1, off offset:64
	v_cvt_pk_bf16_f32 v1, v100, s0
	global_store_short v[156:157], v1, off offset:64
	v_cvt_pk_bf16_f32 v1, v101, s0
	global_store_short v[116:117], v1, off offset:64
	v_cvt_pk_bf16_f32 v1, v102, s0
	global_store_short v[158:159], v1, off offset:64
	v_cvt_pk_bf16_f32 v1, v103, s0
	global_store_short v[118:119], v1, off offset:64
	v_cvt_pk_bf16_f32 v1, v104, s0
	global_store_short v[160:161], v1, off offset:64
	v_cvt_pk_bf16_f32 v1, v105, s0
	global_store_short v[120:121], v1, off offset:64
	v_cvt_pk_bf16_f32 v1, v106, s0
	global_store_short v[162:163], v1, off offset:64
	v_cvt_pk_bf16_f32 v1, v107, s0
; DEV bf16_t f2bf(float f) { return (bf16_t)(cvtpk(f, 0.f) & 0xffffu); }
;   DEV void operator()(f32x16 (&acc)[2][2], int mb, int nb, int r32, int hh) const {
; #pragma unroll
;     for (int mi = 0; mi < 2; ++mi)
; #pragma unroll
;       for (int ni = 0; ni < 2; ++ni)
; #pragma unroll
;         for (int r = 0; r < 16; ++r) {
;           int row = mb + mi * 32 + 8 * (r >> 2) + 4 * hh + (r & 3);
;           C[(size_t)row * ldc + nb + ni * 32 + r32] = f2bf(acc[mi][ni][r]);
;         }
;   }
	global_store_short v[122:123], v1, off offset:64
	v_cvt_pk_bf16_f32 v1, v108, s0
	global_store_short v[164:165], v1, off offset:64
	v_cvt_pk_bf16_f32 v1, v109, s0
	global_store_short v[124:125], v1, off offset:64
	v_cvt_pk_bf16_f32 v1, v110, s0
	global_store_short v[166:167], v1, off offset:64
	v_cvt_pk_bf16_f32 v1, v111, s0
	global_store_short v[126:127], v1, off offset:64
	v_cvt_pk_bf16_f32 v1, v112, s0
	global_store_short v[168:169], v1, off offset:64
	v_cvt_pk_bf16_f32 v1, v113, s0
	global_store_short v[128:129], v1, off offset:64
	v_or_b32_e32 v1, 32, v130
	v_cvt_pk_bf16_f32 v82, v82, s0
	v_mad_i64_i32 v[98:99], s[0:1], v1, s67, v[152:153]
	v_or_b32_e32 v1, 33, v130
	global_store_short v[98:99], v82, off
	v_cvt_pk_bf16_f32 v100, v83, s0
	v_mad_i64_i32 v[82:83], s[0:1], v1, s67, v[152:153]
	v_or_b32_e32 v1, 34, v130
	global_store_short v[82:83], v100, off
	v_cvt_pk_bf16_f32 v84, v84, s0
	v_mad_i64_i32 v[100:101], s[0:1], v1, s67, v[152:153]
	v_or_b32_e32 v1, 35, v130
	global_store_short v[100:101], v84, off
	v_cvt_pk_bf16_f32 v102, v85, s0
	v_mad_i64_i32 v[84:85], s[0:1], v1, s67, v[152:153]
	v_or_b32_e32 v1, 40, v130
	global_store_short v[84:85], v102, off
	v_cvt_pk_bf16_f32 v86, v86, s0
	v_mad_i64_i32 v[102:103], s[0:1], v1, s67, v[152:153]
	v_or_b32_e32 v1, 41, v130
	global_store_short v[102:103], v86, off
	v_cvt_pk_bf16_f32 v104, v87, s0
	v_mad_i64_i32 v[86:87], s[0:1], v1, s67, v[152:153]
	v_or_b32_e32 v1, 42, v130
	global_store_short v[86:87], v104, off
	v_cvt_pk_bf16_f32 v88, v88, s0
	v_mad_i64_i32 v[104:105], s[0:1], v1, s67, v[152:153]
	v_or_b32_e32 v1, 43, v130
	global_store_short v[104:105], v88, off
	v_cvt_pk_bf16_f32 v106, v89, s0
	v_mad_i64_i32 v[88:89], s[0:1], v1, s67, v[152:153]
	v_or_b32_e32 v1, 48, v130
	global_store_short v[88:89], v106, off
	v_cvt_pk_bf16_f32 v90, v90, s0
	v_mad_i64_i32 v[106:107], s[0:1], v1, s67, v[152:153]
	v_or_b32_e32 v1, 49, v130
	global_store_short v[106:107], v90, off
	v_cvt_pk_bf16_f32 v108, v91, s0
	v_mad_i64_i32 v[90:91], s[0:1], v1, s67, v[152:153]
	v_or_b32_e32 v1, 50, v130
	global_store_short v[90:91], v108, off
	v_cvt_pk_bf16_f32 v92, v92, s0
	v_mad_i64_i32 v[108:109], s[0:1], v1, s67, v[152:153]
	v_or_b32_e32 v1, 51, v130
	global_store_short v[108:109], v92, off
	v_cvt_pk_bf16_f32 v110, v93, s0
	v_mad_i64_i32 v[92:93], s[0:1], v1, s67, v[152:153]
	v_or_b32_e32 v1, 56, v130
	global_store_short v[92:93], v110, off
	v_cvt_pk_bf16_f32 v94, v94, s0
	v_mad_i64_i32 v[110:111], s[0:1], v1, s67, v[152:153]
	v_or_b32_e32 v1, 57, v130
	global_store_short v[110:111], v94, off
	v_cvt_pk_bf16_f32 v112, v95, s0
	v_mad_i64_i32 v[94:95], s[0:1], v1, s67, v[152:153]
	v_or_b32_e32 v1, 58, v130
	global_store_short v[94:95], v112, off
	v_cvt_pk_bf16_f32 v96, v96, s0
	v_mad_i64_i32 v[112:113], s[0:1], v1, s67, v[152:153]
	v_or_b32_e32 v1, 59, v130
	global_store_short v[112:113], v96, off
	v_cvt_pk_bf16_f32 v114, v97, s0
	v_mad_i64_i32 v[96:97], s[0:1], v1, s67, v[152:153]
	global_store_short v[96:97], v114, off
	s_nop 0
	v_cvt_pk_bf16_f32 v1, v66, s0
	global_store_short v[98:99], v1, off offset:64
	v_cvt_pk_bf16_f32 v1, v67, s0
	global_store_short v[82:83], v1, off offset:64
	v_cvt_pk_bf16_f32 v1, v68, s0
	global_store_short v[100:101], v1, off offset:64
	v_cvt_pk_bf16_f32 v1, v69, s0
	global_store_short v[84:85], v1, off offset:64
	v_cvt_pk_bf16_f32 v1, v70, s0
	global_store_short v[102:103], v1, off offset:64
	v_cvt_pk_bf16_f32 v1, v71, s0
	global_store_short v[86:87], v1, off offset:64
	v_cvt_pk_bf16_f32 v1, v72, s0
	global_store_short v[104:105], v1, off offset:64
	v_cvt_pk_bf16_f32 v1, v73, s0
	global_store_short v[88:89], v1, off offset:64
	v_cvt_pk_bf16_f32 v1, v74, s0
	global_store_short v[106:107], v1, off offset:64
	v_cvt_pk_bf16_f32 v1, v75, s0
	global_store_short v[90:91], v1, off offset:64
	v_cvt_pk_bf16_f32 v1, v76, s0
	global_store_short v[108:109], v1, off offset:64
	v_cvt_pk_bf16_f32 v1, v77, s0
	global_store_short v[92:93], v1, off offset:64
	v_cvt_pk_bf16_f32 v1, v78, s0
	global_store_short v[110:111], v1, off offset:64
	v_cvt_pk_bf16_f32 v1, v79, s0
	global_store_short v[94:95], v1, off offset:64
	v_cvt_pk_bf16_f32 v1, v80, s0
	global_store_short v[112:113], v1, off offset:64
	v_cvt_pk_bf16_f32 v1, v81, s0
	global_store_short v[96:97], v1, off offset:64
	v_or_b32_e32 v1, 64, v130
	v_cvt_pk_bf16_f32 v50, v50, s0
	v_mad_i64_i32 v[66:67], s[0:1], v1, s67, v[152:153]
	v_or_b32_e32 v1, 0x41, v130
	global_store_short v[66:67], v50, off
	v_cvt_pk_bf16_f32 v68, v51, s0
	v_mad_i64_i32 v[50:51], s[0:1], v1, s67, v[152:153]
	v_or_b32_e32 v1, 0x42, v130
	global_store_short v[50:51], v68, off
	v_cvt_pk_bf16_f32 v52, v52, s0
	v_mad_i64_i32 v[68:69], s[0:1], v1, s67, v[152:153]
	v_or_b32_e32 v1, 0x43, v130
	global_store_short v[68:69], v52, off
	v_cvt_pk_bf16_f32 v70, v53, s0
	v_mad_i64_i32 v[52:53], s[0:1], v1, s67, v[152:153]
	v_or_b32_e32 v1, 0x48, v130
	global_store_short v[52:53], v70, off
	v_cvt_pk_bf16_f32 v54, v54, s0
	v_mad_i64_i32 v[70:71], s[0:1], v1, s67, v[152:153]
	v_or_b32_e32 v1, 0x49, v130
	global_store_short v[70:71], v54, off
	v_cvt_pk_bf16_f32 v72, v55, s0
	v_mad_i64_i32 v[54:55], s[0:1], v1, s67, v[152:153]
	v_or_b32_e32 v1, 0x4a, v130
	global_store_short v[54:55], v72, off
	v_cvt_pk_bf16_f32 v56, v56, s0
	v_mad_i64_i32 v[72:73], s[0:1], v1, s67, v[152:153]
	v_or_b32_e32 v1, 0x4b, v130
	global_store_short v[72:73], v56, off
	v_cvt_pk_bf16_f32 v74, v57, s0
	v_mad_i64_i32 v[56:57], s[0:1], v1, s67, v[152:153]
	v_or_b32_e32 v1, 0x50, v130
	global_store_short v[56:57], v74, off
	v_cvt_pk_bf16_f32 v58, v58, s0
	v_mad_i64_i32 v[74:75], s[0:1], v1, s67, v[152:153]
	v_or_b32_e32 v1, 0x51, v130
; DEV bf16_t f2bf(float f) { return (bf16_t)(cvtpk(f, 0.f) & 0xffffu); }
;   DEV void operator()(f32x16 (&acc)[2][2], int mb, int nb, int r32, int hh) const {
; #pragma unroll
;     for (int mi = 0; mi < 2; ++mi)
; #pragma unroll
;       for (int ni = 0; ni < 2; ++ni)
; #pragma unroll
;         for (int r = 0; r < 16; ++r) {
;           int row = mb + mi * 32 + 8 * (r >> 2) + 4 * hh + (r & 3);
;           C[(size_t)row * ldc + nb + ni * 32 + r32] = f2bf(acc[mi][ni][r]);
;         }
;   }
	global_store_short v[74:75], v58, off
	v_cvt_pk_bf16_f32 v76, v59, s0
	v_mad_i64_i32 v[58:59], s[0:1], v1, s67, v[152:153]
	v_or_b32_e32 v1, 0x52, v130
	global_store_short v[58:59], v76, off
	v_cvt_pk_bf16_f32 v60, v60, s0
	v_mad_i64_i32 v[76:77], s[0:1], v1, s67, v[152:153]
	v_or_b32_e32 v1, 0x53, v130
	global_store_short v[76:77], v60, off
	v_cvt_pk_bf16_f32 v78, v61, s0
	v_mad_i64_i32 v[60:61], s[0:1], v1, s67, v[152:153]
	v_or_b32_e32 v1, 0x58, v130
	global_store_short v[60:61], v78, off
	v_cvt_pk_bf16_f32 v62, v62, s0
	v_mad_i64_i32 v[78:79], s[0:1], v1, s67, v[152:153]
	v_or_b32_e32 v1, 0x59, v130
	global_store_short v[78:79], v62, off
	v_cvt_pk_bf16_f32 v80, v63, s0
	v_mad_i64_i32 v[62:63], s[0:1], v1, s67, v[152:153]
	v_or_b32_e32 v1, 0x5a, v130
	global_store_short v[62:63], v80, off
	v_cvt_pk_bf16_f32 v64, v64, s0
	v_mad_i64_i32 v[80:81], s[0:1], v1, s67, v[152:153]
	v_or_b32_e32 v1, 0x5b, v130
	global_store_short v[80:81], v64, off
	v_cvt_pk_bf16_f32 v82, v65, s0
	v_mad_i64_i32 v[64:65], s[0:1], v1, s67, v[152:153]
	global_store_short v[64:65], v82, off
	s_nop 0
	v_cvt_pk_bf16_f32 v1, v34, s0
	global_store_short v[66:67], v1, off offset:64
	v_cvt_pk_bf16_f32 v1, v35, s0
	global_store_short v[50:51], v1, off offset:64
	v_cvt_pk_bf16_f32 v1, v36, s0
	global_store_short v[68:69], v1, off offset:64
	v_cvt_pk_bf16_f32 v1, v37, s0
	global_store_short v[52:53], v1, off offset:64
	v_cvt_pk_bf16_f32 v1, v38, s0
	global_store_short v[70:71], v1, off offset:64
	v_cvt_pk_bf16_f32 v1, v39, s0
	global_store_short v[54:55], v1, off offset:64
	v_cvt_pk_bf16_f32 v1, v40, s0
	global_store_short v[72:73], v1, off offset:64
	v_cvt_pk_bf16_f32 v1, v41, s0
	global_store_short v[56:57], v1, off offset:64
	v_cvt_pk_bf16_f32 v1, v42, s0
	global_store_short v[74:75], v1, off offset:64
	v_cvt_pk_bf16_f32 v1, v43, s0
	global_store_short v[58:59], v1, off offset:64
	v_cvt_pk_bf16_f32 v1, v44, s0
	global_store_short v[76:77], v1, off offset:64
	v_cvt_pk_bf16_f32 v1, v45, s0
	global_store_short v[60:61], v1, off offset:64
	v_cvt_pk_bf16_f32 v1, v46, s0
	global_store_short v[78:79], v1, off offset:64
	v_cvt_pk_bf16_f32 v1, v47, s0
	global_store_short v[62:63], v1, off offset:64
	v_cvt_pk_bf16_f32 v1, v48, s0
	global_store_short v[80:81], v1, off offset:64
	v_cvt_pk_bf16_f32 v1, v49, s0
	global_store_short v[64:65], v1, off offset:64
	v_or_b32_e32 v1, 0x60, v130
	v_cvt_pk_bf16_f32 v18, v18, s0
	v_mad_i64_i32 v[34:35], s[0:1], v1, s67, v[152:153]
	v_or_b32_e32 v1, 0x61, v130
	global_store_short v[34:35], v18, off
	v_cvt_pk_bf16_f32 v36, v19, s0
	v_mad_i64_i32 v[18:19], s[0:1], v1, s67, v[152:153]
	v_or_b32_e32 v1, 0x62, v130
	global_store_short v[18:19], v36, off
	v_cvt_pk_bf16_f32 v20, v20, s0
	v_mad_i64_i32 v[36:37], s[0:1], v1, s67, v[152:153]
	v_or_b32_e32 v1, 0x63, v130
	global_store_short v[36:37], v20, off
	v_cvt_pk_bf16_f32 v38, v21, s0
	v_mad_i64_i32 v[20:21], s[0:1], v1, s67, v[152:153]
	v_or_b32_e32 v1, 0x68, v130
	global_store_short v[20:21], v38, off
	v_cvt_pk_bf16_f32 v22, v22, s0
	v_mad_i64_i32 v[38:39], s[0:1], v1, s67, v[152:153]
	v_or_b32_e32 v1, 0x69, v130
	global_store_short v[38:39], v22, off
	v_cvt_pk_bf16_f32 v40, v23, s0
	v_mad_i64_i32 v[22:23], s[0:1], v1, s67, v[152:153]
	v_or_b32_e32 v1, 0x6a, v130
	global_store_short v[22:23], v40, off
	v_cvt_pk_bf16_f32 v24, v24, s0
	v_mad_i64_i32 v[40:41], s[0:1], v1, s67, v[152:153]
	v_or_b32_e32 v1, 0x6b, v130
	global_store_short v[40:41], v24, off
	v_cvt_pk_bf16_f32 v42, v25, s0
	v_mad_i64_i32 v[24:25], s[0:1], v1, s67, v[152:153]
	v_or_b32_e32 v1, 0x70, v130
	global_store_short v[24:25], v42, off
	v_cvt_pk_bf16_f32 v26, v26, s0
	v_mad_i64_i32 v[42:43], s[0:1], v1, s67, v[152:153]
	v_or_b32_e32 v1, 0x71, v130
	global_store_short v[42:43], v26, off
	v_cvt_pk_bf16_f32 v44, v27, s0
	v_mad_i64_i32 v[26:27], s[0:1], v1, s67, v[152:153]
	v_or_b32_e32 v1, 0x72, v130
	global_store_short v[26:27], v44, off
	v_cvt_pk_bf16_f32 v28, v28, s0
	v_mad_i64_i32 v[44:45], s[0:1], v1, s67, v[152:153]
	v_or_b32_e32 v1, 0x73, v130
	global_store_short v[44:45], v28, off
	v_cvt_pk_bf16_f32 v46, v29, s0
	v_mad_i64_i32 v[28:29], s[0:1], v1, s67, v[152:153]
	v_or_b32_e32 v1, 0x78, v130
	global_store_short v[28:29], v46, off
	v_cvt_pk_bf16_f32 v30, v30, s0
	v_mad_i64_i32 v[46:47], s[0:1], v1, s67, v[152:153]
	v_or_b32_e32 v1, 0x79, v130
	global_store_short v[46:47], v30, off
	v_cvt_pk_bf16_f32 v48, v31, s0
	v_mad_i64_i32 v[30:31], s[0:1], v1, s67, v[152:153]
	v_or_b32_e32 v1, 0x7a, v130
	global_store_short v[30:31], v48, off
	v_cvt_pk_bf16_f32 v32, v32, s0
	v_mad_i64_i32 v[48:49], s[0:1], v1, s67, v[152:153]
	v_or_b32_e32 v1, 0x7b, v130
	global_store_short v[48:49], v32, off
	v_cvt_pk_bf16_f32 v50, v33, s0
	v_mad_i64_i32 v[32:33], s[0:1], v1, s67, v[152:153]
	global_store_short v[32:33], v50, off
	s_nop 0
	v_cvt_pk_bf16_f32 v1, v2, s0
	global_store_short v[34:35], v1, off offset:64
	v_cvt_pk_bf16_f32 v1, v3, s0
	global_store_short v[18:19], v1, off offset:64
	v_cvt_pk_bf16_f32 v1, v4, s0
	global_store_short v[36:37], v1, off offset:64
	v_cvt_pk_bf16_f32 v1, v5, s0
	global_store_short v[20:21], v1, off offset:64
	v_cvt_pk_bf16_f32 v1, v6, s0
	global_store_short v[38:39], v1, off offset:64
	v_cvt_pk_bf16_f32 v1, v7, s0
	global_store_short v[22:23], v1, off offset:64
	v_cvt_pk_bf16_f32 v1, v8, s0
	global_store_short v[40:41], v1, off offset:64
	v_cvt_pk_bf16_f32 v1, v9, s0
	global_store_short v[24:25], v1, off offset:64
	v_cvt_pk_bf16_f32 v1, v10, s0
	global_store_short v[42:43], v1, off offset:64
	v_cvt_pk_bf16_f32 v1, v11, s0
	global_store_short v[26:27], v1, off offset:64
	v_cvt_pk_bf16_f32 v1, v12, s0
	global_store_short v[44:45], v1, off offset:64
	v_cvt_pk_bf16_f32 v1, v13, s0
	global_store_short v[28:29], v1, off offset:64
	v_cvt_pk_bf16_f32 v1, v14, s0
	global_store_short v[46:47], v1, off offset:64
	v_cvt_pk_bf16_f32 v1, v15, s0
	global_store_short v[30:31], v1, off offset:64
	v_cvt_pk_bf16_f32 v1, v16, s0
	global_store_short v[48:49], v1, off offset:64
	v_cvt_pk_bf16_f32 v1, v17, s0
	global_store_short v[32:33], v1, off offset:64
	s_branch .LBB0_98

; DEV bf16_t f2bf(float f) { return (bf16_t)(cvtpk(f, 0.f) & 0xffffu); }
;   DEV void operator()(f32x16 (&acc)[2][2], int mb, int nb, int r32, int hh) const {
; #pragma unroll
;     for (int mi = 0; mi < 2; ++mi)
; #pragma unroll
;       for (int ni = 0; ni < 2; ++ni)
; #pragma unroll
;         for (int r = 0; r < 16; ++r) {
;           int row = mb + mi * 32 + 8 * (r >> 2) + 4 * hh + (r & 3);
;           C[(size_t)row * ldc + nb + ni * 32 + r32] = f2bf(acc[mi][ni][r]);
;         }
;   }
.LBB0_109:
	s_add_i32 s3, s3, s2
	s_or_b32 s2, s5, s4
	v_lshl_or_b32 v1, v133, 2, s3
	s_ashr_i32 s3, s2, 31
	s_lshl_b64 s[2:3], s[2:3], 1
	s_add_u32 s2, s24, s2
	s_addc_u32 s3, s25, s3
	v_lshlrev_b32_e32 v152, 1, v130
	v_mov_b32_e32 v153, v0
	v_lshl_add_u64 v[152:153], s[2:3], 0, v[152:153]
	v_cvt_pk_bf16_f32 v114, v114, s0
	v_mad_i64_i32 v[154:155], s[2:3], v1, s67, v[152:153]
	global_store_short v[154:155], v114, off
	v_or_b32_e32 v114, 1, v1
	v_cvt_pk_bf16_f32 v130, v115, s0
	v_mad_i64_i32 v[114:115], s[2:3], v114, s67, v[152:153]
	global_store_short v[114:115], v130, off
	v_or_b32_e32 v130, 2, v1
	v_cvt_pk_bf16_f32 v116, v116, s0
	v_mad_i64_i32 v[156:157], s[2:3], v130, s67, v[152:153]
	global_store_short v[156:157], v116, off
	v_or_b32_e32 v116, 3, v1
	v_cvt_pk_bf16_f32 v130, v117, s0
	v_mad_i64_i32 v[116:117], s[2:3], v116, s67, v[152:153]
	global_store_short v[116:117], v130, off
	v_or_b32_e32 v130, 8, v1
	v_cvt_pk_bf16_f32 v118, v118, s0
	v_mad_i64_i32 v[158:159], s[2:3], v130, s67, v[152:153]
	global_store_short v[158:159], v118, off
	v_or_b32_e32 v118, 9, v1
	v_cvt_pk_bf16_f32 v130, v119, s0
	v_mad_i64_i32 v[118:119], s[2:3], v118, s67, v[152:153]
	global_store_short v[118:119], v130, off
	v_or_b32_e32 v130, 10, v1
	v_cvt_pk_bf16_f32 v120, v120, s0
	v_mad_i64_i32 v[160:161], s[2:3], v130, s67, v[152:153]
	global_store_short v[160:161], v120, off
	v_or_b32_e32 v120, 11, v1
	v_cvt_pk_bf16_f32 v130, v121, s0
	v_mad_i64_i32 v[120:121], s[2:3], v120, s67, v[152:153]
	global_store_short v[120:121], v130, off
	v_or_b32_e32 v130, 16, v1
	v_cvt_pk_bf16_f32 v98, v98, s0
	v_cvt_pk_bf16_f32 v122, v122, s0
	v_mad_i64_i32 v[162:163], s[2:3], v130, s67, v[152:153]
	global_store_short v[154:155], v98, off offset:64
	v_cvt_pk_bf16_f32 v98, v99, s0
	global_store_short v[162:163], v122, off
	v_or_b32_e32 v122, 17, v1
	global_store_short v[114:115], v98, off offset:64
	v_cvt_pk_bf16_f32 v98, v100, s0
	v_cvt_pk_bf16_f32 v130, v123, s0
	v_mad_i64_i32 v[122:123], s[2:3], v122, s67, v[152:153]
	global_store_short v[156:157], v98, off offset:64
	v_cvt_pk_bf16_f32 v98, v101, s0
	global_store_short v[122:123], v130, off
	v_or_b32_e32 v130, 18, v1
	global_store_short v[116:117], v98, off offset:64
	v_cvt_pk_bf16_f32 v98, v102, s0
	v_cvt_pk_bf16_f32 v124, v124, s0
	v_mad_i64_i32 v[164:165], s[2:3], v130, s67, v[152:153]
	global_store_short v[158:159], v98, off offset:64
	v_cvt_pk_bf16_f32 v98, v103, s0
	global_store_short v[164:165], v124, off
	v_or_b32_e32 v124, 19, v1
	global_store_short v[118:119], v98, off offset:64
	v_cvt_pk_bf16_f32 v98, v104, s0
	v_cvt_pk_bf16_f32 v130, v125, s0
	v_mad_i64_i32 v[124:125], s[2:3], v124, s67, v[152:153]
	global_store_short v[160:161], v98, off offset:64
	v_cvt_pk_bf16_f32 v98, v105, s0
	global_store_short v[124:125], v130, off
	v_or_b32_e32 v130, 24, v1
	global_store_short v[120:121], v98, off offset:64
	v_cvt_pk_bf16_f32 v98, v106, s0
	v_cvt_pk_bf16_f32 v126, v126, s0
	v_mad_i64_i32 v[166:167], s[2:3], v130, s67, v[152:153]
	global_store_short v[162:163], v98, off offset:64
	v_cvt_pk_bf16_f32 v98, v107, s0
	global_store_short v[166:167], v126, off
	v_or_b32_e32 v126, 25, v1
	global_store_short v[122:123], v98, off offset:64
	v_cvt_pk_bf16_f32 v98, v108, s0
	v_cvt_pk_bf16_f32 v130, v127, s0
	v_mad_i64_i32 v[126:127], s[2:3], v126, s67, v[152:153]
	global_store_short v[164:165], v98, off offset:64
	v_cvt_pk_bf16_f32 v98, v109, s0
	global_store_short v[126:127], v130, off
	v_or_b32_e32 v130, 26, v1
	global_store_short v[124:125], v98, off offset:64
	v_cvt_pk_bf16_f32 v98, v110, s0
	v_cvt_pk_bf16_f32 v128, v128, s0
	v_mad_i64_i32 v[168:169], s[2:3], v130, s67, v[152:153]
	global_store_short v[166:167], v98, off offset:64
	v_cvt_pk_bf16_f32 v98, v111, s0
	global_store_short v[168:169], v128, off
	v_or_b32_e32 v128, 27, v1
	global_store_short v[126:127], v98, off offset:64
	v_cvt_pk_bf16_f32 v98, v112, s0
	v_cvt_pk_bf16_f32 v130, v129, s0
	v_mad_i64_i32 v[128:129], s[2:3], v128, s67, v[152:153]
	global_store_short v[168:169], v98, off offset:64
	v_cvt_pk_bf16_f32 v98, v113, s0
	global_store_short v[128:129], v98, off offset:64
	v_or_b32_e32 v98, 32, v1
	v_cvt_pk_bf16_f32 v82, v82, s0
	v_mad_i64_i32 v[98:99], s[2:3], v98, s67, v[152:153]
	global_store_short v[98:99], v82, off
	v_or_b32_e32 v82, 33, v1
	v_cvt_pk_bf16_f32 v100, v83, s0
	v_mad_i64_i32 v[82:83], s[2:3], v82, s67, v[152:153]
	global_store_short v[82:83], v100, off
	v_or_b32_e32 v100, 34, v1
	v_cvt_pk_bf16_f32 v84, v84, s0
	v_mad_i64_i32 v[100:101], s[2:3], v100, s67, v[152:153]
	global_store_short v[100:101], v84, off
	v_or_b32_e32 v84, 35, v1
	v_cvt_pk_bf16_f32 v102, v85, s0
	v_mad_i64_i32 v[84:85], s[2:3], v84, s67, v[152:153]
	global_store_short v[84:85], v102, off
	v_or_b32_e32 v102, 40, v1
	v_cvt_pk_bf16_f32 v86, v86, s0
	v_mad_i64_i32 v[102:103], s[2:3], v102, s67, v[152:153]
	global_store_short v[102:103], v86, off
	v_or_b32_e32 v86, 41, v1
	v_cvt_pk_bf16_f32 v104, v87, s0
	v_mad_i64_i32 v[86:87], s[2:3], v86, s67, v[152:153]
	global_store_short v[86:87], v104, off
	v_or_b32_e32 v104, 42, v1
	v_cvt_pk_bf16_f32 v88, v88, s0
	v_mad_i64_i32 v[104:105], s[2:3], v104, s67, v[152:153]
	global_store_short v[104:105], v88, off
	v_or_b32_e32 v88, 43, v1
	v_cvt_pk_bf16_f32 v106, v89, s0
	v_mad_i64_i32 v[88:89], s[2:3], v88, s67, v[152:153]
	global_store_short v[88:89], v106, off
	v_or_b32_e32 v106, 48, v1
	v_cvt_pk_bf16_f32 v66, v66, s0
	v_cvt_pk_bf16_f32 v90, v90, s0
	v_mad_i64_i32 v[106:107], s[2:3], v106, s67, v[152:153]
	global_store_short v[98:99], v66, off offset:64
	v_cvt_pk_bf16_f32 v66, v67, s0
	global_store_short v[106:107], v90, off
	v_or_b32_e32 v90, 49, v1
; DEV bf16_t f2bf(float f) { return (bf16_t)(cvtpk(f, 0.f) & 0xffffu); }
;   DEV void operator()(f32x16 (&acc)[2][2], int mb, int nb, int r32, int hh) const {
; #pragma unroll
;     for (int mi = 0; mi < 2; ++mi)
; #pragma unroll
;       for (int ni = 0; ni < 2; ++ni)
; #pragma unroll
;         for (int r = 0; r < 16; ++r) {
;           int row = mb + mi * 32 + 8 * (r >> 2) + 4 * hh + (r & 3);
;           C[(size_t)row * ldc + nb + ni * 32 + r32] = f2bf(acc[mi][ni][r]);
;         }
;   }
	global_store_short v[82:83], v66, off offset:64
	v_cvt_pk_bf16_f32 v66, v68, s0
	v_cvt_pk_bf16_f32 v108, v91, s0
	v_mad_i64_i32 v[90:91], s[2:3], v90, s67, v[152:153]
	global_store_short v[100:101], v66, off offset:64
	v_cvt_pk_bf16_f32 v66, v69, s0
	global_store_short v[90:91], v108, off
	v_or_b32_e32 v108, 50, v1
	global_store_short v[84:85], v66, off offset:64
	v_cvt_pk_bf16_f32 v66, v70, s0
	v_cvt_pk_bf16_f32 v92, v92, s0
	v_mad_i64_i32 v[108:109], s[2:3], v108, s67, v[152:153]
	global_store_short v[102:103], v66, off offset:64
	v_cvt_pk_bf16_f32 v66, v71, s0
	global_store_short v[108:109], v92, off
	v_or_b32_e32 v92, 51, v1
	global_store_short v[86:87], v66, off offset:64
	v_cvt_pk_bf16_f32 v66, v72, s0
	v_cvt_pk_bf16_f32 v110, v93, s0
	v_mad_i64_i32 v[92:93], s[2:3], v92, s67, v[152:153]
	global_store_short v[104:105], v66, off offset:64
	v_cvt_pk_bf16_f32 v66, v73, s0
	global_store_short v[92:93], v110, off
	v_or_b32_e32 v110, 56, v1
	global_store_short v[88:89], v66, off offset:64
	v_cvt_pk_bf16_f32 v66, v74, s0
	v_cvt_pk_bf16_f32 v94, v94, s0
	v_mad_i64_i32 v[110:111], s[2:3], v110, s67, v[152:153]
	global_store_short v[106:107], v66, off offset:64
	v_cvt_pk_bf16_f32 v66, v75, s0
	global_store_short v[110:111], v94, off
	v_or_b32_e32 v94, 57, v1
	global_store_short v[90:91], v66, off offset:64
	v_cvt_pk_bf16_f32 v66, v76, s0
	v_cvt_pk_bf16_f32 v112, v95, s0
	v_mad_i64_i32 v[94:95], s[2:3], v94, s67, v[152:153]
	global_store_short v[108:109], v66, off offset:64
	v_cvt_pk_bf16_f32 v66, v77, s0
	global_store_short v[94:95], v112, off
	v_or_b32_e32 v112, 58, v1
	global_store_short v[92:93], v66, off offset:64
	v_cvt_pk_bf16_f32 v66, v78, s0
	v_cvt_pk_bf16_f32 v96, v96, s0
	v_mad_i64_i32 v[112:113], s[2:3], v112, s67, v[152:153]
	global_store_short v[110:111], v66, off offset:64
	v_cvt_pk_bf16_f32 v66, v79, s0
	global_store_short v[112:113], v96, off
	v_or_b32_e32 v96, 59, v1
	global_store_short v[94:95], v66, off offset:64
	v_cvt_pk_bf16_f32 v66, v80, s0
	v_cvt_pk_bf16_f32 v114, v97, s0
	v_mad_i64_i32 v[96:97], s[2:3], v96, s67, v[152:153]
	global_store_short v[112:113], v66, off offset:64
	v_cvt_pk_bf16_f32 v66, v81, s0
	global_store_short v[96:97], v66, off offset:64
	v_or_b32_e32 v66, 64, v1
	v_cvt_pk_bf16_f32 v50, v50, s0
	v_mad_i64_i32 v[66:67], s[2:3], v66, s67, v[152:153]
	global_store_short v[66:67], v50, off
	v_or_b32_e32 v50, 0x41, v1
	v_cvt_pk_bf16_f32 v68, v51, s0
	v_mad_i64_i32 v[50:51], s[2:3], v50, s67, v[152:153]
	global_store_short v[50:51], v68, off
	v_or_b32_e32 v68, 0x42, v1
	v_cvt_pk_bf16_f32 v52, v52, s0
	v_mad_i64_i32 v[68:69], s[2:3], v68, s67, v[152:153]
	global_store_short v[68:69], v52, off
	v_or_b32_e32 v52, 0x43, v1
	v_cvt_pk_bf16_f32 v70, v53, s0
	v_mad_i64_i32 v[52:53], s[2:3], v52, s67, v[152:153]
	global_store_short v[52:53], v70, off
	v_or_b32_e32 v70, 0x48, v1
	v_cvt_pk_bf16_f32 v54, v54, s0
	v_mad_i64_i32 v[70:71], s[2:3], v70, s67, v[152:153]
	global_store_short v[70:71], v54, off
	v_or_b32_e32 v54, 0x49, v1
	v_cvt_pk_bf16_f32 v72, v55, s0
	v_mad_i64_i32 v[54:55], s[2:3], v54, s67, v[152:153]
	global_store_short v[54:55], v72, off
	v_or_b32_e32 v72, 0x4a, v1
	v_cvt_pk_bf16_f32 v56, v56, s0
	v_mad_i64_i32 v[72:73], s[2:3], v72, s67, v[152:153]
	global_store_short v[72:73], v56, off
	v_or_b32_e32 v56, 0x4b, v1
	v_cvt_pk_bf16_f32 v74, v57, s0
	v_mad_i64_i32 v[56:57], s[2:3], v56, s67, v[152:153]
	global_store_short v[56:57], v74, off
	v_or_b32_e32 v74, 0x50, v1
	v_cvt_pk_bf16_f32 v34, v34, s0
	v_cvt_pk_bf16_f32 v58, v58, s0
	v_mad_i64_i32 v[74:75], s[2:3], v74, s67, v[152:153]
	global_store_short v[66:67], v34, off offset:64
	v_cvt_pk_bf16_f32 v34, v35, s0
	global_store_short v[74:75], v58, off
	v_or_b32_e32 v58, 0x51, v1
	global_store_short v[50:51], v34, off offset:64
	v_cvt_pk_bf16_f32 v34, v36, s0
	v_cvt_pk_bf16_f32 v76, v59, s0
	v_mad_i64_i32 v[58:59], s[2:3], v58, s67, v[152:153]
	global_store_short v[68:69], v34, off offset:64
	v_cvt_pk_bf16_f32 v34, v37, s0
	global_store_short v[58:59], v76, off
	v_or_b32_e32 v76, 0x52, v1
	global_store_short v[52:53], v34, off offset:64
	v_cvt_pk_bf16_f32 v34, v38, s0
	v_cvt_pk_bf16_f32 v60, v60, s0
	v_mad_i64_i32 v[76:77], s[2:3], v76, s67, v[152:153]
	global_store_short v[70:71], v34, off offset:64
	v_cvt_pk_bf16_f32 v34, v39, s0
	global_store_short v[76:77], v60, off
	v_or_b32_e32 v60, 0x53, v1
	global_store_short v[54:55], v34, off offset:64
	v_cvt_pk_bf16_f32 v34, v40, s0
	v_cvt_pk_bf16_f32 v78, v61, s0
	v_mad_i64_i32 v[60:61], s[2:3], v60, s67, v[152:153]
	global_store_short v[72:73], v34, off offset:64
	v_cvt_pk_bf16_f32 v34, v41, s0
	global_store_short v[60:61], v78, off
	v_or_b32_e32 v78, 0x58, v1
	global_store_short v[56:57], v34, off offset:64
	v_cvt_pk_bf16_f32 v34, v42, s0
	v_cvt_pk_bf16_f32 v62, v62, s0
	v_mad_i64_i32 v[78:79], s[2:3], v78, s67, v[152:153]
	global_store_short v[74:75], v34, off offset:64
	v_cvt_pk_bf16_f32 v34, v43, s0
; DEV bf16_t f2bf(float f) { return (bf16_t)(cvtpk(f, 0.f) & 0xffffu); }
;   DEV void operator()(f32x16 (&acc)[2][2], int mb, int nb, int r32, int hh) const {
; #pragma unroll
;     for (int mi = 0; mi < 2; ++mi)
; #pragma unroll
;       for (int ni = 0; ni < 2; ++ni)
; #pragma unroll
;         for (int r = 0; r < 16; ++r) {
;           int row = mb + mi * 32 + 8 * (r >> 2) + 4 * hh + (r & 3);
;           C[(size_t)row * ldc + nb + ni * 32 + r32] = f2bf(acc[mi][ni][r]);
;         }
;   }
	global_store_short v[78:79], v62, off
	v_or_b32_e32 v62, 0x59, v1
	global_store_short v[58:59], v34, off offset:64
	v_cvt_pk_bf16_f32 v34, v44, s0
	v_cvt_pk_bf16_f32 v80, v63, s0
	v_mad_i64_i32 v[62:63], s[2:3], v62, s67, v[152:153]
	global_store_short v[76:77], v34, off offset:64
	v_cvt_pk_bf16_f32 v34, v45, s0
	global_store_short v[62:63], v80, off
	v_or_b32_e32 v80, 0x5a, v1
	global_store_short v[60:61], v34, off offset:64
	v_cvt_pk_bf16_f32 v34, v46, s0
	v_cvt_pk_bf16_f32 v64, v64, s0
	v_mad_i64_i32 v[80:81], s[2:3], v80, s67, v[152:153]
	global_store_short v[78:79], v34, off offset:64
	v_cvt_pk_bf16_f32 v34, v47, s0
	global_store_short v[80:81], v64, off
	v_or_b32_e32 v64, 0x5b, v1
	global_store_short v[62:63], v34, off offset:64
	v_cvt_pk_bf16_f32 v34, v48, s0
	v_cvt_pk_bf16_f32 v82, v65, s0
	v_mad_i64_i32 v[64:65], s[2:3], v64, s67, v[152:153]
	global_store_short v[80:81], v34, off offset:64
	v_cvt_pk_bf16_f32 v34, v49, s0
	global_store_short v[64:65], v34, off offset:64
	v_or_b32_e32 v34, 0x60, v1
	v_cvt_pk_bf16_f32 v18, v18, s0
	v_mad_i64_i32 v[34:35], s[2:3], v34, s67, v[152:153]
	global_store_short v[34:35], v18, off
	v_or_b32_e32 v18, 0x61, v1
	v_cvt_pk_bf16_f32 v36, v19, s0
	v_mad_i64_i32 v[18:19], s[2:3], v18, s67, v[152:153]
	global_store_short v[18:19], v36, off
	v_or_b32_e32 v36, 0x62, v1
	v_cvt_pk_bf16_f32 v20, v20, s0
	v_mad_i64_i32 v[36:37], s[2:3], v36, s67, v[152:153]
	global_store_short v[36:37], v20, off
	v_or_b32_e32 v20, 0x63, v1
	v_cvt_pk_bf16_f32 v38, v21, s0
	v_mad_i64_i32 v[20:21], s[2:3], v20, s67, v[152:153]
	global_store_short v[20:21], v38, off
	v_or_b32_e32 v38, 0x68, v1
	v_cvt_pk_bf16_f32 v22, v22, s0
	v_mad_i64_i32 v[38:39], s[2:3], v38, s67, v[152:153]
	global_store_short v[38:39], v22, off
	v_or_b32_e32 v22, 0x69, v1
	v_cvt_pk_bf16_f32 v40, v23, s0
	v_mad_i64_i32 v[22:23], s[2:3], v22, s67, v[152:153]
	global_store_short v[22:23], v40, off
	v_or_b32_e32 v40, 0x6a, v1
	v_cvt_pk_bf16_f32 v24, v24, s0
	v_mad_i64_i32 v[40:41], s[2:3], v40, s67, v[152:153]
	global_store_short v[40:41], v24, off
	v_or_b32_e32 v24, 0x6b, v1
	v_cvt_pk_bf16_f32 v42, v25, s0
	v_mad_i64_i32 v[24:25], s[2:3], v24, s67, v[152:153]
	global_store_short v[24:25], v42, off
	v_or_b32_e32 v42, 0x70, v1
	v_cvt_pk_bf16_f32 v26, v26, s0
	v_mad_i64_i32 v[42:43], s[2:3], v42, s67, v[152:153]
	global_store_short v[42:43], v26, off
	v_or_b32_e32 v26, 0x71, v1
	v_cvt_pk_bf16_f32 v44, v27, s0
	v_mad_i64_i32 v[26:27], s[2:3], v26, s67, v[152:153]
	global_store_short v[26:27], v44, off
	v_or_b32_e32 v44, 0x72, v1
	v_cvt_pk_bf16_f32 v28, v28, s0
	v_mad_i64_i32 v[44:45], s[2:3], v44, s67, v[152:153]
	global_store_short v[44:45], v28, off
	v_or_b32_e32 v28, 0x73, v1
	v_cvt_pk_bf16_f32 v46, v29, s0
	v_mad_i64_i32 v[28:29], s[2:3], v28, s67, v[152:153]
	global_store_short v[28:29], v46, off
	v_or_b32_e32 v46, 0x78, v1
	v_cvt_pk_bf16_f32 v30, v30, s0
	v_mad_i64_i32 v[46:47], s[2:3], v46, s67, v[152:153]
	global_store_short v[46:47], v30, off
	v_or_b32_e32 v30, 0x79, v1
	v_cvt_pk_bf16_f32 v48, v31, s0
	v_mad_i64_i32 v[30:31], s[2:3], v30, s67, v[152:153]
	global_store_short v[30:31], v48, off
	v_or_b32_e32 v48, 0x7a, v1
	v_cvt_pk_bf16_f32 v32, v32, s0
	v_mad_i64_i32 v[48:49], s[2:3], v48, s67, v[152:153]
	v_or_b32_e32 v1, 0x7b, v1
	global_store_short v[48:49], v32, off
	v_cvt_pk_bf16_f32 v50, v33, s0
	v_mad_i64_i32 v[32:33], s[2:3], v1, s67, v[152:153]
	v_cvt_pk_bf16_f32 v1, v2, s0
	global_store_short v[34:35], v1, off offset:64
	v_cvt_pk_bf16_f32 v1, v3, s0
	global_store_short v[18:19], v1, off offset:64
	v_cvt_pk_bf16_f32 v1, v4, s0
	global_store_short v[36:37], v1, off offset:64
	v_cvt_pk_bf16_f32 v1, v5, s0
	global_store_short v[20:21], v1, off offset:64
	v_cvt_pk_bf16_f32 v1, v6, s0
	global_store_short v[38:39], v1, off offset:64
	v_cvt_pk_bf16_f32 v1, v7, s0
	global_store_short v[22:23], v1, off offset:64
	v_cvt_pk_bf16_f32 v1, v8, s0
	global_store_short v[40:41], v1, off offset:64
	v_cvt_pk_bf16_f32 v1, v9, s0
	global_store_short v[24:25], v1, off offset:64
	v_cvt_pk_bf16_f32 v1, v10, s0
	global_store_short v[42:43], v1, off offset:64
	v_cvt_pk_bf16_f32 v1, v11, s0
	global_store_short v[26:27], v1, off offset:64
	v_cvt_pk_bf16_f32 v1, v12, s0
	global_store_short v[44:45], v1, off offset:64
	v_cvt_pk_bf16_f32 v1, v13, s0
	global_store_short v[28:29], v1, off offset:64
	v_cvt_pk_bf16_f32 v1, v14, s0
	global_store_short v[46:47], v1, off offset:64
	v_cvt_pk_bf16_f32 v1, v15, s0
	global_store_short v[30:31], v1, off offset:64
	v_cvt_pk_bf16_f32 v1, v16, s0
	global_store_short v[48:49], v1, off offset:64
	v_cvt_pk_bf16_f32 v1, v17, s0
	s_mov_b64 s[2:3], -1
	s_andn2_b64 vcc, exec, s[0:1]
	s_mov_b32 s6, s31
	s_mov_b32 s4, s53
	s_mov_b32 s5, s52
	global_store_short v[128:129], v130, off
	global_store_short v[96:97], v114, off
	global_store_short v[64:65], v82, off
	global_store_short v[32:33], v50, off
	global_store_short v[32:33], v1, off offset:64
	s_cbranch_vccz .LBB0_121

; DEV f32x16 mfma(bf16x8 a, bf16x8 b, f32x16 c) { return __builtin_amdgcn_mfma_f32_32x32x16_bf16(a, b, c, 0, 0, 0); }
;     ...
;   for (int kt = 0; kt < nk; ++kt) {
;     if (kt + 1 < nk) { if (MI == 4) asm volatile("s_waitcnt vmcnt(6)" ::: "memory"); else asm volatile("s_waitcnt vmcnt(4)" ::: "memory"); } else asm volatile("s_waitcnt vmcnt(0)" ::: "memory");
;     __builtin_amdgcn_s_barrier();
;     if (kt + 2 < nk) { int s2 = stg + 2; if (s2 >= 3) s2 -= 3; g2_issue<MI>(ag + (size_t)(kt + 2) * 32, bg + (size_t)(kt + 2) * 32, lda, ldb, voffa, voffb, lds + s2 * G2_STAGE, w); }
;     const unsigned so = (unsigned)(stg * G2_STAGE);
;     __builtin_amdgcn_s_setprio(1);
; #pragma unroll
;     for (int ks = 0; ks < 2; ++ks) {
;       const unsigned aa = (ks ? la1 : la0) + so, bb = (ks ? lb1 : lb0) + so;
;       bf16x8 fb0, fb1, fa0, fa1, fa2, fa3;
;       asm volatile("ds_read_b128 %0, %1" : "=v"(fb0) : "v"(bb));
;       asm volatile("ds_read_b128 %0, %1 offset:2048" : "=v"(fb1) : "v"(bb));
;       asm volatile("ds_read_b128 %0, %1" : "=v"(fa0) : "v"(aa));
;       asm volatile("ds_read_b128 %0, %1 offset:2048" : "=v"(fa1) : "v"(aa));
;       if constexpr (MI == 4) {
;         asm volatile("ds_read_b128 %0, %1 offset:4096" : "=v"(fa2) : "v"(aa));
;         asm volatile("ds_read_b128 %0, %1 offset:6144" : "=v"(fa3) : "v"(aa));
;         __builtin_amdgcn_sched_barrier(0);
;         asm volatile("s_waitcnt lgkmcnt(3)" : "+v"(fb0), "+v"(fb1), "+v"(fa0));
;         acc[0][0][0] = mfma(fa0, fb0, acc[0][0][0]); acc[0][0][1] = mfma(fa0, fb1, acc[0][0][1]); __builtin_amdgcn_sched_barrier(0);
;         asm volatile("s_waitcnt lgkmcnt(2)" : "+v"(fa1));
;         acc[0][1][0] = mfma(fa1, fb0, acc[0][1][0]); acc[0][1][1] = mfma(fa1, fb1, acc[0][1][1]); __builtin_amdgcn_sched_barrier(0);
;         asm volatile("s_waitcnt lgkmcnt(1)" : "+v"(fa2));
;         acc[MI / 2 - 1][0][0] = mfma(fa2, fb0, acc[MI / 2 - 1][0][0]); acc[MI / 2 - 1][0][1] = mfma(fa2, fb1, acc[MI / 2 - 1][0][1]); __builtin_amdgcn_sched_barrier(0);
;         asm volatile("s_waitcnt lgkmcnt(0)" : "+v"(fa3));
;         acc[MI / 2 - 1][1][0] = mfma(fa3, fb0, acc[MI / 2 - 1][1][0]); acc[MI / 2 - 1][1][1] = mfma(fa3, fb1, acc[MI / 2 - 1][1][1]); __builtin_amdgcn_sched_barrier(0);
;       } else {
;         __builtin_amdgcn_sched_barrier(0);
;         asm volatile("s_waitcnt lgkmcnt(1)" : "+v"(fb0), "+v"(fb1), "+v"(fa0));
.LBB0_122:
	s_cmp_gt_i32 s10, 0
	s_cselect_b32 s11, -1, 2
	s_add_i32 s11, s11, s10
	s_add_u32 s14, s0, s4
	s_addc_u32 s15, s1, s5
	s_mulk_i32 s11, 0x6000
	s_add_u32 s12, s14, 0x80
	s_addc_u32 s13, s15, 0
	s_add_i32 s16, s8, s11
	s_waitcnt vmcnt(4)
	s_barrier
	s_mov_b32 m0, s16
	s_nop 0
	global_load_lds_dwordx4 v70, s[12:13]
	s_add_u32 s12, s14, 0x10080
	s_addc_u32 s13, s15, 0
	s_add_i32 s14, s9, s11
	s_addk_i32 s11, 0x4000
	s_mov_b32 m0, s14
	s_nop 0
	global_load_lds_dwordx4 v70, s[12:13]
	s_add_u32 s14, s2, s4
	s_addc_u32 s15, s3, s5
	s_add_u32 s12, s14, 0x80
	s_addc_u32 s13, s15, 0
	s_add_i32 s16, s11, s8
	s_mov_b32 m0, s16
	s_nop 0
	global_load_lds_dwordx4 v70, s[12:13]
	s_add_u32 s12, s14, 0x10080
	s_addc_u32 s13, s15, 0
	s_add_i32 s11, s11, s9
	s_mov_b32 m0, s11
	s_nop 0
	global_load_lds_dwordx4 v70, s[12:13]
	s_mul_i32 s11, s10, 0x6000
	s_setprio 1
	v_add_u32_e32 v73, s11, v67
	v_add_u32_e32 v90, s11, v68
	v_add_u32_e32 v86, v73, v71
	v_add_u32_e32 v78, v90, v71
	ds_read_b128 v[74:77], v78
	ds_read_b128 v[78:81], v78 offset:2048
	ds_read_b128 v[82:85], v86
	ds_read_b128 v[86:89], v86 offset:2048
	s_nop 0
	s_waitcnt lgkmcnt(1)
	s_nop 0
	v_mfma_f32_32x32x16_bf16 v[34:49], v[82:85], v[74:77], v[34:49]
	v_mfma_f32_32x32x16_bf16 v[50:65], v[82:85], v[78:81], v[50:65]
	s_waitcnt lgkmcnt(0)
	s_nop 0
	v_mfma_f32_32x32x16_bf16 v[18:33], v[86:89], v[74:77], v[18:33]
	v_mfma_f32_32x32x16_bf16 v[2:17], v[86:89], v[78:81], v[2:17]
	v_add_u32_e32 v78, v90, v69
	v_add_u32_e32 v73, v73, v69
	ds_read_b128 v[74:77], v78
	ds_read_b128 v[78:81], v78 offset:2048
	ds_read_b128 v[82:85], v73
	ds_read_b128 v[86:89], v73 offset:2048
	s_nop 0
	s_waitcnt lgkmcnt(1)
	s_nop 0
	v_mfma_f32_32x32x16_bf16 v[34:49], v[82:85], v[74:77], v[34:49]
	v_mfma_f32_32x32x16_bf16 v[50:65], v[82:85], v[78:81], v[50:65]
	s_waitcnt lgkmcnt(0)
	s_nop 0
	v_mfma_f32_32x32x16_bf16 v[18:33], v[86:89], v[74:77], v[18:33]
	v_mfma_f32_32x32x16_bf16 v[2:17], v[86:89], v[78:81], v[2:17]
	s_setprio 0
	s_add_i32 s11, s10, 1
	s_cmp_lg_u32 s10, 2
	s_cselect_b32 s10, s11, 0
	s_add_u32 s4, s4, 64
	s_addc_u32 s5, s5, 0
	s_cmpk_lg_i32 s4, 0xf80
	s_cbranch_scc1 .LBB0_122
	s_waitcnt vmcnt(4)
	s_barrier
	s_setprio 1
	v_add_u32_e32 v70, 0xc000, v67
	v_or_b32_e32 v88, 0x10000, v72
	v_add_u32_e32 v84, v70, v71
	v_add_u32_e32 v76, v88, v71
	ds_read_b128 v[72:75], v76
	ds_read_b128 v[76:79], v76 offset:2048
	ds_read_b128 v[80:83], v84
	ds_read_b128 v[84:87], v84 offset:2048
	s_nop 0
	s_waitcnt lgkmcnt(1)
	s_nop 0
	v_mfma_f32_32x32x16_bf16 v[34:49], v[80:83], v[72:75], v[34:49]
	v_mfma_f32_32x32x16_bf16 v[50:65], v[80:83], v[76:79], v[50:65]
	s_waitcnt lgkmcnt(0)
	s_nop 0
	v_mfma_f32_32x32x16_bf16 v[18:33], v[84:87], v[72:75], v[18:33]
	v_mfma_f32_32x32x16_bf16 v[2:17], v[84:87], v[76:79], v[2:17]
	v_add_u32_e32 v76, v88, v69
	v_add_u32_e32 v70, v70, v69
	ds_read_b128 v[72:75], v76
	ds_read_b128 v[76:79], v76 offset:2048
	ds_read_b128 v[80:83], v70
	ds_read_b128 v[84:87], v70 offset:2048
	s_nop 0
	s_waitcnt lgkmcnt(1)
	s_nop 0
	v_mfma_f32_32x32x16_bf16 v[34:49], v[80:83], v[72:75], v[34:49]
	v_mfma_f32_32x32x16_bf16 v[50:65], v[80:83], v[76:79], v[50:65]
	s_waitcnt lgkmcnt(0)
	s_nop 0
	v_mfma_f32_32x32x16_bf16 v[18:33], v[84:87], v[72:75], v[18:33]
	v_mfma_f32_32x32x16_bf16 v[2:17], v[84:87], v[76:79], v[2:17]
	s_setprio 0
	s_waitcnt vmcnt(0)
	s_barrier
	s_setprio 1
	v_add_u32_e32 v82, v67, v71
	v_add_u32_e32 v74, v68, v71
	ds_read_b128 v[70:73], v74
	ds_read_b128 v[74:77], v74 offset:2048
	ds_read_b128 v[78:81], v82
	ds_read_b128 v[82:85], v82 offset:2048
	s_nop 0
	s_waitcnt lgkmcnt(1)
	s_nop 0
	v_mfma_f32_32x32x16_bf16 v[34:49], v[78:81], v[70:73], v[34:49]
	v_mfma_f32_32x32x16_bf16 v[50:65], v[78:81], v[74:77], v[50:65]
	s_waitcnt lgkmcnt(0)
	s_nop 0
	v_mfma_f32_32x32x16_bf16 v[18:33], v[82:85], v[70:73], v[18:33]
	v_mfma_f32_32x32x16_bf16 v[2:17], v[82:85], v[74:77], v[2:17]
	v_add_u32_e32 v72, v68, v69
	v_add_u32_e32 v67, v67, v69
	ds_read_b128 v[68:71], v72
	ds_read_b128 v[72:75], v72 offset:2048
	ds_read_b128 v[76:79], v67
	ds_read_b128 v[80:83], v67 offset:2048
	s_nop 0
	s_waitcnt lgkmcnt(1)
	s_nop 0
	v_mfma_f32_32x32x16_bf16 v[34:49], v[76:79], v[68:71], v[34:49]
	v_mfma_f32_32x32x16_bf16 v[50:65], v[76:79], v[72:75], v[50:65]
	s_waitcnt lgkmcnt(0)
	s_nop 0
	v_mfma_f32_32x32x16_bf16 v[18:33], v[80:83], v[68:71], v[18:33]
	v_mfma_f32_32x32x16_bf16 v[2:17], v[80:83], v[72:75], v[2:17]
	s_setprio 0
	v_readlane_b32 s0, v240, 59
	s_add_i32 s6, s6, s0
	v_readlane_b32 s0, v240, 60
	s_or_b32 s0, s7, s0
	s_lshl_b32 s0, s0, 1
	s_add_u32 s0, s24, s0
	v_lshl_or_b32 v84, v66, 2, s6
	s_addc_u32 s1, s25, 0
	v_lshlrev_b32_e32 v66, 1, v1
	v_mov_b32_e32 v67, v0
	v_lshl_add_u64 v[66:67], s[0:1], 0, v[66:67]
	v_cvt_pk_bf16_f32 v1, v34, s0
	v_mad_i64_i32 v[68:69], s[0:1], v84, s67, v[66:67]
	v_or_b32_e32 v34, 1, v84
	s_nop 0
	v_cvt_pk_bf16_f32 v85, v35, s0
	v_mad_i64_i32 v[34:35], s[0:1], v34, s67, v[66:67]
	v_or_b32_e32 v70, 2, v84
	s_nop 0
	v_cvt_pk_bf16_f32 v86, v36, s0
	v_mad_i64_i32 v[70:71], s[0:1], v70, s67, v[66:67]
	v_or_b32_e32 v36, 3, v84
	s_nop 0
	v_cvt_pk_bf16_f32 v87, v37, s0
	v_mad_i64_i32 v[36:37], s[0:1], v36, s67, v[66:67]
	v_or_b32_e32 v72, 8, v84
	s_nop 0
	v_cvt_pk_bf16_f32 v88, v38, s0
	v_mad_i64_i32 v[72:73], s[0:1], v72, s67, v[66:67]
	v_or_b32_e32 v38, 9, v84
	s_nop 0
	v_cvt_pk_bf16_f32 v89, v39, s0
	v_mad_i64_i32 v[38:39], s[0:1], v38, s67, v[66:67]
	v_or_b32_e32 v74, 10, v84
	s_nop 0
	v_cvt_pk_bf16_f32 v90, v40, s0
	v_mad_i64_i32 v[74:75], s[0:1], v74, s67, v[66:67]
	v_or_b32_e32 v40, 11, v84
	s_nop 0
	v_cvt_pk_bf16_f32 v91, v41, s0
	v_mad_i64_i32 v[40:41], s[0:1], v40, s67, v[66:67]
	v_or_b32_e32 v76, 16, v84
	s_nop 0
	v_cvt_pk_bf16_f32 v92, v42, s0
	v_mad_i64_i32 v[76:77], s[0:1], v76, s67, v[66:67]
	v_or_b32_e32 v42, 17, v84
	s_nop 0
	v_cvt_pk_bf16_f32 v93, v43, s0
	v_mad_i64_i32 v[42:43], s[0:1], v42, s67, v[66:67]
	v_or_b32_e32 v78, 18, v84
	s_nop 0
	v_cvt_pk_bf16_f32 v94, v44, s0
	v_mad_i64_i32 v[78:79], s[0:1], v78, s67, v[66:67]
	v_or_b32_e32 v44, 19, v84
	s_nop 0
	v_cvt_pk_bf16_f32 v95, v45, s0
	v_mad_i64_i32 v[44:45], s[0:1], v44, s67, v[66:67]
	v_or_b32_e32 v80, 24, v84
	s_nop 0
	v_cvt_pk_bf16_f32 v96, v46, s0
	v_mad_i64_i32 v[80:81], s[0:1], v80, s67, v[66:67]
	v_or_b32_e32 v46, 25, v84
	s_nop 0
	v_cvt_pk_bf16_f32 v97, v47, s0
	v_mad_i64_i32 v[46:47], s[0:1], v46, s67, v[66:67]
	v_or_b32_e32 v82, 26, v84
	s_nop 0
	v_cvt_pk_bf16_f32 v98, v48, s0
	v_mad_i64_i32 v[82:83], s[0:1], v82, s67, v[66:67]
	v_or_b32_e32 v48, 27, v84
	s_nop 0
	v_cvt_pk_bf16_f32 v99, v49, s0
	v_mad_i64_i32 v[48:49], s[0:1], v48, s67, v[66:67]
	s_waitcnt lgkmcnt(0)
; DEV bf16_t f2bf(float f) { return (bf16_t)(cvtpk(f, 0.f) & 0xffffu); }
;   DEV void operator()(f32x16 (&acc)[2][2], int mb, int nb, int r32, int hh) const {
; #pragma unroll
;     for (int mi = 0; mi < 2; ++mi)
; #pragma unroll
;       for (int ni = 0; ni < 2; ++ni)
; #pragma unroll
;         for (int r = 0; r < 16; ++r) {
;           int row = mb + mi * 32 + 8 * (r >> 2) + 4 * hh + (r & 3);
;           C[(size_t)row * ldc + nb + ni * 32 + r32] = f2bf(acc[mi][ni][r]);
;         }
;   }
	s_nop 0
	v_cvt_pk_bf16_f32 v100, v50, s0
	v_or_b32_e32 v50, 32, v84
	v_cvt_pk_bf16_f32 v101, v51, s0
	v_cvt_pk_bf16_f32 v102, v52, s0
	v_cvt_pk_bf16_f32 v103, v53, s0
	v_cvt_pk_bf16_f32 v104, v54, s0
	v_cvt_pk_bf16_f32 v105, v55, s0
	v_cvt_pk_bf16_f32 v106, v56, s0
	v_cvt_pk_bf16_f32 v107, v57, s0
	v_cvt_pk_bf16_f32 v108, v58, s0
	v_cvt_pk_bf16_f32 v109, v59, s0
	v_cvt_pk_bf16_f32 v110, v60, s0
	v_cvt_pk_bf16_f32 v111, v61, s0
	v_cvt_pk_bf16_f32 v112, v62, s0
	v_cvt_pk_bf16_f32 v113, v63, s0
	v_cvt_pk_bf16_f32 v114, v64, s0
	v_cvt_pk_bf16_f32 v115, v65, s0
	v_cvt_pk_bf16_f32 v116, v18, s0
	v_mad_i64_i32 v[50:51], s[0:1], v50, s67, v[66:67]
	v_or_b32_e32 v18, 33, v84
	s_nop 0
	v_cvt_pk_bf16_f32 v117, v19, s0
	v_mad_i64_i32 v[18:19], s[0:1], v18, s67, v[66:67]
	v_or_b32_e32 v52, 34, v84
	s_nop 0
	v_cvt_pk_bf16_f32 v118, v20, s0
	v_mad_i64_i32 v[52:53], s[0:1], v52, s67, v[66:67]
	v_or_b32_e32 v20, 35, v84
	s_nop 0
	v_cvt_pk_bf16_f32 v119, v21, s0
	v_mad_i64_i32 v[20:21], s[0:1], v20, s67, v[66:67]
	v_or_b32_e32 v54, 40, v84
	s_nop 0
	v_cvt_pk_bf16_f32 v120, v22, s0
	v_mad_i64_i32 v[54:55], s[0:1], v54, s67, v[66:67]
	v_or_b32_e32 v22, 41, v84
	s_nop 0
	v_cvt_pk_bf16_f32 v121, v23, s0
	v_mad_i64_i32 v[22:23], s[0:1], v22, s67, v[66:67]
	v_or_b32_e32 v56, 42, v84
	s_nop 0
	v_cvt_pk_bf16_f32 v122, v24, s0
	v_mad_i64_i32 v[56:57], s[0:1], v56, s67, v[66:67]
	v_or_b32_e32 v24, 43, v84
	s_nop 0
	v_cvt_pk_bf16_f32 v123, v25, s0
	v_mad_i64_i32 v[24:25], s[0:1], v24, s67, v[66:67]
	v_or_b32_e32 v58, 48, v84
	s_nop 0
	v_cvt_pk_bf16_f32 v124, v26, s0
	v_mad_i64_i32 v[58:59], s[0:1], v58, s67, v[66:67]
	v_or_b32_e32 v26, 49, v84
	s_nop 0
	v_cvt_pk_bf16_f32 v125, v27, s0
	v_mad_i64_i32 v[26:27], s[0:1], v26, s67, v[66:67]
	v_or_b32_e32 v60, 50, v84
	s_nop 0
	v_cvt_pk_bf16_f32 v126, v28, s0
	v_mad_i64_i32 v[60:61], s[0:1], v60, s67, v[66:67]
	v_or_b32_e32 v28, 51, v84
	s_nop 0
	v_cvt_pk_bf16_f32 v127, v29, s0
	v_mad_i64_i32 v[28:29], s[0:1], v28, s67, v[66:67]
	v_or_b32_e32 v62, 56, v84
	s_nop 0
	v_cvt_pk_bf16_f32 v128, v30, s0
	v_mad_i64_i32 v[62:63], s[0:1], v62, s67, v[66:67]
	v_or_b32_e32 v30, 57, v84
	s_nop 0
	v_cvt_pk_bf16_f32 v129, v31, s0
	v_mad_i64_i32 v[30:31], s[0:1], v30, s67, v[66:67]
	v_or_b32_e32 v64, 58, v84
	s_nop 0
	v_cvt_pk_bf16_f32 v130, v32, s0
	v_mad_i64_i32 v[64:65], s[0:1], v64, s67, v[66:67]
	v_or_b32_e32 v32, 59, v84
	s_nop 0
	v_cvt_pk_bf16_f32 v84, v33, s0
	v_mad_i64_i32 v[32:33], s[0:1], v32, s67, v[66:67]
	s_barrier
	s_nop 0
	v_cvt_pk_bf16_f32 v2, v2, s0
	v_cvt_pk_bf16_f32 v3, v3, s0
	v_cvt_pk_bf16_f32 v4, v4, s0
	v_cvt_pk_bf16_f32 v5, v5, s0
	v_cvt_pk_bf16_f32 v6, v6, s0
	v_cvt_pk_bf16_f32 v7, v7, s0
	v_cvt_pk_bf16_f32 v8, v8, s0
	v_cvt_pk_bf16_f32 v9, v9, s0
	v_cvt_pk_bf16_f32 v10, v10, s0
	v_cvt_pk_bf16_f32 v11, v11, s0
	v_cvt_pk_bf16_f32 v12, v12, s0
	v_cvt_pk_bf16_f32 v13, v13, s0
	v_cvt_pk_bf16_f32 v14, v14, s0
	v_cvt_pk_bf16_f32 v15, v15, s0
	v_cvt_pk_bf16_f32 v16, v16, s0
	v_cvt_pk_bf16_f32 v17, v17, s0
	global_store_short v[68:69], v1, off
	global_store_short v[34:35], v85, off
	global_store_short v[70:71], v86, off
	global_store_short v[36:37], v87, off
	global_store_short v[72:73], v88, off
	global_store_short v[38:39], v89, off
	global_store_short v[74:75], v90, off
	global_store_short v[40:41], v91, off
	global_store_short v[76:77], v92, off
	global_store_short v[42:43], v93, off
	global_store_short v[78:79], v94, off
	global_store_short v[44:45], v95, off
	global_store_short v[80:81], v96, off
	global_store_short v[46:47], v97, off
	global_store_short v[82:83], v98, off
	global_store_short v[48:49], v99, off
	global_store_short v[68:69], v100, off offset:64
	global_store_short v[34:35], v101, off offset:64
	global_store_short v[70:71], v102, off offset:64
	global_store_short v[36:37], v103, off offset:64
	global_store_short v[72:73], v104, off offset:64
	global_store_short v[38:39], v105, off offset:64
	global_store_short v[74:75], v106, off offset:64
	global_store_short v[40:41], v107, off offset:64
	global_store_short v[76:77], v108, off offset:64
	global_store_short v[42:43], v109, off offset:64
	global_store_short v[78:79], v110, off offset:64
	global_store_short v[44:45], v111, off offset:64
	global_store_short v[80:81], v112, off offset:64
	global_store_short v[46:47], v113, off offset:64
	global_store_short v[82:83], v114, off offset:64
	global_store_short v[48:49], v115, off offset:64
	global_store_short v[50:51], v116, off
	global_store_short v[18:19], v117, off
	global_store_short v[52:53], v118, off
	global_store_short v[20:21], v119, off
	global_store_short v[54:55], v120, off
	global_store_short v[22:23], v121, off
	global_store_short v[56:57], v122, off
	global_store_short v[24:25], v123, off
	global_store_short v[58:59], v124, off
	global_store_short v[26:27], v125, off
	global_store_short v[60:61], v126, off
	global_store_short v[28:29], v127, off
	global_store_short v[62:63], v128, off
	global_store_short v[30:31], v129, off
	global_store_short v[64:65], v130, off
	global_store_short v[32:33], v84, off
	global_store_short v[50:51], v2, off offset:64
	global_store_short v[18:19], v3, off offset:64
	global_store_short v[52:53], v4, off offset:64
	global_store_short v[20:21], v5, off offset:64
	global_store_short v[54:55], v6, off offset:64
	global_store_short v[22:23], v7, off offset:64
	global_store_short v[56:57], v8, off offset:64
	global_store_short v[24:25], v9, off offset:64
	global_store_short v[58:59], v10, off offset:64
	global_store_short v[26:27], v11, off offset:64
	global_store_short v[60:61], v12, off offset:64
	global_store_short v[28:29], v13, off offset:64
	global_store_short v[62:63], v14, off offset:64
	global_store_short v[30:31], v15, off offset:64
	global_store_short v[64:65], v16, off offset:64
	global_store_short v[32:33], v17, off offset:64

; DEV bf16_t f2bf(float f) { return (bf16_t)(cvtpk(f, 0.f) & 0xffffu); }
;   DEV void operator()(f32x16 (&acc)[2][2], int mb, int nb, int r32, int hh) const {
; #pragma unroll
;     for (int mi = 0; mi < 2; ++mi)
; #pragma unroll
;       for (int ni = 0; ni < 2; ++ni)
; #pragma unroll
;         for (int r = 0; r < 16; ++r) {
;           int row = mb + mi * 32 + 8 * (r >> 2) + 4 * hh + (r & 3);
;           C[(size_t)row * ldc + nb + ni * 32 + r32] = f2bf(acc[mi][ni][r]);
;         }
;   }
.LBB0_145:
	s_add_i32 s3, s3, s2
	s_or_b32 s2, s5, s4
	v_lshl_or_b32 v152, v133, 2, s3
	s_ashr_i32 s3, s2, 31
	s_lshl_b64 s[2:3], s[2:3], 1
	s_add_u32 s2, s52, s2
	s_addc_u32 s3, s53, s3
	v_lshlrev_b32_e32 v154, 1, v130
	v_mov_b32_e32 v155, v0
	v_ashrrev_i32_e32 v153, 31, v152
	v_lshl_add_u64 v[154:155], s[2:3], 0, v[154:155]
	v_lshlrev_b64 v[156:157], 12, v[152:153]
	v_cvt_pk_bf16_f32 v1, v114, s0
	v_lshl_add_u64 v[156:157], v[154:155], 0, v[156:157]
	v_or_b32_e32 v114, 1, v152
	global_store_short v[156:157], v1, off
	v_cvt_pk_bf16_f32 v1, v115, s0
	v_ashrrev_i32_e32 v115, 31, v114
	v_or_b32_e32 v158, 2, v152
	v_lshlrev_b64 v[114:115], 12, v[114:115]
	v_ashrrev_i32_e32 v159, 31, v158
	v_lshl_add_u64 v[114:115], v[154:155], 0, v[114:115]
	v_lshlrev_b64 v[158:159], 12, v[158:159]
	global_store_short v[114:115], v1, off
	v_cvt_pk_bf16_f32 v1, v116, s0
	v_lshl_add_u64 v[158:159], v[154:155], 0, v[158:159]
	v_or_b32_e32 v116, 3, v152
	global_store_short v[158:159], v1, off
	v_cvt_pk_bf16_f32 v1, v117, s0
	v_ashrrev_i32_e32 v117, 31, v116
	v_or_b32_e32 v160, 8, v152
	v_lshlrev_b64 v[116:117], 12, v[116:117]
	v_ashrrev_i32_e32 v161, 31, v160
	v_lshl_add_u64 v[116:117], v[154:155], 0, v[116:117]
	v_lshlrev_b64 v[160:161], 12, v[160:161]
	global_store_short v[116:117], v1, off
	v_cvt_pk_bf16_f32 v1, v118, s0
	v_lshl_add_u64 v[160:161], v[154:155], 0, v[160:161]
	v_or_b32_e32 v118, 9, v152
	global_store_short v[160:161], v1, off
	v_cvt_pk_bf16_f32 v1, v119, s0
	v_ashrrev_i32_e32 v119, 31, v118
	v_or_b32_e32 v162, 10, v152
	v_lshlrev_b64 v[118:119], 12, v[118:119]
	v_ashrrev_i32_e32 v163, 31, v162
	v_lshl_add_u64 v[118:119], v[154:155], 0, v[118:119]
	v_lshlrev_b64 v[162:163], 12, v[162:163]
	global_store_short v[118:119], v1, off
	v_cvt_pk_bf16_f32 v1, v120, s0
	v_lshl_add_u64 v[162:163], v[154:155], 0, v[162:163]
	v_or_b32_e32 v120, 11, v152
	global_store_short v[162:163], v1, off
	v_cvt_pk_bf16_f32 v1, v121, s0
	v_ashrrev_i32_e32 v121, 31, v120
	v_or_b32_e32 v164, 16, v152
	v_lshlrev_b64 v[120:121], 12, v[120:121]
	v_ashrrev_i32_e32 v165, 31, v164
	v_lshl_add_u64 v[120:121], v[154:155], 0, v[120:121]
	v_lshlrev_b64 v[164:165], 12, v[164:165]
	global_store_short v[120:121], v1, off
	v_cvt_pk_bf16_f32 v1, v122, s0
	v_lshl_add_u64 v[164:165], v[154:155], 0, v[164:165]
	v_or_b32_e32 v122, 17, v152
	global_store_short v[164:165], v1, off
	v_cvt_pk_bf16_f32 v1, v123, s0
	v_ashrrev_i32_e32 v123, 31, v122
	v_or_b32_e32 v166, 18, v152
	v_lshlrev_b64 v[122:123], 12, v[122:123]
	v_ashrrev_i32_e32 v167, 31, v166
	v_lshl_add_u64 v[122:123], v[154:155], 0, v[122:123]
	v_lshlrev_b64 v[166:167], 12, v[166:167]
	global_store_short v[122:123], v1, off
	v_cvt_pk_bf16_f32 v1, v124, s0
	v_lshl_add_u64 v[166:167], v[154:155], 0, v[166:167]
	v_or_b32_e32 v124, 19, v152
	global_store_short v[166:167], v1, off
	v_cvt_pk_bf16_f32 v1, v125, s0
	v_ashrrev_i32_e32 v125, 31, v124
	v_or_b32_e32 v168, 24, v152
	v_lshlrev_b64 v[124:125], 12, v[124:125]
	v_ashrrev_i32_e32 v169, 31, v168
	v_lshl_add_u64 v[124:125], v[154:155], 0, v[124:125]
	v_lshlrev_b64 v[168:169], 12, v[168:169]
	global_store_short v[124:125], v1, off
	v_cvt_pk_bf16_f32 v1, v126, s0
	v_lshl_add_u64 v[168:169], v[154:155], 0, v[168:169]
	v_or_b32_e32 v126, 25, v152
	global_store_short v[168:169], v1, off
	v_cvt_pk_bf16_f32 v1, v127, s0
	v_ashrrev_i32_e32 v127, 31, v126
	v_or_b32_e32 v170, 26, v152
	v_lshlrev_b64 v[126:127], 12, v[126:127]
	v_ashrrev_i32_e32 v171, 31, v170
	v_lshl_add_u64 v[126:127], v[154:155], 0, v[126:127]
	v_lshlrev_b64 v[170:171], 12, v[170:171]
	global_store_short v[126:127], v1, off
	v_cvt_pk_bf16_f32 v1, v128, s0
	v_lshl_add_u64 v[170:171], v[154:155], 0, v[170:171]
	v_or_b32_e32 v128, 27, v152
	global_store_short v[170:171], v1, off
	v_cvt_pk_bf16_f32 v1, v129, s0
	v_ashrrev_i32_e32 v129, 31, v128
	v_lshlrev_b64 v[128:129], 12, v[128:129]
	v_lshl_add_u64 v[128:129], v[154:155], 0, v[128:129]
	global_store_short v[128:129], v1, off
	v_cvt_pk_bf16_f32 v1, v98, s0
	global_store_short v[156:157], v1, off offset:64
	v_cvt_pk_bf16_f32 v1, v99, s0
	global_store_short v[114:115], v1, off offset:64
	v_cvt_pk_bf16_f32 v1, v100, s0
	global_store_short v[158:159], v1, off offset:64
	v_cvt_pk_bf16_f32 v1, v101, s0
	global_store_short v[116:117], v1, off offset:64
	v_cvt_pk_bf16_f32 v1, v102, s0
	global_store_short v[160:161], v1, off offset:64
	v_cvt_pk_bf16_f32 v1, v103, s0
	global_store_short v[118:119], v1, off offset:64
	v_cvt_pk_bf16_f32 v1, v104, s0
	global_store_short v[162:163], v1, off offset:64
	v_cvt_pk_bf16_f32 v1, v105, s0
	global_store_short v[120:121], v1, off offset:64
	v_cvt_pk_bf16_f32 v1, v106, s0
	global_store_short v[164:165], v1, off offset:64
	v_cvt_pk_bf16_f32 v1, v107, s0
	global_store_short v[122:123], v1, off offset:64
	v_cvt_pk_bf16_f32 v1, v108, s0
	global_store_short v[166:167], v1, off offset:64
	v_cvt_pk_bf16_f32 v1, v109, s0
	global_store_short v[124:125], v1, off offset:64
	v_cvt_pk_bf16_f32 v1, v110, s0
	global_store_short v[168:169], v1, off offset:64
	v_cvt_pk_bf16_f32 v1, v111, s0
	v_or_b32_e32 v98, 32, v152
	global_store_short v[126:127], v1, off offset:64
	v_cvt_pk_bf16_f32 v1, v112, s0
	v_ashrrev_i32_e32 v99, 31, v98
	global_store_short v[170:171], v1, off offset:64
	v_cvt_pk_bf16_f32 v1, v113, s0
	v_lshlrev_b64 v[98:99], 12, v[98:99]
	global_store_short v[128:129], v1, off offset:64
	v_cvt_pk_bf16_f32 v1, v82, s0
	v_lshl_add_u64 v[98:99], v[154:155], 0, v[98:99]
	v_or_b32_e32 v82, 33, v152
	global_store_short v[98:99], v1, off
	v_cvt_pk_bf16_f32 v1, v83, s0
	v_ashrrev_i32_e32 v83, 31, v82
	v_or_b32_e32 v100, 34, v152
	v_lshlrev_b64 v[82:83], 12, v[82:83]
; DEV bf16_t f2bf(float f) { return (bf16_t)(cvtpk(f, 0.f) & 0xffffu); }
;   DEV void operator()(f32x16 (&acc)[2][2], int mb, int nb, int r32, int hh) const {
; #pragma unroll
;     for (int mi = 0; mi < 2; ++mi)
; #pragma unroll
;       for (int ni = 0; ni < 2; ++ni)
; #pragma unroll
;         for (int r = 0; r < 16; ++r) {
;           int row = mb + mi * 32 + 8 * (r >> 2) + 4 * hh + (r & 3);
;           C[(size_t)row * ldc + nb + ni * 32 + r32] = f2bf(acc[mi][ni][r]);
;         }
;   }
	v_ashrrev_i32_e32 v101, 31, v100
	v_lshl_add_u64 v[82:83], v[154:155], 0, v[82:83]
	v_lshlrev_b64 v[100:101], 12, v[100:101]
	global_store_short v[82:83], v1, off
	v_cvt_pk_bf16_f32 v1, v84, s0
	v_lshl_add_u64 v[100:101], v[154:155], 0, v[100:101]
	v_or_b32_e32 v84, 35, v152
	global_store_short v[100:101], v1, off
	v_cvt_pk_bf16_f32 v1, v85, s0
	v_ashrrev_i32_e32 v85, 31, v84
	v_or_b32_e32 v102, 40, v152
	v_lshlrev_b64 v[84:85], 12, v[84:85]
	v_ashrrev_i32_e32 v103, 31, v102
	v_lshl_add_u64 v[84:85], v[154:155], 0, v[84:85]
	v_lshlrev_b64 v[102:103], 12, v[102:103]
	global_store_short v[84:85], v1, off
	v_cvt_pk_bf16_f32 v1, v86, s0
	v_lshl_add_u64 v[102:103], v[154:155], 0, v[102:103]
	v_or_b32_e32 v86, 41, v152
	global_store_short v[102:103], v1, off
	v_cvt_pk_bf16_f32 v1, v87, s0
	v_ashrrev_i32_e32 v87, 31, v86
	v_or_b32_e32 v104, 42, v152
	v_lshlrev_b64 v[86:87], 12, v[86:87]
	v_ashrrev_i32_e32 v105, 31, v104
	v_lshl_add_u64 v[86:87], v[154:155], 0, v[86:87]
	v_lshlrev_b64 v[104:105], 12, v[104:105]
	global_store_short v[86:87], v1, off
	v_cvt_pk_bf16_f32 v1, v88, s0
	v_lshl_add_u64 v[104:105], v[154:155], 0, v[104:105]
	v_or_b32_e32 v88, 43, v152
	global_store_short v[104:105], v1, off
	v_cvt_pk_bf16_f32 v1, v89, s0
	v_ashrrev_i32_e32 v89, 31, v88
	v_or_b32_e32 v106, 48, v152
	v_lshlrev_b64 v[88:89], 12, v[88:89]
	v_ashrrev_i32_e32 v107, 31, v106
	v_lshl_add_u64 v[88:89], v[154:155], 0, v[88:89]
	v_lshlrev_b64 v[106:107], 12, v[106:107]
	global_store_short v[88:89], v1, off
	v_cvt_pk_bf16_f32 v1, v90, s0
	v_lshl_add_u64 v[106:107], v[154:155], 0, v[106:107]
	v_or_b32_e32 v90, 49, v152
	global_store_short v[106:107], v1, off
	v_cvt_pk_bf16_f32 v1, v91, s0
	v_ashrrev_i32_e32 v91, 31, v90
	v_or_b32_e32 v108, 50, v152
	v_lshlrev_b64 v[90:91], 12, v[90:91]
	v_ashrrev_i32_e32 v109, 31, v108
	v_lshl_add_u64 v[90:91], v[154:155], 0, v[90:91]
	v_lshlrev_b64 v[108:109], 12, v[108:109]
	global_store_short v[90:91], v1, off
	v_cvt_pk_bf16_f32 v1, v92, s0
	v_lshl_add_u64 v[108:109], v[154:155], 0, v[108:109]
	v_or_b32_e32 v92, 51, v152
	global_store_short v[108:109], v1, off
	v_cvt_pk_bf16_f32 v1, v93, s0
	v_ashrrev_i32_e32 v93, 31, v92
	v_or_b32_e32 v110, 56, v152
	v_lshlrev_b64 v[92:93], 12, v[92:93]
	v_ashrrev_i32_e32 v111, 31, v110
	v_lshl_add_u64 v[92:93], v[154:155], 0, v[92:93]
	v_lshlrev_b64 v[110:111], 12, v[110:111]
	global_store_short v[92:93], v1, off
	v_cvt_pk_bf16_f32 v1, v94, s0
	v_lshl_add_u64 v[110:111], v[154:155], 0, v[110:111]
	v_or_b32_e32 v94, 57, v152
	global_store_short v[110:111], v1, off
	v_cvt_pk_bf16_f32 v1, v95, s0
	v_ashrrev_i32_e32 v95, 31, v94
	v_or_b32_e32 v112, 58, v152
	v_lshlrev_b64 v[94:95], 12, v[94:95]
	v_ashrrev_i32_e32 v113, 31, v112
	v_lshl_add_u64 v[94:95], v[154:155], 0, v[94:95]
	v_lshlrev_b64 v[112:113], 12, v[112:113]
	global_store_short v[94:95], v1, off
	v_cvt_pk_bf16_f32 v1, v96, s0
	v_lshl_add_u64 v[112:113], v[154:155], 0, v[112:113]
	v_or_b32_e32 v96, 59, v152
	global_store_short v[112:113], v1, off
	v_cvt_pk_bf16_f32 v1, v97, s0
	v_ashrrev_i32_e32 v97, 31, v96
	v_lshlrev_b64 v[96:97], 12, v[96:97]
	v_lshl_add_u64 v[96:97], v[154:155], 0, v[96:97]
	global_store_short v[96:97], v1, off
	v_cvt_pk_bf16_f32 v1, v66, s0
	global_store_short v[98:99], v1, off offset:64
	v_cvt_pk_bf16_f32 v1, v67, s0
	global_store_short v[82:83], v1, off offset:64
	v_cvt_pk_bf16_f32 v1, v68, s0
	global_store_short v[100:101], v1, off offset:64
	v_cvt_pk_bf16_f32 v1, v69, s0
	global_store_short v[84:85], v1, off offset:64
	v_cvt_pk_bf16_f32 v1, v70, s0
	global_store_short v[102:103], v1, off offset:64
	v_cvt_pk_bf16_f32 v1, v71, s0
	global_store_short v[86:87], v1, off offset:64
	v_cvt_pk_bf16_f32 v1, v72, s0
	global_store_short v[104:105], v1, off offset:64
	v_cvt_pk_bf16_f32 v1, v73, s0
	global_store_short v[88:89], v1, off offset:64
	v_cvt_pk_bf16_f32 v1, v74, s0
	global_store_short v[106:107], v1, off offset:64
	v_cvt_pk_bf16_f32 v1, v75, s0
	global_store_short v[90:91], v1, off offset:64
	v_cvt_pk_bf16_f32 v1, v76, s0
	global_store_short v[108:109], v1, off offset:64
	v_cvt_pk_bf16_f32 v1, v77, s0
	global_store_short v[92:93], v1, off offset:64
	v_cvt_pk_bf16_f32 v1, v78, s0
	global_store_short v[110:111], v1, off offset:64
	v_cvt_pk_bf16_f32 v1, v79, s0
	v_or_b32_e32 v66, 64, v152
	global_store_short v[94:95], v1, off offset:64
	v_cvt_pk_bf16_f32 v1, v80, s0
	v_ashrrev_i32_e32 v67, 31, v66
	global_store_short v[112:113], v1, off offset:64
	v_cvt_pk_bf16_f32 v1, v81, s0
	v_lshlrev_b64 v[66:67], 12, v[66:67]
	global_store_short v[96:97], v1, off offset:64
	v_cvt_pk_bf16_f32 v1, v50, s0
	v_lshl_add_u64 v[66:67], v[154:155], 0, v[66:67]
	v_or_b32_e32 v50, 0x41, v152
	global_store_short v[66:67], v1, off
	v_cvt_pk_bf16_f32 v1, v51, s0
	v_ashrrev_i32_e32 v51, 31, v50
	v_or_b32_e32 v68, 0x42, v152
	v_lshlrev_b64 v[50:51], 12, v[50:51]
	v_ashrrev_i32_e32 v69, 31, v68
	v_lshl_add_u64 v[50:51], v[154:155], 0, v[50:51]
	v_lshlrev_b64 v[68:69], 12, v[68:69]
	global_store_short v[50:51], v1, off
	v_cvt_pk_bf16_f32 v1, v52, s0
	v_lshl_add_u64 v[68:69], v[154:155], 0, v[68:69]
	v_or_b32_e32 v52, 0x43, v152
	global_store_short v[68:69], v1, off
	v_cvt_pk_bf16_f32 v1, v53, s0
	v_ashrrev_i32_e32 v53, 31, v52
	v_or_b32_e32 v70, 0x48, v152
	v_lshlrev_b64 v[52:53], 12, v[52:53]
	v_ashrrev_i32_e32 v71, 31, v70
	v_lshl_add_u64 v[52:53], v[154:155], 0, v[52:53]
	v_lshlrev_b64 v[70:71], 12, v[70:71]
	global_store_short v[52:53], v1, off
	v_cvt_pk_bf16_f32 v1, v54, s0
	v_lshl_add_u64 v[70:71], v[154:155], 0, v[70:71]
	v_or_b32_e32 v54, 0x49, v152
	global_store_short v[70:71], v1, off
	v_cvt_pk_bf16_f32 v1, v55, s0
	v_ashrrev_i32_e32 v55, 31, v54
; DEV bf16_t f2bf(float f) { return (bf16_t)(cvtpk(f, 0.f) & 0xffffu); }
;   DEV void operator()(f32x16 (&acc)[2][2], int mb, int nb, int r32, int hh) const {
; #pragma unroll
;     for (int mi = 0; mi < 2; ++mi)
; #pragma unroll
;       for (int ni = 0; ni < 2; ++ni)
; #pragma unroll
;         for (int r = 0; r < 16; ++r) {
;           int row = mb + mi * 32 + 8 * (r >> 2) + 4 * hh + (r & 3);
;           C[(size_t)row * ldc + nb + ni * 32 + r32] = f2bf(acc[mi][ni][r]);
;         }
;   }
	v_or_b32_e32 v72, 0x4a, v152
	v_lshlrev_b64 v[54:55], 12, v[54:55]
	v_ashrrev_i32_e32 v73, 31, v72
	v_lshl_add_u64 v[54:55], v[154:155], 0, v[54:55]
	v_lshlrev_b64 v[72:73], 12, v[72:73]
	global_store_short v[54:55], v1, off
	v_cvt_pk_bf16_f32 v1, v56, s0
	v_lshl_add_u64 v[72:73], v[154:155], 0, v[72:73]
	v_or_b32_e32 v56, 0x4b, v152
	global_store_short v[72:73], v1, off
	v_cvt_pk_bf16_f32 v1, v57, s0
	v_ashrrev_i32_e32 v57, 31, v56
	v_or_b32_e32 v74, 0x50, v152
	v_lshlrev_b64 v[56:57], 12, v[56:57]
	v_ashrrev_i32_e32 v75, 31, v74
	v_lshl_add_u64 v[56:57], v[154:155], 0, v[56:57]
	v_lshlrev_b64 v[74:75], 12, v[74:75]
	global_store_short v[56:57], v1, off
	v_cvt_pk_bf16_f32 v1, v58, s0
	v_lshl_add_u64 v[74:75], v[154:155], 0, v[74:75]
	v_or_b32_e32 v58, 0x51, v152
	global_store_short v[74:75], v1, off
	v_cvt_pk_bf16_f32 v1, v59, s0
	v_ashrrev_i32_e32 v59, 31, v58
	v_or_b32_e32 v76, 0x52, v152
	v_lshlrev_b64 v[58:59], 12, v[58:59]
	v_ashrrev_i32_e32 v77, 31, v76
	v_lshl_add_u64 v[58:59], v[154:155], 0, v[58:59]
	v_lshlrev_b64 v[76:77], 12, v[76:77]
	global_store_short v[58:59], v1, off
	v_cvt_pk_bf16_f32 v1, v60, s0
	v_lshl_add_u64 v[76:77], v[154:155], 0, v[76:77]
	v_or_b32_e32 v60, 0x53, v152
	global_store_short v[76:77], v1, off
	v_cvt_pk_bf16_f32 v1, v61, s0
	v_ashrrev_i32_e32 v61, 31, v60
	v_or_b32_e32 v78, 0x58, v152
	v_lshlrev_b64 v[60:61], 12, v[60:61]
	v_ashrrev_i32_e32 v79, 31, v78
	v_lshl_add_u64 v[60:61], v[154:155], 0, v[60:61]
	v_lshlrev_b64 v[78:79], 12, v[78:79]
	global_store_short v[60:61], v1, off
	v_cvt_pk_bf16_f32 v1, v62, s0
	v_lshl_add_u64 v[78:79], v[154:155], 0, v[78:79]
	v_or_b32_e32 v62, 0x59, v152
	global_store_short v[78:79], v1, off
	v_cvt_pk_bf16_f32 v1, v63, s0
	v_ashrrev_i32_e32 v63, 31, v62
	v_or_b32_e32 v80, 0x5a, v152
	v_lshlrev_b64 v[62:63], 12, v[62:63]
	v_ashrrev_i32_e32 v81, 31, v80
	v_lshl_add_u64 v[62:63], v[154:155], 0, v[62:63]
	v_lshlrev_b64 v[80:81], 12, v[80:81]
	global_store_short v[62:63], v1, off
	v_cvt_pk_bf16_f32 v1, v64, s0
	v_lshl_add_u64 v[80:81], v[154:155], 0, v[80:81]
	v_or_b32_e32 v64, 0x5b, v152
	global_store_short v[80:81], v1, off
	v_cvt_pk_bf16_f32 v1, v65, s0
	v_ashrrev_i32_e32 v65, 31, v64
	v_lshlrev_b64 v[64:65], 12, v[64:65]
	v_lshl_add_u64 v[64:65], v[154:155], 0, v[64:65]
	global_store_short v[64:65], v1, off
	v_cvt_pk_bf16_f32 v1, v34, s0
	global_store_short v[66:67], v1, off offset:64
	v_cvt_pk_bf16_f32 v1, v35, s0
	global_store_short v[50:51], v1, off offset:64
	v_cvt_pk_bf16_f32 v1, v36, s0
	global_store_short v[68:69], v1, off offset:64
	v_cvt_pk_bf16_f32 v1, v37, s0
	global_store_short v[52:53], v1, off offset:64
	v_cvt_pk_bf16_f32 v1, v38, s0
	global_store_short v[70:71], v1, off offset:64
	v_cvt_pk_bf16_f32 v1, v39, s0
	global_store_short v[54:55], v1, off offset:64
	v_cvt_pk_bf16_f32 v1, v40, s0
	global_store_short v[72:73], v1, off offset:64
	v_cvt_pk_bf16_f32 v1, v41, s0
	global_store_short v[56:57], v1, off offset:64
	v_cvt_pk_bf16_f32 v1, v42, s0
	global_store_short v[74:75], v1, off offset:64
	v_cvt_pk_bf16_f32 v1, v43, s0
	global_store_short v[58:59], v1, off offset:64
	v_cvt_pk_bf16_f32 v1, v44, s0
	global_store_short v[76:77], v1, off offset:64
	v_cvt_pk_bf16_f32 v1, v45, s0
	global_store_short v[60:61], v1, off offset:64
	v_cvt_pk_bf16_f32 v1, v46, s0
	global_store_short v[78:79], v1, off offset:64
	v_cvt_pk_bf16_f32 v1, v47, s0
	v_or_b32_e32 v34, 0x60, v152
	global_store_short v[62:63], v1, off offset:64
	v_cvt_pk_bf16_f32 v1, v48, s0
	v_ashrrev_i32_e32 v35, 31, v34
	global_store_short v[80:81], v1, off offset:64
	v_cvt_pk_bf16_f32 v1, v49, s0
	v_lshlrev_b64 v[34:35], 12, v[34:35]
	global_store_short v[64:65], v1, off offset:64
	v_cvt_pk_bf16_f32 v1, v18, s0
	v_lshl_add_u64 v[34:35], v[154:155], 0, v[34:35]
	v_or_b32_e32 v18, 0x61, v152
	global_store_short v[34:35], v1, off
	v_cvt_pk_bf16_f32 v1, v19, s0
	v_ashrrev_i32_e32 v19, 31, v18
	v_or_b32_e32 v36, 0x62, v152
	v_lshlrev_b64 v[18:19], 12, v[18:19]
	v_ashrrev_i32_e32 v37, 31, v36
	v_lshl_add_u64 v[18:19], v[154:155], 0, v[18:19]
	v_lshlrev_b64 v[36:37], 12, v[36:37]
	global_store_short v[18:19], v1, off
	v_cvt_pk_bf16_f32 v1, v20, s0
	v_lshl_add_u64 v[36:37], v[154:155], 0, v[36:37]
; DEV bf16_t f2bf(float f) { return (bf16_t)(cvtpk(f, 0.f) & 0xffffu); }
;   DEV void operator()(f32x16 (&acc)[2][2], int mb, int nb, int r32, int hh) const {
; #pragma unroll
;     for (int mi = 0; mi < 2; ++mi)
; #pragma unroll
;       for (int ni = 0; ni < 2; ++ni)
; #pragma unroll
;         for (int r = 0; r < 16; ++r) {
;           int row = mb + mi * 32 + 8 * (r >> 2) + 4 * hh + (r & 3);
;           C[(size_t)row * ldc + nb + ni * 32 + r32] = f2bf(acc[mi][ni][r]);
;         }
;   }
	v_or_b32_e32 v20, 0x63, v152
	global_store_short v[36:37], v1, off
	v_cvt_pk_bf16_f32 v1, v21, s0
	v_ashrrev_i32_e32 v21, 31, v20
	v_or_b32_e32 v38, 0x68, v152
	v_lshlrev_b64 v[20:21], 12, v[20:21]
	v_ashrrev_i32_e32 v39, 31, v38
	v_lshl_add_u64 v[20:21], v[154:155], 0, v[20:21]
	v_lshlrev_b64 v[38:39], 12, v[38:39]
	global_store_short v[20:21], v1, off
	v_cvt_pk_bf16_f32 v1, v22, s0
	v_lshl_add_u64 v[38:39], v[154:155], 0, v[38:39]
	v_or_b32_e32 v22, 0x69, v152
	global_store_short v[38:39], v1, off
	v_cvt_pk_bf16_f32 v1, v23, s0
	v_ashrrev_i32_e32 v23, 31, v22
	v_or_b32_e32 v40, 0x6a, v152
	v_lshlrev_b64 v[22:23], 12, v[22:23]
	v_ashrrev_i32_e32 v41, 31, v40
	v_lshl_add_u64 v[22:23], v[154:155], 0, v[22:23]
	v_lshlrev_b64 v[40:41], 12, v[40:41]
	global_store_short v[22:23], v1, off
	v_cvt_pk_bf16_f32 v1, v24, s0
	v_lshl_add_u64 v[40:41], v[154:155], 0, v[40:41]
	v_or_b32_e32 v24, 0x6b, v152
	global_store_short v[40:41], v1, off
	v_cvt_pk_bf16_f32 v1, v25, s0
	v_ashrrev_i32_e32 v25, 31, v24
	v_or_b32_e32 v42, 0x70, v152
	v_lshlrev_b64 v[24:25], 12, v[24:25]
	v_ashrrev_i32_e32 v43, 31, v42
	v_lshl_add_u64 v[24:25], v[154:155], 0, v[24:25]
	v_lshlrev_b64 v[42:43], 12, v[42:43]
	global_store_short v[24:25], v1, off
	v_cvt_pk_bf16_f32 v1, v26, s0
	v_lshl_add_u64 v[42:43], v[154:155], 0, v[42:43]
	v_or_b32_e32 v26, 0x71, v152
	global_store_short v[42:43], v1, off
	v_cvt_pk_bf16_f32 v1, v27, s0
	v_ashrrev_i32_e32 v27, 31, v26
	v_or_b32_e32 v44, 0x72, v152
	v_lshlrev_b64 v[26:27], 12, v[26:27]
	v_ashrrev_i32_e32 v45, 31, v44
	v_lshl_add_u64 v[26:27], v[154:155], 0, v[26:27]
	v_lshlrev_b64 v[44:45], 12, v[44:45]
	global_store_short v[26:27], v1, off
	v_cvt_pk_bf16_f32 v1, v28, s0
	v_lshl_add_u64 v[44:45], v[154:155], 0, v[44:45]
	v_or_b32_e32 v28, 0x73, v152
	global_store_short v[44:45], v1, off
	v_cvt_pk_bf16_f32 v1, v29, s0
	v_ashrrev_i32_e32 v29, 31, v28
	v_or_b32_e32 v46, 0x78, v152
	v_lshlrev_b64 v[28:29], 12, v[28:29]
	v_ashrrev_i32_e32 v47, 31, v46
	v_lshl_add_u64 v[28:29], v[154:155], 0, v[28:29]
	v_lshlrev_b64 v[46:47], 12, v[46:47]
	global_store_short v[28:29], v1, off
	v_cvt_pk_bf16_f32 v1, v30, s0
	v_lshl_add_u64 v[46:47], v[154:155], 0, v[46:47]
	v_or_b32_e32 v30, 0x79, v152
	global_store_short v[46:47], v1, off
	v_cvt_pk_bf16_f32 v1, v31, s0
	v_ashrrev_i32_e32 v31, 31, v30
	v_or_b32_e32 v48, 0x7a, v152
	v_lshlrev_b64 v[30:31], 12, v[30:31]
	v_ashrrev_i32_e32 v49, 31, v48
	v_lshl_add_u64 v[30:31], v[154:155], 0, v[30:31]
	v_lshlrev_b64 v[48:49], 12, v[48:49]
	global_store_short v[30:31], v1, off
	v_cvt_pk_bf16_f32 v1, v32, s0
	v_lshl_add_u64 v[48:49], v[154:155], 0, v[48:49]
	v_or_b32_e32 v32, 0x7b, v152
	global_store_short v[48:49], v1, off
	v_cvt_pk_bf16_f32 v1, v33, s0
	v_ashrrev_i32_e32 v33, 31, v32
	v_lshlrev_b64 v[32:33], 12, v[32:33]
	v_lshl_add_u64 v[32:33], v[154:155], 0, v[32:33]
	global_store_short v[32:33], v1, off
	v_cvt_pk_bf16_f32 v1, v2, s0
	global_store_short v[34:35], v1, off offset:64
	v_cvt_pk_bf16_f32 v1, v3, s0
	global_store_short v[18:19], v1, off offset:64
	v_cvt_pk_bf16_f32 v1, v4, s0
	global_store_short v[36:37], v1, off offset:64
	v_cvt_pk_bf16_f32 v1, v5, s0
	global_store_short v[20:21], v1, off offset:64
	v_cvt_pk_bf16_f32 v1, v6, s0
	global_store_short v[38:39], v1, off offset:64
	v_cvt_pk_bf16_f32 v1, v7, s0
	global_store_short v[22:23], v1, off offset:64
	v_cvt_pk_bf16_f32 v1, v8, s0
	global_store_short v[40:41], v1, off offset:64
	v_cvt_pk_bf16_f32 v1, v9, s0
	global_store_short v[24:25], v1, off offset:64
	v_cvt_pk_bf16_f32 v1, v10, s0
	global_store_short v[42:43], v1, off offset:64
	v_cvt_pk_bf16_f32 v1, v11, s0
	global_store_short v[26:27], v1, off offset:64
	v_cvt_pk_bf16_f32 v1, v12, s0
	global_store_short v[44:45], v1, off offset:64
	v_cvt_pk_bf16_f32 v1, v13, s0
	global_store_short v[28:29], v1, off offset:64
	v_cvt_pk_bf16_f32 v1, v14, s0
	global_store_short v[46:47], v1, off offset:64
	v_cvt_pk_bf16_f32 v1, v15, s0
	global_store_short v[30:31], v1, off offset:64
	v_cvt_pk_bf16_f32 v1, v16, s0
	global_store_short v[48:49], v1, off offset:64
	v_cvt_pk_bf16_f32 v1, v17, s0
	s_mov_b64 s[2:3], -1
	s_and_b64 vcc, exec, s[0:1]
	global_store_short v[32:33], v1, off offset:64
	s_cbranch_vccnz .LBB0_160

; DEV float rcpf(float x) { return __builtin_amdgcn_rcpf(x); }
; DEV void fs_init(FlashState& s) { s.o[0] = zero16(); s.o[1] = zero16(); s.o[2] = zero16(); s.o[3] = zero16(); s.m = -1e20f; s.l = 0.f; s.R = 0.f; }
; #define TOKQ ((size_t)b * SEQ + opq(qpos))
; DEV void nsa_acc_store(float* __restrict__ dst, const f32x16 (&o)[4], float scale, int hh, bool first) {
; #pragma unroll
;   for (int dt = 0; dt < 4; ++dt)
; #pragma unroll
;     for (int g = 0; g < 4; ++g) {
;       float4* q = (float4*)(dst + dt * 32 + 8 * g + 4 * hh);
;       float4 v = make_float4(o[dt][4 * g] * scale, o[dt][4 * g + 1] * scale, o[dt][4 * g + 2] * scale, o[dt][4 * g + 3] * scale);
;       if (!first) { float4 old = *q; v.x += old.x; v.y += old.y; v.z += old.z; v.w += old.w; }
;       *q = v;
;     }
; }
; DEV void nsa_item(const Params& p, int b, int tt, char* lds) {
;     ...
;     nsa_acc_store(NACC, s.o, GF[TOKQ * 16 + head * 3 + 1] * rcpf(s.l), hh, false);
;   }
;   {
;     FlashState s; fs_init(s);
;     int lo = t0 - 511; lo = lo < 0 ? 0 : lo;
.LBB0_302:
	v_mov_b32_e32 v2, v128
	v_mov_b32_e32 v153, v0
	v_ashrrev_i32_e32 v3, 31, v2
	v_lshl_add_u64 v[2:3], s[78:79], 0, v[2:3]
	v_lshlrev_b64 v[2:3], 11, v[2:3]
	v_lshl_add_u64 v[2:3], s[82:83], 0, v[2:3]
	v_lshl_add_u64 v[4:5], v[2:3], 0, v[152:153]
	v_mov_b32_e32 v2, v128
	v_lshlrev_b32_e32 v158, 2, v138
	v_ashrrev_i32_e32 v3, 31, v2
	v_lshl_add_u64 v[2:3], s[78:79], 0, v[2:3]
	v_lshlrev_b64 v[2:3], 6, v[2:3]
	v_lshl_add_u64 v[2:3], s[92:93], 0, v[2:3]
	v_mov_b32_e32 v159, v0
	v_lshl_add_u64 v[2:3], v[2:3], 0, v[158:159]
	v_mov_b32_e32 v155, v0
	flat_load_dword v1, v[2:3] offset:4
	v_lshl_add_u64 v[4:5], v[4:5], 0, v[154:155]
	flat_load_dwordx4 v[6:9], v[4:5]
	v_rcp_f32_e32 v2, v167
	s_max_i32 s4, s22, 0x1ff
	s_addk_i32 s4, 0xfe01
	s_lshr_b32 s4, s4, 6
	s_lshl_b64 s[4:5], -1, s4
	s_and_b64 s[2:3], s[4:5], s[2:3]
	s_cmp_eq_u64 s[2:3], 0
	s_waitcnt vmcnt(0) lgkmcnt(0)
	v_mul_f32_e32 v2, v2, v1
	v_pk_fma_f32 v[6:7], v[64:65], v[2:3], v[6:7] op_sel_hi:[1,0,1]
	v_pk_fma_f32 v[8:9], v[66:67], v[2:3], v[8:9] op_sel_hi:[1,0,1]
	flat_store_dwordx4 v[4:5], v[6:9]
	s_nop 1
	flat_load_dwordx4 v[6:9], v[4:5] offset:32
	flat_load_dwordx4 v[234:237], v[4:5] offset:64
	flat_load_dwordx4 v[242:245], v[4:5] offset:96
	flat_load_dwordx4 v[246:249], v[4:5] offset:128
	flat_load_dwordx4 v[250:253], v[4:5] offset:160
	s_waitcnt vmcnt(0) lgkmcnt(0)
	v_pk_fma_f32 v[6:7], v[68:69], v[2:3], v[6:7] op_sel_hi:[1,0,1]
	v_pk_fma_f32 v[8:9], v[70:71], v[2:3], v[8:9] op_sel_hi:[1,0,1]
	v_pk_fma_f32 v[234:235], v[72:73], v[2:3], v[234:235] op_sel_hi:[1,0,1]
	v_pk_fma_f32 v[236:237], v[74:75], v[2:3], v[236:237] op_sel_hi:[1,0,1]
	v_pk_fma_f32 v[242:243], v[76:77], v[2:3], v[242:243] op_sel_hi:[1,0,1]
	v_pk_fma_f32 v[244:245], v[78:79], v[2:3], v[244:245] op_sel_hi:[1,0,1]
	v_pk_fma_f32 v[246:247], v[48:49], v[2:3], v[246:247] op_sel_hi:[1,0,1]
	v_pk_fma_f32 v[248:249], v[50:51], v[2:3], v[248:249] op_sel_hi:[1,0,1]
	v_pk_fma_f32 v[250:251], v[52:53], v[2:3], v[250:251] op_sel_hi:[1,0,1]
	v_pk_fma_f32 v[252:253], v[54:55], v[2:3], v[252:253] op_sel_hi:[1,0,1]
	flat_store_dwordx4 v[4:5], v[6:9] offset:32
	flat_store_dwordx4 v[4:5], v[234:237] offset:64
	flat_store_dwordx4 v[4:5], v[242:245] offset:96
	flat_store_dwordx4 v[4:5], v[246:249] offset:128
	flat_store_dwordx4 v[4:5], v[250:253] offset:160
	s_nop 1
	flat_load_dwordx4 v[6:9], v[4:5] offset:192
	flat_load_dwordx4 v[234:237], v[4:5] offset:224
	flat_load_dwordx4 v[242:245], v[4:5] offset:256
	flat_load_dwordx4 v[246:249], v[4:5] offset:288
	flat_load_dwordx4 v[250:253], v[4:5] offset:320
	s_waitcnt vmcnt(0) lgkmcnt(0)
	v_pk_fma_f32 v[6:7], v[56:57], v[2:3], v[6:7] op_sel_hi:[1,0,1]
	v_pk_fma_f32 v[8:9], v[58:59], v[2:3], v[8:9] op_sel_hi:[1,0,1]
	v_pk_fma_f32 v[234:235], v[60:61], v[2:3], v[234:235] op_sel_hi:[1,0,1]
	v_pk_fma_f32 v[236:237], v[62:63], v[2:3], v[236:237] op_sel_hi:[1,0,1]
	v_pk_fma_f32 v[242:243], v[32:33], v[2:3], v[242:243] op_sel_hi:[1,0,1]
	v_pk_fma_f32 v[244:245], v[34:35], v[2:3], v[244:245] op_sel_hi:[1,0,1]
	v_pk_fma_f32 v[246:247], v[36:37], v[2:3], v[246:247] op_sel_hi:[1,0,1]
	v_pk_fma_f32 v[248:249], v[38:39], v[2:3], v[248:249] op_sel_hi:[1,0,1]
	v_pk_fma_f32 v[250:251], v[40:41], v[2:3], v[250:251] op_sel_hi:[1,0,1]
	v_pk_fma_f32 v[252:253], v[42:43], v[2:3], v[252:253] op_sel_hi:[1,0,1]
	flat_store_dwordx4 v[4:5], v[6:9] offset:192
	flat_store_dwordx4 v[4:5], v[234:237] offset:224
	flat_store_dwordx4 v[4:5], v[242:245] offset:256
	flat_store_dwordx4 v[4:5], v[246:249] offset:288
	flat_store_dwordx4 v[4:5], v[250:253] offset:320
	s_nop 1
	flat_load_dwordx4 v[6:9], v[4:5] offset:352
	flat_load_dwordx4 v[234:237], v[4:5] offset:384
	flat_load_dwordx4 v[242:245], v[4:5] offset:416
	flat_load_dwordx4 v[246:249], v[4:5] offset:448
	flat_load_dwordx4 v[250:253], v[4:5] offset:480
	s_waitcnt vmcnt(0) lgkmcnt(0)
	v_pk_fma_f32 v[6:7], v[44:45], v[2:3], v[6:7] op_sel_hi:[1,0,1]
	v_pk_fma_f32 v[8:9], v[46:47], v[2:3], v[8:9] op_sel_hi:[1,0,1]
	v_pk_fma_f32 v[234:235], v[16:17], v[2:3], v[234:235] op_sel_hi:[1,0,1]
	v_pk_fma_f32 v[236:237], v[18:19], v[2:3], v[236:237] op_sel_hi:[1,0,1]
	v_pk_fma_f32 v[242:243], v[20:21], v[2:3], v[242:243] op_sel_hi:[1,0,1]
	v_pk_fma_f32 v[244:245], v[22:23], v[2:3], v[244:245] op_sel_hi:[1,0,1]
	v_pk_fma_f32 v[246:247], v[24:25], v[2:3], v[246:247] op_sel_hi:[1,0,1]
	v_pk_fma_f32 v[248:249], v[26:27], v[2:3], v[248:249] op_sel_hi:[1,0,1]
	v_pk_fma_f32 v[250:251], v[28:29], v[2:3], v[250:251] op_sel_hi:[1,0,1]
	v_pk_fma_f32 v[252:253], v[30:31], v[2:3], v[252:253] op_sel_hi:[1,0,1]
	flat_store_dwordx4 v[4:5], v[6:9] offset:352
	flat_store_dwordx4 v[4:5], v[234:237] offset:384
	flat_store_dwordx4 v[4:5], v[242:245] offset:416
	flat_store_dwordx4 v[4:5], v[246:249] offset:448
	flat_store_dwordx4 v[4:5], v[250:253] offset:480
	s_cbranch_scc1 .LBB0_325
; DEV void fs_init(FlashState& s) { s.o[0] = zero16(); s.o[1] = zero16(); s.o[2] = zero16(); s.o[3] = zero16(); s.m = -1e20f; s.l = 0.f; s.R = 0.f; }
; template <int DQK, bool FOX>
; DEV void kv_dma(const bf16_t* __restrict__ Kg, int ldk, const bf16_t* __restrict__ Vtg, int ldv, const float* __restrict__ cumk,
;                 int key0, char* st, int w, int lane) {
;   const unsigned base = (unsigned)(size_t)st;
;   const bf16_t* kb = uni_ptr(Kg + (size_t)key0 * ldk);
;   const bf16_t* vb = uni_ptr(Vtg + key0);
;   if (DQK == 128) {
;     const int r0 = w * 16 + (lane >> 4);
;     const unsigned rowoff = (unsigned)r0 * (unsigned)ldk * 2u;
;     const unsigned pz0 = (unsigned)((lane & 15) ^ (lane >> 4));
; #pragma unroll
;     for (int c = 0; c < 4; ++c)
;       dma16s(kb + (size_t)(4 * c) * ldk, rowoff + ((pz0 ^ (unsigned)(4 * c)) << 4), __builtin_amdgcn_readfirstlane(base + (w * 4 + c) * 1024));
;   } else {
;     const int r0 = w * 16 + (lane >> 3);
; #pragma unroll
;     for (int c = 0; c < 2; ++c) {
;       const int row = r0 + 8 * c;
;       dma16s(kb, (unsigned)row * (unsigned)ldk * 2u + (unsigned)((((lane & 7) ^ ((row >> 1) & 7))) << 4), __builtin_amdgcn_readfirstlane(base + (w * 2 + c) * 1024));
;     }
;   }
;   {
;     const int d0 = w * 32 + (lane >> 3);
; #pragma unroll
;     for (int c = 0; c < 4; ++c) {
;       const int d = d0 + 8 * c;
;       dma16s(vb, (unsigned)d * (unsigned)ldv * 2u + (unsigned)((((lane & 7) ^ ((d >> 1) & 7))) << 4), __builtin_amdgcn_readfirstlane(base + 16384 + (w * 4 + c) * 1024));
;     }
;   }
;   if (FOX) { if (w == 0 && lane < 16) dma16s(uni_ptr(cumk + key0), (unsigned)lane * 16u, __builtin_amdgcn_readfirstlane(base + 32768)); }
; }
; DEV void nsa_item(const Params& p, int b, int tt, char* lds) {
;     ...
;     FlashState s; fs_init(s);
;     int lo = t0 - 511; lo = lo < 0 ? 0 : lo;
;     ...
;     flash_loop<M_WIN, 128>(s, nullptr, qf, Kb + PR_KW, PR_LD, VT + (size_t)(b * 14 + 1) * 128 * 4096, 4096,
;                            tile_range(lo >> 6, (t0 + 31) >> 6), qpos, wq0, wq0 + 7, 0.f, nullptr, 0ull, c2, 0.f, lds);
	v_mov_b32_e32 v1, v192
	s_add_u32 s14, s23, 0x100000
	s_addc_u32 s15, s25, 0
	v_readfirstlane_b32 s4, v1
	s_ashr_i32 s7, s4, 6
	s_add_u32 s4, s2, -1
	s_ff1_i32_b64 s6, s[2:3]
	s_addc_u32 s5, s3, -1
	s_and_b64 s[2:3], s[4:5], s[2:3]
	s_mul_i32 s4, s6, 0x88000
	s_add_u32 s4, s20, s4
	s_addc_u32 s5, s21, 0
	s_add_u32 s4, s4, 0x900
	s_addc_u32 s5, s5, 0
	s_lshl_b32 s8, s6, 7
	s_add_u32 s8, s14, s8
	v_bfe_u32 v5, v1, 4, 2
	s_addc_u32 s9, s15, 0
	v_lshl_or_b32 v6, s7, 4, v5
	v_bitop3_b32 v5, v5, v1, 15 bitop3:0x78
	s_lshl_b32 s16, s7, 12
	v_mul_lo_u32 v6, v6, s35
	v_lshlrev_b32_e32 v5, 4, v5
	s_add_u32 s10, s4, 0x8800
	v_or_b32_e32 v138, v6, v5
	s_mov_b32 m0, s16
	s_nop 0
	global_load_lds_dwordx4 v138, s[4:5]
	s_addc_u32 s11, s5, 0
	s_add_i32 s12, s16, 0x400
	v_bitop3_b32 v141, v6, 64, v5 bitop3:0x36
	s_mov_b32 m0, s12
	s_nop 0
	global_load_lds_dwordx4 v141, s[10:11]
	s_add_u32 s10, s4, 0x11000
	s_movk_i32 s12, 0x80
	s_addc_u32 s11, s5, 0
	v_bitop3_b32 v143, v6, s12, v5 bitop3:0x36
	s_add_i32 s12, s16, 0x800
	s_add_u32 s4, s4, 0x19800
	s_mov_b32 m0, s12
	s_nop 0
	global_load_lds_dwordx4 v143, s[10:11]
	s_addc_u32 s5, s5, 0
	s_movk_i32 s10, 0xc0
	v_and_b32_e32 v2, 63, v1
	v_bitop3_b32 v145, v6, s10, v5 bitop3:0x36
	s_add_i32 s10, s16, 0xc00
	s_mov_b32 m0, s10
	s_nop 0
	global_load_lds_dwordx4 v145, s[4:5]
	v_bfe_u32 v5, v1, 3, 3
	v_lshlrev_b32_e32 v6, 4, v1
	s_movk_i32 s5, 0x70
	v_lshl_or_b32 v5, s7, 5, v5
	v_bitop3_b32 v2, v6, s5, v2 bitop3:0x48
	v_lshl_or_b32 v147, v5, 13, v2
	v_or_b32_e32 v2, 8, v5
	v_lshlrev_b32_e32 v6, 13, v2
	v_lshrrev_b32_e32 v2, 1, v2
	v_xor_b32_e32 v2, v2, v1
	v_lshlrev_b32_e32 v2, 4, v2
	v_and_or_b32 v149, v2, s5, v6
	v_or_b32_e32 v2, 24, v5
	v_lshlrev_b32_e32 v5, 13, v2
	v_lshrrev_b32_e32 v2, 1, v2
	v_xor_b32_e32 v2, v2, v1
	v_lshlrev_b32_e32 v2, 4, v2
	v_and_b32_e32 v3, 31, v1
	v_bfe_u32 v4, v1, 5, 1
	v_and_or_b32 v155, v2, s5, v5
	v_and_b32_e32 v2, 19, v1
	v_lshlrev_b32_e32 v5, 1, v1
	v_bfe_u32 v1, v1, 1, 4
	v_and_b32_e32 v5, 8, v5
	v_and_b32_e32 v6, 4, v1
	v_or3_b32 v2, v5, v2, v6
	v_bitop3_b32 v5, v2, v4, 15 bitop3:0x6c
	v_lshlrev_b32_e32 v164, 4, v5
	v_or_b32_e32 v5, 2, v4
	v_bitop3_b32 v5, v2, v5, 15 bitop3:0x6c
	v_lshlrev_b32_e32 v165, 4, v5
	v_or_b32_e32 v5, 4, v4
	v_bitop3_b32 v5, v2, v5, 15 bitop3:0x6c
	v_lshlrev_b32_e32 v166, 4, v5
	v_or_b32_e32 v5, 6, v4
	v_bitop3_b32 v5, v2, v5, 15 bitop3:0x6c
	v_lshlrev_b32_e32 v168, 4, v5
	v_or_b32_e32 v5, 8, v4
	v_bitop3_b32 v5, v2, v5, 15 bitop3:0x6c
	v_lshlrev_b32_e32 v169, 4, v5
	v_or_b32_e32 v5, 10, v4
	v_bitop3_b32 v5, v2, v5, 15 bitop3:0x6c
	v_lshlrev_b32_e32 v170, 4, v5
	v_or_b32_e32 v5, 12, v4
	v_bitop3_b32 v5, v2, v5, 15 bitop3:0x6c
	v_lshlrev_b32_e32 v171, 4, v5
	v_or_b32_e32 v5, 14, v4
	v_lshlrev_b32_e32 v159, 8, v2
	v_bitop3_b32 v2, v2, v5, 15 bitop3:0x6c
	v_lshlrev_b32_e32 v172, 4, v2
	v_bfe_u32 v2, v3, 1, 3
	v_bitop3_b32 v1, v1, v4, 7 bitop3:0x6c
	s_add_i32 s4, s16, 0x4000
	s_mov_b32 m0, s4
	s_nop 0
	global_load_lds_dwordx4 v147, s[8:9]
	v_lshlrev_b32_e32 v177, 4, v1
	v_bitop3_b32 v1, v4, v2, 2 bitop3:0x36
	s_add_i32 s4, s16, 0x4400
	s_mov_b32 m0, s4
	s_nop 0
	global_load_lds_dwordx4 v149, s[8:9]
	v_lshlrev_b32_e32 v178, 4, v1
	v_bitop3_b32 v1, v4, v2, 4 bitop3:0x36
	v_or_b32_e32 v153, 0x20000, v147
	s_add_i32 s4, s16, 0x4800
	s_mov_b32 m0, s4
	s_nop 0
	global_load_lds_dwordx4 v153, s[8:9]
	v_lshlrev_b32_e32 v179, 4, v1
	v_bitop3_b32 v1, v4, v2, 6 bitop3:0x36
	v_cmp_lt_i32_e32 vcc, v203, v202
	s_add_i32 s4, s16, 0x4c00
	s_mov_b32 m0, s4
	s_nop 0
	global_load_lds_dwordx4 v155, s[8:9]
	v_lshlrev_b32_e32 v180, 4, v1
	v_cndmask_b32_e32 v1, v200, v203, vcc
	v_mov_b32_e32 v14, v0
	v_mov_b32_e32 v15, v0
	v_lshlrev_b32_e32 v174, 3, v4
	v_lshlrev_b32_e32 v176, 7, v3
	v_lshlrev_b32_e32 v181, 2, v1
	v_mov_b32_e32 v1, v0
	v_mov_b32_e32 v2, v0
	v_mov_b32_e32 v3, v0
	v_mov_b32_e32 v4, v0
	v_mov_b32_e32 v5, v0
	v_mov_b32_e32 v6, v0
	v_mov_b32_e32 v7, v0
	v_mov_b32_e32 v8, v0
	v_mov_b32_e32 v9, v0
	v_mov_b32_e32 v10, v0
	v_mov_b32_e32 v11, v0
	v_mov_b32_e32 v12, v0
	v_mov_b32_e32 v13, v0
	v_mov_b64_e32 v[30:31], v[14:15]
	v_mov_b64_e32 v[46:47], v[14:15]
	v_mov_b64_e32 v[62:63], v[14:15]
	v_mov_b64_e32 v[78:79], v[14:15]
	v_add_u32_e32 v157, 0xfffffe00, v129
	v_add_u32_e32 v173, 0xfffffe07, v129
	v_add_u32_e32 v175, 0xfffffe00, v128
	s_mov_b32 s17, 0
	v_mov_b32_e32 v182, 0xe0ad78ec
	v_mov_b32_e32 v167, 0
	v_mov_b64_e32 v[28:29], v[12:13]
	v_mov_b64_e32 v[26:27], v[10:11]
	v_mov_b64_e32 v[24:25], v[8:9]
	v_mov_b64_e32 v[22:23], v[6:7]
	v_mov_b64_e32 v[20:21], v[4:5]
	v_mov_b64_e32 v[18:19], v[2:3]
	v_mov_b64_e32 v[16:17], v[0:1]
	v_mov_b64_e32 v[44:45], v[12:13]
	v_mov_b64_e32 v[42:43], v[10:11]
	v_mov_b64_e32 v[40:41], v[8:9]
	v_mov_b64_e32 v[38:39], v[6:7]
	v_mov_b64_e32 v[36:37], v[4:5]
	v_mov_b64_e32 v[34:35], v[2:3]
	v_mov_b64_e32 v[32:33], v[0:1]
	v_mov_b64_e32 v[60:61], v[12:13]
	v_mov_b64_e32 v[58:59], v[10:11]
	v_mov_b64_e32 v[56:57], v[8:9]
	v_mov_b64_e32 v[54:55], v[6:7]
	v_mov_b64_e32 v[52:53], v[4:5]
	v_mov_b64_e32 v[50:51], v[2:3]
	v_mov_b64_e32 v[48:49], v[0:1]
	v_mov_b64_e32 v[76:77], v[12:13]
	v_mov_b64_e32 v[74:75], v[10:11]
	v_mov_b64_e32 v[72:73], v[8:9]
	v_mov_b64_e32 v[70:71], v[6:7]
	v_mov_b64_e32 v[68:69], v[4:5]
	v_mov_b64_e32 v[66:67], v[2:3]
	v_mov_b64_e32 v[64:65], v[0:1]

; DEV float rcpf(float x) { return __builtin_amdgcn_rcpf(x); }
; #define TOKQ ((size_t)b * SEQ + opq(qpos))
; DEV void nsa_acc_store(float* __restrict__ dst, const f32x16 (&o)[4], float scale, int hh, bool first) {
; #pragma unroll
;   for (int dt = 0; dt < 4; ++dt)
; #pragma unroll
;     for (int g = 0; g < 4; ++g) {
;       float4* q = (float4*)(dst + dt * 32 + 8 * g + 4 * hh);
;       float4 v = make_float4(o[dt][4 * g] * scale, o[dt][4 * g + 1] * scale, o[dt][4 * g + 2] * scale, o[dt][4 * g + 3] * scale);
;       if (!first) { float4 old = *q; v.x += old.x; v.y += old.y; v.z += old.z; v.w += old.w; }
;       *q = v;
;     }
; }
; DEV void nsa_item(const Params& p, int b, int tt, char* lds) {
;     ...
;     nsa_acc_store(NACC, s.o, GF[TOKQ * 16 + head * 3 + 2] * rcpf(s.l), hh, false);
;   }
;   asm volatile("" ::: "memory");
;   {
;     bf16_t* dst = AO + TOKQ * DM + head * 128;
;     const float* na = NACC;
; #pragma unroll
;     for (int dt = 0; dt < 4; ++dt)
; #pragma unroll
;       for (int g = 0; g < 4; ++g) {
;         float4 v = *(const float4*)(na + dt * 32 + 8 * g + 4 * hh);
;         uint2 u; u.x = cvtpk(v.x, v.y); u.y = cvtpk(v.z, v.w);
;         *(uint2*)(dst + dt * 32 + 8 * g + 4 * hh) = u;
;       }
.LBB0_326:
	v_mov_b32_e32 v2, v128
	v_mov_b32_e32 v153, v0
	v_ashrrev_i32_e32 v3, 31, v2
	v_lshl_add_u64 v[2:3], s[78:79], 0, v[2:3]
	v_lshlrev_b64 v[2:3], 11, v[2:3]
	v_lshl_add_u64 v[2:3], s[82:83], 0, v[2:3]
	v_lshl_add_u64 v[4:5], v[2:3], 0, v[152:153]
	v_mov_b32_e32 v2, v128
	v_mov_b32_e32 v159, v0
	v_ashrrev_i32_e32 v3, 31, v2
	v_lshl_add_u64 v[2:3], s[78:79], 0, v[2:3]
	v_lshlrev_b64 v[2:3], 6, v[2:3]
	v_lshl_add_u64 v[2:3], s[92:93], 0, v[2:3]
	v_lshl_add_u64 v[2:3], v[2:3], 0, v[158:159]
	v_mov_b32_e32 v155, v0
	flat_load_dword v1, v[2:3] offset:8
	v_lshl_add_u64 v[4:5], v[4:5], 0, v[154:155]
	flat_load_dwordx4 v[6:9], v[4:5]
	v_rcp_f32_e32 v2, v167
	v_mov_b32_e32 v157, v0
	s_mov_b64 s[2:3], 0x1fbc8000
	s_waitcnt vmcnt(0) lgkmcnt(0)
	v_mul_f32_e32 v2, v2, v1
	v_mov_b32_e32 v242, v128
	v_ashrrev_i32_e32 v243, 31, v242
	v_lshl_add_u64 v[242:243], s[78:79], 0, v[242:243]
	v_lshlrev_b64 v[242:243], 12, v[242:243]
	v_lshl_add_u64 v[242:243], s[80:81], 0, v[242:243]
	v_lshl_add_u64 v[242:243], v[242:243], 0, v[156:157]
	v_lshlrev_b32_e32 v244, 1, v130
	v_mov_b32_e32 v245, v0
	v_lshl_add_u64 v[242:243], v[242:243], 0, v[244:245]
	v_lshl_add_u64 v[254:255], v[242:243], 0, s[2:3]
	v_pk_fma_f32 v[6:7], v[64:65], v[2:3], v[6:7] op_sel_hi:[1,0,1]
	v_pk_fma_f32 v[8:9], v[66:67], v[2:3], v[8:9] op_sel_hi:[1,0,1]
	v_cvt_pk_bf16_f32 v6, v6, v7
	v_cvt_pk_bf16_f32 v7, v8, v9
	flat_store_dwordx2 v[254:255], v[6:7]
	s_nop 0
	flat_load_dwordx4 v[6:9], v[4:5] offset:32
	flat_load_dwordx4 v[234:237], v[4:5] offset:64
	flat_load_dwordx4 v[242:245], v[4:5] offset:96
	flat_load_dwordx4 v[246:249], v[4:5] offset:128
	flat_load_dwordx4 v[250:253], v[4:5] offset:160
	s_waitcnt vmcnt(0) lgkmcnt(0)
	v_pk_fma_f32 v[6:7], v[68:69], v[2:3], v[6:7] op_sel_hi:[1,0,1]
	v_pk_fma_f32 v[8:9], v[70:71], v[2:3], v[8:9] op_sel_hi:[1,0,1]
	v_pk_fma_f32 v[234:235], v[72:73], v[2:3], v[234:235] op_sel_hi:[1,0,1]
	v_pk_fma_f32 v[236:237], v[74:75], v[2:3], v[236:237] op_sel_hi:[1,0,1]
	v_pk_fma_f32 v[242:243], v[76:77], v[2:3], v[242:243] op_sel_hi:[1,0,1]
	v_pk_fma_f32 v[244:245], v[78:79], v[2:3], v[244:245] op_sel_hi:[1,0,1]
	v_pk_fma_f32 v[246:247], v[48:49], v[2:3], v[246:247] op_sel_hi:[1,0,1]
	v_pk_fma_f32 v[248:249], v[50:51], v[2:3], v[248:249] op_sel_hi:[1,0,1]
	v_pk_fma_f32 v[250:251], v[52:53], v[2:3], v[250:251] op_sel_hi:[1,0,1]
	v_pk_fma_f32 v[252:253], v[54:55], v[2:3], v[252:253] op_sel_hi:[1,0,1]
	v_cvt_pk_bf16_f32 v6, v6, v7
	v_cvt_pk_bf16_f32 v7, v8, v9
	v_cvt_pk_bf16_f32 v234, v234, v235
	v_cvt_pk_bf16_f32 v235, v236, v237
	v_cvt_pk_bf16_f32 v242, v242, v243
	v_cvt_pk_bf16_f32 v243, v244, v245
	v_cvt_pk_bf16_f32 v246, v246, v247
	v_cvt_pk_bf16_f32 v247, v248, v249
	v_cvt_pk_bf16_f32 v250, v250, v251
	v_cvt_pk_bf16_f32 v251, v252, v253
	flat_store_dwordx2 v[254:255], v[6:7] offset:16
	flat_store_dwordx2 v[254:255], v[234:235] offset:32
	flat_store_dwordx2 v[254:255], v[242:243] offset:48
	flat_store_dwordx2 v[254:255], v[246:247] offset:64
	flat_store_dwordx2 v[254:255], v[250:251] offset:80
	s_nop 0
	flat_load_dwordx4 v[6:9], v[4:5] offset:192
	flat_load_dwordx4 v[234:237], v[4:5] offset:224
	flat_load_dwordx4 v[242:245], v[4:5] offset:256
	flat_load_dwordx4 v[246:249], v[4:5] offset:288
	flat_load_dwordx4 v[250:253], v[4:5] offset:320
	s_waitcnt vmcnt(0) lgkmcnt(0)
	v_pk_fma_f32 v[6:7], v[56:57], v[2:3], v[6:7] op_sel_hi:[1,0,1]
	v_pk_fma_f32 v[8:9], v[58:59], v[2:3], v[8:9] op_sel_hi:[1,0,1]
	v_pk_fma_f32 v[234:235], v[60:61], v[2:3], v[234:235] op_sel_hi:[1,0,1]
	v_pk_fma_f32 v[236:237], v[62:63], v[2:3], v[236:237] op_sel_hi:[1,0,1]
	v_pk_fma_f32 v[242:243], v[32:33], v[2:3], v[242:243] op_sel_hi:[1,0,1]
	v_pk_fma_f32 v[244:245], v[34:35], v[2:3], v[244:245] op_sel_hi:[1,0,1]
	v_pk_fma_f32 v[246:247], v[36:37], v[2:3], v[246:247] op_sel_hi:[1,0,1]
	v_pk_fma_f32 v[248:249], v[38:39], v[2:3], v[248:249] op_sel_hi:[1,0,1]
	v_pk_fma_f32 v[250:251], v[40:41], v[2:3], v[250:251] op_sel_hi:[1,0,1]
	v_pk_fma_f32 v[252:253], v[42:43], v[2:3], v[252:253] op_sel_hi:[1,0,1]
	v_cvt_pk_bf16_f32 v6, v6, v7
	v_cvt_pk_bf16_f32 v7, v8, v9
	v_cvt_pk_bf16_f32 v234, v234, v235
	v_cvt_pk_bf16_f32 v235, v236, v237
	v_cvt_pk_bf16_f32 v242, v242, v243
	v_cvt_pk_bf16_f32 v243, v244, v245
	v_cvt_pk_bf16_f32 v246, v246, v247
	v_cvt_pk_bf16_f32 v247, v248, v249
	v_cvt_pk_bf16_f32 v250, v250, v251
	v_cvt_pk_bf16_f32 v251, v252, v253
	flat_store_dwordx2 v[254:255], v[6:7] offset:96
	flat_store_dwordx2 v[254:255], v[234:235] offset:112
	flat_store_dwordx2 v[254:255], v[242:243] offset:128
	flat_store_dwordx2 v[254:255], v[246:247] offset:144
	flat_store_dwordx2 v[254:255], v[250:251] offset:160
	s_nop 0
	flat_load_dwordx4 v[6:9], v[4:5] offset:352
	flat_load_dwordx4 v[234:237], v[4:5] offset:384
	flat_load_dwordx4 v[242:245], v[4:5] offset:416
	flat_load_dwordx4 v[246:249], v[4:5] offset:448
	flat_load_dwordx4 v[250:253], v[4:5] offset:480
	s_waitcnt vmcnt(0) lgkmcnt(0)
	v_pk_fma_f32 v[6:7], v[44:45], v[2:3], v[6:7] op_sel_hi:[1,0,1]
	v_pk_fma_f32 v[8:9], v[46:47], v[2:3], v[8:9] op_sel_hi:[1,0,1]
	v_pk_fma_f32 v[234:235], v[16:17], v[2:3], v[234:235] op_sel_hi:[1,0,1]
	v_pk_fma_f32 v[236:237], v[18:19], v[2:3], v[236:237] op_sel_hi:[1,0,1]
	v_pk_fma_f32 v[242:243], v[20:21], v[2:3], v[242:243] op_sel_hi:[1,0,1]
	v_pk_fma_f32 v[244:245], v[22:23], v[2:3], v[244:245] op_sel_hi:[1,0,1]
	v_pk_fma_f32 v[246:247], v[24:25], v[2:3], v[246:247] op_sel_hi:[1,0,1]
	v_pk_fma_f32 v[248:249], v[26:27], v[2:3], v[248:249] op_sel_hi:[1,0,1]
	v_pk_fma_f32 v[250:251], v[28:29], v[2:3], v[250:251] op_sel_hi:[1,0,1]
	v_pk_fma_f32 v[252:253], v[30:31], v[2:3], v[252:253] op_sel_hi:[1,0,1]
	v_cvt_pk_bf16_f32 v6, v6, v7
	v_cvt_pk_bf16_f32 v7, v8, v9
	v_cvt_pk_bf16_f32 v234, v234, v235
	v_cvt_pk_bf16_f32 v235, v236, v237
	v_cvt_pk_bf16_f32 v242, v242, v243
	v_cvt_pk_bf16_f32 v243, v244, v245
	v_cvt_pk_bf16_f32 v246, v246, v247
	v_cvt_pk_bf16_f32 v247, v248, v249
	v_cvt_pk_bf16_f32 v250, v250, v251
	v_cvt_pk_bf16_f32 v251, v252, v253
	flat_store_dwordx2 v[254:255], v[6:7] offset:176
	flat_store_dwordx2 v[254:255], v[234:235] offset:192
	flat_store_dwordx2 v[254:255], v[242:243] offset:208
	flat_store_dwordx2 v[254:255], v[246:247] offset:224
	flat_store_dwordx2 v[254:255], v[250:251] offset:240
	s_nop 0
	v_mov_b32_e32 v2, v128
	s_nop 0
	v_ashrrev_i32_e32 v129, 31, v128
	v_ashrrev_i32_e32 v3, 31, v2
	v_lshl_add_u64 v[4:5], s[78:79], 0, v[128:129]
	v_lshl_add_u64 v[2:3], s[78:79], 0, v[2:3]
	v_lshlrev_b64 v[4:5], 11, v[4:5]
	v_lshlrev_b64 v[2:3], 12, v[2:3]
	v_lshl_add_u64 v[4:5], s[82:83], 0, v[4:5]
	v_lshl_add_u64 v[2:3], s[80:81], 0, v[2:3]
	v_lshl_add_u64 v[4:5], v[4:5], 0, v[152:153]
	v_lshl_add_u64 v[2:3], v[2:3], 0, v[156:157]
	v_lshl_add_u64 v[6:7], v[4:5], 0, v[154:155]
	v_lshlrev_b32_e32 v4, 1, v130
	v_mov_b32_e32 v5, v0
	v_lshl_add_u64 v[8:9], v[2:3], 0, v[4:5]
	v_lshl_add_u64 v[10:11], v[8:9], 0, s[2:3]
	s_mov_b32 s2, 0x1fbc8000
	v_add_co_u32_e32 v2, vcc, s2, v8
	s_mov_b64 s[2:3], 0
	s_nop 0
	v_addc_co_u32_e32 v3, vcc, 0, v9, vcc

; DEV char* wsp(const Params& p) { char* w = p.ws; asm volatile("" : "+s"(w)); return w; }
; DEV bf16_t f2bf(float f) { return (bf16_t)(cvtpk(f, 0.f) & 0xffffu); }
; DEV void cmp2_item(const Params& p, int l, int it, char* lds) {
;     ...
;       if (kv == 0) {
; #pragma unroll
;         for (int rr = 0; rr < 8; ++rr) ((bf16_t*)(wsp(p) + OFF_KCC))[((size_t)b * 256 + c0 + rr) * 128 + d] = f2bf(acc[rr]);
.LBB0_479:
	s_andn2_b64 vcc, exec, s[6:7]
	s_cbranch_vccnz .LBB0_481
	v_lshl_or_b32 v10, s64, 10, v2
	v_mov_b32_e32 v11, v0
	s_mov_b64 s[2:3], s[70:71]
	v_lshlrev_b64 v[10:11], 1, v[10:11]
	v_cvt_pk_bf16_f32 v9, v9, s0
	v_lshl_add_u64 v[12:13], s[2:3], 0, v[10:11]
	v_add_co_u32_e32 v12, vcc, 0x1fb68000, v12
	s_mov_b64 s[2:3], s[70:71]
	s_nop 0
	v_addc_co_u32_e32 v13, vcc, 0, v13, vcc
	global_store_short v[12:13], v9, off
	v_cvt_pk_bf16_f32 v2, v8, s0
	v_cvt_pk_bf16_f32 v1, v1, s0
	v_lshl_add_u64 v[8:9], s[2:3], 0, v[10:11]
	v_add_co_u32_e32 v8, vcc, 0x1fb68000, v8
	s_mov_b64 s[2:3], s[70:71]
	s_nop 0
	v_addc_co_u32_e32 v9, vcc, 0, v9, vcc
	global_store_short v[8:9], v2, off offset:256
	v_cvt_pk_bf16_f32 v2, v7, s0
	v_lshl_add_u64 v[8:9], s[2:3], 0, v[10:11]
	v_add_co_u32_e32 v8, vcc, 0x1fb68000, v8
	s_mov_b64 s[2:3], s[70:71]
	s_nop 0
	v_addc_co_u32_e32 v9, vcc, 0, v9, vcc
	global_store_short v[8:9], v2, off offset:512
	v_cvt_pk_bf16_f32 v2, v6, s0
	s_nop 0
	v_lshl_add_u64 v[6:7], s[2:3], 0, v[10:11]
	v_add_co_u32_e32 v6, vcc, 0x1fb68000, v6
	s_mov_b64 s[2:3], s[70:71]
	s_nop 0
	v_addc_co_u32_e32 v7, vcc, 0, v7, vcc
	global_store_short v[6:7], v2, off offset:768
	v_cvt_pk_bf16_f32 v2, v4, s0
	v_lshl_add_u64 v[6:7], s[2:3], 0, v[10:11]
	v_add_co_u32_e32 v6, vcc, 0x1fb68000, v6
	s_mov_b64 s[2:3], s[70:71]
	s_nop 0
	v_addc_co_u32_e32 v7, vcc, 0, v7, vcc
	global_store_short v[6:7], v2, off offset:1024
	s_nop 0
	v_lshl_add_u64 v[6:7], s[2:3], 0, v[10:11]
	v_add_co_u32_e32 v6, vcc, 0x1fb68000, v6
	s_mov_b64 s[2:3], s[70:71]
	s_nop 0
	v_addc_co_u32_e32 v7, vcc, 0, v7, vcc
	global_store_short v[6:7], v1, off offset:1280
	v_cvt_pk_bf16_f32 v1, v5, s0
	s_nop 0
	v_lshl_add_u64 v[4:5], s[2:3], 0, v[10:11]
	v_add_co_u32_e32 v4, vcc, 0x1fb68000, v4
	s_mov_b64 s[2:3], s[70:71]
	s_nop 0
	v_addc_co_u32_e32 v5, vcc, 0, v5, vcc
	global_store_short v[4:5], v1, off offset:1536
	v_cvt_pk_bf16_f32 v1, v3, s0
	s_nop 0
	v_lshl_add_u64 v[2:3], s[2:3], 0, v[10:11]
	v_add_co_u32_e32 v2, vcc, 0x1fb68000, v2
	s_nop 1
	v_addc_co_u32_e32 v3, vcc, 0, v3, vcc
	global_store_short v[2:3], v1, off offset:1792

; DEV bf16_t f2bf(float f) { return (bf16_t)(cvtpk(f, 0.f) & 0xffffu); }
;   DEV void operator()(f32x16 (&acc)[2][2], int mb, int nb, int r32, int hh) const {
;     ...
; #pragma unroll
;     for (int mi = 0; mi < 2; ++mi)
; #pragma unroll
;       for (int ni = 0; ni < 2; ++ni)
; #pragma unroll
;         for (int r = 0; r < 16; ++r) {
;           int row = mb + mi * 32 + 8 * (r >> 2) + 4 * hh + (r & 3);
;           int c = wn64 + ni * 32 + r32;
;           float v = acc[mi][ni][r];
;           if (dcol >= 0) PR[(size_t)row * PR_LD + dcol + c] = f2bf(v);
;           if (dcol2 >= 0) {
;             float o = v;
;             if (rope == 1) {
;               if (wn64 == 0 && ni == 0) {
;                 float pv = __shfl_xor(v, 16);
;                 float2 cs = ropeH[(row & 4095) * 16 + (r32 & 15)];
;                 o = (r32 < 16) ? (v * cs.x - pv * cs.y) : (v * cs.x + pv * cs.y);
;               }
;             } else if (rope == 2) {
;               if (ni == 0) {
;                 float pv = __shfl_xor(v, 8);
;                 float2 cs = ropeD[(row & 4095) * 8 + (r32 & 7)];
;                 float rr = ((r32 & 8) == 0) ? (v * cs.x - pv * cs.y) : (v * cs.x + pv * cs.y);
;                 o = (r32 < 16) ? rr : v;
;               }
;             }
;             PR[(size_t)row * PR_LD + dcol2 + c] = f2bf(o);
;           }
;         }
.LBB0_714:
	s_waitcnt vmcnt(0)
	v_lshlrev_b32_e32 v133, 12, v143
	v_and_b32_e32 v141, 7, v130
	v_and_b32_e32 v138, 15, v130
	v_or_b32_e32 v130, 0x20000, v133
	s_and_b64 vcc, exec, s[6:7]
	s_cbranch_vccz .LBB0_1203
	s_andn2_b64 vcc, exec, s[18:19]
	s_mov_b64 s[6:7], -1
	s_cbranch_vccz .LBB0_1201
	s_xor_b64 s[14:15], s[14:15], -1
	v_or_b32_e32 v154, s62, v1
	s_and_b64 vcc, exec, s[14:15]
	s_cbranch_vccz .LBB0_1198
	s_cmp_gt_i32 s74, -1
	s_mov_b32 s75, s29
	s_cselect_b64 s[6:7], -1, 0
	s_lshl_b64 s[14:15], s[74:75], 1
	s_add_u32 s14, s39, s14
	s_addc_u32 s15, s41, s15
	v_lshlrev_b32_e32 v158, 1, v143
	v_mov_b32_e32 v159, v0
	s_cmp_lt_i32 s74, 0
	v_lshl_add_u64 v[156:157], s[14:15], 0, v[158:159]
	s_cbranch_scc1 .LBB0_719
	v_cvt_pk_bf16_f32 v145, v114, s0
	v_mad_i64_i32 v[160:161], s[14:15], v154, s35, v[156:157]
	global_store_short v[160:161], v145, off

; DEV bf16_t f2bf(float f) { return (bf16_t)(cvtpk(f, 0.f) & 0xffffu); }
;   DEV void operator()(f32x16 (&acc)[2][2], int mb, int nb, int r32, int hh) const {
;     ...
; #pragma unroll
;     for (int mi = 0; mi < 2; ++mi)
; #pragma unroll
;       for (int ni = 0; ni < 2; ++ni)
; #pragma unroll
;         for (int r = 0; r < 16; ++r) {
;           int row = mb + mi * 32 + 8 * (r >> 2) + 4 * hh + (r & 3);
;           int c = wn64 + ni * 32 + r32;
;           float v = acc[mi][ni][r];
;           if (dcol >= 0) PR[(size_t)row * PR_LD + dcol + c] = f2bf(v);
;           if (dcol2 >= 0) {
;             float o = v;
;             if (rope == 1) {
;               if (wn64 == 0 && ni == 0) {
;                 float pv = __shfl_xor(v, 16);
;                 float2 cs = ropeH[(row & 4095) * 16 + (r32 & 15)];
;                 o = (r32 < 16) ? (v * cs.x - pv * cs.y) : (v * cs.x + pv * cs.y);
;               }
;             } else if (rope == 2) {
;               if (ni == 0) {
;                 float pv = __shfl_xor(v, 8);
;                 float2 cs = ropeD[(row & 4095) * 8 + (r32 & 7)];
;                 float rr = ((r32 & 8) == 0) ? (v * cs.x - pv * cs.y) : (v * cs.x + pv * cs.y);
;                 o = (r32 < 16) ? rr : v;
;               }
;             }
;             PR[(size_t)row * PR_LD + dcol2 + c] = f2bf(o);
;           }
;         }
.LBB0_727:
	v_cvt_pk_bf16_f32 v145, v145, s0
	v_mad_i64_i32 v[160:161], s[14:15], v154, s35, v[158:159]
	global_store_short v[160:161], v145, off
.LBB0_728:
	v_cndmask_b32_e64 v145, 0, 1, s[6:7]
	v_cmp_ne_u32_e64 s[14:15], 1, v145
	s_andn2_b64 vcc, exec, s[6:7]
	v_or_b32_e32 v145, 1, v154
	s_cbranch_vccnz .LBB0_730
	v_cvt_pk_bf16_f32 v147, v115, s0
	v_mad_i64_i32 v[160:161], s[6:7], v145, s35, v[156:157]
	global_store_short v[160:161], v147, off

; DEV bf16_t f2bf(float f) { return (bf16_t)(cvtpk(f, 0.f) & 0xffffu); }
;   DEV void operator()(f32x16 (&acc)[2][2], int mb, int nb, int r32, int hh) const {
;     ...
; #pragma unroll
;     for (int mi = 0; mi < 2; ++mi)
; #pragma unroll
;       for (int ni = 0; ni < 2; ++ni)
; #pragma unroll
;         for (int r = 0; r < 16; ++r) {
;           int row = mb + mi * 32 + 8 * (r >> 2) + 4 * hh + (r & 3);
;           int c = wn64 + ni * 32 + r32;
;           float v = acc[mi][ni][r];
;           if (dcol >= 0) PR[(size_t)row * PR_LD + dcol + c] = f2bf(v);
;           if (dcol2 >= 0) {
;             float o = v;
;             if (rope == 1) {
;               if (wn64 == 0 && ni == 0) {
;                 float pv = __shfl_xor(v, 16);
;                 float2 cs = ropeH[(row & 4095) * 16 + (r32 & 15)];
;                 o = (r32 < 16) ? (v * cs.x - pv * cs.y) : (v * cs.x + pv * cs.y);
;               }
;             } else if (rope == 2) {
;               if (ni == 0) {
;                 float pv = __shfl_xor(v, 8);
;                 float2 cs = ropeD[(row & 4095) * 8 + (r32 & 7)];
;                 float rr = ((r32 & 8) == 0) ? (v * cs.x - pv * cs.y) : (v * cs.x + pv * cs.y);
;                 o = (r32 < 16) ? rr : v;
;               }
;             }
;             PR[(size_t)row * PR_LD + dcol2 + c] = f2bf(o);
;           }
.LBB0_738:
	v_cvt_pk_bf16_f32 v147, v147, s0
	v_mad_i64_i32 v[160:161], s[6:7], v145, s35, v[158:159]
	global_store_short v[160:161], v147, off
.LBB0_739:
	s_and_b64 vcc, exec, s[14:15]
	v_or_b32_e32 v147, 2, v154
	s_cbranch_vccnz .LBB0_741
	v_cvt_pk_bf16_f32 v149, v116, s0
	v_mad_i64_i32 v[160:161], s[6:7], v147, s35, v[156:157]
	global_store_short v[160:161], v149, off

; DEV bf16_t f2bf(float f) { return (bf16_t)(cvtpk(f, 0.f) & 0xffffu); }
;   DEV void operator()(f32x16 (&acc)[2][2], int mb, int nb, int r32, int hh) const {
;     ...
; #pragma unroll
;     for (int mi = 0; mi < 2; ++mi)
; #pragma unroll
;       for (int ni = 0; ni < 2; ++ni)
; #pragma unroll
;         for (int r = 0; r < 16; ++r) {
;           int row = mb + mi * 32 + 8 * (r >> 2) + 4 * hh + (r & 3);
;           int c = wn64 + ni * 32 + r32;
;           float v = acc[mi][ni][r];
;           if (dcol >= 0) PR[(size_t)row * PR_LD + dcol + c] = f2bf(v);
;           if (dcol2 >= 0) {
;             float o = v;
;             if (rope == 1) {
;               if (wn64 == 0 && ni == 0) {
;                 float pv = __shfl_xor(v, 16);
;                 float2 cs = ropeH[(row & 4095) * 16 + (r32 & 15)];
;                 o = (r32 < 16) ? (v * cs.x - pv * cs.y) : (v * cs.x + pv * cs.y);
;               }
;             } else if (rope == 2) {
;               if (ni == 0) {
;                 float pv = __shfl_xor(v, 8);
;                 float2 cs = ropeD[(row & 4095) * 8 + (r32 & 7)];
;                 float rr = ((r32 & 8) == 0) ? (v * cs.x - pv * cs.y) : (v * cs.x + pv * cs.y);
;                 o = (r32 < 16) ? rr : v;
;               }
;             }
;             PR[(size_t)row * PR_LD + dcol2 + c] = f2bf(o);
;           }
.LBB0_749:
	v_cvt_pk_bf16_f32 v149, v149, s0
	v_mad_i64_i32 v[160:161], s[6:7], v147, s35, v[158:159]
	global_store_short v[160:161], v149, off
.LBB0_750:
	s_and_b64 vcc, exec, s[14:15]
	v_or_b32_e32 v149, 3, v154
	s_cbranch_vccnz .LBB0_752
	v_cvt_pk_bf16_f32 v155, v117, s0
	v_mad_i64_i32 v[160:161], s[6:7], v149, s35, v[156:157]
	global_store_short v[160:161], v155, off

; DEV bf16_t f2bf(float f) { return (bf16_t)(cvtpk(f, 0.f) & 0xffffu); }
;   DEV void operator()(f32x16 (&acc)[2][2], int mb, int nb, int r32, int hh) const {
;     ...
; #pragma unroll
;     for (int mi = 0; mi < 2; ++mi)
; #pragma unroll
;       for (int ni = 0; ni < 2; ++ni)
; #pragma unroll
;         for (int r = 0; r < 16; ++r) {
;           int row = mb + mi * 32 + 8 * (r >> 2) + 4 * hh + (r & 3);
;           int c = wn64 + ni * 32 + r32;
;           float v = acc[mi][ni][r];
;           if (dcol >= 0) PR[(size_t)row * PR_LD + dcol + c] = f2bf(v);
;           if (dcol2 >= 0) {
;             float o = v;
;             if (rope == 1) {
;               if (wn64 == 0 && ni == 0) {
;                 float pv = __shfl_xor(v, 16);
;                 float2 cs = ropeH[(row & 4095) * 16 + (r32 & 15)];
;                 o = (r32 < 16) ? (v * cs.x - pv * cs.y) : (v * cs.x + pv * cs.y);
;               }
;             } else if (rope == 2) {
;               if (ni == 0) {
;                 float pv = __shfl_xor(v, 8);
;                 float2 cs = ropeD[(row & 4095) * 8 + (r32 & 7)];
;                 float rr = ((r32 & 8) == 0) ? (v * cs.x - pv * cs.y) : (v * cs.x + pv * cs.y);
;                 o = (r32 < 16) ? rr : v;
;               }
;             }
;             PR[(size_t)row * PR_LD + dcol2 + c] = f2bf(o);
;           }
.LBB0_760:
	v_cvt_pk_bf16_f32 v155, v155, s0
	v_mad_i64_i32 v[160:161], s[6:7], v149, s35, v[158:159]
	global_store_short v[160:161], v155, off
.LBB0_761:
	s_and_b64 vcc, exec, s[14:15]
	v_or_b32_e32 v155, 8, v154
	s_cbranch_vccnz .LBB0_763
	v_cvt_pk_bf16_f32 v162, v118, s0
	v_mad_i64_i32 v[160:161], s[6:7], v155, s35, v[156:157]
	global_store_short v[160:161], v162, off

; DEV bf16_t f2bf(float f) { return (bf16_t)(cvtpk(f, 0.f) & 0xffffu); }
;   DEV void operator()(f32x16 (&acc)[2][2], int mb, int nb, int r32, int hh) const {
;     ...
; #pragma unroll
;     for (int mi = 0; mi < 2; ++mi)
; #pragma unroll
;       for (int ni = 0; ni < 2; ++ni)
; #pragma unroll
;         for (int r = 0; r < 16; ++r) {
;           int row = mb + mi * 32 + 8 * (r >> 2) + 4 * hh + (r & 3);
;           int c = wn64 + ni * 32 + r32;
;           float v = acc[mi][ni][r];
;           if (dcol >= 0) PR[(size_t)row * PR_LD + dcol + c] = f2bf(v);
;           if (dcol2 >= 0) {
;             float o = v;
;             if (rope == 1) {
;               if (wn64 == 0 && ni == 0) {
;                 float pv = __shfl_xor(v, 16);
;                 float2 cs = ropeH[(row & 4095) * 16 + (r32 & 15)];
;                 o = (r32 < 16) ? (v * cs.x - pv * cs.y) : (v * cs.x + pv * cs.y);
;               }
;             } else if (rope == 2) {
;               if (ni == 0) {
;                 float pv = __shfl_xor(v, 8);
;                 float2 cs = ropeD[(row & 4095) * 8 + (r32 & 7)];
;                 float rr = ((r32 & 8) == 0) ? (v * cs.x - pv * cs.y) : (v * cs.x + pv * cs.y);
;                 o = (r32 < 16) ? rr : v;
;               }
;             }
;             PR[(size_t)row * PR_LD + dcol2 + c] = f2bf(o);
;           }
.LBB0_771:
	v_cvt_pk_bf16_f32 v162, v160, s0
	v_mad_i64_i32 v[160:161], s[6:7], v155, s35, v[158:159]
	global_store_short v[160:161], v162, off
.LBB0_772:
	s_and_b64 vcc, exec, s[14:15]
	v_or_b32_e32 v160, 9, v154
	s_cbranch_vccnz .LBB0_774
	v_cvt_pk_bf16_f32 v161, v119, s0
	v_mad_i64_i32 v[162:163], s[6:7], v160, s35, v[156:157]
	global_store_short v[162:163], v161, off

; DEV bf16_t f2bf(float f) { return (bf16_t)(cvtpk(f, 0.f) & 0xffffu); }
;   DEV void operator()(f32x16 (&acc)[2][2], int mb, int nb, int r32, int hh) const {
;     ...
; #pragma unroll
;     for (int mi = 0; mi < 2; ++mi)
; #pragma unroll
;       for (int ni = 0; ni < 2; ++ni)
; #pragma unroll
;         for (int r = 0; r < 16; ++r) {
;           int row = mb + mi * 32 + 8 * (r >> 2) + 4 * hh + (r & 3);
;           int c = wn64 + ni * 32 + r32;
;           float v = acc[mi][ni][r];
;           if (dcol >= 0) PR[(size_t)row * PR_LD + dcol + c] = f2bf(v);
;           if (dcol2 >= 0) {
;             float o = v;
;             if (rope == 1) {
;               if (wn64 == 0 && ni == 0) {
;                 float pv = __shfl_xor(v, 16);
;                 float2 cs = ropeH[(row & 4095) * 16 + (r32 & 15)];
;                 o = (r32 < 16) ? (v * cs.x - pv * cs.y) : (v * cs.x + pv * cs.y);
;               }
;             } else if (rope == 2) {
;               if (ni == 0) {
;                 float pv = __shfl_xor(v, 8);
;                 float2 cs = ropeD[(row & 4095) * 8 + (r32 & 7)];
;                 float rr = ((r32 & 8) == 0) ? (v * cs.x - pv * cs.y) : (v * cs.x + pv * cs.y);
;                 o = (r32 < 16) ? rr : v;
;               }
;             }
;             PR[(size_t)row * PR_LD + dcol2 + c] = f2bf(o);
;           }
.LBB0_782:
	v_cvt_pk_bf16_f32 v161, v161, s0
	v_mad_i64_i32 v[162:163], s[6:7], v160, s35, v[158:159]
	global_store_short v[162:163], v161, off
.LBB0_783:
	s_and_b64 vcc, exec, s[14:15]
	v_or_b32_e32 v161, 10, v154
	s_cbranch_vccnz .LBB0_785
	v_cvt_pk_bf16_f32 v164, v120, s0
	v_mad_i64_i32 v[162:163], s[6:7], v161, s35, v[156:157]
	global_store_short v[162:163], v164, off

; DEV bf16_t f2bf(float f) { return (bf16_t)(cvtpk(f, 0.f) & 0xffffu); }
;   DEV void operator()(f32x16 (&acc)[2][2], int mb, int nb, int r32, int hh) const {
;     ...
; #pragma unroll
;     for (int mi = 0; mi < 2; ++mi)
; #pragma unroll
;       for (int ni = 0; ni < 2; ++ni)
; #pragma unroll
;         for (int r = 0; r < 16; ++r) {
;           int row = mb + mi * 32 + 8 * (r >> 2) + 4 * hh + (r & 3);
;           int c = wn64 + ni * 32 + r32;
;           float v = acc[mi][ni][r];
;           if (dcol >= 0) PR[(size_t)row * PR_LD + dcol + c] = f2bf(v);
;           if (dcol2 >= 0) {
;             float o = v;
;             if (rope == 1) {
;               if (wn64 == 0 && ni == 0) {
;                 float pv = __shfl_xor(v, 16);
;                 float2 cs = ropeH[(row & 4095) * 16 + (r32 & 15)];
;                 o = (r32 < 16) ? (v * cs.x - pv * cs.y) : (v * cs.x + pv * cs.y);
;               }
;             } else if (rope == 2) {
;               if (ni == 0) {
;                 float pv = __shfl_xor(v, 8);
;                 float2 cs = ropeD[(row & 4095) * 8 + (r32 & 7)];
;                 float rr = ((r32 & 8) == 0) ? (v * cs.x - pv * cs.y) : (v * cs.x + pv * cs.y);
;                 o = (r32 < 16) ? rr : v;
;               }
;             }
;             PR[(size_t)row * PR_LD + dcol2 + c] = f2bf(o);
;           }
.LBB0_793:
	v_cvt_pk_bf16_f32 v164, v162, s0
	v_mad_i64_i32 v[162:163], s[6:7], v161, s35, v[158:159]
	global_store_short v[162:163], v164, off
.LBB0_794:
	s_and_b64 vcc, exec, s[14:15]
	v_or_b32_e32 v162, 11, v154
	s_cbranch_vccnz .LBB0_796
	v_cvt_pk_bf16_f32 v163, v121, s0
	v_mad_i64_i32 v[164:165], s[6:7], v162, s35, v[156:157]
	global_store_short v[164:165], v163, off

; DEV bf16_t f2bf(float f) { return (bf16_t)(cvtpk(f, 0.f) & 0xffffu); }
;   DEV void operator()(f32x16 (&acc)[2][2], int mb, int nb, int r32, int hh) const {
;     ...
; #pragma unroll
;     for (int mi = 0; mi < 2; ++mi)
; #pragma unroll
;       for (int ni = 0; ni < 2; ++ni)
; #pragma unroll
;         for (int r = 0; r < 16; ++r) {
;           int row = mb + mi * 32 + 8 * (r >> 2) + 4 * hh + (r & 3);
;           int c = wn64 + ni * 32 + r32;
;           float v = acc[mi][ni][r];
;           if (dcol >= 0) PR[(size_t)row * PR_LD + dcol + c] = f2bf(v);
;           if (dcol2 >= 0) {
;             float o = v;
;             if (rope == 1) {
;               if (wn64 == 0 && ni == 0) {
;                 float pv = __shfl_xor(v, 16);
;                 float2 cs = ropeH[(row & 4095) * 16 + (r32 & 15)];
;                 o = (r32 < 16) ? (v * cs.x - pv * cs.y) : (v * cs.x + pv * cs.y);
;               }
;             } else if (rope == 2) {
;               if (ni == 0) {
;                 float pv = __shfl_xor(v, 8);
;                 float2 cs = ropeD[(row & 4095) * 8 + (r32 & 7)];
;                 float rr = ((r32 & 8) == 0) ? (v * cs.x - pv * cs.y) : (v * cs.x + pv * cs.y);
;                 o = (r32 < 16) ? rr : v;
;               }
;             }
;             PR[(size_t)row * PR_LD + dcol2 + c] = f2bf(o);
;           }
.LBB0_804:
	v_cvt_pk_bf16_f32 v163, v163, s0
	v_mad_i64_i32 v[164:165], s[6:7], v162, s35, v[158:159]
	global_store_short v[164:165], v163, off
.LBB0_805:
	s_and_b64 vcc, exec, s[14:15]
	v_or_b32_e32 v163, 16, v154
	s_cbranch_vccnz .LBB0_807
	v_cvt_pk_bf16_f32 v166, v122, s0
	v_mad_i64_i32 v[164:165], s[6:7], v163, s35, v[156:157]
	global_store_short v[164:165], v166, off

; DEV bf16_t f2bf(float f) { return (bf16_t)(cvtpk(f, 0.f) & 0xffffu); }
;   DEV void operator()(f32x16 (&acc)[2][2], int mb, int nb, int r32, int hh) const {
;     ...
; #pragma unroll
;     for (int mi = 0; mi < 2; ++mi)
; #pragma unroll
;       for (int ni = 0; ni < 2; ++ni)
; #pragma unroll
;         for (int r = 0; r < 16; ++r) {
;           int row = mb + mi * 32 + 8 * (r >> 2) + 4 * hh + (r & 3);
;           int c = wn64 + ni * 32 + r32;
;           float v = acc[mi][ni][r];
;           if (dcol >= 0) PR[(size_t)row * PR_LD + dcol + c] = f2bf(v);
;           if (dcol2 >= 0) {
;             float o = v;
;             if (rope == 1) {
;               if (wn64 == 0 && ni == 0) {
;                 float pv = __shfl_xor(v, 16);
;                 float2 cs = ropeH[(row & 4095) * 16 + (r32 & 15)];
;                 o = (r32 < 16) ? (v * cs.x - pv * cs.y) : (v * cs.x + pv * cs.y);
;               }
;             } else if (rope == 2) {
;               if (ni == 0) {
;                 float pv = __shfl_xor(v, 8);
;                 float2 cs = ropeD[(row & 4095) * 8 + (r32 & 7)];
;                 float rr = ((r32 & 8) == 0) ? (v * cs.x - pv * cs.y) : (v * cs.x + pv * cs.y);
;                 o = (r32 < 16) ? rr : v;
;               }
;             }
;             PR[(size_t)row * PR_LD + dcol2 + c] = f2bf(o);
;           }
.LBB0_815:
	v_cvt_pk_bf16_f32 v166, v164, s0
	v_mad_i64_i32 v[164:165], s[6:7], v163, s35, v[158:159]
	global_store_short v[164:165], v166, off
.LBB0_816:
	s_and_b64 vcc, exec, s[14:15]
	v_or_b32_e32 v164, 17, v154
	s_cbranch_vccnz .LBB0_818
	v_cvt_pk_bf16_f32 v165, v123, s0
	v_mad_i64_i32 v[166:167], s[6:7], v164, s35, v[156:157]
	global_store_short v[166:167], v165, off

; DEV bf16_t f2bf(float f) { return (bf16_t)(cvtpk(f, 0.f) & 0xffffu); }
;   DEV void operator()(f32x16 (&acc)[2][2], int mb, int nb, int r32, int hh) const {
;     ...
; #pragma unroll
;     for (int mi = 0; mi < 2; ++mi)
; #pragma unroll
;       for (int ni = 0; ni < 2; ++ni)
; #pragma unroll
;         for (int r = 0; r < 16; ++r) {
;           int row = mb + mi * 32 + 8 * (r >> 2) + 4 * hh + (r & 3);
;           int c = wn64 + ni * 32 + r32;
;           float v = acc[mi][ni][r];
;           if (dcol >= 0) PR[(size_t)row * PR_LD + dcol + c] = f2bf(v);
;           if (dcol2 >= 0) {
;             float o = v;
;             if (rope == 1) {
;               if (wn64 == 0 && ni == 0) {
;                 float pv = __shfl_xor(v, 16);
;                 float2 cs = ropeH[(row & 4095) * 16 + (r32 & 15)];
;                 o = (r32 < 16) ? (v * cs.x - pv * cs.y) : (v * cs.x + pv * cs.y);
;               }
;             } else if (rope == 2) {
;               if (ni == 0) {
;                 float pv = __shfl_xor(v, 8);
;                 float2 cs = ropeD[(row & 4095) * 8 + (r32 & 7)];
;                 float rr = ((r32 & 8) == 0) ? (v * cs.x - pv * cs.y) : (v * cs.x + pv * cs.y);
;                 o = (r32 < 16) ? rr : v;
;               }
;             }
;             PR[(size_t)row * PR_LD + dcol2 + c] = f2bf(o);
;           }
.LBB0_826:
	v_cvt_pk_bf16_f32 v165, v165, s0
	v_mad_i64_i32 v[166:167], s[6:7], v164, s35, v[158:159]
	global_store_short v[166:167], v165, off
.LBB0_827:
	s_and_b64 vcc, exec, s[14:15]
	v_or_b32_e32 v165, 18, v154
	s_cbranch_vccnz .LBB0_829
	v_cvt_pk_bf16_f32 v168, v124, s0
	v_mad_i64_i32 v[166:167], s[6:7], v165, s35, v[156:157]
	global_store_short v[166:167], v168, off

; DEV bf16_t f2bf(float f) { return (bf16_t)(cvtpk(f, 0.f) & 0xffffu); }
;   DEV void operator()(f32x16 (&acc)[2][2], int mb, int nb, int r32, int hh) const {
;     ...
; #pragma unroll
;     for (int mi = 0; mi < 2; ++mi)
; #pragma unroll
;       for (int ni = 0; ni < 2; ++ni)
; #pragma unroll
;         for (int r = 0; r < 16; ++r) {
;           int row = mb + mi * 32 + 8 * (r >> 2) + 4 * hh + (r & 3);
;           int c = wn64 + ni * 32 + r32;
;           float v = acc[mi][ni][r];
;           if (dcol >= 0) PR[(size_t)row * PR_LD + dcol + c] = f2bf(v);
;           if (dcol2 >= 0) {
;             float o = v;
;             if (rope == 1) {
;               if (wn64 == 0 && ni == 0) {
;                 float pv = __shfl_xor(v, 16);
;                 float2 cs = ropeH[(row & 4095) * 16 + (r32 & 15)];
;                 o = (r32 < 16) ? (v * cs.x - pv * cs.y) : (v * cs.x + pv * cs.y);
;               }
;             } else if (rope == 2) {
;               if (ni == 0) {
;                 float pv = __shfl_xor(v, 8);
;                 float2 cs = ropeD[(row & 4095) * 8 + (r32 & 7)];
;                 float rr = ((r32 & 8) == 0) ? (v * cs.x - pv * cs.y) : (v * cs.x + pv * cs.y);
;                 o = (r32 < 16) ? rr : v;
;               }
;             }
;             PR[(size_t)row * PR_LD + dcol2 + c] = f2bf(o);
;           }
.LBB0_837:
	v_cvt_pk_bf16_f32 v168, v166, s0
	v_mad_i64_i32 v[166:167], s[6:7], v165, s35, v[158:159]
	global_store_short v[166:167], v168, off
.LBB0_838:
	s_and_b64 vcc, exec, s[14:15]
	v_or_b32_e32 v166, 19, v154
	s_cbranch_vccnz .LBB0_840
	v_cvt_pk_bf16_f32 v167, v125, s0
	v_mad_i64_i32 v[168:169], s[6:7], v166, s35, v[156:157]
	global_store_short v[168:169], v167, off

; DEV bf16_t f2bf(float f) { return (bf16_t)(cvtpk(f, 0.f) & 0xffffu); }
;   DEV void operator()(f32x16 (&acc)[2][2], int mb, int nb, int r32, int hh) const {
;     ...
; #pragma unroll
;     for (int mi = 0; mi < 2; ++mi)
; #pragma unroll
;       for (int ni = 0; ni < 2; ++ni)
; #pragma unroll
;         for (int r = 0; r < 16; ++r) {
;           int row = mb + mi * 32 + 8 * (r >> 2) + 4 * hh + (r & 3);
;           int c = wn64 + ni * 32 + r32;
;           float v = acc[mi][ni][r];
;           if (dcol >= 0) PR[(size_t)row * PR_LD + dcol + c] = f2bf(v);
;           if (dcol2 >= 0) {
;             float o = v;
;             if (rope == 1) {
;               if (wn64 == 0 && ni == 0) {
;                 float pv = __shfl_xor(v, 16);
;                 float2 cs = ropeH[(row & 4095) * 16 + (r32 & 15)];
;                 o = (r32 < 16) ? (v * cs.x - pv * cs.y) : (v * cs.x + pv * cs.y);
;               }
;             } else if (rope == 2) {
;               if (ni == 0) {
;                 float pv = __shfl_xor(v, 8);
;                 float2 cs = ropeD[(row & 4095) * 8 + (r32 & 7)];
;                 float rr = ((r32 & 8) == 0) ? (v * cs.x - pv * cs.y) : (v * cs.x + pv * cs.y);
;                 o = (r32 < 16) ? rr : v;
;               }
;             }
;             PR[(size_t)row * PR_LD + dcol2 + c] = f2bf(o);
;           }
.LBB0_848:
	v_cvt_pk_bf16_f32 v167, v167, s0
	v_mad_i64_i32 v[168:169], s[6:7], v166, s35, v[158:159]
	global_store_short v[168:169], v167, off
.LBB0_849:
	s_and_b64 vcc, exec, s[14:15]
	v_or_b32_e32 v167, 24, v154
	s_cbranch_vccnz .LBB0_851
	v_cvt_pk_bf16_f32 v170, v126, s0
	v_mad_i64_i32 v[168:169], s[6:7], v167, s35, v[156:157]
	global_store_short v[168:169], v170, off

; DEV bf16_t f2bf(float f) { return (bf16_t)(cvtpk(f, 0.f) & 0xffffu); }
;   DEV void operator()(f32x16 (&acc)[2][2], int mb, int nb, int r32, int hh) const {
;     ...
; #pragma unroll
;     for (int mi = 0; mi < 2; ++mi)
; #pragma unroll
;       for (int ni = 0; ni < 2; ++ni)
; #pragma unroll
;         for (int r = 0; r < 16; ++r) {
;           int row = mb + mi * 32 + 8 * (r >> 2) + 4 * hh + (r & 3);
;           int c = wn64 + ni * 32 + r32;
;           float v = acc[mi][ni][r];
;           if (dcol >= 0) PR[(size_t)row * PR_LD + dcol + c] = f2bf(v);
;           if (dcol2 >= 0) {
;             float o = v;
;             if (rope == 1) {
;               if (wn64 == 0 && ni == 0) {
;                 float pv = __shfl_xor(v, 16);
;                 float2 cs = ropeH[(row & 4095) * 16 + (r32 & 15)];
;                 o = (r32 < 16) ? (v * cs.x - pv * cs.y) : (v * cs.x + pv * cs.y);
;               }
;             } else if (rope == 2) {
;               if (ni == 0) {
;                 float pv = __shfl_xor(v, 8);
;                 float2 cs = ropeD[(row & 4095) * 8 + (r32 & 7)];
;                 float rr = ((r32 & 8) == 0) ? (v * cs.x - pv * cs.y) : (v * cs.x + pv * cs.y);
;                 o = (r32 < 16) ? rr : v;
;               }
;             }
;             PR[(size_t)row * PR_LD + dcol2 + c] = f2bf(o);
;           }
.LBB0_859:
	v_cvt_pk_bf16_f32 v170, v168, s0
	v_mad_i64_i32 v[168:169], s[6:7], v167, s35, v[158:159]
	global_store_short v[168:169], v170, off
.LBB0_860:
	s_and_b64 vcc, exec, s[14:15]
	v_or_b32_e32 v168, 25, v154
	s_cbranch_vccnz .LBB0_862
	v_cvt_pk_bf16_f32 v169, v127, s0
	v_mad_i64_i32 v[170:171], s[6:7], v168, s35, v[156:157]
	global_store_short v[170:171], v169, off

; DEV bf16_t f2bf(float f) { return (bf16_t)(cvtpk(f, 0.f) & 0xffffu); }
;   DEV void operator()(f32x16 (&acc)[2][2], int mb, int nb, int r32, int hh) const {
;     ...
; #pragma unroll
;     for (int mi = 0; mi < 2; ++mi)
; #pragma unroll
;       for (int ni = 0; ni < 2; ++ni)
; #pragma unroll
;         for (int r = 0; r < 16; ++r) {
;           int row = mb + mi * 32 + 8 * (r >> 2) + 4 * hh + (r & 3);
;           int c = wn64 + ni * 32 + r32;
;           float v = acc[mi][ni][r];
;           if (dcol >= 0) PR[(size_t)row * PR_LD + dcol + c] = f2bf(v);
;           if (dcol2 >= 0) {
;             float o = v;
;             if (rope == 1) {
;               if (wn64 == 0 && ni == 0) {
;                 float pv = __shfl_xor(v, 16);
;                 float2 cs = ropeH[(row & 4095) * 16 + (r32 & 15)];
;                 o = (r32 < 16) ? (v * cs.x - pv * cs.y) : (v * cs.x + pv * cs.y);
;               }
;             } else if (rope == 2) {
;               if (ni == 0) {
;                 float pv = __shfl_xor(v, 8);
;                 float2 cs = ropeD[(row & 4095) * 8 + (r32 & 7)];
;                 float rr = ((r32 & 8) == 0) ? (v * cs.x - pv * cs.y) : (v * cs.x + pv * cs.y);
;                 o = (r32 < 16) ? rr : v;
;               }
;             }
;             PR[(size_t)row * PR_LD + dcol2 + c] = f2bf(o);
;           }
.LBB0_870:
	v_cvt_pk_bf16_f32 v169, v169, s0
	v_mad_i64_i32 v[170:171], s[6:7], v168, s35, v[158:159]
	global_store_short v[170:171], v169, off
.LBB0_871:
	s_and_b64 vcc, exec, s[14:15]
	v_or_b32_e32 v169, 26, v154
	s_cbranch_vccnz .LBB0_873
	v_cvt_pk_bf16_f32 v172, v128, s0
	v_mad_i64_i32 v[170:171], s[6:7], v169, s35, v[156:157]
	global_store_short v[170:171], v172, off

; DEV bf16_t f2bf(float f) { return (bf16_t)(cvtpk(f, 0.f) & 0xffffu); }
;   DEV void operator()(f32x16 (&acc)[2][2], int mb, int nb, int r32, int hh) const {
;     ...
; #pragma unroll
;     for (int mi = 0; mi < 2; ++mi)
; #pragma unroll
;       for (int ni = 0; ni < 2; ++ni)
; #pragma unroll
;         for (int r = 0; r < 16; ++r) {
;           int row = mb + mi * 32 + 8 * (r >> 2) + 4 * hh + (r & 3);
;           int c = wn64 + ni * 32 + r32;
;           float v = acc[mi][ni][r];
;           if (dcol >= 0) PR[(size_t)row * PR_LD + dcol + c] = f2bf(v);
;           if (dcol2 >= 0) {
;             float o = v;
;             if (rope == 1) {
;               if (wn64 == 0 && ni == 0) {
;                 float pv = __shfl_xor(v, 16);
;                 float2 cs = ropeH[(row & 4095) * 16 + (r32 & 15)];
;                 o = (r32 < 16) ? (v * cs.x - pv * cs.y) : (v * cs.x + pv * cs.y);
;               }
;             } else if (rope == 2) {
;               if (ni == 0) {
;                 float pv = __shfl_xor(v, 8);
;                 float2 cs = ropeD[(row & 4095) * 8 + (r32 & 7)];
;                 float rr = ((r32 & 8) == 0) ? (v * cs.x - pv * cs.y) : (v * cs.x + pv * cs.y);
;                 o = (r32 < 16) ? rr : v;
;               }
;             }
;             PR[(size_t)row * PR_LD + dcol2 + c] = f2bf(o);
;           }
.LBB0_881:
	v_cvt_pk_bf16_f32 v172, v170, s0
	v_mad_i64_i32 v[170:171], s[6:7], v169, s35, v[158:159]
	global_store_short v[170:171], v172, off
.LBB0_882:
	s_and_b64 vcc, exec, s[14:15]
	v_or_b32_e32 v170, 27, v154
	s_cbranch_vccnz .LBB0_884
	v_cvt_pk_bf16_f32 v171, v129, s0
	v_mad_i64_i32 v[172:173], s[6:7], v170, s35, v[156:157]
	global_store_short v[172:173], v171, off

; DEV bf16_t f2bf(float f) { return (bf16_t)(cvtpk(f, 0.f) & 0xffffu); }
;   DEV void operator()(f32x16 (&acc)[2][2], int mb, int nb, int r32, int hh) const {
;     ...
; #pragma unroll
;     for (int mi = 0; mi < 2; ++mi)
; #pragma unroll
;       for (int ni = 0; ni < 2; ++ni)
; #pragma unroll
;         for (int r = 0; r < 16; ++r) {
;           int row = mb + mi * 32 + 8 * (r >> 2) + 4 * hh + (r & 3);
;           int c = wn64 + ni * 32 + r32;
;           float v = acc[mi][ni][r];
;           if (dcol >= 0) PR[(size_t)row * PR_LD + dcol + c] = f2bf(v);
;           if (dcol2 >= 0) {
;             float o = v;
;             if (rope == 1) {
;               if (wn64 == 0 && ni == 0) {
;                 float pv = __shfl_xor(v, 16);
;                 float2 cs = ropeH[(row & 4095) * 16 + (r32 & 15)];
;                 o = (r32 < 16) ? (v * cs.x - pv * cs.y) : (v * cs.x + pv * cs.y);
;               }
;             } else if (rope == 2) {
;               if (ni == 0) {
;                 float pv = __shfl_xor(v, 8);
;                 float2 cs = ropeD[(row & 4095) * 8 + (r32 & 7)];
;                 float rr = ((r32 & 8) == 0) ? (v * cs.x - pv * cs.y) : (v * cs.x + pv * cs.y);
;                 o = (r32 < 16) ? rr : v;
;               }
;             }
;             PR[(size_t)row * PR_LD + dcol2 + c] = f2bf(o);
;           }
.LBB0_892:
	v_cvt_pk_bf16_f32 v171, v171, s0
	v_mad_i64_i32 v[172:173], s[6:7], v170, s35, v[158:159]
	global_store_short v[172:173], v171, off
.LBB0_893:
	s_and_b64 vcc, exec, s[14:15]
	s_cbranch_vccnz .LBB0_895
	v_cvt_pk_bf16_f32 v171, v98, s0
	v_mad_i64_i32 v[172:173], s[6:7], v154, s35, v[156:157]
	global_store_short v[172:173], v171, off offset:64
.LBB0_895:
	s_and_b64 vcc, exec, s[16:17]
	s_cbranch_vccnz .LBB0_897
	v_cvt_pk_bf16_f32 v171, v98, s0
	v_mad_i64_i32 v[172:173], s[6:7], v154, s35, v[158:159]
	global_store_short v[172:173], v171, off offset:64
.LBB0_897:
	s_and_b64 vcc, exec, s[14:15]
	s_cbranch_vccnz .LBB0_899
	v_cvt_pk_bf16_f32 v171, v99, s0
	v_mad_i64_i32 v[172:173], s[6:7], v145, s35, v[156:157]
	global_store_short v[172:173], v171, off offset:64
.LBB0_899:
	s_and_b64 vcc, exec, s[16:17]
	s_cbranch_vccnz .LBB0_901
	v_cvt_pk_bf16_f32 v171, v99, s0
	v_mad_i64_i32 v[172:173], s[6:7], v145, s35, v[158:159]
	global_store_short v[172:173], v171, off offset:64
.LBB0_901:
	s_and_b64 vcc, exec, s[14:15]
	s_cbranch_vccnz .LBB0_903
	v_cvt_pk_bf16_f32 v145, v100, s0
	v_mad_i64_i32 v[172:173], s[6:7], v147, s35, v[156:157]
	global_store_short v[172:173], v145, off offset:64
.LBB0_903:
	s_and_b64 vcc, exec, s[16:17]
	s_cbranch_vccnz .LBB0_905
	v_cvt_pk_bf16_f32 v145, v100, s0
	v_mad_i64_i32 v[172:173], s[6:7], v147, s35, v[158:159]
	global_store_short v[172:173], v145, off offset:64
.LBB0_905:
	s_and_b64 vcc, exec, s[14:15]
	s_cbranch_vccnz .LBB0_907
	v_cvt_pk_bf16_f32 v145, v101, s0
	v_mad_i64_i32 v[172:173], s[6:7], v149, s35, v[156:157]
	global_store_short v[172:173], v145, off offset:64
.LBB0_907:
	s_and_b64 vcc, exec, s[16:17]
	s_cbranch_vccnz .LBB0_909
	v_cvt_pk_bf16_f32 v145, v101, s0
	v_mad_i64_i32 v[172:173], s[6:7], v149, s35, v[158:159]
	global_store_short v[172:173], v145, off offset:64
.LBB0_909:
	s_and_b64 vcc, exec, s[14:15]
	s_cbranch_vccnz .LBB0_911
	v_cvt_pk_bf16_f32 v145, v102, s0
	v_mad_i64_i32 v[172:173], s[6:7], v155, s35, v[156:157]
	global_store_short v[172:173], v145, off offset:64
.LBB0_911:
	s_and_b64 vcc, exec, s[16:17]
	s_cbranch_vccnz .LBB0_913
	v_cvt_pk_bf16_f32 v145, v102, s0
	v_mad_i64_i32 v[172:173], s[6:7], v155, s35, v[158:159]
	global_store_short v[172:173], v145, off offset:64
.LBB0_913:
	s_and_b64 vcc, exec, s[14:15]
	s_cbranch_vccnz .LBB0_915
	v_cvt_pk_bf16_f32 v145, v103, s0
	v_mad_i64_i32 v[172:173], s[6:7], v160, s35, v[156:157]
	global_store_short v[172:173], v145, off offset:64
.LBB0_915:
	s_and_b64 vcc, exec, s[16:17]
	s_cbranch_vccnz .LBB0_917
	v_cvt_pk_bf16_f32 v145, v103, s0
	v_mad_i64_i32 v[172:173], s[6:7], v160, s35, v[158:159]
	global_store_short v[172:173], v145, off offset:64
.LBB0_917:
	s_and_b64 vcc, exec, s[14:15]
	s_cbranch_vccnz .LBB0_919
	v_cvt_pk_bf16_f32 v145, v104, s0
	v_mad_i64_i32 v[172:173], s[6:7], v161, s35, v[156:157]
	global_store_short v[172:173], v145, off offset:64
.LBB0_919:
	s_and_b64 vcc, exec, s[16:17]
	s_cbranch_vccnz .LBB0_921
	v_cvt_pk_bf16_f32 v145, v104, s0
	v_mad_i64_i32 v[160:161], s[6:7], v161, s35, v[158:159]
	global_store_short v[160:161], v145, off offset:64
.LBB0_921:
	s_and_b64 vcc, exec, s[14:15]
	s_cbranch_vccnz .LBB0_923
	v_cvt_pk_bf16_f32 v145, v105, s0
	v_mad_i64_i32 v[160:161], s[6:7], v162, s35, v[156:157]
	global_store_short v[160:161], v145, off offset:64
.LBB0_923:
	s_and_b64 vcc, exec, s[16:17]
	s_cbranch_vccnz .LBB0_925
	v_cvt_pk_bf16_f32 v145, v105, s0
	v_mad_i64_i32 v[160:161], s[6:7], v162, s35, v[158:159]
	global_store_short v[160:161], v145, off offset:64
; DEV bf16_t f2bf(float f) { return (bf16_t)(cvtpk(f, 0.f) & 0xffffu); }
;   DEV void operator()(f32x16 (&acc)[2][2], int mb, int nb, int r32, int hh) const {
;     ...
; #pragma unroll
;     for (int mi = 0; mi < 2; ++mi)
; #pragma unroll
;       for (int ni = 0; ni < 2; ++ni)
; #pragma unroll
;         for (int r = 0; r < 16; ++r) {
;           int row = mb + mi * 32 + 8 * (r >> 2) + 4 * hh + (r & 3);
;           int c = wn64 + ni * 32 + r32;
;           float v = acc[mi][ni][r];
;           if (dcol >= 0) PR[(size_t)row * PR_LD + dcol + c] = f2bf(v);
;           if (dcol2 >= 0) {
;             float o = v;
;             if (rope == 1) {
;               if (wn64 == 0 && ni == 0) {
;                 float pv = __shfl_xor(v, 16);
;                 float2 cs = ropeH[(row & 4095) * 16 + (r32 & 15)];
;                 o = (r32 < 16) ? (v * cs.x - pv * cs.y) : (v * cs.x + pv * cs.y);
;               }
;             } else if (rope == 2) {
;               if (ni == 0) {
;                 float pv = __shfl_xor(v, 8);
;                 float2 cs = ropeD[(row & 4095) * 8 + (r32 & 7)];
;                 float rr = ((r32 & 8) == 0) ? (v * cs.x - pv * cs.y) : (v * cs.x + pv * cs.y);
;                 o = (r32 < 16) ? rr : v;
;               }
;             }
;             PR[(size_t)row * PR_LD + dcol2 + c] = f2bf(o);
;           }
.LBB0_925:
	s_and_b64 vcc, exec, s[14:15]
	s_cbranch_vccnz .LBB0_927
	v_cvt_pk_bf16_f32 v145, v106, s0
	v_mad_i64_i32 v[160:161], s[6:7], v163, s35, v[156:157]
	global_store_short v[160:161], v145, off offset:64
.LBB0_927:
	s_and_b64 vcc, exec, s[16:17]
	s_cbranch_vccnz .LBB0_929
	v_cvt_pk_bf16_f32 v145, v106, s0
	v_mad_i64_i32 v[160:161], s[6:7], v163, s35, v[158:159]
	global_store_short v[160:161], v145, off offset:64
.LBB0_929:
	s_and_b64 vcc, exec, s[14:15]
	s_cbranch_vccnz .LBB0_931
	v_cvt_pk_bf16_f32 v145, v107, s0
	v_mad_i64_i32 v[160:161], s[6:7], v164, s35, v[156:157]
	global_store_short v[160:161], v145, off offset:64
.LBB0_931:
	s_and_b64 vcc, exec, s[16:17]
	s_cbranch_vccnz .LBB0_933
	v_cvt_pk_bf16_f32 v145, v107, s0
	v_mad_i64_i32 v[160:161], s[6:7], v164, s35, v[158:159]
	global_store_short v[160:161], v145, off offset:64
.LBB0_933:
	s_and_b64 vcc, exec, s[14:15]
	s_cbranch_vccnz .LBB0_935
	v_cvt_pk_bf16_f32 v145, v108, s0
	v_mad_i64_i32 v[160:161], s[6:7], v165, s35, v[156:157]
	global_store_short v[160:161], v145, off offset:64
.LBB0_935:
	s_and_b64 vcc, exec, s[16:17]
	s_cbranch_vccnz .LBB0_937
	v_cvt_pk_bf16_f32 v145, v108, s0
	v_mad_i64_i32 v[160:161], s[6:7], v165, s35, v[158:159]
	global_store_short v[160:161], v145, off offset:64
.LBB0_937:
	s_and_b64 vcc, exec, s[14:15]
	s_cbranch_vccnz .LBB0_939
	v_cvt_pk_bf16_f32 v145, v109, s0
	v_mad_i64_i32 v[160:161], s[6:7], v166, s35, v[156:157]
	global_store_short v[160:161], v145, off offset:64
.LBB0_939:
	s_and_b64 vcc, exec, s[16:17]
	s_cbranch_vccnz .LBB0_941
	v_cvt_pk_bf16_f32 v145, v109, s0
	v_mad_i64_i32 v[160:161], s[6:7], v166, s35, v[158:159]
	global_store_short v[160:161], v145, off offset:64
.LBB0_941:
	s_and_b64 vcc, exec, s[14:15]
	s_cbranch_vccnz .LBB0_943
	v_cvt_pk_bf16_f32 v145, v110, s0
	v_mad_i64_i32 v[160:161], s[6:7], v167, s35, v[156:157]
	global_store_short v[160:161], v145, off offset:64
.LBB0_943:
	s_and_b64 vcc, exec, s[16:17]
	s_cbranch_vccnz .LBB0_945
	v_cvt_pk_bf16_f32 v145, v110, s0
	v_mad_i64_i32 v[160:161], s[6:7], v167, s35, v[158:159]
	global_store_short v[160:161], v145, off offset:64
.LBB0_945:
	s_and_b64 vcc, exec, s[14:15]
	s_cbranch_vccnz .LBB0_947
	v_cvt_pk_bf16_f32 v145, v111, s0
	v_mad_i64_i32 v[160:161], s[6:7], v168, s35, v[156:157]
	global_store_short v[160:161], v145, off offset:64
.LBB0_947:
	s_and_b64 vcc, exec, s[16:17]
	s_cbranch_vccnz .LBB0_949
	v_cvt_pk_bf16_f32 v145, v111, s0
	v_mad_i64_i32 v[160:161], s[6:7], v168, s35, v[158:159]
	global_store_short v[160:161], v145, off offset:64
.LBB0_949:
	s_and_b64 vcc, exec, s[14:15]
	s_cbranch_vccnz .LBB0_951
	v_cvt_pk_bf16_f32 v145, v112, s0
	v_mad_i64_i32 v[160:161], s[6:7], v169, s35, v[156:157]
	global_store_short v[160:161], v145, off offset:64
.LBB0_951:
	s_and_b64 vcc, exec, s[16:17]
	s_cbranch_vccnz .LBB0_953
	v_cvt_pk_bf16_f32 v145, v112, s0
	v_mad_i64_i32 v[160:161], s[6:7], v169, s35, v[158:159]
	global_store_short v[160:161], v145, off offset:64
.LBB0_953:
	s_and_b64 vcc, exec, s[14:15]
	s_cbranch_vccnz .LBB0_955
	v_cvt_pk_bf16_f32 v145, v113, s0
	v_mad_i64_i32 v[160:161], s[6:7], v170, s35, v[156:157]
	global_store_short v[160:161], v145, off offset:64
.LBB0_955:
	s_and_b64 vcc, exec, s[16:17]
	s_cbranch_vccnz .LBB0_957
	v_cvt_pk_bf16_f32 v145, v113, s0
	v_mad_i64_i32 v[160:161], s[6:7], v170, s35, v[158:159]
	global_store_short v[160:161], v145, off offset:64
.LBB0_957:
	s_and_b64 vcc, exec, s[14:15]
	v_or_b32_e32 v145, 32, v154
	s_cbranch_vccnz .LBB0_959
	v_cvt_pk_bf16_f32 v147, v82, s0
	v_mad_i64_i32 v[160:161], s[6:7], v145, s35, v[156:157]
	global_store_short v[160:161], v147, off

; DEV bf16_t f2bf(float f) { return (bf16_t)(cvtpk(f, 0.f) & 0xffffu); }
;   DEV void operator()(f32x16 (&acc)[2][2], int mb, int nb, int r32, int hh) const {
;     ...
; #pragma unroll
;     for (int mi = 0; mi < 2; ++mi)
; #pragma unroll
;       for (int ni = 0; ni < 2; ++ni)
; #pragma unroll
;         for (int r = 0; r < 16; ++r) {
;           int row = mb + mi * 32 + 8 * (r >> 2) + 4 * hh + (r & 3);
;           int c = wn64 + ni * 32 + r32;
;           float v = acc[mi][ni][r];
;           if (dcol >= 0) PR[(size_t)row * PR_LD + dcol + c] = f2bf(v);
;           if (dcol2 >= 0) {
;             float o = v;
;             if (rope == 1) {
;               if (wn64 == 0 && ni == 0) {
;                 float pv = __shfl_xor(v, 16);
;                 float2 cs = ropeH[(row & 4095) * 16 + (r32 & 15)];
;                 o = (r32 < 16) ? (v * cs.x - pv * cs.y) : (v * cs.x + pv * cs.y);
;               }
;             } else if (rope == 2) {
;               if (ni == 0) {
;                 float pv = __shfl_xor(v, 8);
;                 float2 cs = ropeD[(row & 4095) * 8 + (r32 & 7)];
;                 float rr = ((r32 & 8) == 0) ? (v * cs.x - pv * cs.y) : (v * cs.x + pv * cs.y);
;                 o = (r32 < 16) ? rr : v;
;               }
;             }
;             PR[(size_t)row * PR_LD + dcol2 + c] = f2bf(o);
;           }
.LBB0_968:
	s_and_b64 vcc, exec, s[14:15]
	v_or_b32_e32 v147, 33, v154
	s_cbranch_vccnz .LBB0_970
	v_cvt_pk_bf16_f32 v149, v83, s0
	v_mad_i64_i32 v[160:161], s[6:7], v147, s35, v[156:157]
	global_store_short v[160:161], v149, off

; DEV bf16_t f2bf(float f) { return (bf16_t)(cvtpk(f, 0.f) & 0xffffu); }
;   DEV void operator()(f32x16 (&acc)[2][2], int mb, int nb, int r32, int hh) const {
;     ...
; #pragma unroll
;     for (int mi = 0; mi < 2; ++mi)
; #pragma unroll
;       for (int ni = 0; ni < 2; ++ni)
; #pragma unroll
;         for (int r = 0; r < 16; ++r) {
;           int row = mb + mi * 32 + 8 * (r >> 2) + 4 * hh + (r & 3);
;           int c = wn64 + ni * 32 + r32;
;           float v = acc[mi][ni][r];
;           if (dcol >= 0) PR[(size_t)row * PR_LD + dcol + c] = f2bf(v);
;           if (dcol2 >= 0) {
;             float o = v;
;             if (rope == 1) {
;               if (wn64 == 0 && ni == 0) {
;                 float pv = __shfl_xor(v, 16);
;                 float2 cs = ropeH[(row & 4095) * 16 + (r32 & 15)];
;                 o = (r32 < 16) ? (v * cs.x - pv * cs.y) : (v * cs.x + pv * cs.y);
;               }
;             } else if (rope == 2) {
;               if (ni == 0) {
;                 float pv = __shfl_xor(v, 8);
;                 float2 cs = ropeD[(row & 4095) * 8 + (r32 & 7)];
;                 float rr = ((r32 & 8) == 0) ? (v * cs.x - pv * cs.y) : (v * cs.x + pv * cs.y);
;                 o = (r32 < 16) ? rr : v;
;               }
;             }
;             PR[(size_t)row * PR_LD + dcol2 + c] = f2bf(o);
;           }
.LBB0_979:
	s_and_b64 vcc, exec, s[14:15]
	v_or_b32_e32 v149, 34, v154
	s_cbranch_vccnz .LBB0_981
	v_cvt_pk_bf16_f32 v155, v84, s0
	v_mad_i64_i32 v[160:161], s[6:7], v149, s35, v[156:157]
	global_store_short v[160:161], v155, off

; DEV bf16_t f2bf(float f) { return (bf16_t)(cvtpk(f, 0.f) & 0xffffu); }
;   DEV void operator()(f32x16 (&acc)[2][2], int mb, int nb, int r32, int hh) const {
;     ...
; #pragma unroll
;     for (int mi = 0; mi < 2; ++mi)
; #pragma unroll
;       for (int ni = 0; ni < 2; ++ni)
; #pragma unroll
;         for (int r = 0; r < 16; ++r) {
;           int row = mb + mi * 32 + 8 * (r >> 2) + 4 * hh + (r & 3);
;           int c = wn64 + ni * 32 + r32;
;           float v = acc[mi][ni][r];
;           if (dcol >= 0) PR[(size_t)row * PR_LD + dcol + c] = f2bf(v);
;           if (dcol2 >= 0) {
;             float o = v;
;             if (rope == 1) {
;               if (wn64 == 0 && ni == 0) {
;                 float pv = __shfl_xor(v, 16);
;                 float2 cs = ropeH[(row & 4095) * 16 + (r32 & 15)];
;                 o = (r32 < 16) ? (v * cs.x - pv * cs.y) : (v * cs.x + pv * cs.y);
;               }
;             } else if (rope == 2) {
;               if (ni == 0) {
;                 float pv = __shfl_xor(v, 8);
;                 float2 cs = ropeD[(row & 4095) * 8 + (r32 & 7)];
;                 float rr = ((r32 & 8) == 0) ? (v * cs.x - pv * cs.y) : (v * cs.x + pv * cs.y);
;                 o = (r32 < 16) ? rr : v;
;               }
;             }
;             PR[(size_t)row * PR_LD + dcol2 + c] = f2bf(o);
;           }
.LBB0_990:
	s_and_b64 vcc, exec, s[14:15]
	v_or_b32_e32 v155, 35, v154
	s_cbranch_vccnz .LBB0_992
	v_cvt_pk_bf16_f32 v162, v85, s0
	v_mad_i64_i32 v[160:161], s[6:7], v155, s35, v[156:157]
	global_store_short v[160:161], v162, off

; DEV bf16_t f2bf(float f) { return (bf16_t)(cvtpk(f, 0.f) & 0xffffu); }
;   DEV void operator()(f32x16 (&acc)[2][2], int mb, int nb, int r32, int hh) const {
;     ...
; #pragma unroll
;     for (int mi = 0; mi < 2; ++mi)
; #pragma unroll
;       for (int ni = 0; ni < 2; ++ni)
; #pragma unroll
;         for (int r = 0; r < 16; ++r) {
;           int row = mb + mi * 32 + 8 * (r >> 2) + 4 * hh + (r & 3);
;           int c = wn64 + ni * 32 + r32;
;           float v = acc[mi][ni][r];
;           if (dcol >= 0) PR[(size_t)row * PR_LD + dcol + c] = f2bf(v);
;           if (dcol2 >= 0) {
;             float o = v;
;             if (rope == 1) {
;               if (wn64 == 0 && ni == 0) {
;                 float pv = __shfl_xor(v, 16);
;                 float2 cs = ropeH[(row & 4095) * 16 + (r32 & 15)];
;                 o = (r32 < 16) ? (v * cs.x - pv * cs.y) : (v * cs.x + pv * cs.y);
;               }
;             } else if (rope == 2) {
;               if (ni == 0) {
;                 float pv = __shfl_xor(v, 8);
;                 float2 cs = ropeD[(row & 4095) * 8 + (r32 & 7)];
;                 float rr = ((r32 & 8) == 0) ? (v * cs.x - pv * cs.y) : (v * cs.x + pv * cs.y);
;                 o = (r32 < 16) ? rr : v;
;               }
;             }
;             PR[(size_t)row * PR_LD + dcol2 + c] = f2bf(o);
;           }
.LBB0_1001:
	s_and_b64 vcc, exec, s[14:15]
	v_or_b32_e32 v160, 40, v154
	s_cbranch_vccnz .LBB0_1003
	v_cvt_pk_bf16_f32 v161, v86, s0
	v_mad_i64_i32 v[162:163], s[6:7], v160, s35, v[156:157]
	global_store_short v[162:163], v161, off

; DEV bf16_t f2bf(float f) { return (bf16_t)(cvtpk(f, 0.f) & 0xffffu); }
;   DEV void operator()(f32x16 (&acc)[2][2], int mb, int nb, int r32, int hh) const {
;     ...
; #pragma unroll
;     for (int mi = 0; mi < 2; ++mi)
; #pragma unroll
;       for (int ni = 0; ni < 2; ++ni)
; #pragma unroll
;         for (int r = 0; r < 16; ++r) {
;           int row = mb + mi * 32 + 8 * (r >> 2) + 4 * hh + (r & 3);
;           int c = wn64 + ni * 32 + r32;
;           float v = acc[mi][ni][r];
;           if (dcol >= 0) PR[(size_t)row * PR_LD + dcol + c] = f2bf(v);
;           if (dcol2 >= 0) {
;             float o = v;
;             if (rope == 1) {
;               if (wn64 == 0 && ni == 0) {
;                 float pv = __shfl_xor(v, 16);
;                 float2 cs = ropeH[(row & 4095) * 16 + (r32 & 15)];
;                 o = (r32 < 16) ? (v * cs.x - pv * cs.y) : (v * cs.x + pv * cs.y);
;               }
;             } else if (rope == 2) {
;               if (ni == 0) {
;                 float pv = __shfl_xor(v, 8);
;                 float2 cs = ropeD[(row & 4095) * 8 + (r32 & 7)];
;                 float rr = ((r32 & 8) == 0) ? (v * cs.x - pv * cs.y) : (v * cs.x + pv * cs.y);
;                 o = (r32 < 16) ? rr : v;
;               }
;             }
;             PR[(size_t)row * PR_LD + dcol2 + c] = f2bf(o);
;           }
.LBB0_1012:
	s_and_b64 vcc, exec, s[14:15]
	v_or_b32_e32 v161, 41, v154
	s_cbranch_vccnz .LBB0_1014
	v_cvt_pk_bf16_f32 v164, v87, s0
	v_mad_i64_i32 v[162:163], s[6:7], v161, s35, v[156:157]
	global_store_short v[162:163], v164, off

; DEV bf16_t f2bf(float f) { return (bf16_t)(cvtpk(f, 0.f) & 0xffffu); }
;   DEV void operator()(f32x16 (&acc)[2][2], int mb, int nb, int r32, int hh) const {
;     ...
; #pragma unroll
;     for (int mi = 0; mi < 2; ++mi)
; #pragma unroll
;       for (int ni = 0; ni < 2; ++ni)
; #pragma unroll
;         for (int r = 0; r < 16; ++r) {
;           int row = mb + mi * 32 + 8 * (r >> 2) + 4 * hh + (r & 3);
;           int c = wn64 + ni * 32 + r32;
;           float v = acc[mi][ni][r];
;           if (dcol >= 0) PR[(size_t)row * PR_LD + dcol + c] = f2bf(v);
;           if (dcol2 >= 0) {
;             float o = v;
;             if (rope == 1) {
;               if (wn64 == 0 && ni == 0) {
;                 float pv = __shfl_xor(v, 16);
;                 float2 cs = ropeH[(row & 4095) * 16 + (r32 & 15)];
;                 o = (r32 < 16) ? (v * cs.x - pv * cs.y) : (v * cs.x + pv * cs.y);
;               }
;             } else if (rope == 2) {
;               if (ni == 0) {
;                 float pv = __shfl_xor(v, 8);
;                 float2 cs = ropeD[(row & 4095) * 8 + (r32 & 7)];
;                 float rr = ((r32 & 8) == 0) ? (v * cs.x - pv * cs.y) : (v * cs.x + pv * cs.y);
;                 o = (r32 < 16) ? rr : v;
;               }
;             }
;             PR[(size_t)row * PR_LD + dcol2 + c] = f2bf(o);
;           }
.LBB0_1023:
	s_and_b64 vcc, exec, s[14:15]
	v_or_b32_e32 v162, 42, v154
	s_cbranch_vccnz .LBB0_1025
	v_cvt_pk_bf16_f32 v163, v88, s0
	v_mad_i64_i32 v[164:165], s[6:7], v162, s35, v[156:157]
	global_store_short v[164:165], v163, off

; DEV bf16_t f2bf(float f) { return (bf16_t)(cvtpk(f, 0.f) & 0xffffu); }
;   DEV void operator()(f32x16 (&acc)[2][2], int mb, int nb, int r32, int hh) const {
;     ...
; #pragma unroll
;     for (int mi = 0; mi < 2; ++mi)
; #pragma unroll
;       for (int ni = 0; ni < 2; ++ni)
; #pragma unroll
;         for (int r = 0; r < 16; ++r) {
;           int row = mb + mi * 32 + 8 * (r >> 2) + 4 * hh + (r & 3);
;           int c = wn64 + ni * 32 + r32;
;           float v = acc[mi][ni][r];
;           if (dcol >= 0) PR[(size_t)row * PR_LD + dcol + c] = f2bf(v);
;           if (dcol2 >= 0) {
;             float o = v;
;             if (rope == 1) {
;               if (wn64 == 0 && ni == 0) {
;                 float pv = __shfl_xor(v, 16);
;                 float2 cs = ropeH[(row & 4095) * 16 + (r32 & 15)];
;                 o = (r32 < 16) ? (v * cs.x - pv * cs.y) : (v * cs.x + pv * cs.y);
;               }
;             } else if (rope == 2) {
;               if (ni == 0) {
;                 float pv = __shfl_xor(v, 8);
;                 float2 cs = ropeD[(row & 4095) * 8 + (r32 & 7)];
;                 float rr = ((r32 & 8) == 0) ? (v * cs.x - pv * cs.y) : (v * cs.x + pv * cs.y);
;                 o = (r32 < 16) ? rr : v;
;               }
;             }
;             PR[(size_t)row * PR_LD + dcol2 + c] = f2bf(o);
;           }
.LBB0_1034:
	s_and_b64 vcc, exec, s[14:15]
	v_or_b32_e32 v163, 43, v154
	s_cbranch_vccnz .LBB0_1036
	v_cvt_pk_bf16_f32 v166, v89, s0
	v_mad_i64_i32 v[164:165], s[6:7], v163, s35, v[156:157]
	global_store_short v[164:165], v166, off

; DEV bf16_t f2bf(float f) { return (bf16_t)(cvtpk(f, 0.f) & 0xffffu); }
;   DEV void operator()(f32x16 (&acc)[2][2], int mb, int nb, int r32, int hh) const {
;     ...
; #pragma unroll
;     for (int mi = 0; mi < 2; ++mi)
; #pragma unroll
;       for (int ni = 0; ni < 2; ++ni)
; #pragma unroll
;         for (int r = 0; r < 16; ++r) {
;           int row = mb + mi * 32 + 8 * (r >> 2) + 4 * hh + (r & 3);
;           int c = wn64 + ni * 32 + r32;
;           float v = acc[mi][ni][r];
;           if (dcol >= 0) PR[(size_t)row * PR_LD + dcol + c] = f2bf(v);
;           if (dcol2 >= 0) {
;             float o = v;
;             if (rope == 1) {
;               if (wn64 == 0 && ni == 0) {
;                 float pv = __shfl_xor(v, 16);
;                 float2 cs = ropeH[(row & 4095) * 16 + (r32 & 15)];
;                 o = (r32 < 16) ? (v * cs.x - pv * cs.y) : (v * cs.x + pv * cs.y);
;               }
;             } else if (rope == 2) {
;               if (ni == 0) {
;                 float pv = __shfl_xor(v, 8);
;                 float2 cs = ropeD[(row & 4095) * 8 + (r32 & 7)];
;                 float rr = ((r32 & 8) == 0) ? (v * cs.x - pv * cs.y) : (v * cs.x + pv * cs.y);
;                 o = (r32 < 16) ? rr : v;
;               }
;             }
;             PR[(size_t)row * PR_LD + dcol2 + c] = f2bf(o);
;           }
.LBB0_1045:
	s_and_b64 vcc, exec, s[14:15]
	v_or_b32_e32 v164, 48, v154
	s_cbranch_vccnz .LBB0_1047
	v_cvt_pk_bf16_f32 v165, v90, s0
	v_mad_i64_i32 v[166:167], s[6:7], v164, s35, v[156:157]
	global_store_short v[166:167], v165, off

; DEV bf16_t f2bf(float f) { return (bf16_t)(cvtpk(f, 0.f) & 0xffffu); }
;   DEV void operator()(f32x16 (&acc)[2][2], int mb, int nb, int r32, int hh) const {
;     ...
; #pragma unroll
;     for (int mi = 0; mi < 2; ++mi)
; #pragma unroll
;       for (int ni = 0; ni < 2; ++ni)
; #pragma unroll
;         for (int r = 0; r < 16; ++r) {
;           int row = mb + mi * 32 + 8 * (r >> 2) + 4 * hh + (r & 3);
;           int c = wn64 + ni * 32 + r32;
;           float v = acc[mi][ni][r];
;           if (dcol >= 0) PR[(size_t)row * PR_LD + dcol + c] = f2bf(v);
;           if (dcol2 >= 0) {
;             float o = v;
;             if (rope == 1) {
;               if (wn64 == 0 && ni == 0) {
;                 float pv = __shfl_xor(v, 16);
;                 float2 cs = ropeH[(row & 4095) * 16 + (r32 & 15)];
;                 o = (r32 < 16) ? (v * cs.x - pv * cs.y) : (v * cs.x + pv * cs.y);
;               }
;             } else if (rope == 2) {
;               if (ni == 0) {
;                 float pv = __shfl_xor(v, 8);
;                 float2 cs = ropeD[(row & 4095) * 8 + (r32 & 7)];
;                 float rr = ((r32 & 8) == 0) ? (v * cs.x - pv * cs.y) : (v * cs.x + pv * cs.y);
;                 o = (r32 < 16) ? rr : v;
;               }
;             }
;             PR[(size_t)row * PR_LD + dcol2 + c] = f2bf(o);
;           }
.LBB0_1056:
	s_and_b64 vcc, exec, s[14:15]
	v_or_b32_e32 v165, 49, v154
	s_cbranch_vccnz .LBB0_1058
	v_cvt_pk_bf16_f32 v168, v91, s0
	v_mad_i64_i32 v[166:167], s[6:7], v165, s35, v[156:157]
	global_store_short v[166:167], v168, off

; DEV bf16_t f2bf(float f) { return (bf16_t)(cvtpk(f, 0.f) & 0xffffu); }
;   DEV void operator()(f32x16 (&acc)[2][2], int mb, int nb, int r32, int hh) const {
;     ...
; #pragma unroll
;     for (int mi = 0; mi < 2; ++mi)
; #pragma unroll
;       for (int ni = 0; ni < 2; ++ni)
; #pragma unroll
;         for (int r = 0; r < 16; ++r) {
;           int row = mb + mi * 32 + 8 * (r >> 2) + 4 * hh + (r & 3);
;           int c = wn64 + ni * 32 + r32;
;           float v = acc[mi][ni][r];
;           if (dcol >= 0) PR[(size_t)row * PR_LD + dcol + c] = f2bf(v);
;           if (dcol2 >= 0) {
;             float o = v;
;             if (rope == 1) {
;               if (wn64 == 0 && ni == 0) {
;                 float pv = __shfl_xor(v, 16);
;                 float2 cs = ropeH[(row & 4095) * 16 + (r32 & 15)];
;                 o = (r32 < 16) ? (v * cs.x - pv * cs.y) : (v * cs.x + pv * cs.y);
;               }
;             } else if (rope == 2) {
;               if (ni == 0) {
;                 float pv = __shfl_xor(v, 8);
;                 float2 cs = ropeD[(row & 4095) * 8 + (r32 & 7)];
;                 float rr = ((r32 & 8) == 0) ? (v * cs.x - pv * cs.y) : (v * cs.x + pv * cs.y);
;                 o = (r32 < 16) ? rr : v;
;               }
;             }
;             PR[(size_t)row * PR_LD + dcol2 + c] = f2bf(o);
;           }
.LBB0_1067:
	s_and_b64 vcc, exec, s[14:15]
	v_or_b32_e32 v166, 50, v154
	s_cbranch_vccnz .LBB0_1069
	v_cvt_pk_bf16_f32 v167, v92, s0
	v_mad_i64_i32 v[168:169], s[6:7], v166, s35, v[156:157]
	global_store_short v[168:169], v167, off

; DEV bf16_t f2bf(float f) { return (bf16_t)(cvtpk(f, 0.f) & 0xffffu); }
;   DEV void operator()(f32x16 (&acc)[2][2], int mb, int nb, int r32, int hh) const {
;     ...
; #pragma unroll
;     for (int mi = 0; mi < 2; ++mi)
; #pragma unroll
;       for (int ni = 0; ni < 2; ++ni)
; #pragma unroll
;         for (int r = 0; r < 16; ++r) {
;           int row = mb + mi * 32 + 8 * (r >> 2) + 4 * hh + (r & 3);
;           int c = wn64 + ni * 32 + r32;
;           float v = acc[mi][ni][r];
;           if (dcol >= 0) PR[(size_t)row * PR_LD + dcol + c] = f2bf(v);
;           if (dcol2 >= 0) {
;             float o = v;
;             if (rope == 1) {
;               if (wn64 == 0 && ni == 0) {
;                 float pv = __shfl_xor(v, 16);
;                 float2 cs = ropeH[(row & 4095) * 16 + (r32 & 15)];
;                 o = (r32 < 16) ? (v * cs.x - pv * cs.y) : (v * cs.x + pv * cs.y);
;               }
;             } else if (rope == 2) {
;               if (ni == 0) {
;                 float pv = __shfl_xor(v, 8);
;                 float2 cs = ropeD[(row & 4095) * 8 + (r32 & 7)];
;                 float rr = ((r32 & 8) == 0) ? (v * cs.x - pv * cs.y) : (v * cs.x + pv * cs.y);
;                 o = (r32 < 16) ? rr : v;
;               }
;             }
;             PR[(size_t)row * PR_LD + dcol2 + c] = f2bf(o);
;           }
.LBB0_1078:
	s_and_b64 vcc, exec, s[14:15]
	v_or_b32_e32 v167, 51, v154
	s_cbranch_vccnz .LBB0_1080
	v_cvt_pk_bf16_f32 v170, v93, s0
	v_mad_i64_i32 v[168:169], s[6:7], v167, s35, v[156:157]
	global_store_short v[168:169], v170, off

; DEV bf16_t f2bf(float f) { return (bf16_t)(cvtpk(f, 0.f) & 0xffffu); }
;   DEV void operator()(f32x16 (&acc)[2][2], int mb, int nb, int r32, int hh) const {
;     ...
; #pragma unroll
;     for (int mi = 0; mi < 2; ++mi)
; #pragma unroll
;       for (int ni = 0; ni < 2; ++ni)
; #pragma unroll
;         for (int r = 0; r < 16; ++r) {
;           int row = mb + mi * 32 + 8 * (r >> 2) + 4 * hh + (r & 3);
;           int c = wn64 + ni * 32 + r32;
;           float v = acc[mi][ni][r];
;           if (dcol >= 0) PR[(size_t)row * PR_LD + dcol + c] = f2bf(v);
;           if (dcol2 >= 0) {
;             float o = v;
;             if (rope == 1) {
;               if (wn64 == 0 && ni == 0) {
;                 float pv = __shfl_xor(v, 16);
;                 float2 cs = ropeH[(row & 4095) * 16 + (r32 & 15)];
;                 o = (r32 < 16) ? (v * cs.x - pv * cs.y) : (v * cs.x + pv * cs.y);
;               }
;             } else if (rope == 2) {
;               if (ni == 0) {
;                 float pv = __shfl_xor(v, 8);
;                 float2 cs = ropeD[(row & 4095) * 8 + (r32 & 7)];
;                 float rr = ((r32 & 8) == 0) ? (v * cs.x - pv * cs.y) : (v * cs.x + pv * cs.y);
;                 o = (r32 < 16) ? rr : v;
;               }
;             }
;             PR[(size_t)row * PR_LD + dcol2 + c] = f2bf(o);
;           }
.LBB0_1089:
	s_and_b64 vcc, exec, s[14:15]
	v_or_b32_e32 v168, 56, v154
	s_cbranch_vccnz .LBB0_1091
	v_cvt_pk_bf16_f32 v169, v94, s0
	v_mad_i64_i32 v[170:171], s[6:7], v168, s35, v[156:157]
	global_store_short v[170:171], v169, off

; DEV bf16_t f2bf(float f) { return (bf16_t)(cvtpk(f, 0.f) & 0xffffu); }
;   DEV void operator()(f32x16 (&acc)[2][2], int mb, int nb, int r32, int hh) const {
;     ...
; #pragma unroll
;     for (int mi = 0; mi < 2; ++mi)
; #pragma unroll
;       for (int ni = 0; ni < 2; ++ni)
; #pragma unroll
;         for (int r = 0; r < 16; ++r) {
;           int row = mb + mi * 32 + 8 * (r >> 2) + 4 * hh + (r & 3);
;           int c = wn64 + ni * 32 + r32;
;           float v = acc[mi][ni][r];
;           if (dcol >= 0) PR[(size_t)row * PR_LD + dcol + c] = f2bf(v);
;           if (dcol2 >= 0) {
;             float o = v;
;             if (rope == 1) {
;               if (wn64 == 0 && ni == 0) {
;                 float pv = __shfl_xor(v, 16);
;                 float2 cs = ropeH[(row & 4095) * 16 + (r32 & 15)];
;                 o = (r32 < 16) ? (v * cs.x - pv * cs.y) : (v * cs.x + pv * cs.y);
;               }
;             } else if (rope == 2) {
;               if (ni == 0) {
;                 float pv = __shfl_xor(v, 8);
;                 float2 cs = ropeD[(row & 4095) * 8 + (r32 & 7)];
;                 float rr = ((r32 & 8) == 0) ? (v * cs.x - pv * cs.y) : (v * cs.x + pv * cs.y);
;                 o = (r32 < 16) ? rr : v;
;               }
;             }
;             PR[(size_t)row * PR_LD + dcol2 + c] = f2bf(o);
;           }
.LBB0_1100:
	s_and_b64 vcc, exec, s[14:15]
	v_or_b32_e32 v169, 57, v154
	s_cbranch_vccnz .LBB0_1102
	v_cvt_pk_bf16_f32 v172, v95, s0
	v_mad_i64_i32 v[170:171], s[6:7], v169, s35, v[156:157]
	global_store_short v[170:171], v172, off

; DEV bf16_t f2bf(float f) { return (bf16_t)(cvtpk(f, 0.f) & 0xffffu); }
;   DEV void operator()(f32x16 (&acc)[2][2], int mb, int nb, int r32, int hh) const {
;     ...
; #pragma unroll
;     for (int mi = 0; mi < 2; ++mi)
; #pragma unroll
;       for (int ni = 0; ni < 2; ++ni)
; #pragma unroll
;         for (int r = 0; r < 16; ++r) {
;           int row = mb + mi * 32 + 8 * (r >> 2) + 4 * hh + (r & 3);
;           int c = wn64 + ni * 32 + r32;
;           float v = acc[mi][ni][r];
;           if (dcol >= 0) PR[(size_t)row * PR_LD + dcol + c] = f2bf(v);
;           if (dcol2 >= 0) {
;             float o = v;
;             if (rope == 1) {
;               if (wn64 == 0 && ni == 0) {
;                 float pv = __shfl_xor(v, 16);
;                 float2 cs = ropeH[(row & 4095) * 16 + (r32 & 15)];
;                 o = (r32 < 16) ? (v * cs.x - pv * cs.y) : (v * cs.x + pv * cs.y);
;               }
;             } else if (rope == 2) {
;               if (ni == 0) {
;                 float pv = __shfl_xor(v, 8);
;                 float2 cs = ropeD[(row & 4095) * 8 + (r32 & 7)];
;                 float rr = ((r32 & 8) == 0) ? (v * cs.x - pv * cs.y) : (v * cs.x + pv * cs.y);
;                 o = (r32 < 16) ? rr : v;
;               }
;             }
;             PR[(size_t)row * PR_LD + dcol2 + c] = f2bf(o);
;           }
.LBB0_1111:
	s_and_b64 vcc, exec, s[14:15]
	v_or_b32_e32 v170, 58, v154
	s_cbranch_vccnz .LBB0_1113
	v_cvt_pk_bf16_f32 v171, v96, s0
	v_mad_i64_i32 v[172:173], s[6:7], v170, s35, v[156:157]
	global_store_short v[172:173], v171, off

; DEV bf16_t f2bf(float f) { return (bf16_t)(cvtpk(f, 0.f) & 0xffffu); }
;   DEV void operator()(f32x16 (&acc)[2][2], int mb, int nb, int r32, int hh) const {
;     ...
; #pragma unroll
;     for (int mi = 0; mi < 2; ++mi)
; #pragma unroll
;       for (int ni = 0; ni < 2; ++ni)
; #pragma unroll
;         for (int r = 0; r < 16; ++r) {
;           int row = mb + mi * 32 + 8 * (r >> 2) + 4 * hh + (r & 3);
;           int c = wn64 + ni * 32 + r32;
;           float v = acc[mi][ni][r];
;           if (dcol >= 0) PR[(size_t)row * PR_LD + dcol + c] = f2bf(v);
;           if (dcol2 >= 0) {
;             float o = v;
;             if (rope == 1) {
;               if (wn64 == 0 && ni == 0) {
;                 float pv = __shfl_xor(v, 16);
;                 float2 cs = ropeH[(row & 4095) * 16 + (r32 & 15)];
;                 o = (r32 < 16) ? (v * cs.x - pv * cs.y) : (v * cs.x + pv * cs.y);
;               }
;             } else if (rope == 2) {
;               if (ni == 0) {
;                 float pv = __shfl_xor(v, 8);
;                 float2 cs = ropeD[(row & 4095) * 8 + (r32 & 7)];
;                 float rr = ((r32 & 8) == 0) ? (v * cs.x - pv * cs.y) : (v * cs.x + pv * cs.y);
;                 o = (r32 < 16) ? rr : v;
;               }
;             }
;             PR[(size_t)row * PR_LD + dcol2 + c] = f2bf(o);
;           }
.LBB0_1122:
	s_and_b64 vcc, exec, s[14:15]
	v_or_b32_e32 v171, 59, v154
	s_cbranch_vccnz .LBB0_1124
	v_cvt_pk_bf16_f32 v174, v97, s0
	v_mad_i64_i32 v[172:173], s[6:7], v171, s35, v[156:157]
	global_store_short v[172:173], v174, off

; DEV bf16_t f2bf(float f) { return (bf16_t)(cvtpk(f, 0.f) & 0xffffu); }
;   DEV void operator()(f32x16 (&acc)[2][2], int mb, int nb, int r32, int hh) const {
;     ...
; #pragma unroll
;     for (int mi = 0; mi < 2; ++mi)
; #pragma unroll
;       for (int ni = 0; ni < 2; ++ni)
; #pragma unroll
;         for (int r = 0; r < 16; ++r) {
;           int row = mb + mi * 32 + 8 * (r >> 2) + 4 * hh + (r & 3);
;           int c = wn64 + ni * 32 + r32;
;           float v = acc[mi][ni][r];
;           if (dcol >= 0) PR[(size_t)row * PR_LD + dcol + c] = f2bf(v);
;           if (dcol2 >= 0) {
;             float o = v;
;             if (rope == 1) {
;               if (wn64 == 0 && ni == 0) {
;                 float pv = __shfl_xor(v, 16);
;                 float2 cs = ropeH[(row & 4095) * 16 + (r32 & 15)];
;                 o = (r32 < 16) ? (v * cs.x - pv * cs.y) : (v * cs.x + pv * cs.y);
;               }
;             } else if (rope == 2) {
;               if (ni == 0) {
;                 float pv = __shfl_xor(v, 8);
;                 float2 cs = ropeD[(row & 4095) * 8 + (r32 & 7)];
;                 float rr = ((r32 & 8) == 0) ? (v * cs.x - pv * cs.y) : (v * cs.x + pv * cs.y);
;                 o = (r32 < 16) ? rr : v;
;               }
;             }
;             PR[(size_t)row * PR_LD + dcol2 + c] = f2bf(o);
;           }
.LBB0_1132:
	v_cvt_pk_bf16_f32 v174, v172, s0
	v_mad_i64_i32 v[172:173], s[6:7], v171, s35, v[158:159]
	global_store_short v[172:173], v174, off
.LBB0_1133:
	s_and_b64 vcc, exec, s[14:15]
	s_cbranch_vccnz .LBB0_1135
	v_cvt_pk_bf16_f32 v174, v66, s0
	v_mad_i64_i32 v[172:173], s[6:7], v145, s35, v[156:157]
	global_store_short v[172:173], v174, off offset:64
.LBB0_1135:
	s_and_b64 vcc, exec, s[16:17]
	s_cbranch_vccnz .LBB0_1137
	v_cvt_pk_bf16_f32 v174, v66, s0
	v_mad_i64_i32 v[172:173], s[6:7], v145, s35, v[158:159]
	global_store_short v[172:173], v174, off offset:64
.LBB0_1137:
	s_and_b64 vcc, exec, s[14:15]
	s_cbranch_vccnz .LBB0_1139
	v_cvt_pk_bf16_f32 v145, v67, s0
	v_mad_i64_i32 v[172:173], s[6:7], v147, s35, v[156:157]
	global_store_short v[172:173], v145, off offset:64
.LBB0_1139:
	s_and_b64 vcc, exec, s[16:17]
	s_cbranch_vccnz .LBB0_1141
	v_cvt_pk_bf16_f32 v145, v67, s0
	v_mad_i64_i32 v[172:173], s[6:7], v147, s35, v[158:159]
	global_store_short v[172:173], v145, off offset:64
.LBB0_1141:
	s_and_b64 vcc, exec, s[14:15]
	s_cbranch_vccnz .LBB0_1143
	v_cvt_pk_bf16_f32 v145, v68, s0
	v_mad_i64_i32 v[172:173], s[6:7], v149, s35, v[156:157]
	global_store_short v[172:173], v145, off offset:64
.LBB0_1143:
	s_and_b64 vcc, exec, s[16:17]
	s_cbranch_vccnz .LBB0_1145
	v_cvt_pk_bf16_f32 v145, v68, s0
	v_mad_i64_i32 v[172:173], s[6:7], v149, s35, v[158:159]
	global_store_short v[172:173], v145, off offset:64
.LBB0_1145:
	s_and_b64 vcc, exec, s[14:15]
	s_cbranch_vccnz .LBB0_1147
	v_cvt_pk_bf16_f32 v145, v69, s0
	v_mad_i64_i32 v[172:173], s[6:7], v155, s35, v[156:157]
	global_store_short v[172:173], v145, off offset:64
.LBB0_1147:
	s_and_b64 vcc, exec, s[16:17]
	s_cbranch_vccnz .LBB0_1149
	v_cvt_pk_bf16_f32 v145, v69, s0
	v_mad_i64_i32 v[172:173], s[6:7], v155, s35, v[158:159]
	global_store_short v[172:173], v145, off offset:64
.LBB0_1149:
	s_and_b64 vcc, exec, s[14:15]
	s_cbranch_vccnz .LBB0_1151
	v_cvt_pk_bf16_f32 v145, v70, s0
	v_mad_i64_i32 v[172:173], s[6:7], v160, s35, v[156:157]
	global_store_short v[172:173], v145, off offset:64
.LBB0_1151:
	s_and_b64 vcc, exec, s[16:17]
	s_cbranch_vccnz .LBB0_1153
	v_cvt_pk_bf16_f32 v145, v70, s0
	v_mad_i64_i32 v[172:173], s[6:7], v160, s35, v[158:159]
	global_store_short v[172:173], v145, off offset:64
.LBB0_1153:
	s_and_b64 vcc, exec, s[14:15]
	s_cbranch_vccnz .LBB0_1155
	v_cvt_pk_bf16_f32 v145, v71, s0
	v_mad_i64_i32 v[172:173], s[6:7], v161, s35, v[156:157]
	global_store_short v[172:173], v145, off offset:64
.LBB0_1155:
	s_and_b64 vcc, exec, s[16:17]
	s_cbranch_vccnz .LBB0_1157
	v_cvt_pk_bf16_f32 v145, v71, s0
	v_mad_i64_i32 v[160:161], s[6:7], v161, s35, v[158:159]
	global_store_short v[160:161], v145, off offset:64
.LBB0_1157:
	s_and_b64 vcc, exec, s[14:15]
	s_cbranch_vccnz .LBB0_1159
	v_cvt_pk_bf16_f32 v145, v72, s0
	v_mad_i64_i32 v[160:161], s[6:7], v162, s35, v[156:157]
	global_store_short v[160:161], v145, off offset:64
.LBB0_1159:
	s_and_b64 vcc, exec, s[16:17]
	s_cbranch_vccnz .LBB0_1161
	v_cvt_pk_bf16_f32 v145, v72, s0
	v_mad_i64_i32 v[160:161], s[6:7], v162, s35, v[158:159]
	global_store_short v[160:161], v145, off offset:64
.LBB0_1161:
	s_and_b64 vcc, exec, s[14:15]
	s_cbranch_vccnz .LBB0_1163
	v_cvt_pk_bf16_f32 v145, v73, s0
	v_mad_i64_i32 v[160:161], s[6:7], v163, s35, v[156:157]
	global_store_short v[160:161], v145, off offset:64
.LBB0_1163:
	s_and_b64 vcc, exec, s[16:17]
	s_cbranch_vccnz .LBB0_1165
	v_cvt_pk_bf16_f32 v145, v73, s0
	v_mad_i64_i32 v[160:161], s[6:7], v163, s35, v[158:159]
	global_store_short v[160:161], v145, off offset:64
.LBB0_1165:
	s_and_b64 vcc, exec, s[14:15]
	s_cbranch_vccnz .LBB0_1167
	v_cvt_pk_bf16_f32 v145, v74, s0
	v_mad_i64_i32 v[160:161], s[6:7], v164, s35, v[156:157]
	global_store_short v[160:161], v145, off offset:64
.LBB0_1167:
	s_and_b64 vcc, exec, s[16:17]
	s_cbranch_vccnz .LBB0_1169
	v_cvt_pk_bf16_f32 v145, v74, s0
	v_mad_i64_i32 v[160:161], s[6:7], v164, s35, v[158:159]
	global_store_short v[160:161], v145, off offset:64
.LBB0_1169:
	s_and_b64 vcc, exec, s[14:15]
	s_cbranch_vccnz .LBB0_1171
	v_cvt_pk_bf16_f32 v145, v75, s0
	v_mad_i64_i32 v[160:161], s[6:7], v165, s35, v[156:157]
	global_store_short v[160:161], v145, off offset:64
.LBB0_1171:
	s_and_b64 vcc, exec, s[16:17]
	s_cbranch_vccnz .LBB0_1173
	v_cvt_pk_bf16_f32 v145, v75, s0
	v_mad_i64_i32 v[160:161], s[6:7], v165, s35, v[158:159]
	global_store_short v[160:161], v145, off offset:64
.LBB0_1173:
	s_and_b64 vcc, exec, s[14:15]
	s_cbranch_vccnz .LBB0_1175
	v_cvt_pk_bf16_f32 v145, v76, s0
	v_mad_i64_i32 v[160:161], s[6:7], v166, s35, v[156:157]
	global_store_short v[160:161], v145, off offset:64
.LBB0_1175:
	s_and_b64 vcc, exec, s[16:17]
	s_cbranch_vccnz .LBB0_1177
	v_cvt_pk_bf16_f32 v145, v76, s0
	v_mad_i64_i32 v[160:161], s[6:7], v166, s35, v[158:159]
	global_store_short v[160:161], v145, off offset:64
.LBB0_1177:
	s_and_b64 vcc, exec, s[14:15]
	s_cbranch_vccnz .LBB0_1179
	v_cvt_pk_bf16_f32 v145, v77, s0
	v_mad_i64_i32 v[160:161], s[6:7], v167, s35, v[156:157]
	global_store_short v[160:161], v145, off offset:64
.LBB0_1179:
	s_and_b64 vcc, exec, s[16:17]
	s_cbranch_vccnz .LBB0_1181
	v_cvt_pk_bf16_f32 v145, v77, s0
	v_mad_i64_i32 v[160:161], s[6:7], v167, s35, v[158:159]
	global_store_short v[160:161], v145, off offset:64
.LBB0_1181:
	s_and_b64 vcc, exec, s[14:15]
	s_cbranch_vccnz .LBB0_1183
	v_cvt_pk_bf16_f32 v145, v78, s0
	v_mad_i64_i32 v[160:161], s[6:7], v168, s35, v[156:157]
	global_store_short v[160:161], v145, off offset:64
.LBB0_1183:
	s_and_b64 vcc, exec, s[16:17]
	s_cbranch_vccnz .LBB0_1185
	v_cvt_pk_bf16_f32 v145, v78, s0
	v_mad_i64_i32 v[160:161], s[6:7], v168, s35, v[158:159]
	global_store_short v[160:161], v145, off offset:64
.LBB0_1185:
	s_and_b64 vcc, exec, s[14:15]
	s_cbranch_vccnz .LBB0_1187
	v_cvt_pk_bf16_f32 v145, v79, s0
	v_mad_i64_i32 v[160:161], s[6:7], v169, s35, v[156:157]
	global_store_short v[160:161], v145, off offset:64
.LBB0_1187:
	s_and_b64 vcc, exec, s[16:17]
	s_cbranch_vccnz .LBB0_1189
	v_cvt_pk_bf16_f32 v145, v79, s0
	v_mad_i64_i32 v[160:161], s[6:7], v169, s35, v[158:159]
	global_store_short v[160:161], v145, off offset:64
.LBB0_1189:
	s_and_b64 vcc, exec, s[14:15]
	s_cbranch_vccnz .LBB0_1191
	v_cvt_pk_bf16_f32 v145, v80, s0
	v_mad_i64_i32 v[160:161], s[6:7], v170, s35, v[156:157]
	global_store_short v[160:161], v145, off offset:64
.LBB0_1191:
	s_and_b64 vcc, exec, s[16:17]
	s_cbranch_vccnz .LBB0_1193
	v_cvt_pk_bf16_f32 v145, v80, s0
	v_mad_i64_i32 v[160:161], s[6:7], v170, s35, v[158:159]
	global_store_short v[160:161], v145, off offset:64
.LBB0_1193:
	s_and_b64 vcc, exec, s[14:15]
	s_cbranch_vccnz .LBB0_1195
	v_cvt_pk_bf16_f32 v145, v81, s0
	v_mad_i64_i32 v[156:157], s[6:7], v171, s35, v[156:157]
	global_store_short v[156:157], v145, off offset:64
.LBB0_1195:
	s_and_b64 vcc, exec, s[16:17]
	s_cbranch_vccnz .LBB0_1197
	v_cvt_pk_bf16_f32 v145, v81, s0
	v_mad_i64_i32 v[156:157], s[6:7], v171, s35, v[158:159]
	global_store_short v[156:157], v145, off offset:64

; DEV bf16_t f2bf(float f) { return (bf16_t)(cvtpk(f, 0.f) & 0xffffu); }
;   DEV void operator()(f32x16 (&acc)[2][2], int mb, int nb, int r32, int hh) const {
;     ...
;     if (kind == 1) {
; #pragma unroll
;       for (int mi = 0; mi < 2; ++mi)
; #pragma unroll
;         for (int ni = 0; ni < 2; ++ni)
; #pragma unroll
;           for (int r = 0; r < 16; ++r) {
;             int row = mb + mi * 32 + 8 * (r >> 2) + 4 * hh + (r & 3);
;             cbuf[(size_t)row * 128 + wn64 + ni * 32 + r32] = f2bf(acc[mi][ni][r]);
;           }
;       return;
;     }
.LBB0_1198:
	s_and_b64 vcc, exec, s[6:7]
	s_cbranch_vccz .LBB0_1200
	s_lshl_b32 s6, s61, 1
	s_add_u32 s6, s84, s6
	s_addc_u32 s7, s85, 0
	v_ashrrev_i32_e32 v155, 31, v154
	v_or_b32_e32 v160, 1, v154
	v_lshl_add_u64 v[156:157], v[152:153], 1, s[6:7]
	v_lshlrev_b64 v[158:159], 8, v[154:155]
	v_ashrrev_i32_e32 v161, 31, v160
	v_or_b32_e32 v162, 2, v154
	v_cvt_pk_bf16_f32 v145, v114, s0
	v_lshl_add_u64 v[158:159], v[156:157], 0, v[158:159]
	v_lshlrev_b64 v[160:161], 8, v[160:161]
	v_ashrrev_i32_e32 v163, 31, v162
	v_or_b32_e32 v164, 3, v154
	global_store_short v[158:159], v145, off
	v_cvt_pk_bf16_f32 v145, v115, s0
	v_lshl_add_u64 v[160:161], v[156:157], 0, v[160:161]
	v_lshlrev_b64 v[162:163], 8, v[162:163]
	v_ashrrev_i32_e32 v165, 31, v164
	v_or_b32_e32 v166, 8, v154
	global_store_short v[160:161], v145, off
	v_cvt_pk_bf16_f32 v145, v116, s0
	v_lshl_add_u64 v[162:163], v[156:157], 0, v[162:163]
	v_lshlrev_b64 v[164:165], 8, v[164:165]
	v_ashrrev_i32_e32 v167, 31, v166
	v_or_b32_e32 v168, 9, v154
	global_store_short v[162:163], v145, off
	v_cvt_pk_bf16_f32 v145, v117, s0
	v_lshl_add_u64 v[164:165], v[156:157], 0, v[164:165]
	v_lshlrev_b64 v[166:167], 8, v[166:167]
	v_ashrrev_i32_e32 v169, 31, v168
	v_or_b32_e32 v170, 10, v154
	global_store_short v[164:165], v145, off
	v_cvt_pk_bf16_f32 v145, v118, s0
	v_lshl_add_u64 v[166:167], v[156:157], 0, v[166:167]
	v_lshlrev_b64 v[168:169], 8, v[168:169]
	v_ashrrev_i32_e32 v171, 31, v170
	v_or_b32_e32 v172, 11, v154
	global_store_short v[166:167], v145, off
	v_cvt_pk_bf16_f32 v145, v119, s0
	v_lshl_add_u64 v[168:169], v[156:157], 0, v[168:169]
	v_lshlrev_b64 v[170:171], 8, v[170:171]
	v_ashrrev_i32_e32 v173, 31, v172
	v_or_b32_e32 v174, 16, v154
	global_store_short v[168:169], v145, off
	v_cvt_pk_bf16_f32 v145, v120, s0
	v_lshl_add_u64 v[170:171], v[156:157], 0, v[170:171]
	v_lshlrev_b64 v[172:173], 8, v[172:173]
	v_ashrrev_i32_e32 v175, 31, v174
	v_or_b32_e32 v176, 17, v154
	global_store_short v[170:171], v145, off
	v_cvt_pk_bf16_f32 v145, v121, s0
	v_lshl_add_u64 v[172:173], v[156:157], 0, v[172:173]
	v_lshlrev_b64 v[174:175], 8, v[174:175]
	v_ashrrev_i32_e32 v177, 31, v176
	v_or_b32_e32 v178, 18, v154
	global_store_short v[172:173], v145, off
	v_cvt_pk_bf16_f32 v145, v122, s0
	v_lshl_add_u64 v[174:175], v[156:157], 0, v[174:175]
	v_lshlrev_b64 v[176:177], 8, v[176:177]
	v_ashrrev_i32_e32 v179, 31, v178
	v_or_b32_e32 v180, 19, v154
	global_store_short v[174:175], v145, off
	v_cvt_pk_bf16_f32 v145, v123, s0
	v_lshl_add_u64 v[176:177], v[156:157], 0, v[176:177]
	v_lshlrev_b64 v[178:179], 8, v[178:179]
	v_ashrrev_i32_e32 v181, 31, v180
	v_or_b32_e32 v182, 24, v154
	global_store_short v[176:177], v145, off
	v_cvt_pk_bf16_f32 v145, v124, s0
	v_lshl_add_u64 v[178:179], v[156:157], 0, v[178:179]
	v_lshlrev_b64 v[180:181], 8, v[180:181]
	v_ashrrev_i32_e32 v183, 31, v182
	v_or_b32_e32 v184, 25, v154
	global_store_short v[178:179], v145, off
	v_cvt_pk_bf16_f32 v145, v125, s0
	v_lshl_add_u64 v[180:181], v[156:157], 0, v[180:181]
	v_lshlrev_b64 v[182:183], 8, v[182:183]
	v_ashrrev_i32_e32 v185, 31, v184
	v_or_b32_e32 v186, 26, v154
	global_store_short v[180:181], v145, off
	v_cvt_pk_bf16_f32 v145, v126, s0
	v_lshl_add_u64 v[182:183], v[156:157], 0, v[182:183]
	v_lshlrev_b64 v[184:185], 8, v[184:185]
	v_ashrrev_i32_e32 v187, 31, v186
	v_or_b32_e32 v188, 27, v154
	global_store_short v[182:183], v145, off
	v_cvt_pk_bf16_f32 v145, v127, s0
	v_lshl_add_u64 v[184:185], v[156:157], 0, v[184:185]
	v_lshlrev_b64 v[186:187], 8, v[186:187]
	v_ashrrev_i32_e32 v189, 31, v188
	global_store_short v[184:185], v145, off
	v_cvt_pk_bf16_f32 v145, v128, s0
	v_lshl_add_u64 v[186:187], v[156:157], 0, v[186:187]
	v_lshlrev_b64 v[188:189], 8, v[188:189]
	global_store_short v[186:187], v145, off
	v_cvt_pk_bf16_f32 v145, v129, s0
	v_lshl_add_u64 v[188:189], v[156:157], 0, v[188:189]
	global_store_short v[188:189], v145, off
	v_cvt_pk_bf16_f32 v145, v98, s0
	global_store_short v[158:159], v145, off offset:64
	v_cvt_pk_bf16_f32 v145, v99, s0
	global_store_short v[160:161], v145, off offset:64
	v_cvt_pk_bf16_f32 v145, v100, s0
	global_store_short v[162:163], v145, off offset:64
	v_cvt_pk_bf16_f32 v145, v101, s0
	global_store_short v[164:165], v145, off offset:64
	v_cvt_pk_bf16_f32 v145, v102, s0
	global_store_short v[166:167], v145, off offset:64
	v_cvt_pk_bf16_f32 v145, v103, s0
	global_store_short v[168:169], v145, off offset:64
	v_cvt_pk_bf16_f32 v145, v104, s0
	global_store_short v[170:171], v145, off offset:64
	v_cvt_pk_bf16_f32 v145, v105, s0
	global_store_short v[172:173], v145, off offset:64
	v_cvt_pk_bf16_f32 v145, v106, s0
	global_store_short v[174:175], v145, off offset:64
	v_cvt_pk_bf16_f32 v145, v107, s0
	global_store_short v[176:177], v145, off offset:64
	v_cvt_pk_bf16_f32 v145, v108, s0
	global_store_short v[178:179], v145, off offset:64
	v_cvt_pk_bf16_f32 v145, v109, s0
	global_store_short v[180:181], v145, off offset:64
	v_cvt_pk_bf16_f32 v145, v110, s0
	global_store_short v[182:183], v145, off offset:64
	v_cvt_pk_bf16_f32 v145, v111, s0
	v_or_b32_e32 v158, 32, v154
	global_store_short v[184:185], v145, off offset:64
	v_cvt_pk_bf16_f32 v145, v112, s0
; DEV bf16_t f2bf(float f) { return (bf16_t)(cvtpk(f, 0.f) & 0xffffu); }
;   DEV void operator()(f32x16 (&acc)[2][2], int mb, int nb, int r32, int hh) const {
;     ...
;     if (kind == 1) {
; #pragma unroll
;       for (int mi = 0; mi < 2; ++mi)
; #pragma unroll
;         for (int ni = 0; ni < 2; ++ni)
; #pragma unroll
;           for (int r = 0; r < 16; ++r) {
;             int row = mb + mi * 32 + 8 * (r >> 2) + 4 * hh + (r & 3);
;             cbuf[(size_t)row * 128 + wn64 + ni * 32 + r32] = f2bf(acc[mi][ni][r]);
;           }
;       return;
;     }
	v_ashrrev_i32_e32 v159, 31, v158
	v_or_b32_e32 v160, 33, v154
	global_store_short v[186:187], v145, off offset:64
	v_cvt_pk_bf16_f32 v145, v113, s0
	v_lshlrev_b64 v[158:159], 8, v[158:159]
	v_ashrrev_i32_e32 v161, 31, v160
	v_or_b32_e32 v162, 34, v154
	global_store_short v[188:189], v145, off offset:64
	v_cvt_pk_bf16_f32 v145, v82, s0
	v_lshl_add_u64 v[158:159], v[156:157], 0, v[158:159]
	v_lshlrev_b64 v[160:161], 8, v[160:161]
	v_ashrrev_i32_e32 v163, 31, v162
	v_or_b32_e32 v164, 35, v154
	global_store_short v[158:159], v145, off
	v_cvt_pk_bf16_f32 v145, v83, s0
	v_lshl_add_u64 v[160:161], v[156:157], 0, v[160:161]
	v_lshlrev_b64 v[162:163], 8, v[162:163]
	v_ashrrev_i32_e32 v165, 31, v164
	v_or_b32_e32 v166, 40, v154
	global_store_short v[160:161], v145, off
	v_cvt_pk_bf16_f32 v145, v84, s0
	v_lshl_add_u64 v[162:163], v[156:157], 0, v[162:163]
	v_lshlrev_b64 v[164:165], 8, v[164:165]
	v_ashrrev_i32_e32 v167, 31, v166
	v_or_b32_e32 v168, 41, v154
	global_store_short v[162:163], v145, off
	v_cvt_pk_bf16_f32 v145, v85, s0
	v_lshl_add_u64 v[164:165], v[156:157], 0, v[164:165]
	v_lshlrev_b64 v[166:167], 8, v[166:167]
	v_ashrrev_i32_e32 v169, 31, v168
	v_or_b32_e32 v170, 42, v154
	global_store_short v[164:165], v145, off
	v_cvt_pk_bf16_f32 v145, v86, s0
	v_lshl_add_u64 v[166:167], v[156:157], 0, v[166:167]
	v_lshlrev_b64 v[168:169], 8, v[168:169]
	v_ashrrev_i32_e32 v171, 31, v170
	v_or_b32_e32 v172, 43, v154
	global_store_short v[166:167], v145, off
	v_cvt_pk_bf16_f32 v145, v87, s0
	v_lshl_add_u64 v[168:169], v[156:157], 0, v[168:169]
	v_lshlrev_b64 v[170:171], 8, v[170:171]
	v_ashrrev_i32_e32 v173, 31, v172
	v_or_b32_e32 v174, 48, v154
	global_store_short v[168:169], v145, off
	v_cvt_pk_bf16_f32 v145, v88, s0
	v_lshl_add_u64 v[170:171], v[156:157], 0, v[170:171]
	v_lshlrev_b64 v[172:173], 8, v[172:173]
	v_ashrrev_i32_e32 v175, 31, v174
	v_or_b32_e32 v176, 49, v154
	global_store_short v[170:171], v145, off
	v_cvt_pk_bf16_f32 v145, v89, s0
	v_lshl_add_u64 v[172:173], v[156:157], 0, v[172:173]
	v_lshlrev_b64 v[174:175], 8, v[174:175]
	v_ashrrev_i32_e32 v177, 31, v176
	v_or_b32_e32 v178, 50, v154
	global_store_short v[172:173], v145, off
	v_cvt_pk_bf16_f32 v145, v90, s0
	v_lshl_add_u64 v[174:175], v[156:157], 0, v[174:175]
	v_lshlrev_b64 v[176:177], 8, v[176:177]
	v_ashrrev_i32_e32 v179, 31, v178
	v_or_b32_e32 v180, 51, v154
	global_store_short v[174:175], v145, off
	v_cvt_pk_bf16_f32 v145, v91, s0
	v_lshl_add_u64 v[176:177], v[156:157], 0, v[176:177]
	v_lshlrev_b64 v[178:179], 8, v[178:179]
	v_ashrrev_i32_e32 v181, 31, v180
	v_or_b32_e32 v182, 56, v154
	global_store_short v[176:177], v145, off
	v_cvt_pk_bf16_f32 v145, v92, s0
	v_lshl_add_u64 v[178:179], v[156:157], 0, v[178:179]
	v_lshlrev_b64 v[180:181], 8, v[180:181]
	v_ashrrev_i32_e32 v183, 31, v182
	v_or_b32_e32 v184, 57, v154
	global_store_short v[178:179], v145, off
	v_cvt_pk_bf16_f32 v145, v93, s0
	v_lshl_add_u64 v[180:181], v[156:157], 0, v[180:181]
	v_lshlrev_b64 v[182:183], 8, v[182:183]
	v_ashrrev_i32_e32 v185, 31, v184
	v_or_b32_e32 v186, 58, v154
	global_store_short v[180:181], v145, off
	v_cvt_pk_bf16_f32 v145, v94, s0
	v_lshl_add_u64 v[182:183], v[156:157], 0, v[182:183]
	v_lshlrev_b64 v[184:185], 8, v[184:185]
	v_ashrrev_i32_e32 v187, 31, v186
	v_or_b32_e32 v154, 59, v154
	global_store_short v[182:183], v145, off
	v_cvt_pk_bf16_f32 v145, v95, s0
	v_lshl_add_u64 v[184:185], v[156:157], 0, v[184:185]
	v_lshlrev_b64 v[186:187], 8, v[186:187]
	v_ashrrev_i32_e32 v155, 31, v154
	global_store_short v[184:185], v145, off
	v_cvt_pk_bf16_f32 v145, v96, s0
	v_lshl_add_u64 v[186:187], v[156:157], 0, v[186:187]
	v_lshlrev_b64 v[154:155], 8, v[154:155]
	global_store_short v[186:187], v145, off
	v_cvt_pk_bf16_f32 v145, v97, s0
	v_lshl_add_u64 v[154:155], v[156:157], 0, v[154:155]
	global_store_short v[154:155], v145, off
	v_cvt_pk_bf16_f32 v145, v66, s0
	global_store_short v[158:159], v145, off offset:64
	v_cvt_pk_bf16_f32 v145, v67, s0
	global_store_short v[160:161], v145, off offset:64
	v_cvt_pk_bf16_f32 v145, v68, s0
	global_store_short v[162:163], v145, off offset:64
	v_cvt_pk_bf16_f32 v145, v69, s0
	global_store_short v[164:165], v145, off offset:64
	v_cvt_pk_bf16_f32 v145, v70, s0
	global_store_short v[166:167], v145, off offset:64
	v_cvt_pk_bf16_f32 v145, v71, s0
	global_store_short v[168:169], v145, off offset:64
	v_cvt_pk_bf16_f32 v145, v72, s0
	global_store_short v[170:171], v145, off offset:64
	v_cvt_pk_bf16_f32 v145, v73, s0
	global_store_short v[172:173], v145, off offset:64
	v_cvt_pk_bf16_f32 v145, v74, s0
	global_store_short v[174:175], v145, off offset:64
	v_cvt_pk_bf16_f32 v145, v75, s0
	global_store_short v[176:177], v145, off offset:64
	v_cvt_pk_bf16_f32 v145, v76, s0
	global_store_short v[178:179], v145, off offset:64
	v_cvt_pk_bf16_f32 v145, v77, s0
	global_store_short v[180:181], v145, off offset:64
	v_cvt_pk_bf16_f32 v145, v78, s0
	global_store_short v[182:183], v145, off offset:64
	v_cvt_pk_bf16_f32 v145, v79, s0
	global_store_short v[184:185], v145, off offset:64
	v_cvt_pk_bf16_f32 v145, v80, s0
	global_store_short v[186:187], v145, off offset:64
	v_cvt_pk_bf16_f32 v145, v81, s0
	global_store_short v[154:155], v145, off offset:64

; DEV bf16_t f2bf(float f) { return (bf16_t)(cvtpk(f, 0.f) & 0xffffu); }
;   DEV void operator()(f32x16 (&acc)[2][2], int mb, int nb, int r32, int hh) const {
;     ...
; #pragma unroll
;     for (int mi = 0; mi < 2; ++mi)
; #pragma unroll
;       for (int ni = 0; ni < 2; ++ni)
; #pragma unroll
;         for (int r = 0; r < 16; ++r) {
;           int row = mb + mi * 32 + 8 * (r >> 2) + 4 * hh + (r & 3);
;           int c = wn64 + ni * 32 + r32;
;           float v = acc[mi][ni][r];
;           if (dcol >= 0) PR[(size_t)row * PR_LD + dcol + c] = f2bf(v);
;           if (dcol2 >= 0) {
;             float o = v;
;             if (rope == 1) {
;               if (wn64 == 0 && ni == 0) {
;                 float pv = __shfl_xor(v, 16);
;                 float2 cs = ropeH[(row & 4095) * 16 + (r32 & 15)];
;                 o = (r32 < 16) ? (v * cs.x - pv * cs.y) : (v * cs.x + pv * cs.y);
;               }
;             } else if (rope == 2) {
;               if (ni == 0) {
;                 float pv = __shfl_xor(v, 8);
;                 float2 cs = ropeD[(row & 4095) * 8 + (r32 & 7)];
;                 float rr = ((r32 & 8) == 0) ? (v * cs.x - pv * cs.y) : (v * cs.x + pv * cs.y);
;                 o = (r32 < 16) ? rr : v;
;               }
;             }
;             PR[(size_t)row * PR_LD + dcol2 + c] = f2bf(o);
;           }
.LBB0_1389:
	v_readlane_b32 s94, v239, 26
	v_readlane_b32 s90, v239, 28
	v_readlane_b32 s95, v239, 27
	v_readlane_b32 s91, v239, 29
	s_and_b64 vcc, exec, s[24:25]
	s_cbranch_vccz .LBB0_525
	s_mov_b64 s[0:1], -1
	s_and_b64 vcc, exec, s[16:17]
	s_cbranch_vccnz .LBB0_1876
	s_xor_b64 s[0:1], s[14:15], -1
	v_or_b32_e32 v66, s28, v1
	s_andn2_b64 vcc, exec, s[0:1]
	s_mov_b64 s[0:1], -1
	s_cbranch_vccnz .LBB0_1873
	s_cmp_gt_i32 s78, -1
	s_mov_b32 s79, s29
	s_cselect_b64 s[0:1], -1, 0
	s_lshl_b64 s[4:5], s[78:79], 1
	s_add_u32 s4, s39, s4
	s_addc_u32 s5, s41, s5
	v_lshlrev_b32_e32 v70, 1, v143
	v_mov_b32_e32 v71, v0
	s_cmp_lt_i32 s78, 0
	v_lshl_add_u64 v[68:69], s[4:5], 0, v[70:71]
	s_cbranch_scc1 .LBB0_1394
	v_cvt_pk_bf16_f32 v67, v50, s0
	v_mad_i64_i32 v[72:73], s[4:5], v66, s35, v[68:69]
	global_store_short v[72:73], v67, off

; DEV bf16_t f2bf(float f) { return (bf16_t)(cvtpk(f, 0.f) & 0xffffu); }
;   DEV void operator()(f32x16 (&acc)[2][2], int mb, int nb, int r32, int hh) const {
;     ...
; #pragma unroll
;     for (int mi = 0; mi < 2; ++mi)
; #pragma unroll
;       for (int ni = 0; ni < 2; ++ni)
; #pragma unroll
;         for (int r = 0; r < 16; ++r) {
;           int row = mb + mi * 32 + 8 * (r >> 2) + 4 * hh + (r & 3);
;           int c = wn64 + ni * 32 + r32;
;           float v = acc[mi][ni][r];
;           if (dcol >= 0) PR[(size_t)row * PR_LD + dcol + c] = f2bf(v);
;           if (dcol2 >= 0) {
;             float o = v;
;             if (rope == 1) {
;               if (wn64 == 0 && ni == 0) {
;                 float pv = __shfl_xor(v, 16);
;                 float2 cs = ropeH[(row & 4095) * 16 + (r32 & 15)];
;                 o = (r32 < 16) ? (v * cs.x - pv * cs.y) : (v * cs.x + pv * cs.y);
;               }
;             } else if (rope == 2) {
;               if (ni == 0) {
;                 float pv = __shfl_xor(v, 8);
;                 float2 cs = ropeD[(row & 4095) * 8 + (r32 & 7)];
;                 float rr = ((r32 & 8) == 0) ? (v * cs.x - pv * cs.y) : (v * cs.x + pv * cs.y);
;                 o = (r32 < 16) ? rr : v;
;               }
;             }
;             PR[(size_t)row * PR_LD + dcol2 + c] = f2bf(o);
;           }
.LBB0_1402:
	v_cvt_pk_bf16_f32 v67, v67, s0
	v_mad_i64_i32 v[72:73], s[2:3], v66, s35, v[70:71]
	global_store_short v[72:73], v67, off
.LBB0_1403:
	v_cndmask_b32_e64 v67, 0, 1, s[0:1]
	v_cmp_ne_u32_e64 s[12:13], 1, v67
	s_andn2_b64 vcc, exec, s[0:1]
	v_or_b32_e32 v67, 1, v66
	s_cbranch_vccnz .LBB0_1405
	v_cvt_pk_bf16_f32 v74, v51, s0
	v_mad_i64_i32 v[72:73], s[0:1], v67, s35, v[68:69]
	global_store_short v[72:73], v74, off

; DEV bf16_t f2bf(float f) { return (bf16_t)(cvtpk(f, 0.f) & 0xffffu); }
;   DEV void operator()(f32x16 (&acc)[2][2], int mb, int nb, int r32, int hh) const {
;     ...
; #pragma unroll
;     for (int mi = 0; mi < 2; ++mi)
; #pragma unroll
;       for (int ni = 0; ni < 2; ++ni)
; #pragma unroll
;         for (int r = 0; r < 16; ++r) {
;           int row = mb + mi * 32 + 8 * (r >> 2) + 4 * hh + (r & 3);
;           int c = wn64 + ni * 32 + r32;
;           float v = acc[mi][ni][r];
;           if (dcol >= 0) PR[(size_t)row * PR_LD + dcol + c] = f2bf(v);
;           if (dcol2 >= 0) {
;             float o = v;
;             if (rope == 1) {
;               if (wn64 == 0 && ni == 0) {
;                 float pv = __shfl_xor(v, 16);
;                 float2 cs = ropeH[(row & 4095) * 16 + (r32 & 15)];
;                 o = (r32 < 16) ? (v * cs.x - pv * cs.y) : (v * cs.x + pv * cs.y);
;               }
;             } else if (rope == 2) {
;               if (ni == 0) {
;                 float pv = __shfl_xor(v, 8);
;                 float2 cs = ropeD[(row & 4095) * 8 + (r32 & 7)];
;                 float rr = ((r32 & 8) == 0) ? (v * cs.x - pv * cs.y) : (v * cs.x + pv * cs.y);
;                 o = (r32 < 16) ? rr : v;
;               }
;             }
;             PR[(size_t)row * PR_LD + dcol2 + c] = f2bf(o);
;           }
.LBB0_1413:
	v_cvt_pk_bf16_f32 v74, v72, s0
	v_mad_i64_i32 v[72:73], s[0:1], v67, s35, v[70:71]
	global_store_short v[72:73], v74, off
.LBB0_1414:
	s_and_b64 vcc, exec, s[12:13]
	v_or_b32_e32 v72, 2, v66
	s_cbranch_vccnz .LBB0_1416
	v_cvt_pk_bf16_f32 v73, v52, s0
	v_mad_i64_i32 v[74:75], s[0:1], v72, s35, v[68:69]
	global_store_short v[74:75], v73, off

; DEV bf16_t f2bf(float f) { return (bf16_t)(cvtpk(f, 0.f) & 0xffffu); }
;   DEV void operator()(f32x16 (&acc)[2][2], int mb, int nb, int r32, int hh) const {
;     ...
; #pragma unroll
;     for (int mi = 0; mi < 2; ++mi)
; #pragma unroll
;       for (int ni = 0; ni < 2; ++ni)
; #pragma unroll
;         for (int r = 0; r < 16; ++r) {
;           int row = mb + mi * 32 + 8 * (r >> 2) + 4 * hh + (r & 3);
;           int c = wn64 + ni * 32 + r32;
;           float v = acc[mi][ni][r];
;           if (dcol >= 0) PR[(size_t)row * PR_LD + dcol + c] = f2bf(v);
;           if (dcol2 >= 0) {
;             float o = v;
;             if (rope == 1) {
;               if (wn64 == 0 && ni == 0) {
;                 float pv = __shfl_xor(v, 16);
;                 float2 cs = ropeH[(row & 4095) * 16 + (r32 & 15)];
;                 o = (r32 < 16) ? (v * cs.x - pv * cs.y) : (v * cs.x + pv * cs.y);
;               }
;             } else if (rope == 2) {
;               if (ni == 0) {
;                 float pv = __shfl_xor(v, 8);
;                 float2 cs = ropeD[(row & 4095) * 8 + (r32 & 7)];
;                 float rr = ((r32 & 8) == 0) ? (v * cs.x - pv * cs.y) : (v * cs.x + pv * cs.y);
;                 o = (r32 < 16) ? rr : v;
;               }
;             }
;             PR[(size_t)row * PR_LD + dcol2 + c] = f2bf(o);
;           }
.LBB0_1424:
	v_cvt_pk_bf16_f32 v73, v73, s0
	v_mad_i64_i32 v[74:75], s[0:1], v72, s35, v[70:71]
	global_store_short v[74:75], v73, off
.LBB0_1425:
	s_and_b64 vcc, exec, s[12:13]
	v_or_b32_e32 v73, 3, v66
	s_cbranch_vccnz .LBB0_1427
	v_cvt_pk_bf16_f32 v76, v53, s0
	v_mad_i64_i32 v[74:75], s[0:1], v73, s35, v[68:69]
	global_store_short v[74:75], v76, off

; DEV bf16_t f2bf(float f) { return (bf16_t)(cvtpk(f, 0.f) & 0xffffu); }
;   DEV void operator()(f32x16 (&acc)[2][2], int mb, int nb, int r32, int hh) const {
;     ...
; #pragma unroll
;     for (int mi = 0; mi < 2; ++mi)
; #pragma unroll
;       for (int ni = 0; ni < 2; ++ni)
; #pragma unroll
;         for (int r = 0; r < 16; ++r) {
;           int row = mb + mi * 32 + 8 * (r >> 2) + 4 * hh + (r & 3);
;           int c = wn64 + ni * 32 + r32;
;           float v = acc[mi][ni][r];
;           if (dcol >= 0) PR[(size_t)row * PR_LD + dcol + c] = f2bf(v);
;           if (dcol2 >= 0) {
;             float o = v;
;             if (rope == 1) {
;               if (wn64 == 0 && ni == 0) {
;                 float pv = __shfl_xor(v, 16);
;                 float2 cs = ropeH[(row & 4095) * 16 + (r32 & 15)];
;                 o = (r32 < 16) ? (v * cs.x - pv * cs.y) : (v * cs.x + pv * cs.y);
;               }
;             } else if (rope == 2) {
;               if (ni == 0) {
;                 float pv = __shfl_xor(v, 8);
;                 float2 cs = ropeD[(row & 4095) * 8 + (r32 & 7)];
;                 float rr = ((r32 & 8) == 0) ? (v * cs.x - pv * cs.y) : (v * cs.x + pv * cs.y);
;                 o = (r32 < 16) ? rr : v;
;               }
;             }
;             PR[(size_t)row * PR_LD + dcol2 + c] = f2bf(o);
;           }
.LBB0_1435:
	v_cvt_pk_bf16_f32 v76, v74, s0
	v_mad_i64_i32 v[74:75], s[0:1], v73, s35, v[70:71]
	global_store_short v[74:75], v76, off
.LBB0_1436:
	s_and_b64 vcc, exec, s[12:13]
	v_or_b32_e32 v74, 8, v66
	s_cbranch_vccnz .LBB0_1438
	v_cvt_pk_bf16_f32 v75, v54, s0
	v_mad_i64_i32 v[76:77], s[0:1], v74, s35, v[68:69]
	global_store_short v[76:77], v75, off

; DEV bf16_t f2bf(float f) { return (bf16_t)(cvtpk(f, 0.f) & 0xffffu); }
;   DEV void operator()(f32x16 (&acc)[2][2], int mb, int nb, int r32, int hh) const {
;     ...
; #pragma unroll
;     for (int mi = 0; mi < 2; ++mi)
; #pragma unroll
;       for (int ni = 0; ni < 2; ++ni)
; #pragma unroll
;         for (int r = 0; r < 16; ++r) {
;           int row = mb + mi * 32 + 8 * (r >> 2) + 4 * hh + (r & 3);
;           int c = wn64 + ni * 32 + r32;
;           float v = acc[mi][ni][r];
;           if (dcol >= 0) PR[(size_t)row * PR_LD + dcol + c] = f2bf(v);
;           if (dcol2 >= 0) {
;             float o = v;
;             if (rope == 1) {
;               if (wn64 == 0 && ni == 0) {
;                 float pv = __shfl_xor(v, 16);
;                 float2 cs = ropeH[(row & 4095) * 16 + (r32 & 15)];
;                 o = (r32 < 16) ? (v * cs.x - pv * cs.y) : (v * cs.x + pv * cs.y);
;               }
;             } else if (rope == 2) {
;               if (ni == 0) {
;                 float pv = __shfl_xor(v, 8);
;                 float2 cs = ropeD[(row & 4095) * 8 + (r32 & 7)];
;                 float rr = ((r32 & 8) == 0) ? (v * cs.x - pv * cs.y) : (v * cs.x + pv * cs.y);
;                 o = (r32 < 16) ? rr : v;
;               }
;             }
;             PR[(size_t)row * PR_LD + dcol2 + c] = f2bf(o);
;           }
.LBB0_1446:
	v_cvt_pk_bf16_f32 v75, v75, s0
	v_mad_i64_i32 v[76:77], s[0:1], v74, s35, v[70:71]
	global_store_short v[76:77], v75, off
.LBB0_1447:
	s_and_b64 vcc, exec, s[12:13]
	v_or_b32_e32 v75, 9, v66
	s_cbranch_vccnz .LBB0_1449
	v_cvt_pk_bf16_f32 v78, v55, s0
	v_mad_i64_i32 v[76:77], s[0:1], v75, s35, v[68:69]
	global_store_short v[76:77], v78, off

; DEV bf16_t f2bf(float f) { return (bf16_t)(cvtpk(f, 0.f) & 0xffffu); }
;   DEV void operator()(f32x16 (&acc)[2][2], int mb, int nb, int r32, int hh) const {
;     ...
; #pragma unroll
;     for (int mi = 0; mi < 2; ++mi)
; #pragma unroll
;       for (int ni = 0; ni < 2; ++ni)
; #pragma unroll
;         for (int r = 0; r < 16; ++r) {
;           int row = mb + mi * 32 + 8 * (r >> 2) + 4 * hh + (r & 3);
;           int c = wn64 + ni * 32 + r32;
;           float v = acc[mi][ni][r];
;           if (dcol >= 0) PR[(size_t)row * PR_LD + dcol + c] = f2bf(v);
;           if (dcol2 >= 0) {
;             float o = v;
;             if (rope == 1) {
;               if (wn64 == 0 && ni == 0) {
;                 float pv = __shfl_xor(v, 16);
;                 float2 cs = ropeH[(row & 4095) * 16 + (r32 & 15)];
;                 o = (r32 < 16) ? (v * cs.x - pv * cs.y) : (v * cs.x + pv * cs.y);
;               }
;             } else if (rope == 2) {
;               if (ni == 0) {
;                 float pv = __shfl_xor(v, 8);
;                 float2 cs = ropeD[(row & 4095) * 8 + (r32 & 7)];
;                 float rr = ((r32 & 8) == 0) ? (v * cs.x - pv * cs.y) : (v * cs.x + pv * cs.y);
;                 o = (r32 < 16) ? rr : v;
;               }
;             }
;             PR[(size_t)row * PR_LD + dcol2 + c] = f2bf(o);
;           }
.LBB0_1457:
	v_cvt_pk_bf16_f32 v78, v76, s0
	v_mad_i64_i32 v[76:77], s[0:1], v75, s35, v[70:71]
	global_store_short v[76:77], v78, off
.LBB0_1458:
	s_and_b64 vcc, exec, s[12:13]
	v_or_b32_e32 v76, 10, v66
	s_cbranch_vccnz .LBB0_1460
	v_cvt_pk_bf16_f32 v77, v56, s0
	v_mad_i64_i32 v[78:79], s[0:1], v76, s35, v[68:69]
	global_store_short v[78:79], v77, off

; DEV bf16_t f2bf(float f) { return (bf16_t)(cvtpk(f, 0.f) & 0xffffu); }
;   DEV void operator()(f32x16 (&acc)[2][2], int mb, int nb, int r32, int hh) const {
;     ...
; #pragma unroll
;     for (int mi = 0; mi < 2; ++mi)
; #pragma unroll
;       for (int ni = 0; ni < 2; ++ni)
; #pragma unroll
;         for (int r = 0; r < 16; ++r) {
;           int row = mb + mi * 32 + 8 * (r >> 2) + 4 * hh + (r & 3);
;           int c = wn64 + ni * 32 + r32;
;           float v = acc[mi][ni][r];
;           if (dcol >= 0) PR[(size_t)row * PR_LD + dcol + c] = f2bf(v);
;           if (dcol2 >= 0) {
;             float o = v;
;             if (rope == 1) {
;               if (wn64 == 0 && ni == 0) {
;                 float pv = __shfl_xor(v, 16);
;                 float2 cs = ropeH[(row & 4095) * 16 + (r32 & 15)];
;                 o = (r32 < 16) ? (v * cs.x - pv * cs.y) : (v * cs.x + pv * cs.y);
;               }
;             } else if (rope == 2) {
;               if (ni == 0) {
;                 float pv = __shfl_xor(v, 8);
;                 float2 cs = ropeD[(row & 4095) * 8 + (r32 & 7)];
;                 float rr = ((r32 & 8) == 0) ? (v * cs.x - pv * cs.y) : (v * cs.x + pv * cs.y);
;                 o = (r32 < 16) ? rr : v;
;               }
;             }
;             PR[(size_t)row * PR_LD + dcol2 + c] = f2bf(o);
;           }
.LBB0_1468:
	v_cvt_pk_bf16_f32 v77, v77, s0
	v_mad_i64_i32 v[78:79], s[0:1], v76, s35, v[70:71]
	global_store_short v[78:79], v77, off
.LBB0_1469:
	s_and_b64 vcc, exec, s[12:13]
	v_or_b32_e32 v77, 11, v66
	s_cbranch_vccnz .LBB0_1471
	v_cvt_pk_bf16_f32 v80, v57, s0
	v_mad_i64_i32 v[78:79], s[0:1], v77, s35, v[68:69]
	global_store_short v[78:79], v80, off

; DEV bf16_t f2bf(float f) { return (bf16_t)(cvtpk(f, 0.f) & 0xffffu); }
;   DEV void operator()(f32x16 (&acc)[2][2], int mb, int nb, int r32, int hh) const {
;     ...
; #pragma unroll
;     for (int mi = 0; mi < 2; ++mi)
; #pragma unroll
;       for (int ni = 0; ni < 2; ++ni)
; #pragma unroll
;         for (int r = 0; r < 16; ++r) {
;           int row = mb + mi * 32 + 8 * (r >> 2) + 4 * hh + (r & 3);
;           int c = wn64 + ni * 32 + r32;
;           float v = acc[mi][ni][r];
;           if (dcol >= 0) PR[(size_t)row * PR_LD + dcol + c] = f2bf(v);
;           if (dcol2 >= 0) {
;             float o = v;
;             if (rope == 1) {
;               if (wn64 == 0 && ni == 0) {
;                 float pv = __shfl_xor(v, 16);
;                 float2 cs = ropeH[(row & 4095) * 16 + (r32 & 15)];
;                 o = (r32 < 16) ? (v * cs.x - pv * cs.y) : (v * cs.x + pv * cs.y);
;               }
;             } else if (rope == 2) {
;               if (ni == 0) {
;                 float pv = __shfl_xor(v, 8);
;                 float2 cs = ropeD[(row & 4095) * 8 + (r32 & 7)];
;                 float rr = ((r32 & 8) == 0) ? (v * cs.x - pv * cs.y) : (v * cs.x + pv * cs.y);
;                 o = (r32 < 16) ? rr : v;
;               }
;             }
;             PR[(size_t)row * PR_LD + dcol2 + c] = f2bf(o);
;           }
.LBB0_1479:
	v_cvt_pk_bf16_f32 v80, v78, s0
	v_mad_i64_i32 v[78:79], s[0:1], v77, s35, v[70:71]
	global_store_short v[78:79], v80, off
.LBB0_1480:
	s_and_b64 vcc, exec, s[12:13]
	v_or_b32_e32 v78, 16, v66
	s_cbranch_vccnz .LBB0_1482
	v_cvt_pk_bf16_f32 v79, v58, s0
	v_mad_i64_i32 v[80:81], s[0:1], v78, s35, v[68:69]
	global_store_short v[80:81], v79, off

; DEV bf16_t f2bf(float f) { return (bf16_t)(cvtpk(f, 0.f) & 0xffffu); }
;   DEV void operator()(f32x16 (&acc)[2][2], int mb, int nb, int r32, int hh) const {
;     ...
; #pragma unroll
;     for (int mi = 0; mi < 2; ++mi)
; #pragma unroll
;       for (int ni = 0; ni < 2; ++ni)
; #pragma unroll
;         for (int r = 0; r < 16; ++r) {
;           int row = mb + mi * 32 + 8 * (r >> 2) + 4 * hh + (r & 3);
;           int c = wn64 + ni * 32 + r32;
;           float v = acc[mi][ni][r];
;           if (dcol >= 0) PR[(size_t)row * PR_LD + dcol + c] = f2bf(v);
;           if (dcol2 >= 0) {
;             float o = v;
;             if (rope == 1) {
;               if (wn64 == 0 && ni == 0) {
;                 float pv = __shfl_xor(v, 16);
;                 float2 cs = ropeH[(row & 4095) * 16 + (r32 & 15)];
;                 o = (r32 < 16) ? (v * cs.x - pv * cs.y) : (v * cs.x + pv * cs.y);
;               }
;             } else if (rope == 2) {
;               if (ni == 0) {
;                 float pv = __shfl_xor(v, 8);
;                 float2 cs = ropeD[(row & 4095) * 8 + (r32 & 7)];
;                 float rr = ((r32 & 8) == 0) ? (v * cs.x - pv * cs.y) : (v * cs.x + pv * cs.y);
;                 o = (r32 < 16) ? rr : v;
;               }
;             }
;             PR[(size_t)row * PR_LD + dcol2 + c] = f2bf(o);
;           }
.LBB0_1490:
	v_cvt_pk_bf16_f32 v79, v79, s0
	v_mad_i64_i32 v[80:81], s[0:1], v78, s35, v[70:71]
	global_store_short v[80:81], v79, off
.LBB0_1491:
	s_and_b64 vcc, exec, s[12:13]
	v_or_b32_e32 v79, 17, v66
	s_cbranch_vccnz .LBB0_1493
	v_cvt_pk_bf16_f32 v82, v59, s0
	v_mad_i64_i32 v[80:81], s[0:1], v79, s35, v[68:69]
	global_store_short v[80:81], v82, off

; DEV bf16_t f2bf(float f) { return (bf16_t)(cvtpk(f, 0.f) & 0xffffu); }
;   DEV void operator()(f32x16 (&acc)[2][2], int mb, int nb, int r32, int hh) const {
;     ...
; #pragma unroll
;     for (int mi = 0; mi < 2; ++mi)
; #pragma unroll
;       for (int ni = 0; ni < 2; ++ni)
; #pragma unroll
;         for (int r = 0; r < 16; ++r) {
;           int row = mb + mi * 32 + 8 * (r >> 2) + 4 * hh + (r & 3);
;           int c = wn64 + ni * 32 + r32;
;           float v = acc[mi][ni][r];
;           if (dcol >= 0) PR[(size_t)row * PR_LD + dcol + c] = f2bf(v);
;           if (dcol2 >= 0) {
;             float o = v;
;             if (rope == 1) {
;               if (wn64 == 0 && ni == 0) {
;                 float pv = __shfl_xor(v, 16);
;                 float2 cs = ropeH[(row & 4095) * 16 + (r32 & 15)];
;                 o = (r32 < 16) ? (v * cs.x - pv * cs.y) : (v * cs.x + pv * cs.y);
;               }
;             } else if (rope == 2) {
;               if (ni == 0) {
;                 float pv = __shfl_xor(v, 8);
;                 float2 cs = ropeD[(row & 4095) * 8 + (r32 & 7)];
;                 float rr = ((r32 & 8) == 0) ? (v * cs.x - pv * cs.y) : (v * cs.x + pv * cs.y);
;                 o = (r32 < 16) ? rr : v;
;               }
;             }
;             PR[(size_t)row * PR_LD + dcol2 + c] = f2bf(o);
;           }
.LBB0_1501:
	v_cvt_pk_bf16_f32 v82, v80, s0
	v_mad_i64_i32 v[80:81], s[0:1], v79, s35, v[70:71]
	global_store_short v[80:81], v82, off
.LBB0_1502:
	s_and_b64 vcc, exec, s[12:13]
	v_or_b32_e32 v80, 18, v66
	s_cbranch_vccnz .LBB0_1504
	v_cvt_pk_bf16_f32 v81, v60, s0
	v_mad_i64_i32 v[82:83], s[0:1], v80, s35, v[68:69]
	global_store_short v[82:83], v81, off

; DEV bf16_t f2bf(float f) { return (bf16_t)(cvtpk(f, 0.f) & 0xffffu); }
;   DEV void operator()(f32x16 (&acc)[2][2], int mb, int nb, int r32, int hh) const {
;     ...
; #pragma unroll
;     for (int mi = 0; mi < 2; ++mi)
; #pragma unroll
;       for (int ni = 0; ni < 2; ++ni)
; #pragma unroll
;         for (int r = 0; r < 16; ++r) {
;           int row = mb + mi * 32 + 8 * (r >> 2) + 4 * hh + (r & 3);
;           int c = wn64 + ni * 32 + r32;
;           float v = acc[mi][ni][r];
;           if (dcol >= 0) PR[(size_t)row * PR_LD + dcol + c] = f2bf(v);
;           if (dcol2 >= 0) {
;             float o = v;
;             if (rope == 1) {
;               if (wn64 == 0 && ni == 0) {
;                 float pv = __shfl_xor(v, 16);
;                 float2 cs = ropeH[(row & 4095) * 16 + (r32 & 15)];
;                 o = (r32 < 16) ? (v * cs.x - pv * cs.y) : (v * cs.x + pv * cs.y);
;               }
;             } else if (rope == 2) {
;               if (ni == 0) {
;                 float pv = __shfl_xor(v, 8);
;                 float2 cs = ropeD[(row & 4095) * 8 + (r32 & 7)];
;                 float rr = ((r32 & 8) == 0) ? (v * cs.x - pv * cs.y) : (v * cs.x + pv * cs.y);
;                 o = (r32 < 16) ? rr : v;
;               }
;             }
;             PR[(size_t)row * PR_LD + dcol2 + c] = f2bf(o);
;           }
.LBB0_1512:
	v_cvt_pk_bf16_f32 v81, v81, s0
	v_mad_i64_i32 v[82:83], s[0:1], v80, s35, v[70:71]
	global_store_short v[82:83], v81, off
.LBB0_1513:
	s_and_b64 vcc, exec, s[12:13]
	v_or_b32_e32 v81, 19, v66
	s_cbranch_vccnz .LBB0_1515
	v_cvt_pk_bf16_f32 v84, v61, s0
	v_mad_i64_i32 v[82:83], s[0:1], v81, s35, v[68:69]
	global_store_short v[82:83], v84, off

; DEV bf16_t f2bf(float f) { return (bf16_t)(cvtpk(f, 0.f) & 0xffffu); }
;   DEV void operator()(f32x16 (&acc)[2][2], int mb, int nb, int r32, int hh) const {
;     ...
; #pragma unroll
;     for (int mi = 0; mi < 2; ++mi)
; #pragma unroll
;       for (int ni = 0; ni < 2; ++ni)
; #pragma unroll
;         for (int r = 0; r < 16; ++r) {
;           int row = mb + mi * 32 + 8 * (r >> 2) + 4 * hh + (r & 3);
;           int c = wn64 + ni * 32 + r32;
;           float v = acc[mi][ni][r];
;           if (dcol >= 0) PR[(size_t)row * PR_LD + dcol + c] = f2bf(v);
;           if (dcol2 >= 0) {
;             float o = v;
;             if (rope == 1) {
;               if (wn64 == 0 && ni == 0) {
;                 float pv = __shfl_xor(v, 16);
;                 float2 cs = ropeH[(row & 4095) * 16 + (r32 & 15)];
;                 o = (r32 < 16) ? (v * cs.x - pv * cs.y) : (v * cs.x + pv * cs.y);
;               }
;             } else if (rope == 2) {
;               if (ni == 0) {
;                 float pv = __shfl_xor(v, 8);
;                 float2 cs = ropeD[(row & 4095) * 8 + (r32 & 7)];
;                 float rr = ((r32 & 8) == 0) ? (v * cs.x - pv * cs.y) : (v * cs.x + pv * cs.y);
;                 o = (r32 < 16) ? rr : v;
;               }
;             }
;             PR[(size_t)row * PR_LD + dcol2 + c] = f2bf(o);
;           }
.LBB0_1523:
	v_cvt_pk_bf16_f32 v84, v82, s0
	v_mad_i64_i32 v[82:83], s[0:1], v81, s35, v[70:71]
	global_store_short v[82:83], v84, off
.LBB0_1524:
	s_and_b64 vcc, exec, s[12:13]
	v_or_b32_e32 v82, 24, v66
	s_cbranch_vccnz .LBB0_1526
	v_cvt_pk_bf16_f32 v83, v62, s0
	v_mad_i64_i32 v[84:85], s[0:1], v82, s35, v[68:69]
	global_store_short v[84:85], v83, off

; DEV bf16_t f2bf(float f) { return (bf16_t)(cvtpk(f, 0.f) & 0xffffu); }
;   DEV void operator()(f32x16 (&acc)[2][2], int mb, int nb, int r32, int hh) const {
;     ...
; #pragma unroll
;     for (int mi = 0; mi < 2; ++mi)
; #pragma unroll
;       for (int ni = 0; ni < 2; ++ni)
; #pragma unroll
;         for (int r = 0; r < 16; ++r) {
;           int row = mb + mi * 32 + 8 * (r >> 2) + 4 * hh + (r & 3);
;           int c = wn64 + ni * 32 + r32;
;           float v = acc[mi][ni][r];
;           if (dcol >= 0) PR[(size_t)row * PR_LD + dcol + c] = f2bf(v);
;           if (dcol2 >= 0) {
;             float o = v;
;             if (rope == 1) {
;               if (wn64 == 0 && ni == 0) {
;                 float pv = __shfl_xor(v, 16);
;                 float2 cs = ropeH[(row & 4095) * 16 + (r32 & 15)];
;                 o = (r32 < 16) ? (v * cs.x - pv * cs.y) : (v * cs.x + pv * cs.y);
;               }
;             } else if (rope == 2) {
;               if (ni == 0) {
;                 float pv = __shfl_xor(v, 8);
;                 float2 cs = ropeD[(row & 4095) * 8 + (r32 & 7)];
;                 float rr = ((r32 & 8) == 0) ? (v * cs.x - pv * cs.y) : (v * cs.x + pv * cs.y);
;                 o = (r32 < 16) ? rr : v;
;               }
;             }
;             PR[(size_t)row * PR_LD + dcol2 + c] = f2bf(o);
;           }
.LBB0_1534:
	v_cvt_pk_bf16_f32 v83, v83, s0
	v_mad_i64_i32 v[84:85], s[0:1], v82, s35, v[70:71]
	global_store_short v[84:85], v83, off
.LBB0_1535:
	s_and_b64 vcc, exec, s[12:13]
	v_or_b32_e32 v83, 25, v66
	s_cbranch_vccnz .LBB0_1537
	v_cvt_pk_bf16_f32 v86, v63, s0
	v_mad_i64_i32 v[84:85], s[0:1], v83, s35, v[68:69]
	global_store_short v[84:85], v86, off

; DEV bf16_t f2bf(float f) { return (bf16_t)(cvtpk(f, 0.f) & 0xffffu); }
;   DEV void operator()(f32x16 (&acc)[2][2], int mb, int nb, int r32, int hh) const {
;     ...
; #pragma unroll
;     for (int mi = 0; mi < 2; ++mi)
; #pragma unroll
;       for (int ni = 0; ni < 2; ++ni)
; #pragma unroll
;         for (int r = 0; r < 16; ++r) {
;           int row = mb + mi * 32 + 8 * (r >> 2) + 4 * hh + (r & 3);
;           int c = wn64 + ni * 32 + r32;
;           float v = acc[mi][ni][r];
;           if (dcol >= 0) PR[(size_t)row * PR_LD + dcol + c] = f2bf(v);
;           if (dcol2 >= 0) {
;             float o = v;
;             if (rope == 1) {
;               if (wn64 == 0 && ni == 0) {
;                 float pv = __shfl_xor(v, 16);
;                 float2 cs = ropeH[(row & 4095) * 16 + (r32 & 15)];
;                 o = (r32 < 16) ? (v * cs.x - pv * cs.y) : (v * cs.x + pv * cs.y);
;               }
;             } else if (rope == 2) {
;               if (ni == 0) {
;                 float pv = __shfl_xor(v, 8);
;                 float2 cs = ropeD[(row & 4095) * 8 + (r32 & 7)];
;                 float rr = ((r32 & 8) == 0) ? (v * cs.x - pv * cs.y) : (v * cs.x + pv * cs.y);
;                 o = (r32 < 16) ? rr : v;
;               }
;             }
;             PR[(size_t)row * PR_LD + dcol2 + c] = f2bf(o);
;           }
.LBB0_1545:
	v_cvt_pk_bf16_f32 v86, v84, s0
	v_mad_i64_i32 v[84:85], s[0:1], v83, s35, v[70:71]
	global_store_short v[84:85], v86, off
.LBB0_1546:
	s_and_b64 vcc, exec, s[12:13]
	v_or_b32_e32 v84, 26, v66
	s_cbranch_vccnz .LBB0_1548
	v_cvt_pk_bf16_f32 v85, v64, s0
	v_mad_i64_i32 v[86:87], s[0:1], v84, s35, v[68:69]
	global_store_short v[86:87], v85, off

; DEV bf16_t f2bf(float f) { return (bf16_t)(cvtpk(f, 0.f) & 0xffffu); }
;   DEV void operator()(f32x16 (&acc)[2][2], int mb, int nb, int r32, int hh) const {
;     ...
; #pragma unroll
;     for (int mi = 0; mi < 2; ++mi)
; #pragma unroll
;       for (int ni = 0; ni < 2; ++ni)
; #pragma unroll
;         for (int r = 0; r < 16; ++r) {
;           int row = mb + mi * 32 + 8 * (r >> 2) + 4 * hh + (r & 3);
;           int c = wn64 + ni * 32 + r32;
;           float v = acc[mi][ni][r];
;           if (dcol >= 0) PR[(size_t)row * PR_LD + dcol + c] = f2bf(v);
;           if (dcol2 >= 0) {
;             float o = v;
;             if (rope == 1) {
;               if (wn64 == 0 && ni == 0) {
;                 float pv = __shfl_xor(v, 16);
;                 float2 cs = ropeH[(row & 4095) * 16 + (r32 & 15)];
;                 o = (r32 < 16) ? (v * cs.x - pv * cs.y) : (v * cs.x + pv * cs.y);
;               }
;             } else if (rope == 2) {
;               if (ni == 0) {
;                 float pv = __shfl_xor(v, 8);
;                 float2 cs = ropeD[(row & 4095) * 8 + (r32 & 7)];
;                 float rr = ((r32 & 8) == 0) ? (v * cs.x - pv * cs.y) : (v * cs.x + pv * cs.y);
;                 o = (r32 < 16) ? rr : v;
;               }
;             }
;             PR[(size_t)row * PR_LD + dcol2 + c] = f2bf(o);
;           }
.LBB0_1556:
	v_cvt_pk_bf16_f32 v85, v85, s0
	v_mad_i64_i32 v[86:87], s[0:1], v84, s35, v[70:71]
	global_store_short v[86:87], v85, off
.LBB0_1557:
	s_and_b64 vcc, exec, s[12:13]
	v_or_b32_e32 v85, 27, v66
	s_cbranch_vccnz .LBB0_1559
	v_cvt_pk_bf16_f32 v88, v65, s0
	v_mad_i64_i32 v[86:87], s[0:1], v85, s35, v[68:69]
	global_store_short v[86:87], v88, off

; DEV bf16_t f2bf(float f) { return (bf16_t)(cvtpk(f, 0.f) & 0xffffu); }
;   DEV void operator()(f32x16 (&acc)[2][2], int mb, int nb, int r32, int hh) const {
;     ...
; #pragma unroll
;     for (int mi = 0; mi < 2; ++mi)
; #pragma unroll
;       for (int ni = 0; ni < 2; ++ni)
; #pragma unroll
;         for (int r = 0; r < 16; ++r) {
;           int row = mb + mi * 32 + 8 * (r >> 2) + 4 * hh + (r & 3);
;           int c = wn64 + ni * 32 + r32;
;           float v = acc[mi][ni][r];
;           if (dcol >= 0) PR[(size_t)row * PR_LD + dcol + c] = f2bf(v);
;           if (dcol2 >= 0) {
;             float o = v;
;             if (rope == 1) {
;               if (wn64 == 0 && ni == 0) {
;                 float pv = __shfl_xor(v, 16);
;                 float2 cs = ropeH[(row & 4095) * 16 + (r32 & 15)];
;                 o = (r32 < 16) ? (v * cs.x - pv * cs.y) : (v * cs.x + pv * cs.y);
;               }
;             } else if (rope == 2) {
;               if (ni == 0) {
;                 float pv = __shfl_xor(v, 8);
;                 float2 cs = ropeD[(row & 4095) * 8 + (r32 & 7)];
;                 float rr = ((r32 & 8) == 0) ? (v * cs.x - pv * cs.y) : (v * cs.x + pv * cs.y);
;                 o = (r32 < 16) ? rr : v;
;               }
;             }
;             PR[(size_t)row * PR_LD + dcol2 + c] = f2bf(o);
;           }
.LBB0_1567:
	v_cvt_pk_bf16_f32 v88, v86, s0
	v_mad_i64_i32 v[86:87], s[0:1], v85, s35, v[70:71]
	global_store_short v[86:87], v88, off
.LBB0_1568:
	s_and_b64 vcc, exec, s[12:13]
	s_cbranch_vccnz .LBB0_1570
	v_cvt_pk_bf16_f32 v88, v34, s0
	v_mad_i64_i32 v[86:87], s[0:1], v66, s35, v[68:69]
	global_store_short v[86:87], v88, off offset:64
.LBB0_1570:
	s_and_b64 vcc, exec, s[14:15]
	s_cbranch_vccnz .LBB0_1572
	v_cvt_pk_bf16_f32 v88, v34, s0
	v_mad_i64_i32 v[86:87], s[0:1], v66, s35, v[70:71]
	global_store_short v[86:87], v88, off offset:64
.LBB0_1572:
	s_and_b64 vcc, exec, s[12:13]
	s_cbranch_vccnz .LBB0_1574
	v_cvt_pk_bf16_f32 v88, v35, s0
	v_mad_i64_i32 v[86:87], s[0:1], v67, s35, v[68:69]
	global_store_short v[86:87], v88, off offset:64
.LBB0_1574:
	s_and_b64 vcc, exec, s[14:15]
	s_cbranch_vccnz .LBB0_1576
	v_cvt_pk_bf16_f32 v88, v35, s0
	v_mad_i64_i32 v[86:87], s[0:1], v67, s35, v[70:71]
	global_store_short v[86:87], v88, off offset:64
.LBB0_1576:
	s_and_b64 vcc, exec, s[12:13]
	s_cbranch_vccnz .LBB0_1578
	v_cvt_pk_bf16_f32 v67, v36, s0
	v_mad_i64_i32 v[86:87], s[0:1], v72, s35, v[68:69]
	global_store_short v[86:87], v67, off offset:64
.LBB0_1578:
	s_and_b64 vcc, exec, s[14:15]
	s_cbranch_vccnz .LBB0_1580
	v_cvt_pk_bf16_f32 v67, v36, s0
	v_mad_i64_i32 v[86:87], s[0:1], v72, s35, v[70:71]
	global_store_short v[86:87], v67, off offset:64
.LBB0_1580:
	s_and_b64 vcc, exec, s[12:13]
	s_cbranch_vccnz .LBB0_1582
	v_cvt_pk_bf16_f32 v67, v37, s0
	v_mad_i64_i32 v[86:87], s[0:1], v73, s35, v[68:69]
	global_store_short v[86:87], v67, off offset:64
.LBB0_1582:
	s_and_b64 vcc, exec, s[14:15]
	s_cbranch_vccnz .LBB0_1584
	v_cvt_pk_bf16_f32 v67, v37, s0
	v_mad_i64_i32 v[72:73], s[0:1], v73, s35, v[70:71]
	global_store_short v[72:73], v67, off offset:64
.LBB0_1584:
	s_and_b64 vcc, exec, s[12:13]
	s_cbranch_vccnz .LBB0_1586
	v_cvt_pk_bf16_f32 v67, v38, s0
	v_mad_i64_i32 v[72:73], s[0:1], v74, s35, v[68:69]
	global_store_short v[72:73], v67, off offset:64
.LBB0_1586:
	s_and_b64 vcc, exec, s[14:15]
	s_cbranch_vccnz .LBB0_1588
	v_cvt_pk_bf16_f32 v67, v38, s0
	v_mad_i64_i32 v[72:73], s[0:1], v74, s35, v[70:71]
	global_store_short v[72:73], v67, off offset:64
.LBB0_1588:
	s_and_b64 vcc, exec, s[12:13]
	s_cbranch_vccnz .LBB0_1590
	v_cvt_pk_bf16_f32 v67, v39, s0
	v_mad_i64_i32 v[72:73], s[0:1], v75, s35, v[68:69]
	global_store_short v[72:73], v67, off offset:64
.LBB0_1590:
	s_and_b64 vcc, exec, s[14:15]
	s_cbranch_vccnz .LBB0_1592
	v_cvt_pk_bf16_f32 v67, v39, s0
	v_mad_i64_i32 v[72:73], s[0:1], v75, s35, v[70:71]
	global_store_short v[72:73], v67, off offset:64
.LBB0_1592:
	s_and_b64 vcc, exec, s[12:13]
	s_cbranch_vccnz .LBB0_1594
	v_cvt_pk_bf16_f32 v67, v40, s0
	v_mad_i64_i32 v[72:73], s[0:1], v76, s35, v[68:69]
	global_store_short v[72:73], v67, off offset:64
.LBB0_1594:
	s_and_b64 vcc, exec, s[14:15]
	s_cbranch_vccnz .LBB0_1596
	v_cvt_pk_bf16_f32 v67, v40, s0
	v_mad_i64_i32 v[72:73], s[0:1], v76, s35, v[70:71]
	global_store_short v[72:73], v67, off offset:64
.LBB0_1596:
	s_and_b64 vcc, exec, s[12:13]
	s_cbranch_vccnz .LBB0_1598
	v_cvt_pk_bf16_f32 v67, v41, s0
	v_mad_i64_i32 v[72:73], s[0:1], v77, s35, v[68:69]
	global_store_short v[72:73], v67, off offset:64
.LBB0_1598:
	s_and_b64 vcc, exec, s[14:15]
	s_cbranch_vccnz .LBB0_1600
	v_cvt_pk_bf16_f32 v67, v41, s0
	v_mad_i64_i32 v[72:73], s[0:1], v77, s35, v[70:71]
	global_store_short v[72:73], v67, off offset:64
.LBB0_1600:
	s_and_b64 vcc, exec, s[12:13]
	s_cbranch_vccnz .LBB0_1602
	v_cvt_pk_bf16_f32 v67, v42, s0
	v_mad_i64_i32 v[72:73], s[0:1], v78, s35, v[68:69]
	global_store_short v[72:73], v67, off offset:64
.LBB0_1602:
	s_and_b64 vcc, exec, s[14:15]
	s_cbranch_vccnz .LBB0_1604
	v_cvt_pk_bf16_f32 v67, v42, s0
	v_mad_i64_i32 v[72:73], s[0:1], v78, s35, v[70:71]
	global_store_short v[72:73], v67, off offset:64
.LBB0_1604:
	s_and_b64 vcc, exec, s[12:13]
	s_cbranch_vccnz .LBB0_1606
	v_cvt_pk_bf16_f32 v67, v43, s0
	v_mad_i64_i32 v[72:73], s[0:1], v79, s35, v[68:69]
	global_store_short v[72:73], v67, off offset:64
.LBB0_1606:
	s_and_b64 vcc, exec, s[14:15]
	s_cbranch_vccnz .LBB0_1608
	v_cvt_pk_bf16_f32 v67, v43, s0
	v_mad_i64_i32 v[72:73], s[0:1], v79, s35, v[70:71]
	global_store_short v[72:73], v67, off offset:64
.LBB0_1608:
	s_and_b64 vcc, exec, s[12:13]
	s_cbranch_vccnz .LBB0_1610
	v_cvt_pk_bf16_f32 v67, v44, s0
	v_mad_i64_i32 v[72:73], s[0:1], v80, s35, v[68:69]
	global_store_short v[72:73], v67, off offset:64
.LBB0_1610:
	s_and_b64 vcc, exec, s[14:15]
	s_cbranch_vccnz .LBB0_1612
	v_cvt_pk_bf16_f32 v67, v44, s0
	v_mad_i64_i32 v[72:73], s[0:1], v80, s35, v[70:71]
	global_store_short v[72:73], v67, off offset:64
.LBB0_1612:
	s_and_b64 vcc, exec, s[12:13]
	s_cbranch_vccnz .LBB0_1614
	v_cvt_pk_bf16_f32 v67, v45, s0
	v_mad_i64_i32 v[72:73], s[0:1], v81, s35, v[68:69]
	global_store_short v[72:73], v67, off offset:64
.LBB0_1614:
	s_and_b64 vcc, exec, s[14:15]
	s_cbranch_vccnz .LBB0_1616
	v_cvt_pk_bf16_f32 v67, v45, s0
	v_mad_i64_i32 v[72:73], s[0:1], v81, s35, v[70:71]
	global_store_short v[72:73], v67, off offset:64
.LBB0_1616:
	s_and_b64 vcc, exec, s[12:13]
	s_cbranch_vccnz .LBB0_1618
	v_cvt_pk_bf16_f32 v67, v46, s0
	v_mad_i64_i32 v[72:73], s[0:1], v82, s35, v[68:69]
	global_store_short v[72:73], v67, off offset:64
.LBB0_1618:
	s_and_b64 vcc, exec, s[14:15]
	s_cbranch_vccnz .LBB0_1620
	v_cvt_pk_bf16_f32 v67, v46, s0
	v_mad_i64_i32 v[72:73], s[0:1], v82, s35, v[70:71]
	global_store_short v[72:73], v67, off offset:64
.LBB0_1620:
	s_and_b64 vcc, exec, s[12:13]
	s_cbranch_vccnz .LBB0_1622
	v_cvt_pk_bf16_f32 v67, v47, s0
	v_mad_i64_i32 v[72:73], s[0:1], v83, s35, v[68:69]
	global_store_short v[72:73], v67, off offset:64
.LBB0_1622:
	s_and_b64 vcc, exec, s[14:15]
	s_cbranch_vccnz .LBB0_1624
	v_cvt_pk_bf16_f32 v67, v47, s0
	v_mad_i64_i32 v[72:73], s[0:1], v83, s35, v[70:71]
	global_store_short v[72:73], v67, off offset:64
.LBB0_1624:
	s_and_b64 vcc, exec, s[12:13]
	s_cbranch_vccnz .LBB0_1626
	v_cvt_pk_bf16_f32 v67, v48, s0
	v_mad_i64_i32 v[72:73], s[0:1], v84, s35, v[68:69]
	global_store_short v[72:73], v67, off offset:64
.LBB0_1626:
	s_and_b64 vcc, exec, s[14:15]
	s_cbranch_vccnz .LBB0_1628
	v_cvt_pk_bf16_f32 v67, v48, s0
	v_mad_i64_i32 v[72:73], s[0:1], v84, s35, v[70:71]
	global_store_short v[72:73], v67, off offset:64
.LBB0_1628:
	s_and_b64 vcc, exec, s[12:13]
	s_cbranch_vccnz .LBB0_1630
	v_cvt_pk_bf16_f32 v67, v49, s0
	v_mad_i64_i32 v[72:73], s[0:1], v85, s35, v[68:69]
	global_store_short v[72:73], v67, off offset:64
.LBB0_1630:
	s_and_b64 vcc, exec, s[14:15]
	s_cbranch_vccnz .LBB0_1632
	v_cvt_pk_bf16_f32 v67, v49, s0
	v_mad_i64_i32 v[72:73], s[0:1], v85, s35, v[70:71]
	global_store_short v[72:73], v67, off offset:64
.LBB0_1632:
	s_and_b64 vcc, exec, s[12:13]
	v_or_b32_e32 v67, 32, v66
	s_cbranch_vccnz .LBB0_1634
	v_cvt_pk_bf16_f32 v74, v18, s0
	v_mad_i64_i32 v[72:73], s[0:1], v67, s35, v[68:69]
	global_store_short v[72:73], v74, off

; DEV bf16_t f2bf(float f) { return (bf16_t)(cvtpk(f, 0.f) & 0xffffu); }
;   DEV void operator()(f32x16 (&acc)[2][2], int mb, int nb, int r32, int hh) const {
;     ...
; #pragma unroll
;     for (int mi = 0; mi < 2; ++mi)
; #pragma unroll
;       for (int ni = 0; ni < 2; ++ni)
; #pragma unroll
;         for (int r = 0; r < 16; ++r) {
;           int row = mb + mi * 32 + 8 * (r >> 2) + 4 * hh + (r & 3);
;           int c = wn64 + ni * 32 + r32;
;           float v = acc[mi][ni][r];
;           if (dcol >= 0) PR[(size_t)row * PR_LD + dcol + c] = f2bf(v);
;           if (dcol2 >= 0) {
;             float o = v;
;             if (rope == 1) {
;               if (wn64 == 0 && ni == 0) {
;                 float pv = __shfl_xor(v, 16);
;                 float2 cs = ropeH[(row & 4095) * 16 + (r32 & 15)];
;                 o = (r32 < 16) ? (v * cs.x - pv * cs.y) : (v * cs.x + pv * cs.y);
;               }
;             } else if (rope == 2) {
;               if (ni == 0) {
;                 float pv = __shfl_xor(v, 8);
;                 float2 cs = ropeD[(row & 4095) * 8 + (r32 & 7)];
;                 float rr = ((r32 & 8) == 0) ? (v * cs.x - pv * cs.y) : (v * cs.x + pv * cs.y);
;                 o = (r32 < 16) ? rr : v;
;               }
;             }
;             PR[(size_t)row * PR_LD + dcol2 + c] = f2bf(o);
;           }
.LBB0_1643:
	s_and_b64 vcc, exec, s[12:13]
	v_or_b32_e32 v72, 33, v66
	s_cbranch_vccnz .LBB0_1645
	v_cvt_pk_bf16_f32 v73, v19, s0
	v_mad_i64_i32 v[74:75], s[0:1], v72, s35, v[68:69]
	global_store_short v[74:75], v73, off

; DEV bf16_t f2bf(float f) { return (bf16_t)(cvtpk(f, 0.f) & 0xffffu); }
;   DEV void operator()(f32x16 (&acc)[2][2], int mb, int nb, int r32, int hh) const {
;     ...
; #pragma unroll
;     for (int mi = 0; mi < 2; ++mi)
; #pragma unroll
;       for (int ni = 0; ni < 2; ++ni)
; #pragma unroll
;         for (int r = 0; r < 16; ++r) {
;           int row = mb + mi * 32 + 8 * (r >> 2) + 4 * hh + (r & 3);
;           int c = wn64 + ni * 32 + r32;
;           float v = acc[mi][ni][r];
;           if (dcol >= 0) PR[(size_t)row * PR_LD + dcol + c] = f2bf(v);
;           if (dcol2 >= 0) {
;             float o = v;
;             if (rope == 1) {
;               if (wn64 == 0 && ni == 0) {
;                 float pv = __shfl_xor(v, 16);
;                 float2 cs = ropeH[(row & 4095) * 16 + (r32 & 15)];
;                 o = (r32 < 16) ? (v * cs.x - pv * cs.y) : (v * cs.x + pv * cs.y);
;               }
;             } else if (rope == 2) {
;               if (ni == 0) {
;                 float pv = __shfl_xor(v, 8);
;                 float2 cs = ropeD[(row & 4095) * 8 + (r32 & 7)];
;                 float rr = ((r32 & 8) == 0) ? (v * cs.x - pv * cs.y) : (v * cs.x + pv * cs.y);
;                 o = (r32 < 16) ? rr : v;
;               }
;             }
;             PR[(size_t)row * PR_LD + dcol2 + c] = f2bf(o);
;           }
.LBB0_1654:
	s_and_b64 vcc, exec, s[12:13]
	v_or_b32_e32 v73, 34, v66
	s_cbranch_vccnz .LBB0_1656
	v_cvt_pk_bf16_f32 v76, v20, s0
	v_mad_i64_i32 v[74:75], s[0:1], v73, s35, v[68:69]
	global_store_short v[74:75], v76, off

; DEV bf16_t f2bf(float f) { return (bf16_t)(cvtpk(f, 0.f) & 0xffffu); }
;   DEV void operator()(f32x16 (&acc)[2][2], int mb, int nb, int r32, int hh) const {
;     ...
; #pragma unroll
;     for (int mi = 0; mi < 2; ++mi)
; #pragma unroll
;       for (int ni = 0; ni < 2; ++ni)
; #pragma unroll
;         for (int r = 0; r < 16; ++r) {
;           int row = mb + mi * 32 + 8 * (r >> 2) + 4 * hh + (r & 3);
;           int c = wn64 + ni * 32 + r32;
;           float v = acc[mi][ni][r];
;           if (dcol >= 0) PR[(size_t)row * PR_LD + dcol + c] = f2bf(v);
;           if (dcol2 >= 0) {
;             float o = v;
;             if (rope == 1) {
;               if (wn64 == 0 && ni == 0) {
;                 float pv = __shfl_xor(v, 16);
;                 float2 cs = ropeH[(row & 4095) * 16 + (r32 & 15)];
;                 o = (r32 < 16) ? (v * cs.x - pv * cs.y) : (v * cs.x + pv * cs.y);
;               }
;             } else if (rope == 2) {
;               if (ni == 0) {
;                 float pv = __shfl_xor(v, 8);
;                 float2 cs = ropeD[(row & 4095) * 8 + (r32 & 7)];
;                 float rr = ((r32 & 8) == 0) ? (v * cs.x - pv * cs.y) : (v * cs.x + pv * cs.y);
;                 o = (r32 < 16) ? rr : v;
;               }
;             }
;             PR[(size_t)row * PR_LD + dcol2 + c] = f2bf(o);
;           }
.LBB0_1665:
	s_and_b64 vcc, exec, s[12:13]
	v_or_b32_e32 v74, 35, v66
	s_cbranch_vccnz .LBB0_1667
	v_cvt_pk_bf16_f32 v75, v21, s0
	v_mad_i64_i32 v[76:77], s[0:1], v74, s35, v[68:69]
	global_store_short v[76:77], v75, off

; DEV bf16_t f2bf(float f) { return (bf16_t)(cvtpk(f, 0.f) & 0xffffu); }
;   DEV void operator()(f32x16 (&acc)[2][2], int mb, int nb, int r32, int hh) const {
;     ...
; #pragma unroll
;     for (int mi = 0; mi < 2; ++mi)
; #pragma unroll
;       for (int ni = 0; ni < 2; ++ni)
; #pragma unroll
;         for (int r = 0; r < 16; ++r) {
;           int row = mb + mi * 32 + 8 * (r >> 2) + 4 * hh + (r & 3);
;           int c = wn64 + ni * 32 + r32;
;           float v = acc[mi][ni][r];
;           if (dcol >= 0) PR[(size_t)row * PR_LD + dcol + c] = f2bf(v);
;           if (dcol2 >= 0) {
;             float o = v;
;             if (rope == 1) {
;               if (wn64 == 0 && ni == 0) {
;                 float pv = __shfl_xor(v, 16);
;                 float2 cs = ropeH[(row & 4095) * 16 + (r32 & 15)];
;                 o = (r32 < 16) ? (v * cs.x - pv * cs.y) : (v * cs.x + pv * cs.y);
;               }
;             } else if (rope == 2) {
;               if (ni == 0) {
;                 float pv = __shfl_xor(v, 8);
;                 float2 cs = ropeD[(row & 4095) * 8 + (r32 & 7)];
;                 float rr = ((r32 & 8) == 0) ? (v * cs.x - pv * cs.y) : (v * cs.x + pv * cs.y);
;                 o = (r32 < 16) ? rr : v;
;               }
;             }
;             PR[(size_t)row * PR_LD + dcol2 + c] = f2bf(o);
;           }
.LBB0_1676:
	s_and_b64 vcc, exec, s[12:13]
	v_or_b32_e32 v75, 40, v66
	s_cbranch_vccnz .LBB0_1678
	v_cvt_pk_bf16_f32 v78, v22, s0
	v_mad_i64_i32 v[76:77], s[0:1], v75, s35, v[68:69]
	global_store_short v[76:77], v78, off

; DEV bf16_t f2bf(float f) { return (bf16_t)(cvtpk(f, 0.f) & 0xffffu); }
;   DEV void operator()(f32x16 (&acc)[2][2], int mb, int nb, int r32, int hh) const {
;     ...
; #pragma unroll
;     for (int mi = 0; mi < 2; ++mi)
; #pragma unroll
;       for (int ni = 0; ni < 2; ++ni)
; #pragma unroll
;         for (int r = 0; r < 16; ++r) {
;           int row = mb + mi * 32 + 8 * (r >> 2) + 4 * hh + (r & 3);
;           int c = wn64 + ni * 32 + r32;
;           float v = acc[mi][ni][r];
;           if (dcol >= 0) PR[(size_t)row * PR_LD + dcol + c] = f2bf(v);
;           if (dcol2 >= 0) {
;             float o = v;
;             if (rope == 1) {
;               if (wn64 == 0 && ni == 0) {
;                 float pv = __shfl_xor(v, 16);
;                 float2 cs = ropeH[(row & 4095) * 16 + (r32 & 15)];
;                 o = (r32 < 16) ? (v * cs.x - pv * cs.y) : (v * cs.x + pv * cs.y);
;               }
;             } else if (rope == 2) {
;               if (ni == 0) {
;                 float pv = __shfl_xor(v, 8);
;                 float2 cs = ropeD[(row & 4095) * 8 + (r32 & 7)];
;                 float rr = ((r32 & 8) == 0) ? (v * cs.x - pv * cs.y) : (v * cs.x + pv * cs.y);
;                 o = (r32 < 16) ? rr : v;
;               }
;             }
;             PR[(size_t)row * PR_LD + dcol2 + c] = f2bf(o);
;           }
.LBB0_1687:
	s_and_b64 vcc, exec, s[12:13]
	v_or_b32_e32 v76, 41, v66
	s_cbranch_vccnz .LBB0_1689
	v_cvt_pk_bf16_f32 v77, v23, s0
	v_mad_i64_i32 v[78:79], s[0:1], v76, s35, v[68:69]
	global_store_short v[78:79], v77, off

; DEV bf16_t f2bf(float f) { return (bf16_t)(cvtpk(f, 0.f) & 0xffffu); }
;   DEV void operator()(f32x16 (&acc)[2][2], int mb, int nb, int r32, int hh) const {
;     ...
; #pragma unroll
;     for (int mi = 0; mi < 2; ++mi)
; #pragma unroll
;       for (int ni = 0; ni < 2; ++ni)
; #pragma unroll
;         for (int r = 0; r < 16; ++r) {
;           int row = mb + mi * 32 + 8 * (r >> 2) + 4 * hh + (r & 3);
;           int c = wn64 + ni * 32 + r32;
;           float v = acc[mi][ni][r];
;           if (dcol >= 0) PR[(size_t)row * PR_LD + dcol + c] = f2bf(v);
;           if (dcol2 >= 0) {
;             float o = v;
;             if (rope == 1) {
;               if (wn64 == 0 && ni == 0) {
;                 float pv = __shfl_xor(v, 16);
;                 float2 cs = ropeH[(row & 4095) * 16 + (r32 & 15)];
;                 o = (r32 < 16) ? (v * cs.x - pv * cs.y) : (v * cs.x + pv * cs.y);
;               }
;             } else if (rope == 2) {
;               if (ni == 0) {
;                 float pv = __shfl_xor(v, 8);
;                 float2 cs = ropeD[(row & 4095) * 8 + (r32 & 7)];
;                 float rr = ((r32 & 8) == 0) ? (v * cs.x - pv * cs.y) : (v * cs.x + pv * cs.y);
;                 o = (r32 < 16) ? rr : v;
;               }
;             }
;             PR[(size_t)row * PR_LD + dcol2 + c] = f2bf(o);
;           }
.LBB0_1698:
	s_and_b64 vcc, exec, s[12:13]
	v_or_b32_e32 v77, 42, v66
	s_cbranch_vccnz .LBB0_1700
	v_cvt_pk_bf16_f32 v80, v24, s0
	v_mad_i64_i32 v[78:79], s[0:1], v77, s35, v[68:69]
	global_store_short v[78:79], v80, off

; DEV bf16_t f2bf(float f) { return (bf16_t)(cvtpk(f, 0.f) & 0xffffu); }
;   DEV void operator()(f32x16 (&acc)[2][2], int mb, int nb, int r32, int hh) const {
;     ...
; #pragma unroll
;     for (int mi = 0; mi < 2; ++mi)
; #pragma unroll
;       for (int ni = 0; ni < 2; ++ni)
; #pragma unroll
;         for (int r = 0; r < 16; ++r) {
;           int row = mb + mi * 32 + 8 * (r >> 2) + 4 * hh + (r & 3);
;           int c = wn64 + ni * 32 + r32;
;           float v = acc[mi][ni][r];
;           if (dcol >= 0) PR[(size_t)row * PR_LD + dcol + c] = f2bf(v);
;           if (dcol2 >= 0) {
;             float o = v;
;             if (rope == 1) {
;               if (wn64 == 0 && ni == 0) {
;                 float pv = __shfl_xor(v, 16);
;                 float2 cs = ropeH[(row & 4095) * 16 + (r32 & 15)];
;                 o = (r32 < 16) ? (v * cs.x - pv * cs.y) : (v * cs.x + pv * cs.y);
;               }
;             } else if (rope == 2) {
;               if (ni == 0) {
;                 float pv = __shfl_xor(v, 8);
;                 float2 cs = ropeD[(row & 4095) * 8 + (r32 & 7)];
;                 float rr = ((r32 & 8) == 0) ? (v * cs.x - pv * cs.y) : (v * cs.x + pv * cs.y);
;                 o = (r32 < 16) ? rr : v;
;               }
;             }
;             PR[(size_t)row * PR_LD + dcol2 + c] = f2bf(o);
;           }
.LBB0_1709:
	s_and_b64 vcc, exec, s[12:13]
	v_or_b32_e32 v78, 43, v66
	s_cbranch_vccnz .LBB0_1711
	v_cvt_pk_bf16_f32 v79, v25, s0
	v_mad_i64_i32 v[80:81], s[0:1], v78, s35, v[68:69]
	global_store_short v[80:81], v79, off

; DEV bf16_t f2bf(float f) { return (bf16_t)(cvtpk(f, 0.f) & 0xffffu); }
;   DEV void operator()(f32x16 (&acc)[2][2], int mb, int nb, int r32, int hh) const {
;     ...
; #pragma unroll
;     for (int mi = 0; mi < 2; ++mi)
; #pragma unroll
;       for (int ni = 0; ni < 2; ++ni)
; #pragma unroll
;         for (int r = 0; r < 16; ++r) {
;           int row = mb + mi * 32 + 8 * (r >> 2) + 4 * hh + (r & 3);
;           int c = wn64 + ni * 32 + r32;
;           float v = acc[mi][ni][r];
;           if (dcol >= 0) PR[(size_t)row * PR_LD + dcol + c] = f2bf(v);
;           if (dcol2 >= 0) {
;             float o = v;
;             if (rope == 1) {
;               if (wn64 == 0 && ni == 0) {
;                 float pv = __shfl_xor(v, 16);
;                 float2 cs = ropeH[(row & 4095) * 16 + (r32 & 15)];
;                 o = (r32 < 16) ? (v * cs.x - pv * cs.y) : (v * cs.x + pv * cs.y);
;               }
;             } else if (rope == 2) {
;               if (ni == 0) {
;                 float pv = __shfl_xor(v, 8);
;                 float2 cs = ropeD[(row & 4095) * 8 + (r32 & 7)];
;                 float rr = ((r32 & 8) == 0) ? (v * cs.x - pv * cs.y) : (v * cs.x + pv * cs.y);
;                 o = (r32 < 16) ? rr : v;
;               }
;             }
;             PR[(size_t)row * PR_LD + dcol2 + c] = f2bf(o);
;           }
.LBB0_1720:
	s_and_b64 vcc, exec, s[12:13]
	v_or_b32_e32 v79, 48, v66
	s_cbranch_vccnz .LBB0_1722
	v_cvt_pk_bf16_f32 v82, v26, s0
	v_mad_i64_i32 v[80:81], s[0:1], v79, s35, v[68:69]
	global_store_short v[80:81], v82, off

; DEV bf16_t f2bf(float f) { return (bf16_t)(cvtpk(f, 0.f) & 0xffffu); }
;   DEV void operator()(f32x16 (&acc)[2][2], int mb, int nb, int r32, int hh) const {
;     ...
; #pragma unroll
;     for (int mi = 0; mi < 2; ++mi)
; #pragma unroll
;       for (int ni = 0; ni < 2; ++ni)
; #pragma unroll
;         for (int r = 0; r < 16; ++r) {
;           int row = mb + mi * 32 + 8 * (r >> 2) + 4 * hh + (r & 3);
;           int c = wn64 + ni * 32 + r32;
;           float v = acc[mi][ni][r];
;           if (dcol >= 0) PR[(size_t)row * PR_LD + dcol + c] = f2bf(v);
;           if (dcol2 >= 0) {
;             float o = v;
;             if (rope == 1) {
;               if (wn64 == 0 && ni == 0) {
;                 float pv = __shfl_xor(v, 16);
;                 float2 cs = ropeH[(row & 4095) * 16 + (r32 & 15)];
;                 o = (r32 < 16) ? (v * cs.x - pv * cs.y) : (v * cs.x + pv * cs.y);
;               }
;             } else if (rope == 2) {
;               if (ni == 0) {
;                 float pv = __shfl_xor(v, 8);
;                 float2 cs = ropeD[(row & 4095) * 8 + (r32 & 7)];
;                 float rr = ((r32 & 8) == 0) ? (v * cs.x - pv * cs.y) : (v * cs.x + pv * cs.y);
;                 o = (r32 < 16) ? rr : v;
;               }
;             }
;             PR[(size_t)row * PR_LD + dcol2 + c] = f2bf(o);
;           }
.LBB0_1731:
	s_and_b64 vcc, exec, s[12:13]
	v_or_b32_e32 v80, 49, v66
	s_cbranch_vccnz .LBB0_1733
	v_cvt_pk_bf16_f32 v81, v27, s0
	v_mad_i64_i32 v[82:83], s[0:1], v80, s35, v[68:69]
	global_store_short v[82:83], v81, off

; DEV bf16_t f2bf(float f) { return (bf16_t)(cvtpk(f, 0.f) & 0xffffu); }
;   DEV void operator()(f32x16 (&acc)[2][2], int mb, int nb, int r32, int hh) const {
;     ...
; #pragma unroll
;     for (int mi = 0; mi < 2; ++mi)
; #pragma unroll
;       for (int ni = 0; ni < 2; ++ni)
; #pragma unroll
;         for (int r = 0; r < 16; ++r) {
;           int row = mb + mi * 32 + 8 * (r >> 2) + 4 * hh + (r & 3);
;           int c = wn64 + ni * 32 + r32;
;           float v = acc[mi][ni][r];
;           if (dcol >= 0) PR[(size_t)row * PR_LD + dcol + c] = f2bf(v);
;           if (dcol2 >= 0) {
;             float o = v;
;             if (rope == 1) {
;               if (wn64 == 0 && ni == 0) {
;                 float pv = __shfl_xor(v, 16);
;                 float2 cs = ropeH[(row & 4095) * 16 + (r32 & 15)];
;                 o = (r32 < 16) ? (v * cs.x - pv * cs.y) : (v * cs.x + pv * cs.y);
;               }
;             } else if (rope == 2) {
;               if (ni == 0) {
;                 float pv = __shfl_xor(v, 8);
;                 float2 cs = ropeD[(row & 4095) * 8 + (r32 & 7)];
;                 float rr = ((r32 & 8) == 0) ? (v * cs.x - pv * cs.y) : (v * cs.x + pv * cs.y);
;                 o = (r32 < 16) ? rr : v;
;               }
;             }
;             PR[(size_t)row * PR_LD + dcol2 + c] = f2bf(o);
;           }
.LBB0_1742:
	s_and_b64 vcc, exec, s[12:13]
	v_or_b32_e32 v81, 50, v66
	s_cbranch_vccnz .LBB0_1744
	v_cvt_pk_bf16_f32 v84, v28, s0
	v_mad_i64_i32 v[82:83], s[0:1], v81, s35, v[68:69]
	global_store_short v[82:83], v84, off

; DEV bf16_t f2bf(float f) { return (bf16_t)(cvtpk(f, 0.f) & 0xffffu); }
;   DEV void operator()(f32x16 (&acc)[2][2], int mb, int nb, int r32, int hh) const {
;     ...
; #pragma unroll
;     for (int mi = 0; mi < 2; ++mi)
; #pragma unroll
;       for (int ni = 0; ni < 2; ++ni)
; #pragma unroll
;         for (int r = 0; r < 16; ++r) {
;           int row = mb + mi * 32 + 8 * (r >> 2) + 4 * hh + (r & 3);
;           int c = wn64 + ni * 32 + r32;
;           float v = acc[mi][ni][r];
;           if (dcol >= 0) PR[(size_t)row * PR_LD + dcol + c] = f2bf(v);
;           if (dcol2 >= 0) {
;             float o = v;
;             if (rope == 1) {
;               if (wn64 == 0 && ni == 0) {
;                 float pv = __shfl_xor(v, 16);
;                 float2 cs = ropeH[(row & 4095) * 16 + (r32 & 15)];
;                 o = (r32 < 16) ? (v * cs.x - pv * cs.y) : (v * cs.x + pv * cs.y);
;               }
;             } else if (rope == 2) {
;               if (ni == 0) {
;                 float pv = __shfl_xor(v, 8);
;                 float2 cs = ropeD[(row & 4095) * 8 + (r32 & 7)];
;                 float rr = ((r32 & 8) == 0) ? (v * cs.x - pv * cs.y) : (v * cs.x + pv * cs.y);
;                 o = (r32 < 16) ? rr : v;
;               }
;             }
;             PR[(size_t)row * PR_LD + dcol2 + c] = f2bf(o);
;           }
.LBB0_1753:
	s_and_b64 vcc, exec, s[12:13]
	v_or_b32_e32 v82, 51, v66
	s_cbranch_vccnz .LBB0_1755
	v_cvt_pk_bf16_f32 v83, v29, s0
	v_mad_i64_i32 v[84:85], s[0:1], v82, s35, v[68:69]
	global_store_short v[84:85], v83, off

; DEV bf16_t f2bf(float f) { return (bf16_t)(cvtpk(f, 0.f) & 0xffffu); }
;   DEV void operator()(f32x16 (&acc)[2][2], int mb, int nb, int r32, int hh) const {
;     ...
; #pragma unroll
;     for (int mi = 0; mi < 2; ++mi)
; #pragma unroll
;       for (int ni = 0; ni < 2; ++ni)
; #pragma unroll
;         for (int r = 0; r < 16; ++r) {
;           int row = mb + mi * 32 + 8 * (r >> 2) + 4 * hh + (r & 3);
;           int c = wn64 + ni * 32 + r32;
;           float v = acc[mi][ni][r];
;           if (dcol >= 0) PR[(size_t)row * PR_LD + dcol + c] = f2bf(v);
;           if (dcol2 >= 0) {
;             float o = v;
;             if (rope == 1) {
;               if (wn64 == 0 && ni == 0) {
;                 float pv = __shfl_xor(v, 16);
;                 float2 cs = ropeH[(row & 4095) * 16 + (r32 & 15)];
;                 o = (r32 < 16) ? (v * cs.x - pv * cs.y) : (v * cs.x + pv * cs.y);
;               }
;             } else if (rope == 2) {
;               if (ni == 0) {
;                 float pv = __shfl_xor(v, 8);
;                 float2 cs = ropeD[(row & 4095) * 8 + (r32 & 7)];
;                 float rr = ((r32 & 8) == 0) ? (v * cs.x - pv * cs.y) : (v * cs.x + pv * cs.y);
;                 o = (r32 < 16) ? rr : v;
;               }
;             }
;             PR[(size_t)row * PR_LD + dcol2 + c] = f2bf(o);
;           }
.LBB0_1764:
	s_and_b64 vcc, exec, s[12:13]
	v_or_b32_e32 v83, 56, v66
	s_cbranch_vccnz .LBB0_1766
	v_cvt_pk_bf16_f32 v86, v30, s0
	v_mad_i64_i32 v[84:85], s[0:1], v83, s35, v[68:69]
	global_store_short v[84:85], v86, off

; DEV bf16_t f2bf(float f) { return (bf16_t)(cvtpk(f, 0.f) & 0xffffu); }
;   DEV void operator()(f32x16 (&acc)[2][2], int mb, int nb, int r32, int hh) const {
;     ...
; #pragma unroll
;     for (int mi = 0; mi < 2; ++mi)
; #pragma unroll
;       for (int ni = 0; ni < 2; ++ni)
; #pragma unroll
;         for (int r = 0; r < 16; ++r) {
;           int row = mb + mi * 32 + 8 * (r >> 2) + 4 * hh + (r & 3);
;           int c = wn64 + ni * 32 + r32;
;           float v = acc[mi][ni][r];
;           if (dcol >= 0) PR[(size_t)row * PR_LD + dcol + c] = f2bf(v);
;           if (dcol2 >= 0) {
;             float o = v;
;             if (rope == 1) {
;               if (wn64 == 0 && ni == 0) {
;                 float pv = __shfl_xor(v, 16);
;                 float2 cs = ropeH[(row & 4095) * 16 + (r32 & 15)];
;                 o = (r32 < 16) ? (v * cs.x - pv * cs.y) : (v * cs.x + pv * cs.y);
;               }
;             } else if (rope == 2) {
;               if (ni == 0) {
;                 float pv = __shfl_xor(v, 8);
;                 float2 cs = ropeD[(row & 4095) * 8 + (r32 & 7)];
;                 float rr = ((r32 & 8) == 0) ? (v * cs.x - pv * cs.y) : (v * cs.x + pv * cs.y);
;                 o = (r32 < 16) ? rr : v;
;               }
;             }
;             PR[(size_t)row * PR_LD + dcol2 + c] = f2bf(o);
;           }
.LBB0_1775:
	s_and_b64 vcc, exec, s[12:13]
	v_or_b32_e32 v84, 57, v66
	s_cbranch_vccnz .LBB0_1777
	v_cvt_pk_bf16_f32 v85, v31, s0
	v_mad_i64_i32 v[86:87], s[0:1], v84, s35, v[68:69]
	global_store_short v[86:87], v85, off

; DEV bf16_t f2bf(float f) { return (bf16_t)(cvtpk(f, 0.f) & 0xffffu); }
;   DEV void operator()(f32x16 (&acc)[2][2], int mb, int nb, int r32, int hh) const {
;     ...
; #pragma unroll
;     for (int mi = 0; mi < 2; ++mi)
; #pragma unroll
;       for (int ni = 0; ni < 2; ++ni)
; #pragma unroll
;         for (int r = 0; r < 16; ++r) {
;           int row = mb + mi * 32 + 8 * (r >> 2) + 4 * hh + (r & 3);
;           int c = wn64 + ni * 32 + r32;
;           float v = acc[mi][ni][r];
;           if (dcol >= 0) PR[(size_t)row * PR_LD + dcol + c] = f2bf(v);
;           if (dcol2 >= 0) {
;             float o = v;
;             if (rope == 1) {
;               if (wn64 == 0 && ni == 0) {
;                 float pv = __shfl_xor(v, 16);
;                 float2 cs = ropeH[(row & 4095) * 16 + (r32 & 15)];
;                 o = (r32 < 16) ? (v * cs.x - pv * cs.y) : (v * cs.x + pv * cs.y);
;               }
;             } else if (rope == 2) {
;               if (ni == 0) {
;                 float pv = __shfl_xor(v, 8);
;                 float2 cs = ropeD[(row & 4095) * 8 + (r32 & 7)];
;                 float rr = ((r32 & 8) == 0) ? (v * cs.x - pv * cs.y) : (v * cs.x + pv * cs.y);
;                 o = (r32 < 16) ? rr : v;
;               }
;             }
;             PR[(size_t)row * PR_LD + dcol2 + c] = f2bf(o);
;           }
.LBB0_1786:
	s_and_b64 vcc, exec, s[12:13]
	v_or_b32_e32 v85, 58, v66
	s_cbranch_vccnz .LBB0_1788
	v_cvt_pk_bf16_f32 v88, v32, s0
	v_mad_i64_i32 v[86:87], s[0:1], v85, s35, v[68:69]
	global_store_short v[86:87], v88, off

; DEV bf16_t f2bf(float f) { return (bf16_t)(cvtpk(f, 0.f) & 0xffffu); }
;   DEV void operator()(f32x16 (&acc)[2][2], int mb, int nb, int r32, int hh) const {
;     ...
; #pragma unroll
;     for (int mi = 0; mi < 2; ++mi)
; #pragma unroll
;       for (int ni = 0; ni < 2; ++ni)
; #pragma unroll
;         for (int r = 0; r < 16; ++r) {
;           int row = mb + mi * 32 + 8 * (r >> 2) + 4 * hh + (r & 3);
;           int c = wn64 + ni * 32 + r32;
;           float v = acc[mi][ni][r];
;           if (dcol >= 0) PR[(size_t)row * PR_LD + dcol + c] = f2bf(v);
;           if (dcol2 >= 0) {
;             float o = v;
;             if (rope == 1) {
;               if (wn64 == 0 && ni == 0) {
;                 float pv = __shfl_xor(v, 16);
;                 float2 cs = ropeH[(row & 4095) * 16 + (r32 & 15)];
;                 o = (r32 < 16) ? (v * cs.x - pv * cs.y) : (v * cs.x + pv * cs.y);
;               }
;             } else if (rope == 2) {
;               if (ni == 0) {
;                 float pv = __shfl_xor(v, 8);
;                 float2 cs = ropeD[(row & 4095) * 8 + (r32 & 7)];
;                 float rr = ((r32 & 8) == 0) ? (v * cs.x - pv * cs.y) : (v * cs.x + pv * cs.y);
;                 o = (r32 < 16) ? rr : v;
;               }
;             }
;             PR[(size_t)row * PR_LD + dcol2 + c] = f2bf(o);
;           }
.LBB0_1797:
	s_and_b64 vcc, exec, s[12:13]
	v_or_b32_e32 v86, 59, v66
	s_cbranch_vccnz .LBB0_1799
	v_cvt_pk_bf16_f32 v87, v33, s0
	v_mad_i64_i32 v[88:89], s[0:1], v86, s35, v[68:69]
	global_store_short v[88:89], v87, off

; DEV bf16_t f2bf(float f) { return (bf16_t)(cvtpk(f, 0.f) & 0xffffu); }
;   DEV void operator()(f32x16 (&acc)[2][2], int mb, int nb, int r32, int hh) const {
;     ...
; #pragma unroll
;     for (int mi = 0; mi < 2; ++mi)
; #pragma unroll
;       for (int ni = 0; ni < 2; ++ni)
; #pragma unroll
;         for (int r = 0; r < 16; ++r) {
;           int row = mb + mi * 32 + 8 * (r >> 2) + 4 * hh + (r & 3);
;           int c = wn64 + ni * 32 + r32;
;           float v = acc[mi][ni][r];
;           if (dcol >= 0) PR[(size_t)row * PR_LD + dcol + c] = f2bf(v);
;           if (dcol2 >= 0) {
;             float o = v;
;             if (rope == 1) {
;               if (wn64 == 0 && ni == 0) {
;                 float pv = __shfl_xor(v, 16);
;                 float2 cs = ropeH[(row & 4095) * 16 + (r32 & 15)];
;                 o = (r32 < 16) ? (v * cs.x - pv * cs.y) : (v * cs.x + pv * cs.y);
;               }
;             } else if (rope == 2) {
;               if (ni == 0) {
;                 float pv = __shfl_xor(v, 8);
;                 float2 cs = ropeD[(row & 4095) * 8 + (r32 & 7)];
;                 float rr = ((r32 & 8) == 0) ? (v * cs.x - pv * cs.y) : (v * cs.x + pv * cs.y);
;                 o = (r32 < 16) ? rr : v;
;               }
;             }
;             PR[(size_t)row * PR_LD + dcol2 + c] = f2bf(o);
;           }
.LBB0_1807:
	v_cvt_pk_bf16_f32 v87, v87, s0
	v_mad_i64_i32 v[88:89], s[0:1], v86, s35, v[70:71]
	global_store_short v[88:89], v87, off
.LBB0_1808:
	s_and_b64 vcc, exec, s[12:13]
	s_cbranch_vccnz .LBB0_1810
	v_cvt_pk_bf16_f32 v87, v2, s0
	v_mad_i64_i32 v[88:89], s[0:1], v67, s35, v[68:69]
	global_store_short v[88:89], v87, off offset:64
.LBB0_1810:
	s_and_b64 vcc, exec, s[14:15]
	s_cbranch_vccnz .LBB0_1812
	v_cvt_pk_bf16_f32 v87, v2, s0
	v_mad_i64_i32 v[88:89], s[0:1], v67, s35, v[70:71]
	global_store_short v[88:89], v87, off offset:64
.LBB0_1812:
	s_and_b64 vcc, exec, s[12:13]
	s_cbranch_vccnz .LBB0_1814
	v_cvt_pk_bf16_f32 v67, v3, s0
	v_mad_i64_i32 v[88:89], s[0:1], v72, s35, v[68:69]
	global_store_short v[88:89], v67, off offset:64
.LBB0_1814:
	s_and_b64 vcc, exec, s[14:15]
	s_cbranch_vccnz .LBB0_1816
	v_cvt_pk_bf16_f32 v67, v3, s0
	v_mad_i64_i32 v[88:89], s[0:1], v72, s35, v[70:71]
	global_store_short v[88:89], v67, off offset:64
.LBB0_1816:
	s_and_b64 vcc, exec, s[12:13]
	s_cbranch_vccnz .LBB0_1818
	v_cvt_pk_bf16_f32 v67, v4, s0
	v_mad_i64_i32 v[88:89], s[0:1], v73, s35, v[68:69]
	global_store_short v[88:89], v67, off offset:64
.LBB0_1818:
	s_and_b64 vcc, exec, s[14:15]
	s_cbranch_vccnz .LBB0_1820
	v_cvt_pk_bf16_f32 v67, v4, s0
	v_mad_i64_i32 v[72:73], s[0:1], v73, s35, v[70:71]
	global_store_short v[72:73], v67, off offset:64
.LBB0_1820:
	s_and_b64 vcc, exec, s[12:13]
	s_cbranch_vccnz .LBB0_1822
	v_cvt_pk_bf16_f32 v67, v5, s0
	v_mad_i64_i32 v[72:73], s[0:1], v74, s35, v[68:69]
	global_store_short v[72:73], v67, off offset:64
.LBB0_1822:
	s_and_b64 vcc, exec, s[14:15]
	s_cbranch_vccnz .LBB0_1824
	v_cvt_pk_bf16_f32 v67, v5, s0
	v_mad_i64_i32 v[72:73], s[0:1], v74, s35, v[70:71]
	global_store_short v[72:73], v67, off offset:64
.LBB0_1824:
	s_and_b64 vcc, exec, s[12:13]
	s_cbranch_vccnz .LBB0_1826
	v_cvt_pk_bf16_f32 v67, v6, s0
	v_mad_i64_i32 v[72:73], s[0:1], v75, s35, v[68:69]
	global_store_short v[72:73], v67, off offset:64
.LBB0_1826:
	s_and_b64 vcc, exec, s[14:15]
	s_cbranch_vccnz .LBB0_1828
	v_cvt_pk_bf16_f32 v67, v6, s0
	v_mad_i64_i32 v[72:73], s[0:1], v75, s35, v[70:71]
	global_store_short v[72:73], v67, off offset:64
.LBB0_1828:
	s_and_b64 vcc, exec, s[12:13]
	s_cbranch_vccnz .LBB0_1830
	v_cvt_pk_bf16_f32 v67, v7, s0
	v_mad_i64_i32 v[72:73], s[0:1], v76, s35, v[68:69]
	global_store_short v[72:73], v67, off offset:64
.LBB0_1830:
	s_and_b64 vcc, exec, s[14:15]
	s_cbranch_vccnz .LBB0_1832
	v_cvt_pk_bf16_f32 v67, v7, s0
	v_mad_i64_i32 v[72:73], s[0:1], v76, s35, v[70:71]
	global_store_short v[72:73], v67, off offset:64
.LBB0_1832:
	s_and_b64 vcc, exec, s[12:13]
	s_cbranch_vccnz .LBB0_1834
	v_cvt_pk_bf16_f32 v67, v8, s0
	v_mad_i64_i32 v[72:73], s[0:1], v77, s35, v[68:69]
	global_store_short v[72:73], v67, off offset:64
.LBB0_1834:
	s_and_b64 vcc, exec, s[14:15]
	s_cbranch_vccnz .LBB0_1836
	v_cvt_pk_bf16_f32 v67, v8, s0
	v_mad_i64_i32 v[72:73], s[0:1], v77, s35, v[70:71]
	global_store_short v[72:73], v67, off offset:64
.LBB0_1836:
	s_and_b64 vcc, exec, s[12:13]
	s_cbranch_vccnz .LBB0_1838
	v_cvt_pk_bf16_f32 v67, v9, s0
	v_mad_i64_i32 v[72:73], s[0:1], v78, s35, v[68:69]
	global_store_short v[72:73], v67, off offset:64
.LBB0_1838:
	s_and_b64 vcc, exec, s[14:15]
	s_cbranch_vccnz .LBB0_1840
	v_cvt_pk_bf16_f32 v67, v9, s0
	v_mad_i64_i32 v[72:73], s[0:1], v78, s35, v[70:71]
	global_store_short v[72:73], v67, off offset:64
.LBB0_1840:
	s_and_b64 vcc, exec, s[12:13]
	s_cbranch_vccnz .LBB0_1842
	v_cvt_pk_bf16_f32 v67, v10, s0
	v_mad_i64_i32 v[72:73], s[0:1], v79, s35, v[68:69]
	global_store_short v[72:73], v67, off offset:64
.LBB0_1842:
	s_and_b64 vcc, exec, s[14:15]
	s_cbranch_vccnz .LBB0_1844
	v_cvt_pk_bf16_f32 v67, v10, s0
	v_mad_i64_i32 v[72:73], s[0:1], v79, s35, v[70:71]
	global_store_short v[72:73], v67, off offset:64
.LBB0_1844:
	s_and_b64 vcc, exec, s[12:13]
	s_cbranch_vccnz .LBB0_1846
	v_cvt_pk_bf16_f32 v67, v11, s0
	v_mad_i64_i32 v[72:73], s[0:1], v80, s35, v[68:69]
	global_store_short v[72:73], v67, off offset:64
.LBB0_1846:
	s_and_b64 vcc, exec, s[14:15]
	s_cbranch_vccnz .LBB0_1848
	v_cvt_pk_bf16_f32 v67, v11, s0
	v_mad_i64_i32 v[72:73], s[0:1], v80, s35, v[70:71]
	global_store_short v[72:73], v67, off offset:64
.LBB0_1848:
	s_and_b64 vcc, exec, s[12:13]
	s_cbranch_vccnz .LBB0_1850
	v_cvt_pk_bf16_f32 v67, v12, s0
	v_mad_i64_i32 v[72:73], s[0:1], v81, s35, v[68:69]
	global_store_short v[72:73], v67, off offset:64
.LBB0_1850:
	s_and_b64 vcc, exec, s[14:15]
	s_cbranch_vccnz .LBB0_1852
	v_cvt_pk_bf16_f32 v67, v12, s0
	v_mad_i64_i32 v[72:73], s[0:1], v81, s35, v[70:71]
	global_store_short v[72:73], v67, off offset:64
.LBB0_1852:
	s_and_b64 vcc, exec, s[12:13]
	s_cbranch_vccnz .LBB0_1854
	v_cvt_pk_bf16_f32 v67, v13, s0
	v_mad_i64_i32 v[72:73], s[0:1], v82, s35, v[68:69]
	global_store_short v[72:73], v67, off offset:64
.LBB0_1854:
	s_and_b64 vcc, exec, s[14:15]
	s_cbranch_vccnz .LBB0_1856
	v_cvt_pk_bf16_f32 v67, v13, s0
	v_mad_i64_i32 v[72:73], s[0:1], v82, s35, v[70:71]
	global_store_short v[72:73], v67, off offset:64
.LBB0_1856:
	s_and_b64 vcc, exec, s[12:13]
	s_cbranch_vccnz .LBB0_1858
	v_cvt_pk_bf16_f32 v67, v14, s0
	v_mad_i64_i32 v[72:73], s[0:1], v83, s35, v[68:69]
	global_store_short v[72:73], v67, off offset:64
.LBB0_1858:
	s_and_b64 vcc, exec, s[14:15]
	s_cbranch_vccnz .LBB0_1860
	v_cvt_pk_bf16_f32 v67, v14, s0
	v_mad_i64_i32 v[72:73], s[0:1], v83, s35, v[70:71]
	global_store_short v[72:73], v67, off offset:64
.LBB0_1860:
	s_and_b64 vcc, exec, s[12:13]
	s_cbranch_vccnz .LBB0_1862
	v_cvt_pk_bf16_f32 v67, v15, s0
	v_mad_i64_i32 v[72:73], s[0:1], v84, s35, v[68:69]
	global_store_short v[72:73], v67, off offset:64
.LBB0_1862:
	s_and_b64 vcc, exec, s[14:15]
	s_cbranch_vccnz .LBB0_1864
	v_cvt_pk_bf16_f32 v67, v15, s0
	v_mad_i64_i32 v[72:73], s[0:1], v84, s35, v[70:71]
	global_store_short v[72:73], v67, off offset:64
.LBB0_1864:
	s_and_b64 vcc, exec, s[12:13]
	s_cbranch_vccnz .LBB0_1866
	v_cvt_pk_bf16_f32 v67, v16, s0
	v_mad_i64_i32 v[72:73], s[0:1], v85, s35, v[68:69]
	global_store_short v[72:73], v67, off offset:64
.LBB0_1866:
	s_and_b64 vcc, exec, s[14:15]
	s_cbranch_vccnz .LBB0_1868
	v_cvt_pk_bf16_f32 v67, v16, s0
	v_mad_i64_i32 v[72:73], s[0:1], v85, s35, v[70:71]
	global_store_short v[72:73], v67, off offset:64
.LBB0_1868:
	s_and_b64 vcc, exec, s[12:13]
	s_cbranch_vccnz .LBB0_1870
	v_cvt_pk_bf16_f32 v67, v17, s0
	v_mad_i64_i32 v[68:69], s[0:1], v86, s35, v[68:69]
	global_store_short v[68:69], v67, off offset:64
.LBB0_1870:
	s_and_b64 vcc, exec, s[14:15]
	s_cbranch_vccnz .LBB0_1872
	v_cvt_pk_bf16_f32 v67, v17, s0
	v_mad_i64_i32 v[68:69], s[0:1], v86, s35, v[70:71]
	global_store_short v[68:69], v67, off offset:64

; DEV bf16_t f2bf(float f) { return (bf16_t)(cvtpk(f, 0.f) & 0xffffu); }
;   DEV void operator()(f32x16 (&acc)[2][2], int mb, int nb, int r32, int hh) const {
;     ...
;     if (kind == 1) {
; #pragma unroll
;       for (int mi = 0; mi < 2; ++mi)
; #pragma unroll
;         for (int ni = 0; ni < 2; ++ni)
; #pragma unroll
;           for (int r = 0; r < 16; ++r) {
;             int row = mb + mi * 32 + 8 * (r >> 2) + 4 * hh + (r & 3);
;             cbuf[(size_t)row * 128 + wn64 + ni * 32 + r32] = f2bf(acc[mi][ni][r]);
;           }
;       return;
.LBB0_1873:
	s_and_b64 vcc, exec, s[0:1]
	s_cbranch_vccz .LBB0_1875
	s_lshl_b32 s0, s61, 1
	s_add_u32 s0, s18, s0
	s_addc_u32 s1, s19, 0
	v_ashrrev_i32_e32 v67, 31, v66
	v_lshl_add_u64 v[68:69], v[152:153], 1, s[0:1]
	v_lshlrev_b64 v[70:71], 8, v[66:67]
	v_cvt_pk_bf16_f32 v72, v50, s0
	v_lshl_add_u64 v[70:71], v[68:69], 0, v[70:71]
	global_store_short v[70:71], v72, off
	v_or_b32_e32 v72, 1, v66
	v_ashrrev_i32_e32 v73, 31, v72
	v_or_b32_e32 v74, 2, v66
	v_lshlrev_b64 v[72:73], 8, v[72:73]
	v_ashrrev_i32_e32 v75, 31, v74
	v_or_b32_e32 v76, 3, v66
	v_cvt_pk_bf16_f32 v67, v51, s0
	v_lshl_add_u64 v[72:73], v[68:69], 0, v[72:73]
	v_lshlrev_b64 v[74:75], 8, v[74:75]
	v_ashrrev_i32_e32 v77, 31, v76
	v_or_b32_e32 v78, 8, v66
	global_store_short v[72:73], v67, off
	v_cvt_pk_bf16_f32 v67, v52, s0
	v_lshl_add_u64 v[74:75], v[68:69], 0, v[74:75]
	v_lshlrev_b64 v[76:77], 8, v[76:77]
	v_ashrrev_i32_e32 v79, 31, v78
	v_or_b32_e32 v80, 9, v66
	global_store_short v[74:75], v67, off
	v_cvt_pk_bf16_f32 v67, v53, s0
	v_lshl_add_u64 v[76:77], v[68:69], 0, v[76:77]
	v_lshlrev_b64 v[78:79], 8, v[78:79]
	v_ashrrev_i32_e32 v81, 31, v80
	v_or_b32_e32 v82, 10, v66
	global_store_short v[76:77], v67, off
	v_cvt_pk_bf16_f32 v67, v54, s0
	v_lshl_add_u64 v[78:79], v[68:69], 0, v[78:79]
	v_lshlrev_b64 v[80:81], 8, v[80:81]
	v_ashrrev_i32_e32 v83, 31, v82
	v_or_b32_e32 v84, 11, v66
	global_store_short v[78:79], v67, off
	v_cvt_pk_bf16_f32 v67, v55, s0
	v_lshl_add_u64 v[80:81], v[68:69], 0, v[80:81]
	v_lshlrev_b64 v[82:83], 8, v[82:83]
	v_ashrrev_i32_e32 v85, 31, v84
	v_or_b32_e32 v86, 16, v66
	global_store_short v[80:81], v67, off
	v_cvt_pk_bf16_f32 v67, v56, s0
	v_lshl_add_u64 v[82:83], v[68:69], 0, v[82:83]
	v_lshlrev_b64 v[84:85], 8, v[84:85]
	v_ashrrev_i32_e32 v87, 31, v86
	v_or_b32_e32 v88, 17, v66
	global_store_short v[82:83], v67, off
	v_cvt_pk_bf16_f32 v67, v57, s0
	v_lshl_add_u64 v[84:85], v[68:69], 0, v[84:85]
	v_lshlrev_b64 v[86:87], 8, v[86:87]
	v_ashrrev_i32_e32 v89, 31, v88
	v_or_b32_e32 v90, 18, v66
	global_store_short v[84:85], v67, off
	v_cvt_pk_bf16_f32 v67, v58, s0
	v_lshl_add_u64 v[86:87], v[68:69], 0, v[86:87]
	v_lshlrev_b64 v[88:89], 8, v[88:89]
	v_ashrrev_i32_e32 v91, 31, v90
	v_or_b32_e32 v92, 19, v66
	global_store_short v[86:87], v67, off
	v_cvt_pk_bf16_f32 v67, v59, s0
	v_lshl_add_u64 v[88:89], v[68:69], 0, v[88:89]
	v_lshlrev_b64 v[90:91], 8, v[90:91]
	v_ashrrev_i32_e32 v93, 31, v92
	v_or_b32_e32 v94, 24, v66
	global_store_short v[88:89], v67, off
	v_cvt_pk_bf16_f32 v67, v60, s0
	v_lshl_add_u64 v[90:91], v[68:69], 0, v[90:91]
	v_lshlrev_b64 v[92:93], 8, v[92:93]
	v_ashrrev_i32_e32 v95, 31, v94
	v_or_b32_e32 v96, 25, v66
	global_store_short v[90:91], v67, off
	v_cvt_pk_bf16_f32 v67, v61, s0
	v_lshl_add_u64 v[92:93], v[68:69], 0, v[92:93]
	v_lshlrev_b64 v[94:95], 8, v[94:95]
	v_ashrrev_i32_e32 v97, 31, v96
	v_or_b32_e32 v98, 26, v66
	global_store_short v[92:93], v67, off
	v_cvt_pk_bf16_f32 v67, v62, s0
	v_lshl_add_u64 v[94:95], v[68:69], 0, v[94:95]
	v_lshlrev_b64 v[96:97], 8, v[96:97]
	v_ashrrev_i32_e32 v99, 31, v98
	v_or_b32_e32 v100, 27, v66
	global_store_short v[94:95], v67, off
	v_cvt_pk_bf16_f32 v67, v63, s0
	v_lshl_add_u64 v[96:97], v[68:69], 0, v[96:97]
	v_lshlrev_b64 v[98:99], 8, v[98:99]
	v_ashrrev_i32_e32 v101, 31, v100
	global_store_short v[96:97], v67, off
	v_cvt_pk_bf16_f32 v67, v64, s0
	v_lshl_add_u64 v[98:99], v[68:69], 0, v[98:99]
	v_lshlrev_b64 v[100:101], 8, v[100:101]
	global_store_short v[98:99], v67, off
	v_cvt_pk_bf16_f32 v67, v65, s0
	v_lshl_add_u64 v[100:101], v[68:69], 0, v[100:101]
	global_store_short v[100:101], v67, off
	v_cvt_pk_bf16_f32 v67, v34, s0
	global_store_short v[70:71], v67, off offset:64
	v_cvt_pk_bf16_f32 v67, v35, s0
	global_store_short v[72:73], v67, off offset:64
	v_cvt_pk_bf16_f32 v67, v36, s0
	global_store_short v[74:75], v67, off offset:64
	v_cvt_pk_bf16_f32 v67, v37, s0
	global_store_short v[76:77], v67, off offset:64
	v_cvt_pk_bf16_f32 v67, v38, s0
	global_store_short v[78:79], v67, off offset:64
	v_cvt_pk_bf16_f32 v67, v39, s0
	global_store_short v[80:81], v67, off offset:64
	v_cvt_pk_bf16_f32 v67, v40, s0
	global_store_short v[82:83], v67, off offset:64
	v_cvt_pk_bf16_f32 v67, v41, s0
	global_store_short v[84:85], v67, off offset:64
	v_cvt_pk_bf16_f32 v67, v42, s0
	global_store_short v[86:87], v67, off offset:64
	v_cvt_pk_bf16_f32 v67, v43, s0
	global_store_short v[88:89], v67, off offset:64
	v_cvt_pk_bf16_f32 v67, v44, s0
	global_store_short v[90:91], v67, off offset:64
	v_cvt_pk_bf16_f32 v67, v45, s0
	global_store_short v[92:93], v67, off offset:64
	v_cvt_pk_bf16_f32 v67, v46, s0
	global_store_short v[94:95], v67, off offset:64
	v_cvt_pk_bf16_f32 v67, v47, s0
	v_or_b32_e32 v70, 32, v66
	global_store_short v[96:97], v67, off offset:64
	v_cvt_pk_bf16_f32 v67, v48, s0
	v_ashrrev_i32_e32 v71, 31, v70
; DEV bf16_t f2bf(float f) { return (bf16_t)(cvtpk(f, 0.f) & 0xffffu); }
;   DEV void operator()(f32x16 (&acc)[2][2], int mb, int nb, int r32, int hh) const {
;     ...
;     if (kind == 1) {
; #pragma unroll
;       for (int mi = 0; mi < 2; ++mi)
; #pragma unroll
;         for (int ni = 0; ni < 2; ++ni)
; #pragma unroll
;           for (int r = 0; r < 16; ++r) {
;             int row = mb + mi * 32 + 8 * (r >> 2) + 4 * hh + (r & 3);
;             cbuf[(size_t)row * 128 + wn64 + ni * 32 + r32] = f2bf(acc[mi][ni][r]);
;           }
;       return;
	v_or_b32_e32 v72, 33, v66
	global_store_short v[98:99], v67, off offset:64
	v_cvt_pk_bf16_f32 v67, v49, s0
	v_lshlrev_b64 v[70:71], 8, v[70:71]
	v_ashrrev_i32_e32 v73, 31, v72
	v_or_b32_e32 v74, 34, v66
	global_store_short v[100:101], v67, off offset:64
	v_cvt_pk_bf16_f32 v67, v18, s0
	v_lshl_add_u64 v[70:71], v[68:69], 0, v[70:71]
	v_lshlrev_b64 v[72:73], 8, v[72:73]
	v_ashrrev_i32_e32 v75, 31, v74
	v_or_b32_e32 v76, 35, v66
	global_store_short v[70:71], v67, off
	v_cvt_pk_bf16_f32 v67, v19, s0
	v_lshl_add_u64 v[72:73], v[68:69], 0, v[72:73]
	v_lshlrev_b64 v[74:75], 8, v[74:75]
	v_ashrrev_i32_e32 v77, 31, v76
	v_or_b32_e32 v78, 40, v66
	global_store_short v[72:73], v67, off
	v_cvt_pk_bf16_f32 v67, v20, s0
	v_lshl_add_u64 v[74:75], v[68:69], 0, v[74:75]
	v_lshlrev_b64 v[76:77], 8, v[76:77]
	v_ashrrev_i32_e32 v79, 31, v78
	v_or_b32_e32 v80, 41, v66
	global_store_short v[74:75], v67, off
	v_cvt_pk_bf16_f32 v67, v21, s0
	v_lshl_add_u64 v[76:77], v[68:69], 0, v[76:77]
	v_lshlrev_b64 v[78:79], 8, v[78:79]
	v_ashrrev_i32_e32 v81, 31, v80
	v_or_b32_e32 v82, 42, v66
	global_store_short v[76:77], v67, off
	v_cvt_pk_bf16_f32 v67, v22, s0
	v_lshl_add_u64 v[78:79], v[68:69], 0, v[78:79]
	v_lshlrev_b64 v[80:81], 8, v[80:81]
	v_ashrrev_i32_e32 v83, 31, v82
	v_or_b32_e32 v84, 43, v66
	global_store_short v[78:79], v67, off
	v_cvt_pk_bf16_f32 v67, v23, s0
	v_lshl_add_u64 v[80:81], v[68:69], 0, v[80:81]
	v_lshlrev_b64 v[82:83], 8, v[82:83]
	v_ashrrev_i32_e32 v85, 31, v84
	v_or_b32_e32 v86, 48, v66
	global_store_short v[80:81], v67, off
	v_cvt_pk_bf16_f32 v67, v24, s0
	v_lshl_add_u64 v[82:83], v[68:69], 0, v[82:83]
	v_lshlrev_b64 v[84:85], 8, v[84:85]
	v_ashrrev_i32_e32 v87, 31, v86
	v_or_b32_e32 v88, 49, v66
	global_store_short v[82:83], v67, off
	v_cvt_pk_bf16_f32 v67, v25, s0
	v_lshl_add_u64 v[84:85], v[68:69], 0, v[84:85]
	v_lshlrev_b64 v[86:87], 8, v[86:87]
	v_ashrrev_i32_e32 v89, 31, v88
	v_or_b32_e32 v90, 50, v66
	global_store_short v[84:85], v67, off
	v_cvt_pk_bf16_f32 v67, v26, s0
	v_lshl_add_u64 v[86:87], v[68:69], 0, v[86:87]
	v_lshlrev_b64 v[88:89], 8, v[88:89]
	v_ashrrev_i32_e32 v91, 31, v90
	v_or_b32_e32 v92, 51, v66
	global_store_short v[86:87], v67, off
	v_cvt_pk_bf16_f32 v67, v27, s0
	v_lshl_add_u64 v[88:89], v[68:69], 0, v[88:89]
	v_lshlrev_b64 v[90:91], 8, v[90:91]
	v_ashrrev_i32_e32 v93, 31, v92
	v_or_b32_e32 v94, 56, v66
	global_store_short v[88:89], v67, off
	v_cvt_pk_bf16_f32 v67, v28, s0
	v_lshl_add_u64 v[90:91], v[68:69], 0, v[90:91]
	v_lshlrev_b64 v[92:93], 8, v[92:93]
	v_ashrrev_i32_e32 v95, 31, v94
	v_or_b32_e32 v96, 57, v66
	global_store_short v[90:91], v67, off
	v_cvt_pk_bf16_f32 v67, v29, s0
	v_lshl_add_u64 v[92:93], v[68:69], 0, v[92:93]
	v_lshlrev_b64 v[94:95], 8, v[94:95]
	v_ashrrev_i32_e32 v97, 31, v96
	v_or_b32_e32 v98, 58, v66
	global_store_short v[92:93], v67, off
	v_cvt_pk_bf16_f32 v67, v30, s0
	v_lshl_add_u64 v[94:95], v[68:69], 0, v[94:95]
	v_lshlrev_b64 v[96:97], 8, v[96:97]
	v_ashrrev_i32_e32 v99, 31, v98
	global_store_short v[94:95], v67, off
	v_cvt_pk_bf16_f32 v67, v31, s0
	v_lshl_add_u64 v[96:97], v[68:69], 0, v[96:97]
	v_lshlrev_b64 v[98:99], 8, v[98:99]
	global_store_short v[96:97], v67, off
	v_cvt_pk_bf16_f32 v67, v32, s0
	v_lshl_add_u64 v[98:99], v[68:69], 0, v[98:99]
	v_or_b32_e32 v66, 59, v66
	global_store_short v[98:99], v67, off
	v_ashrrev_i32_e32 v67, 31, v66
	v_lshlrev_b64 v[66:67], 8, v[66:67]
	v_lshl_add_u64 v[66:67], v[68:69], 0, v[66:67]
	v_cvt_pk_bf16_f32 v68, v2, s0
	global_store_short v[70:71], v68, off offset:64
	v_cvt_pk_bf16_f32 v68, v3, s0
	global_store_short v[72:73], v68, off offset:64
	v_cvt_pk_bf16_f32 v68, v4, s0
	global_store_short v[74:75], v68, off offset:64
	v_cvt_pk_bf16_f32 v68, v5, s0
	global_store_short v[76:77], v68, off offset:64
	v_cvt_pk_bf16_f32 v68, v6, s0
	global_store_short v[78:79], v68, off offset:64
	v_cvt_pk_bf16_f32 v68, v7, s0
	global_store_short v[80:81], v68, off offset:64
	v_cvt_pk_bf16_f32 v68, v8, s0
	global_store_short v[82:83], v68, off offset:64
	v_cvt_pk_bf16_f32 v68, v9, s0
	global_store_short v[84:85], v68, off offset:64
	v_cvt_pk_bf16_f32 v68, v10, s0
	global_store_short v[86:87], v68, off offset:64
	v_cvt_pk_bf16_f32 v68, v11, s0
	global_store_short v[88:89], v68, off offset:64
	v_cvt_pk_bf16_f32 v68, v12, s0
	global_store_short v[90:91], v68, off offset:64
	v_cvt_pk_bf16_f32 v68, v13, s0
	global_store_short v[92:93], v68, off offset:64
	v_cvt_pk_bf16_f32 v68, v14, s0
	global_store_short v[94:95], v68, off offset:64
	v_cvt_pk_bf16_f32 v68, v15, s0
	global_store_short v[96:97], v68, off offset:64
	v_cvt_pk_bf16_f32 v68, v16, s0
	v_cvt_pk_bf16_f32 v100, v33, s0
	global_store_short v[98:99], v68, off offset:64
	v_cvt_pk_bf16_f32 v68, v17, s0
	global_store_short v[66:67], v100, off
	global_store_short v[66:67], v68, off offset:64

; __global__ void __launch_bounds__(256, 2) mega(Params p, int ph0, int ph1, int coop) {
;   __shared__ __attribute__((aligned(16))) char lds[LDS_BYTES];
	.amdhsa_kernel _Z4mega6Paramsiii
		.amdhsa_group_segment_fixed_size 73744
		.amdhsa_private_segment_fixed_size 0
		.amdhsa_kernarg_size 448
		.amdhsa_user_sgpr_count 2
		.amdhsa_user_sgpr_dispatch_ptr 0
		.amdhsa_user_sgpr_queue_ptr 0
		.amdhsa_user_sgpr_kernarg_segment_ptr 1
		.amdhsa_user_sgpr_dispatch_id 0
		.amdhsa_user_sgpr_kernarg_preload_length 0
		.amdhsa_user_sgpr_kernarg_preload_offset 0
		.amdhsa_user_sgpr_private_segment_size 0
		.amdhsa_uses_dynamic_stack 0
		.amdhsa_enable_private_segment 0
		.amdhsa_system_sgpr_workgroup_id_x 1
		.amdhsa_system_sgpr_workgroup_id_y 0
		.amdhsa_system_sgpr_workgroup_id_z 0
		.amdhsa_system_sgpr_workgroup_info 0
		.amdhsa_system_vgpr_workitem_id 2
		.amdhsa_next_free_vgpr 256
		.amdhsa_next_free_sgpr 100
		.amdhsa_accum_offset 256
		.amdhsa_reserve_vcc 1
		.amdhsa_float_round_mode_32 0
		.amdhsa_float_round_mode_16_64 0
		.amdhsa_float_denorm_mode_32 3
		.amdhsa_float_denorm_mode_16_64 3
		.amdhsa_dx10_clamp 1
		.amdhsa_ieee_mode 1
		.amdhsa_fp16_overflow 0
		.amdhsa_tg_split 0
		.amdhsa_exception_fp_ieee_invalid_op 0
		.amdhsa_exception_fp_denorm_src 0
		.amdhsa_exception_fp_ieee_div_zero 0
		.amdhsa_exception_fp_ieee_overflow 0
		.amdhsa_exception_fp_ieee_underflow 0
		.amdhsa_exception_fp_ieee_inexact 0
		.amdhsa_exception_int_div_zero 0
	.end_amdhsa_kernel

; __global__ void __launch_bounds__(256, 2) mega(Params p, int ph0, int ph1, int coop) {
;   __shared__ __attribute__((aligned(16))) char lds[LDS_BYTES];
amdhsa.kernels:
  - .agpr_count:     0
    .args:
      - .offset:         0
        .size:           176
        .value_kind:     by_value
      - .offset:         176
        .size:           4
        .value_kind:     by_value
      - .offset:         180
        .size:           4
        .value_kind:     by_value
      - .offset:         184
        .size:           4
        .value_kind:     by_value
      - .offset:         192
        .size:           4
        .value_kind:     hidden_block_count_x
      - .offset:         196
        .size:           4
        .value_kind:     hidden_block_count_y
      - .offset:         200
        .size:           4
        .value_kind:     hidden_block_count_z
      - .offset:         204
        .size:           2
        .value_kind:     hidden_group_size_x
      - .offset:         206
        .size:           2
        .value_kind:     hidden_group_size_y
      - .offset:         208
        .size:           2
        .value_kind:     hidden_group_size_z
      - .offset:         210
        .size:           2
        .value_kind:     hidden_remainder_x
      - .offset:         212
        .size:           2
        .value_kind:     hidden_remainder_y
      - .offset:         214
        .size:           2
        .value_kind:     hidden_remainder_z
      - .offset:         232
        .size:           8
        .value_kind:     hidden_global_offset_x
      - .offset:         240
        .size:           8
        .value_kind:     hidden_global_offset_y
      - .offset:         248
        .size:           8
        .value_kind:     hidden_global_offset_z
      - .offset:         256
        .size:           2
        .value_kind:     hidden_grid_dims
      - .offset:         280
        .size:           8
        .value_kind:     hidden_multigrid_sync_arg
    .group_segment_fixed_size: 73744
    .kernarg_segment_align: 8
    .kernarg_segment_size: 448
    .language:       OpenCL C
    .language_version:
      - 2
      - 0
    .max_flat_workgroup_size: 256
    .name:           _Z4mega6Paramsiii
    .private_segment_fixed_size: 0
    .sgpr_count:     106
    .sgpr_spill_count: 124
    .symbol:         _Z4mega6Paramsiii.kd
    .uniform_work_group_size: 1
    .uses_dynamic_stack: false
    .vgpr_count:     256
    .vgpr_spill_count: 0
    .wavefront_size: 64
